# v10_lru_m1_counted_waits
# baseline (speedup 1.0000x reference)
; __device__ __forceinline__ void ld8bf(const bf16_t* p, float (&o)[8]) { unpack8(*(const u32x4*)p, o); }
; __device__ __forceinline__ const float* in_ptr(const Args& a, int i) { asm volatile("" : "+s"(i)); return a.in[i]; }
; __device__ __forceinline__ void w_lru_m1(const Args& a, int l, unsigned char* ws, const bf16_t* proj, bf16_t* y, LAS unsigned char* wl, int b, int ck_, int h, int lane) {
;     ...
;     const float* cw = in_ptr(a, I_LCW) + (size_t)l * 4 * 512; const float* cbias = in_ptr(a, I_LCB) + l * 512;
;     const bf16_t* gwt = (const bf16_t*)(ws + WS_GATE) + (size_t)l * 65536;
;     const bf16_t* waT = gwt + h * 4096; const bf16_t* wxT = gwt + 32768 + h * 4096;
;     const float* ba = in_ptr(a, I_BA) + l * 512 + 64 * h; const float* bx = in_ptr(a, I_BX) + l * 512 + 64 * h; const float* lam = in_ptr(a, I_LAM) + l * 512 + 64 * h;
;     bf16x8 nWa[2], nWx[2]; f32x4 nba, nbx, nlam;
; #pragma unroll
;     for (int kk = 0; kk < 2; ++kk) { nWa[kk] = *(const bf16x8*)(waT + lo * 64 + 32 * kk + 8 * fq); nWx[kk] = *(const bf16x8*)(wxT + lo * 64 + 32 * kk + 8 * fq); }
;     nba = *(const f32x4*)(ba + 4 * fq); nbx = *(const f32x4*)(bx + 4 * fq); nlam = *(const f32x4*)(lam + 4 * fq);
;     bf16x8 Xf[4][2];
; #pragma unroll
;     for (int kk = 0; kk < 2; ++kk) { const int ch0 = 64 * h + 32 * kk + 8 * fq; float w[4][8], bs[8];
; #pragma unroll
;         for (int j = 0; j < 8; ++j) { bs[j] = cbias[ch0 + j];
; #pragma unroll
;             for (int k = 0; k < 4; ++k) w[k][j] = cw[k * 512 + ch0 + j]; }
; #pragma unroll
;         for (int tb = 0; tb < 4; ++tb) { const int tok = 16 * tb + lo, t = 64 * ck_ + tok; float s[8];
; #pragma unroll
;             for (int j = 0; j < 8; ++j) s[j] = bs[j];
; #pragma unroll
;             for (int k = 0; k < 4; ++k) { const int tt = t - 3 + k; float x[8];
;                 ld8bf(proj + (size_t)(b * SEQ + (tt >= 0 ? tt : 0)) * NIN + C_LX + ch0, x);
; #pragma unroll
;                 for (int j = 0; j < 8; ++j) s[j] += (tt >= 0 ? w[k][j] : 0.f) * x[j]; }
.LBB0_520:
	s_lshr_b32 s20, s24, 8
	s_lshr_b32 s21, s24, 9
	s_add_i32 s20, s20, s24
	s_and_b32 s21, s21, 12
	s_add_i32 s20, s20, s21
	s_and_b32 s91, s20, 15
	s_cmp_gt_u32 s91, 7
	s_cbranch_scc1 .LBB0_519
	s_ashr_i32 s20, s24, 31
	s_ashr_i32 s90, s24, 4
	s_lshr_b32 s20, s20, 25
	s_add_i32 s27, s90, s20
	s_and_b32 s20, s27, 0xffffff80
	v_mov_b32_e32 v122, v144
	s_mov_b32 s34, 3
	s_sub_i32 s46, s90, s20
	s_ashr_i32 s35, s34, 31
	s_lshl_b32 s20, s46, 6
	s_lshl_b64 s[34:35], s[34:35], 3
	s_add_u32 s34, s0, s34
	s_addc_u32 s35, s1, s35
	s_load_dwordx2 s[40:41], s[34:35], 0x0
	s_mov_b32 s34, 4
	s_ashr_i32 s35, s34, 31
	s_lshl_b64 s[34:35], s[34:35], 3
	s_add_u32 s34, s0, s34
	s_addc_u32 s35, s1, s35
	s_lshl_b32 s21, s91, 13
	s_add_u32 s92, s2, s21
	s_addc_u32 s93, s3, 0
	s_load_dwordx2 s[42:43], s[34:35], 0x0
	s_add_u32 s34, s68, s21
	s_mov_b32 s44, 6
	s_addc_u32 s35, s70, 0
	s_ashr_i32 s45, s44, 31
	s_lshl_b64 s[44:45], s[44:45], 3
	s_add_u32 s44, s0, s44
	s_addc_u32 s45, s1, s45
	s_waitcnt lgkmcnt(0)
	s_mov_b32 s48, 8
	s_load_dwordx2 s[44:45], s[44:45], 0x0
	s_ashr_i32 s49, s48, 31
	s_lshl_b32 s21, s91, 6
	s_lshl_b64 s[48:49], s[48:49], 3
	s_add_u32 s48, s0, s48
	s_addc_u32 s49, s1, s49
	s_load_dwordx2 s[48:49], s[48:49], 0x0
	v_ashrrev_i32_e32 v8, 4, v122
	v_and_b32_e32 v136, 15, v122
	v_lshlrev_b32_e32 v4, 3, v8
	v_lshlrev_b32_e32 v2, 7, v136
	s_waitcnt lgkmcnt(0)
	s_add_u32 s47, s48, s88
	s_mov_b32 s48, 9
	s_addc_u32 s50, s49, s89
	s_ashr_i32 s49, s48, 31
	s_lshl_b64 s[48:49], s[48:49], 3
	s_add_u32 s48, s0, s48
	s_addc_u32 s49, s1, s49
	s_load_dwordx2 s[48:49], s[48:49], 0x0
	v_ashrrev_i32_e32 v5, 31, v4
	v_lshl_add_u64 v[0:1], s[92:93], 0, v[2:3]
	v_lshlrev_b64 v[100:101], 1, v[4:5]
	v_lshl_add_u64 v[0:1], v[0:1], 0, v[100:101]
	s_waitcnt lgkmcnt(0)
	s_add_u32 s51, s48, s88
	s_addc_u32 s52, s49, s89
	s_lshl_b32 s27, s27, 6
	s_and_b32 s27, s27, 0xffffe000
	s_add_u32 s48, s40, s96
	s_addc_u32 s49, s41, s97
	s_add_u32 s42, s42, s88
	s_addc_u32 s43, s43, s89
	s_add_u32 s40, s44, s88
	s_addc_u32 s41, s45, s89
	s_lshl_b32 s53, s91, 8
	s_add_u32 s40, s40, s53
	v_lshl_add_u64 v[6:7], s[34:35], 0, v[2:3]
	s_addc_u32 s41, s41, 0
	v_lshl_add_u64 v[6:7], v[6:7], 0, v[100:101]
	flat_load_dwordx4 v[52:55], v[0:1]
	flat_load_dwordx4 v[56:59], v[6:7]
	flat_load_dwordx4 v[60:63], v[0:1] offset:64
	flat_load_dwordx4 v[64:67], v[6:7] offset:64
	s_add_u32 s44, s47, s53
	v_lshlrev_b32_e32 v0, 2, v8
	s_addc_u32 s45, s50, 0
	v_ashrrev_i32_e32 v1, 31, v0
	s_add_u32 s50, s51, s53
	v_lshlrev_b64 v[6:7], 2, v[0:1]
	s_addc_u32 s51, s52, 0
	v_lshl_add_u64 v[108:109], s[40:41], 0, v[6:7]
	s_add_i32 s40, s20, -3
	v_add_u32_e32 v78, s21, v4
	v_lshl_add_u64 v[110:111], s[44:45], 0, v[6:7]
	v_lshl_add_u64 v[112:113], s[50:51], 0, v[6:7]
	v_ashrrev_i32_e32 v79, 31, v78
	v_add_u32_e32 v6, s40, v136
	v_lshlrev_b64 v[4:5], 2, v[78:79]
	v_cmp_lt_i32_e64 s[50:51], -1, v6
	v_lshl_add_u64 v[76:77], s[42:43], 0, v[4:5]
	v_lshl_add_u64 v[86:87], s[48:49], 0, v[4:5]
	s_mov_b64 s[42:43], 0x1000
	v_cndmask_b32_e64 v4, 0, v6, s[50:51]
	v_lshl_add_u64 v[36:37], v[86:87], 0, s[42:43]
	s_mov_b64 s[42:43], 0x1800
	v_lshl_add_u64 v[80:81], v[78:79], 1, s[8:9]
	v_add_u32_e32 v79, s27, v4
	v_lshl_add_u64 v[82:83], v[86:87], 0, s[42:43]
	v_mad_i64_i32 v[4:5], s[42:43], v79, s72, v[80:81]
	global_load_dwordx4 v[72:75], v[4:5], off
	v_max_i32_e32 v4, -1, v6
	s_or_b32 s80, s27, 1
	v_add_u32_e32 v92, s80, v4
	v_mad_i64_i32 v[4:5], s[42:43], v92, s72, v[80:81]
	global_load_dwordx4 v[16:19], v[4:5], off
	v_max_i32_e32 v4, -2, v6
	s_or_b32 s81, s27, 2
	v_add_u32_e32 v93, s81, v4
	v_mad_i64_i32 v[4:5], s[42:43], v93, s72, v[80:81]
	s_cmp_gt_i32 s46, -1
	global_load_dwordx4 v[12:15], v[4:5], off
	v_or_b32_e32 v4, s20, v136
	s_cselect_b64 s[42:43], -1, 0
	v_cndmask_b32_e64 v4, 0, v4, s[42:43]
	v_add_u32_e32 v94, s27, v4
	v_mad_i64_i32 v[4:5], s[46:47], v94, s72, v[80:81]
	global_load_dwordx4 v[48:51], v[108:109], off
	global_load_dwordx4 v[44:47], v[110:111], off
	global_load_dwordx4 v[88:91], v[112:113], off
	v_lshl_add_u32 v95, v8, 5, s6
	v_cmp_lt_i32_e64 s[48:49], -2, v6
	v_cmp_lt_i32_e64 s[44:45], -3, v6
	global_load_dwordx4 v[8:11], v[4:5], off
	global_load_dwordx4 v[20:23], v[76:77], off offset:16
	s_nop 0
	global_load_dwordx4 v[4:7], v[76:77], off
	global_load_dwordx4 v[24:27], v[86:87], off offset:16
	global_load_dwordx4 v[32:35], v[86:87], off
	global_load_dwordx4 v[28:31], v[86:87], off offset:2064
	global_load_dwordx4 v[40:43], v[86:87], off offset:2048
	v_add_co_u32_e32 v96, vcc, s73, v86
	v_mad_u32_u24 v121, v136, s76, v95
	s_nop 0
	v_addc_co_u32_e32 v97, vcc, 0, v87, vcc
	global_load_dwordx4 v[68:71], v[96:97], off
	s_nop 0
	global_load_dwordx4 v[36:39], v[36:37], off offset:16
	s_nop 0
	global_load_dwordx4 v[104:107], v[96:97], off offset:2048
	global_load_dwordx4 v[114:117], v[82:83], off offset:16
	v_add_u32_e32 v186, s40, v136
	v_add_u32_e32 v186, s27, v186
	v_add_u32_e32 v187, 16, v186
	v_mad_i64_i32 v[188:189], s[46:47], v187, s72, v[80:81]
	global_load_dwordx4 v[222:225], v[188:189], off
	v_add_u32_e32 v187, 17, v186
	v_mad_i64_i32 v[188:189], s[46:47], v187, s72, v[80:81]
	global_load_dwordx4 v[226:229], v[188:189], off
	v_add_u32_e32 v187, 18, v186
	v_mad_i64_i32 v[188:189], s[46:47], v187, s72, v[80:81]
	global_load_dwordx4 v[230:233], v[188:189], off
	v_add_u32_e32 v187, 19, v186
	v_mad_i64_i32 v[188:189], s[46:47], v187, s72, v[80:81]
	global_load_dwordx4 v[234:237], v[188:189], off
	v_add_u32_e32 v187, 32, v186
	v_mad_i64_i32 v[188:189], s[46:47], v187, s72, v[80:81]
	global_load_dwordx4 v[238:241], v[188:189], off
	v_add_u32_e32 v187, 33, v186
	v_mad_i64_i32 v[188:189], s[46:47], v187, s72, v[80:81]
	global_load_dwordx4 v[242:245], v[188:189], off
	v_add_u32_e32 v187, 34, v186
	v_mad_i64_i32 v[188:189], s[46:47], v187, s72, v[80:81]
	global_load_dwordx4 v[246:249], v[188:189], off
	v_add_u32_e32 v187, 35, v186
	v_mad_i64_i32 v[188:189], s[46:47], v187, s72, v[80:81]
	global_load_dwordx4 v[250:253], v[188:189], off
	v_add_u32_e32 v187, 48, v186
	v_mad_i64_i32 v[188:189], s[46:47], v187, s72, v[80:81]
	global_load_dwordx4 v[190:193], v[188:189], off
	v_add_u32_e32 v187, 49, v186
	v_mad_i64_i32 v[188:189], s[46:47], v187, s72, v[80:81]
	global_load_dwordx4 v[194:197], v[188:189], off
	v_or_b32_e32 v140, 16, v136
	v_or_b32_e32 v139, 32, v136
	v_or_b32_e32 v137, 48, v136
	v_mov_b64_e32 v[102:103], s[8:9]
	s_waitcnt vmcnt(0) lgkmcnt(0)
; __device__ __forceinline__ void ld8bf(const bf16_t* p, float (&o)[8]) { unpack8(*(const u32x4*)p, o); }
; __device__ __forceinline__ bf16x8 pack_frag(const float (&v)[8]) { return __builtin_bit_cast(bf16x8, pack8(v)); }
; __device__ __forceinline__ void w_lru_m1(const Args& a, int l, unsigned char* ws, const bf16_t* proj, bf16_t* y, LAS unsigned char* wl, int b, int ck_, int h, int lane) {
;     ...
;         for (int tb = 0; tb < 4; ++tb) { const int tok = 16 * tb + lo, t = 64 * ck_ + tok; float s[8];
; #pragma unroll
;             for (int j = 0; j < 8; ++j) s[j] = bs[j];
; #pragma unroll
;             for (int k = 0; k < 4; ++k) { const int tt = t - 3 + k; float x[8];
;                 ld8bf(proj + (size_t)(b * SEQ + (tt >= 0 ? tt : 0)) * NIN + C_LX + ch0, x);
; #pragma unroll
;                 for (int j = 0; j < 8; ++j) s[j] += (tt >= 0 ? w[k][j] : 0.f) * x[j]; }
;             Xf[tb][kk] = pack_frag(s);
; #pragma unroll
;             for (int j = 0; j < 8; ++j) xcf[tok * 65 + 32 * kk + 8 * fq + j] = s[j]; }
	v_lshlrev_b32_e32 v82, 16, v72
	v_lshlrev_b32_e32 v84, 16, v73
	v_and_b32_e32 v83, 0xffff0000, v72
	v_and_b32_e32 v85, 0xffff0000, v73
	v_cndmask_b32_e64 v73, 0, v33, s[50:51]
	v_cndmask_b32_e64 v72, 0, v32, s[50:51]
	v_cndmask_b32_e64 v99, 0, v35, s[50:51]
	v_cndmask_b32_e64 v98, 0, v34, s[50:51]
	v_pk_fma_f32 v[84:85], v[98:99], v[84:85], v[6:7]
	v_pk_fma_f32 v[72:73], v[72:73], v[82:83], v[4:5]
	v_lshlrev_b32_e32 v82, 16, v17
	v_lshlrev_b32_e32 v98, 16, v16
	v_and_b32_e32 v83, 0xffff0000, v17
	v_and_b32_e32 v99, 0xffff0000, v16
	v_cndmask_b32_e64 v17, 0, v43, s[48:49]
	v_cndmask_b32_e64 v16, 0, v42, s[48:49]
	v_cndmask_b32_e64 v119, 0, v41, s[48:49]
	v_cndmask_b32_e64 v118, 0, v40, s[48:49]
	v_pk_fma_f32 v[72:73], v[118:119], v[98:99], v[72:73]
	v_pk_fma_f32 v[16:17], v[16:17], v[82:83], v[84:85]
	v_lshlrev_b32_e32 v82, 16, v12
	v_lshlrev_b32_e32 v84, 16, v13
	v_and_b32_e32 v83, 0xffff0000, v12
	v_and_b32_e32 v85, 0xffff0000, v13
	v_cndmask_b32_e64 v13, 0, v69, s[44:45]
	v_cndmask_b32_e64 v12, 0, v68, s[44:45]
	v_cndmask_b32_e64 v99, 0, v71, s[44:45]
	v_cndmask_b32_e64 v98, 0, v70, s[44:45]
	v_pk_fma_f32 v[16:17], v[98:99], v[84:85], v[16:17]
	v_pk_fma_f32 v[12:13], v[12:13], v[82:83], v[72:73]
	v_lshlrev_b32_e32 v84, 16, v9
	v_lshlrev_b32_e32 v98, 16, v8
	v_and_b32_e32 v85, 0xffff0000, v9
	v_and_b32_e32 v99, 0xffff0000, v8
	v_cndmask_b32_e64 v73, 0, v107, s[42:43]
	v_cndmask_b32_e64 v72, 0, v106, s[42:43]
	v_cndmask_b32_e64 v83, 0, v105, s[42:43]
	v_cndmask_b32_e64 v82, 0, v104, s[42:43]
	v_pk_fma_f32 v[8:9], v[82:83], v[98:99], v[12:13]
	v_pk_fma_f32 v[12:13], v[72:73], v[84:85], v[16:17]
	v_cvt_pk_bf16_f32 v16, v8, v9
	v_cvt_pk_bf16_f32 v17, v12, v13
	ds_write2_b32 v121, v12, v13 offset0:2 offset1:3
	ds_write2_b32 v121, v8, v9 offset1:1
	v_lshlrev_b32_e32 v8, 16, v74
	v_lshlrev_b32_e32 v12, 16, v75
	v_and_b32_e32 v9, 0xffff0000, v74
	v_and_b32_e32 v13, 0xffff0000, v75
	v_cndmask_b32_e64 v75, 0, v25, s[50:51]
	v_cndmask_b32_e64 v74, 0, v24, s[50:51]
	v_cndmask_b32_e64 v85, 0, v27, s[50:51]
	v_cndmask_b32_e64 v84, 0, v26, s[50:51]
	v_pk_fma_f32 v[12:13], v[84:85], v[12:13], v[22:23]
	v_pk_fma_f32 v[8:9], v[74:75], v[8:9], v[20:21]
	v_lshlrev_b32_e32 v74, 16, v19
	v_lshlrev_b32_e32 v84, 16, v18
	v_and_b32_e32 v75, 0xffff0000, v19
	v_and_b32_e32 v85, 0xffff0000, v18
	v_cndmask_b32_e64 v19, 0, v31, s[48:49]
	v_cndmask_b32_e64 v18, 0, v30, s[48:49]
	v_cndmask_b32_e64 v99, 0, v29, s[48:49]
	v_cndmask_b32_e64 v98, 0, v28, s[48:49]
	v_pk_fma_f32 v[8:9], v[98:99], v[84:85], v[8:9]
	v_pk_fma_f32 v[12:13], v[18:19], v[74:75], v[12:13]
	v_lshlrev_b32_e32 v18, 16, v14
	v_lshlrev_b32_e32 v74, 16, v15
	v_and_b32_e32 v19, 0xffff0000, v14
	v_and_b32_e32 v75, 0xffff0000, v15
	v_cndmask_b32_e64 v15, 0, v37, s[44:45]
	v_cndmask_b32_e64 v14, 0, v36, s[44:45]
	v_cndmask_b32_e64 v85, 0, v39, s[44:45]
	v_cndmask_b32_e64 v84, 0, v38, s[44:45]
	v_pk_fma_f32 v[12:13], v[84:85], v[74:75], v[12:13]
	v_pk_fma_f32 v[8:9], v[14:15], v[18:19], v[8:9]
	v_lshlrev_b32_e32 v14, 16, v11
	v_lshlrev_b32_e32 v18, 16, v10
	v_and_b32_e32 v15, 0xffff0000, v11
	v_and_b32_e32 v19, 0xffff0000, v10
	v_cndmask_b32_e64 v75, 0, v117, s[42:43]
	v_cndmask_b32_e64 v74, 0, v116, s[42:43]
	v_cndmask_b32_e64 v85, 0, v115, s[42:43]
	v_cndmask_b32_e64 v84, 0, v114, s[42:43]
	v_add_u32_e32 v98, s40, v140
	v_pk_fma_f32 v[8:9], v[84:85], v[18:19], v[8:9]
	v_pk_fma_f32 v[10:11], v[74:75], v[14:15], v[12:13]
	v_cmp_lt_i32_e64 s[62:63], -1, v98
	v_cvt_pk_bf16_f32 v18, v8, v9
	ds_write2_b32 v121, v10, v11 offset0:6 offset1:7
	ds_write2_b32 v121, v8, v9 offset0:4 offset1:5
	v_cndmask_b32_e64 v8, 0, v98, s[62:63]
	v_cmp_lt_i32_e64 s[60:61], -2, v98
	v_max_i32_e32 v12, -1, v98
	v_cmp_lt_i32_e64 s[58:59], -3, v98
	v_max_i32_e32 v98, -2, v98
	v_add_u32_e32 v142, s81, v98
	v_add_u32_e32 v134, s27, v8
	v_mad_i64_i32 v[98:99], s[46:47], v142, s72, v[80:81]
	v_mad_i64_i32 v[8:9], s[46:47], v134, s72, v[80:81]
	v_add_u32_e32 v135, s80, v12
	v_mov_b64_e32 v[104:105], v[230:231]
	v_mov_b64_e32 v[106:107], v[232:233]
	v_or_b32_e32 v98, s20, v140
	v_cvt_pk_bf16_f32 v19, v10, v11
	v_mov_b64_e32 v[8:9], v[222:223]
	v_mov_b64_e32 v[10:11], v[224:225]
	v_mad_i64_i32 v[12:13], s[46:47], v135, s72, v[80:81]
	v_cndmask_b32_e64 v98, 0, v98, s[42:43]
	v_mov_b64_e32 v[12:13], v[226:227]
	v_mov_b64_e32 v[14:15], v[228:229]
	v_add_u32_e32 v143, s27, v98
	v_mad_i64_i32 v[98:99], s[46:47], v143, s72, v[80:81]
	v_mov_b64_e32 v[114:115], v[234:235]
	v_mov_b64_e32 v[116:117], v[236:237]
	v_mov_b32_e32 v98, 0x1040
	v_mad_u32_u24 v123, v136, s76, v98
	v_cndmask_b32_e64 v127, 0, v35, s[62:63]
	v_cndmask_b32_e64 v126, 0, v34, s[62:63]
	v_cndmask_b32_e64 v129, 0, v41, s[60:61]
	v_cndmask_b32_e64 v128, 0, v40, s[60:61]
	v_add_u32_e32 v125, v95, v123
	s_waitcnt vmcnt(0) lgkmcnt(0)
; __device__ __forceinline__ void ld8bf(const bf16_t* p, float (&o)[8]) { unpack8(*(const u32x4*)p, o); }
; __device__ __forceinline__ bf16x8 pack_frag(const float (&v)[8]) { return __builtin_bit_cast(bf16x8, pack8(v)); }
; __device__ __forceinline__ void w_lru_m1(const Args& a, int l, unsigned char* ws, const bf16_t* proj, bf16_t* y, LAS unsigned char* wl, int b, int ck_, int h, int lane) {
;     ...
;         for (int tb = 0; tb < 4; ++tb) { const int tok = 16 * tb + lo, t = 64 * ck_ + tok; float s[8];
; #pragma unroll
;             for (int j = 0; j < 8; ++j) s[j] = bs[j];
; #pragma unroll
;             for (int k = 0; k < 4; ++k) { const int tt = t - 3 + k; float x[8];
;                 ld8bf(proj + (size_t)(b * SEQ + (tt >= 0 ? tt : 0)) * NIN + C_LX + ch0, x);
; #pragma unroll
;                 for (int j = 0; j < 8; ++j) s[j] += (tt >= 0 ? w[k][j] : 0.f) * x[j]; }
;             Xf[tb][kk] = pack_frag(s);
; #pragma unroll
;             for (int j = 0; j < 8; ++j) xcf[tok * 65 + 32 * kk + 8 * fq + j] = s[j]; }
	v_lshlrev_b32_e32 v98, 16, v8
	v_lshlrev_b32_e32 v118, 16, v9
	v_and_b32_e32 v99, 0xffff0000, v8
	v_and_b32_e32 v119, 0xffff0000, v9
	v_cndmask_b32_e64 v9, 0, v33, s[62:63]
	v_cndmask_b32_e64 v8, 0, v32, s[62:63]
	v_pk_fma_f32 v[118:119], v[126:127], v[118:119], v[6:7]
	v_pk_fma_f32 v[8:9], v[8:9], v[98:99], v[4:5]
	v_lshlrev_b32_e32 v98, 16, v13
	v_lshlrev_b32_e32 v126, 16, v12
	v_and_b32_e32 v99, 0xffff0000, v13
	v_and_b32_e32 v127, 0xffff0000, v12
	v_cndmask_b32_e64 v13, 0, v43, s[60:61]
	v_cndmask_b32_e64 v12, 0, v42, s[60:61]
	v_pk_fma_f32 v[8:9], v[128:129], v[126:127], v[8:9]
	v_pk_fma_f32 v[12:13], v[12:13], v[98:99], v[118:119]
	v_lshlrev_b32_e32 v98, 16, v104
	v_lshlrev_b32_e32 v118, 16, v105
	v_and_b32_e32 v99, 0xffff0000, v104
	v_and_b32_e32 v119, 0xffff0000, v105
	v_cndmask_b32_e64 v105, 0, v69, s[58:59]
	v_cndmask_b32_e64 v104, 0, v68, s[58:59]
	v_cndmask_b32_e64 v127, 0, v71, s[58:59]
	v_cndmask_b32_e64 v126, 0, v70, s[58:59]
	v_pk_fma_f32 v[12:13], v[126:127], v[118:119], v[12:13]
	v_pk_fma_f32 v[8:9], v[104:105], v[98:99], v[8:9]
	v_lshlrev_b32_e32 v98, 16, v115
	v_lshlrev_b32_e32 v104, 16, v114
	v_and_b32_e32 v99, 0xffff0000, v115
	v_and_b32_e32 v105, 0xffff0000, v114
	v_pk_fma_f32 v[8:9], v[82:83], v[104:105], v[8:9]
	v_pk_fma_f32 v[98:99], v[72:73], v[98:99], v[12:13]
	v_cvt_pk_bf16_f32 v12, v8, v9
	v_cvt_pk_bf16_f32 v13, v98, v99
	ds_write2_b32 v125, v98, v99 offset0:2 offset1:3
	ds_write2_b32 v125, v8, v9 offset1:1
	v_lshlrev_b32_e32 v8, 16, v10
	v_lshlrev_b32_e32 v98, 16, v11
	v_and_b32_e32 v9, 0xffff0000, v10
	v_and_b32_e32 v99, 0xffff0000, v11
	v_cndmask_b32_e64 v11, 0, v25, s[62:63]
	v_cndmask_b32_e64 v10, 0, v24, s[62:63]
	v_cndmask_b32_e64 v105, 0, v27, s[62:63]
	v_cndmask_b32_e64 v104, 0, v26, s[62:63]
	v_pk_fma_f32 v[98:99], v[104:105], v[98:99], v[22:23]
	v_pk_fma_f32 v[8:9], v[10:11], v[8:9], v[20:21]
	v_lshlrev_b32_e32 v10, 16, v15
	v_lshlrev_b32_e32 v104, 16, v14
	v_and_b32_e32 v11, 0xffff0000, v15
	v_and_b32_e32 v105, 0xffff0000, v14
	v_cndmask_b32_e64 v15, 0, v31, s[60:61]
	v_cndmask_b32_e64 v14, 0, v30, s[60:61]
	v_cndmask_b32_e64 v115, 0, v29, s[60:61]
	v_cndmask_b32_e64 v114, 0, v28, s[60:61]
	v_pk_fma_f32 v[8:9], v[114:115], v[104:105], v[8:9]
	v_pk_fma_f32 v[10:11], v[14:15], v[10:11], v[98:99]
	v_lshlrev_b32_e32 v14, 16, v106
	v_lshlrev_b32_e32 v98, 16, v107
	v_and_b32_e32 v15, 0xffff0000, v106
	v_and_b32_e32 v99, 0xffff0000, v107
	v_cndmask_b32_e64 v105, 0, v37, s[58:59]
	v_cndmask_b32_e64 v104, 0, v36, s[58:59]
	v_cndmask_b32_e64 v107, 0, v39, s[58:59]
	v_cndmask_b32_e64 v106, 0, v38, s[58:59]
	v_pk_fma_f32 v[10:11], v[106:107], v[98:99], v[10:11]
	v_pk_fma_f32 v[8:9], v[104:105], v[14:15], v[8:9]
	v_lshlrev_b32_e32 v14, 16, v117
	v_lshlrev_b32_e32 v98, 16, v116
	v_and_b32_e32 v15, 0xffff0000, v117
	v_and_b32_e32 v99, 0xffff0000, v116
	v_add_u32_e32 v114, s40, v139
	v_pk_fma_f32 v[8:9], v[84:85], v[98:99], v[8:9]
	v_pk_fma_f32 v[10:11], v[74:75], v[14:15], v[10:11]
	v_cmp_lt_i32_e64 s[56:57], -1, v114
	v_cvt_pk_bf16_f32 v14, v8, v9
	ds_write2_b32 v125, v10, v11 offset0:6 offset1:7
	ds_write2_b32 v125, v8, v9 offset0:4 offset1:5
	v_cndmask_b32_e64 v8, 0, v114, s[56:57]
	v_max_i32_e32 v98, -1, v114
	v_add_u32_e32 v130, s27, v8
	v_add_u32_e32 v131, s80, v98
	v_mad_i64_i32 v[8:9], s[46:47], v130, s72, v[80:81]
	v_mad_i64_i32 v[98:99], s[46:47], v131, s72, v[80:81]
	v_cvt_pk_bf16_f32 v15, v10, v11
	v_mov_b64_e32 v[8:9], v[238:239]
	v_mov_b64_e32 v[10:11], v[240:241]
	v_cmp_lt_i32_e64 s[54:55], -2, v114
	v_mov_b64_e32 v[104:105], v[242:243]
	v_mov_b64_e32 v[106:107], v[244:245]
	v_max_i32_e32 v98, -2, v114
	v_add_u32_e32 v132, s81, v98
	v_mad_i64_i32 v[98:99], s[46:47], v132, s72, v[80:81]
	v_cmp_lt_i32_e64 s[52:53], -3, v114
	v_mov_b64_e32 v[114:115], v[246:247]
	v_mov_b64_e32 v[116:117], v[248:249]
	v_or_b32_e32 v98, s20, v139
	v_cndmask_b32_e64 v98, 0, v98, s[42:43]
	v_add_u32_e32 v133, s27, v98
	v_mad_i64_i32 v[98:99], s[46:47], v133, s72, v[80:81]
	v_mov_b64_e32 v[126:127], v[250:251]
	v_mov_b64_e32 v[128:129], v[252:253]
	v_mov_b32_e32 v98, 0x2080
	v_mad_u32_u24 v141, v136, s76, v98
	v_cndmask_b32_e64 v147, 0, v35, s[56:57]
	v_cndmask_b32_e64 v146, 0, v34, s[56:57]
	v_cndmask_b32_e64 v149, 0, v41, s[54:55]
	v_cndmask_b32_e64 v148, 0, v40, s[54:55]
	v_add_u32_e32 v124, v95, v141
	s_waitcnt vmcnt(0) lgkmcnt(0)
; __device__ __forceinline__ void ld8bf(const bf16_t* p, float (&o)[8]) { unpack8(*(const u32x4*)p, o); }
; __device__ __forceinline__ bf16x8 pack_frag(const float (&v)[8]) { return __builtin_bit_cast(bf16x8, pack8(v)); }
; __device__ __forceinline__ void w_lru_m1(const Args& a, int l, unsigned char* ws, const bf16_t* proj, bf16_t* y, LAS unsigned char* wl, int b, int ck_, int h, int lane) {
;     ...
;         for (int tb = 0; tb < 4; ++tb) { const int tok = 16 * tb + lo, t = 64 * ck_ + tok; float s[8];
; #pragma unroll
;             for (int j = 0; j < 8; ++j) s[j] = bs[j];
; #pragma unroll
;             for (int k = 0; k < 4; ++k) { const int tt = t - 3 + k; float x[8];
;                 ld8bf(proj + (size_t)(b * SEQ + (tt >= 0 ? tt : 0)) * NIN + C_LX + ch0, x);
; #pragma unroll
;                 for (int j = 0; j < 8; ++j) s[j] += (tt >= 0 ? w[k][j] : 0.f) * x[j]; }
;             Xf[tb][kk] = pack_frag(s);
; #pragma unroll
;             for (int j = 0; j < 8; ++j) xcf[tok * 65 + 32 * kk + 8 * fq + j] = s[j]; }
	v_lshlrev_b32_e32 v98, 16, v8
	v_lshlrev_b32_e32 v118, 16, v9
	v_and_b32_e32 v99, 0xffff0000, v8
	v_and_b32_e32 v119, 0xffff0000, v9
	v_cndmask_b32_e64 v9, 0, v33, s[56:57]
	v_cndmask_b32_e64 v8, 0, v32, s[56:57]
	v_pk_fma_f32 v[118:119], v[146:147], v[118:119], v[6:7]
	v_pk_fma_f32 v[8:9], v[8:9], v[98:99], v[4:5]
	v_lshlrev_b32_e32 v98, 16, v105
	v_lshlrev_b32_e32 v146, 16, v104
	v_and_b32_e32 v99, 0xffff0000, v105
	v_and_b32_e32 v147, 0xffff0000, v104
	v_cndmask_b32_e64 v105, 0, v43, s[54:55]
	v_cndmask_b32_e64 v104, 0, v42, s[54:55]
	v_pk_fma_f32 v[8:9], v[148:149], v[146:147], v[8:9]
	v_pk_fma_f32 v[98:99], v[104:105], v[98:99], v[118:119]
	v_lshlrev_b32_e32 v104, 16, v114
	v_lshlrev_b32_e32 v118, 16, v115
	v_and_b32_e32 v105, 0xffff0000, v114
	v_and_b32_e32 v119, 0xffff0000, v115
	v_cndmask_b32_e64 v115, 0, v69, s[52:53]
	v_cndmask_b32_e64 v114, 0, v68, s[52:53]
	v_cndmask_b32_e64 v147, 0, v71, s[52:53]
	v_cndmask_b32_e64 v146, 0, v70, s[52:53]
	v_pk_fma_f32 v[98:99], v[146:147], v[118:119], v[98:99]
	v_pk_fma_f32 v[8:9], v[114:115], v[104:105], v[8:9]
	v_lshlrev_b32_e32 v104, 16, v127
	v_lshlrev_b32_e32 v114, 16, v126
	v_and_b32_e32 v105, 0xffff0000, v127
	v_and_b32_e32 v115, 0xffff0000, v126
	v_pk_fma_f32 v[114:115], v[82:83], v[114:115], v[8:9]
	v_pk_fma_f32 v[98:99], v[72:73], v[104:105], v[98:99]
	v_cvt_pk_bf16_f32 v8, v114, v115
	v_cvt_pk_bf16_f32 v9, v98, v99
	ds_write2_b32 v124, v98, v99 offset0:2 offset1:3
	ds_write2_b32 v124, v114, v115 offset1:1
	v_lshlrev_b32_e32 v98, 16, v10
	v_lshlrev_b32_e32 v104, 16, v11
	v_and_b32_e32 v99, 0xffff0000, v10
	v_and_b32_e32 v105, 0xffff0000, v11
	v_cndmask_b32_e64 v11, 0, v25, s[56:57]
	v_cndmask_b32_e64 v10, 0, v24, s[56:57]
	v_cndmask_b32_e64 v115, 0, v27, s[56:57]
	v_cndmask_b32_e64 v114, 0, v26, s[56:57]
	v_pk_fma_f32 v[104:105], v[114:115], v[104:105], v[22:23]
	v_pk_fma_f32 v[10:11], v[10:11], v[98:99], v[20:21]
	v_lshlrev_b32_e32 v98, 16, v107
	v_lshlrev_b32_e32 v114, 16, v106
	v_and_b32_e32 v99, 0xffff0000, v107
	v_and_b32_e32 v115, 0xffff0000, v106
	v_cndmask_b32_e64 v107, 0, v31, s[54:55]
	v_cndmask_b32_e64 v106, 0, v30, s[54:55]
	v_cndmask_b32_e64 v119, 0, v29, s[54:55]
	v_cndmask_b32_e64 v118, 0, v28, s[54:55]
	v_pk_fma_f32 v[10:11], v[118:119], v[114:115], v[10:11]
	v_pk_fma_f32 v[98:99], v[106:107], v[98:99], v[104:105]
	v_lshlrev_b32_e32 v104, 16, v116
	v_lshlrev_b32_e32 v106, 16, v117
	v_and_b32_e32 v105, 0xffff0000, v116
	v_and_b32_e32 v107, 0xffff0000, v117
	v_cndmask_b32_e64 v115, 0, v37, s[52:53]
	v_cndmask_b32_e64 v114, 0, v36, s[52:53]
	v_cndmask_b32_e64 v117, 0, v39, s[52:53]
	v_cndmask_b32_e64 v116, 0, v38, s[52:53]
	v_pk_fma_f32 v[98:99], v[116:117], v[106:107], v[98:99]
	v_pk_fma_f32 v[10:11], v[114:115], v[104:105], v[10:11]
	v_lshlrev_b32_e32 v104, 16, v129
	v_and_b32_e32 v105, 0xffff0000, v129
	v_add_u32_e32 v118, s40, v137
	v_lshlrev_b32_e32 v106, 16, v128
	v_and_b32_e32 v107, 0xffff0000, v128
	v_pk_fma_f32 v[98:99], v[74:75], v[104:105], v[98:99]
	v_cmp_lt_i32_e64 s[46:47], -1, v118
	v_pk_fma_f32 v[106:107], v[84:85], v[106:107], v[10:11]
	v_cvt_pk_bf16_f32 v11, v98, v99
	ds_write2_b32 v124, v98, v99 offset0:6 offset1:7
	ds_write2_b32 v124, v106, v107 offset0:4 offset1:5
	v_cndmask_b32_e64 v98, 0, v118, s[46:47]
	v_add_u32_e32 v126, s27, v98
	v_mad_i64_i32 v[98:99], s[40:41], v126, s72, v[80:81]
	v_cvt_pk_bf16_f32 v10, v106, v107
	v_mov_b64_e32 v[104:105], v[190:191]
	v_mov_b64_e32 v[106:107], v[192:193]
	v_max_i32_e32 v98, -1, v118
	v_add_u32_e32 v127, s80, v98
	v_mad_i64_i32 v[98:99], vcc, v127, s72, v[80:81]
	v_mov_b64_e32 v[114:115], v[194:195]
	v_mov_b64_e32 v[116:117], v[196:197]
	v_max_i32_e32 v98, -2, v118
	v_add_u32_e32 v128, s81, v98
	v_mad_i64_i32 v[98:99], s[80:81], v128, s72, v[80:81]
	global_load_dwordx4 v[146:149], v[98:99], off
	v_or_b32_e32 v98, s20, v137
	v_cndmask_b32_e64 v98, 0, v98, s[42:43]
	v_add_u32_e32 v129, s27, v98
	v_mad_i64_i32 v[80:81], s[80:81], v129, s72, v[80:81]
	global_load_dwordx4 v[150:153], v[80:81], off
	v_mov_b32_e32 v80, 0x30c0
	v_cmp_lt_i32_e64 s[40:41], -2, v118
	v_mad_u32_u24 v138, v136, s76, v80
	v_cndmask_b32_e64 v33, 0, v33, s[46:47]
	v_cndmask_b32_e64 v32, 0, v32, s[46:47]
	v_cndmask_b32_e64 v35, 0, v35, s[46:47]
	v_cndmask_b32_e64 v34, 0, v34, s[46:47]
	v_cmp_lt_i32_e32 vcc, -3, v118
	v_cndmask_b32_e64 v43, 0, v43, s[40:41]
	v_cndmask_b32_e64 v42, 0, v42, s[40:41]
	v_cndmask_b32_e64 v41, 0, v41, s[40:41]
	v_cndmask_b32_e64 v40, 0, v40, s[40:41]
	v_add_u32_e32 v120, v95, v138
	v_cndmask_b32_e64 v25, 0, v25, s[46:47]
	v_cndmask_b32_e64 v24, 0, v24, s[46:47]
	v_cndmask_b32_e64 v27, 0, v27, s[46:47]
	v_cndmask_b32_e64 v26, 0, v26, s[46:47]
	v_cndmask_b32_e64 v29, 0, v29, s[40:41]
	v_cndmask_b32_e64 v28, 0, v28, s[40:41]
	s_mov_b64 s[80:81], 0x1080
	s_waitcnt vmcnt(0) lgkmcnt(0)
; __device__ __forceinline__ void ld8bf(const bf16_t* p, float (&o)[8]) { unpack8(*(const u32x4*)p, o); }
; __device__ __forceinline__ bf16x8 pack_frag(const float (&v)[8]) { return __builtin_bit_cast(bf16x8, pack8(v)); }
; __device__ __forceinline__ void w_lru_m1(const Args& a, int l, unsigned char* ws, const bf16_t* proj, bf16_t* y, LAS unsigned char* wl, int b, int ck_, int h, int lane) {
;     ...
;     for (int kk = 0; kk < 2; ++kk) { const int ch0 = 64 * h + 32 * kk + 8 * fq; float w[4][8], bs[8];
; #pragma unroll
;         for (int j = 0; j < 8; ++j) { bs[j] = cbias[ch0 + j];
; #pragma unroll
;             for (int k = 0; k < 4; ++k) w[k][j] = cw[k * 512 + ch0 + j]; }
; #pragma unroll
;         for (int tb = 0; tb < 4; ++tb) { const int tok = 16 * tb + lo, t = 64 * ck_ + tok; float s[8];
; #pragma unroll
;             for (int j = 0; j < 8; ++j) s[j] = bs[j];
; #pragma unroll
;             for (int k = 0; k < 4; ++k) { const int tt = t - 3 + k; float x[8];
;                 ld8bf(proj + (size_t)(b * SEQ + (tt >= 0 ? tt : 0)) * NIN + C_LX + ch0, x);
; #pragma unroll
;                 for (int j = 0; j < 8; ++j) s[j] += (tt >= 0 ? w[k][j] : 0.f) * x[j]; }
;             Xf[tb][kk] = pack_frag(s);
; #pragma unroll
;             for (int j = 0; j < 8; ++j) xcf[tok * 65 + 32 * kk + 8 * fq + j] = s[j]; }
	v_lshlrev_b32_e32 v80, 16, v104
	v_lshlrev_b32_e32 v98, 16, v105
	v_and_b32_e32 v81, 0xffff0000, v104
	v_and_b32_e32 v99, 0xffff0000, v105
	v_pk_fma_f32 v[6:7], v[34:35], v[98:99], v[6:7]
	v_pk_fma_f32 v[4:5], v[32:33], v[80:81], v[4:5]
	v_lshlrev_b32_e32 v32, 16, v115
	v_lshlrev_b32_e32 v34, 16, v114
	v_and_b32_e32 v33, 0xffff0000, v115
	v_and_b32_e32 v35, 0xffff0000, v114
	v_pk_fma_f32 v[4:5], v[40:41], v[34:35], v[4:5]
	v_pk_fma_f32 v[6:7], v[42:43], v[32:33], v[6:7]
	v_lshlrev_b32_e32 v32, 16, v146
	v_lshlrev_b32_e32 v34, 16, v147
	v_and_b32_e32 v33, 0xffff0000, v146
	v_and_b32_e32 v35, 0xffff0000, v147
	v_cndmask_b32_e32 v41, 0, v69, vcc
	v_cndmask_b32_e32 v40, 0, v68, vcc
	v_cndmask_b32_e32 v43, 0, v71, vcc
	v_cndmask_b32_e32 v42, 0, v70, vcc
	v_pk_fma_f32 v[6:7], v[42:43], v[34:35], v[6:7]
	v_pk_fma_f32 v[4:5], v[40:41], v[32:33], v[4:5]
	v_lshlrev_b32_e32 v32, 16, v151
	v_and_b32_e32 v33, 0xffff0000, v151
	v_lshlrev_b32_e32 v34, 16, v150
	v_and_b32_e32 v35, 0xffff0000, v150
	v_pk_fma_f32 v[6:7], v[72:73], v[32:33], v[6:7]
	v_pk_fma_f32 v[34:35], v[82:83], v[34:35], v[4:5]
	v_cvt_pk_bf16_f32 v5, v6, v7
	ds_write2_b32 v120, v6, v7 offset0:2 offset1:3
	ds_write2_b32 v120, v34, v35 offset1:1
	v_lshlrev_b32_e32 v6, 16, v106
	v_lshlrev_b32_e32 v32, 16, v107
	v_and_b32_e32 v7, 0xffff0000, v106
	v_and_b32_e32 v33, 0xffff0000, v107
	v_pk_fma_f32 v[22:23], v[26:27], v[32:33], v[22:23]
	v_pk_fma_f32 v[6:7], v[24:25], v[6:7], v[20:21]
	v_lshlrev_b32_e32 v20, 16, v117
	v_lshlrev_b32_e32 v24, 16, v116
	v_and_b32_e32 v21, 0xffff0000, v117
	v_and_b32_e32 v25, 0xffff0000, v116
	v_cndmask_b32_e64 v27, 0, v31, s[40:41]
	v_cndmask_b32_e64 v26, 0, v30, s[40:41]
	v_pk_fma_f32 v[6:7], v[28:29], v[24:25], v[6:7]
	v_pk_fma_f32 v[20:21], v[26:27], v[20:21], v[22:23]
	v_lshlrev_b32_e32 v22, 16, v148
	v_lshlrev_b32_e32 v24, 16, v149
	v_and_b32_e32 v23, 0xffff0000, v148
	v_and_b32_e32 v25, 0xffff0000, v149
	v_cndmask_b32_e32 v27, 0, v37, vcc
	v_cndmask_b32_e32 v26, 0, v36, vcc
	v_cndmask_b32_e32 v29, 0, v39, vcc
	v_cndmask_b32_e32 v28, 0, v38, vcc
	v_pk_fma_f32 v[20:21], v[28:29], v[24:25], v[20:21]
	v_pk_fma_f32 v[6:7], v[26:27], v[22:23], v[6:7]
	v_lshlrev_b32_e32 v22, 16, v153
	v_and_b32_e32 v23, 0xffff0000, v153
	v_lshlrev_b32_e32 v24, 16, v152
	v_and_b32_e32 v25, 0xffff0000, v152
	v_pk_fma_f32 v[20:21], v[74:75], v[22:23], v[20:21]
	v_pk_fma_f32 v[24:25], v[84:85], v[24:25], v[6:7]
	v_cvt_pk_bf16_f32 v7, v20, v21
	ds_write2_b32 v120, v20, v21 offset0:6 offset1:7
	ds_write2_b32 v120, v24, v25 offset0:4 offset1:5
	v_add_u32_e32 v20, 32, v78
	v_ashrrev_i32_e32 v21, 31, v20
	v_lshl_add_u64 v[84:85], v[86:87], 0, s[80:81]
	s_mov_b64 s[80:81], 0x1880
	v_lshl_add_u64 v[106:107], v[86:87], 0, s[80:81]
	v_mad_i64_i32 v[22:23], s[80:81], v79, s72, v[102:103]
	v_lshlrev_b64 v[104:105], 1, v[20:21]
	v_lshl_add_u64 v[20:21], v[22:23], 0, v[104:105]
	flat_load_dwordx4 v[80:83], v[20:21]
	v_mad_i64_i32 v[20:21], s[80:81], v92, s72, v[102:103]
	v_lshl_add_u64 v[20:21], v[20:21], 0, v[104:105]
	v_cvt_pk_bf16_f32 v4, v34, v35
	flat_load_dwordx4 v[32:35], v[20:21]
	v_mad_i64_i32 v[20:21], s[80:81], v93, s72, v[102:103]
	v_lshl_add_u64 v[20:21], v[20:21], 0, v[104:105]
	flat_load_dwordx4 v[28:31], v[20:21]
	v_mad_i64_i32 v[20:21], s[80:81], v94, s72, v[102:103]
	v_lshl_add_u64 v[20:21], v[20:21], 0, v[104:105]
	v_cvt_pk_bf16_f32 v6, v24, v25
	flat_load_dwordx4 v[24:27], v[20:21]
	global_load_dwordx4 v[40:43], v[76:77], off offset:144
	global_load_dwordx4 v[72:75], v[76:77], off offset:128
	global_load_dwordx4 v[68:71], v[86:87], off offset:144
	s_nop 0
	global_load_dwordx4 v[76:79], v[86:87], off offset:128
	global_load_dwordx4 v[36:39], v[86:87], off offset:2192
	global_load_dwordx4 v[20:23], v[86:87], off offset:2176
	global_load_dwordx4 v[92:95], v[96:97], off offset:128
	s_nop 0
	global_load_dwordx4 v[84:87], v[84:85], off offset:16
	s_nop 0
	global_load_dwordx4 v[96:99], v[96:97], off offset:2176
	s_nop 0
	global_load_dwordx4 v[146:149], v[106:107], off offset:16
	s_waitcnt vmcnt(0) lgkmcnt(0)
	v_lshlrev_b32_e32 v106, 16, v80
	v_lshlrev_b32_e32 v114, 16, v81
	v_and_b32_e32 v107, 0xffff0000, v80
	v_and_b32_e32 v115, 0xffff0000, v81
	v_cndmask_b32_e64 v81, 0, v77, s[50:51]
	v_cndmask_b32_e64 v80, 0, v76, s[50:51]
	v_cndmask_b32_e64 v117, 0, v79, s[50:51]
	v_cndmask_b32_e64 v116, 0, v78, s[50:51]
	v_pk_fma_f32 v[114:115], v[116:117], v[114:115], v[74:75]
	v_pk_fma_f32 v[80:81], v[80:81], v[106:107], v[72:73]
	v_lshlrev_b32_e32 v106, 16, v33
	v_lshlrev_b32_e32 v116, 16, v32
	v_and_b32_e32 v107, 0xffff0000, v33
	v_and_b32_e32 v117, 0xffff0000, v32
	v_cndmask_b32_e64 v33, 0, v23, s[48:49]
	v_cndmask_b32_e64 v32, 0, v22, s[48:49]
	v_cndmask_b32_e64 v119, 0, v21, s[48:49]
	v_cndmask_b32_e64 v118, 0, v20, s[48:49]
	v_pk_fma_f32 v[80:81], v[118:119], v[116:117], v[80:81]
	v_pk_fma_f32 v[32:33], v[32:33], v[106:107], v[114:115]
	v_lshlrev_b32_e32 v106, 16, v28
	v_lshlrev_b32_e32 v114, 16, v29
	v_and_b32_e32 v107, 0xffff0000, v28
	v_and_b32_e32 v115, 0xffff0000, v29
	v_cndmask_b32_e64 v29, 0, v93, s[44:45]
	v_cndmask_b32_e64 v28, 0, v92, s[44:45]
	v_cndmask_b32_e64 v117, 0, v95, s[44:45]
	v_cndmask_b32_e64 v116, 0, v94, s[44:45]
	v_pk_fma_f32 v[32:33], v[116:117], v[114:115], v[32:33]
	v_pk_fma_f32 v[28:29], v[28:29], v[106:107], v[80:81]
	v_lshlrev_b32_e32 v80, 16, v25
	v_lshlrev_b32_e32 v116, 16, v24
	v_and_b32_e32 v81, 0xffff0000, v25
	v_and_b32_e32 v117, 0xffff0000, v24
	v_cndmask_b32_e64 v107, 0, v99, s[42:43]
	v_cndmask_b32_e64 v106, 0, v98, s[42:43]
	v_cndmask_b32_e64 v115, 0, v97, s[42:43]
	v_cndmask_b32_e64 v114, 0, v96, s[42:43]
	v_pk_fma_f32 v[24:25], v[114:115], v[116:117], v[28:29]
; __device__ __forceinline__ void ld8bf(const bf16_t* p, float (&o)[8]) { unpack8(*(const u32x4*)p, o); }
; __device__ __forceinline__ bf16x8 pack_frag(const float (&v)[8]) { return __builtin_bit_cast(bf16x8, pack8(v)); }
; __device__ __forceinline__ void w_lru_m1(const Args& a, int l, unsigned char* ws, const bf16_t* proj, bf16_t* y, LAS unsigned char* wl, int b, int ck_, int h, int lane) {
;     ...
;         for (int tb = 0; tb < 4; ++tb) { const int tok = 16 * tb + lo, t = 64 * ck_ + tok; float s[8];
; #pragma unroll
;             for (int j = 0; j < 8; ++j) s[j] = bs[j];
; #pragma unroll
;             for (int k = 0; k < 4; ++k) { const int tt = t - 3 + k; float x[8];
;                 ld8bf(proj + (size_t)(b * SEQ + (tt >= 0 ? tt : 0)) * NIN + C_LX + ch0, x);
; #pragma unroll
;                 for (int j = 0; j < 8; ++j) s[j] += (tt >= 0 ? w[k][j] : 0.f) * x[j]; }
;             Xf[tb][kk] = pack_frag(s);
; #pragma unroll
;             for (int j = 0; j < 8; ++j) xcf[tok * 65 + 32 * kk + 8 * fq + j] = s[j]; }
	v_pk_fma_f32 v[28:29], v[106:107], v[80:81], v[32:33]
	v_cvt_pk_bf16_f32 v32, v24, v25
	v_cvt_pk_bf16_f32 v33, v28, v29
	ds_write2_b32 v121, v28, v29 offset0:34 offset1:35
	ds_write2_b32 v121, v24, v25 offset0:32 offset1:33
	v_lshlrev_b32_e32 v24, 16, v82
	v_lshlrev_b32_e32 v28, 16, v83
	v_and_b32_e32 v25, 0xffff0000, v82
	v_and_b32_e32 v29, 0xffff0000, v83
	v_cndmask_b32_e64 v81, 0, v69, s[50:51]
	v_cndmask_b32_e64 v80, 0, v68, s[50:51]
	v_cndmask_b32_e64 v83, 0, v71, s[50:51]
	v_cndmask_b32_e64 v82, 0, v70, s[50:51]
	v_pk_fma_f32 v[28:29], v[82:83], v[28:29], v[42:43]
	v_pk_fma_f32 v[24:25], v[80:81], v[24:25], v[40:41]
	v_lshlrev_b32_e32 v80, 16, v35
	v_lshlrev_b32_e32 v82, 16, v34
	v_and_b32_e32 v81, 0xffff0000, v35
	v_and_b32_e32 v83, 0xffff0000, v34
	v_cndmask_b32_e64 v35, 0, v39, s[48:49]
	v_cndmask_b32_e64 v34, 0, v38, s[48:49]
	v_cndmask_b32_e64 v97, 0, v37, s[48:49]
	v_cndmask_b32_e64 v96, 0, v36, s[48:49]
	v_pk_fma_f32 v[24:25], v[96:97], v[82:83], v[24:25]
	v_pk_fma_f32 v[28:29], v[34:35], v[80:81], v[28:29]
	v_lshlrev_b32_e32 v34, 16, v30
	v_lshlrev_b32_e32 v80, 16, v31
	v_and_b32_e32 v35, 0xffff0000, v30
	v_and_b32_e32 v81, 0xffff0000, v31
	v_cndmask_b32_e64 v31, 0, v85, s[44:45]
	v_cndmask_b32_e64 v30, 0, v84, s[44:45]
	v_cndmask_b32_e64 v83, 0, v87, s[44:45]
	v_cndmask_b32_e64 v82, 0, v86, s[44:45]
	v_pk_fma_f32 v[28:29], v[82:83], v[80:81], v[28:29]
	v_pk_fma_f32 v[24:25], v[30:31], v[34:35], v[24:25]
	v_lshlrev_b32_e32 v30, 16, v27
	v_lshlrev_b32_e32 v34, 16, v26
	v_and_b32_e32 v31, 0xffff0000, v27
	v_and_b32_e32 v35, 0xffff0000, v26
	v_cndmask_b32_e64 v117, 0, v149, s[42:43]
	v_cndmask_b32_e64 v116, 0, v148, s[42:43]
	v_cndmask_b32_e64 v119, 0, v147, s[42:43]
	v_cndmask_b32_e64 v118, 0, v146, s[42:43]
	v_pk_fma_f32 v[24:25], v[118:119], v[34:35], v[24:25]
	v_pk_fma_f32 v[26:27], v[116:117], v[30:31], v[28:29]
	v_cvt_pk_bf16_f32 v34, v24, v25
	ds_write2_b32 v121, v26, v27 offset0:38 offset1:39
	ds_write2_b32 v121, v24, v25 offset0:36 offset1:37
	v_mad_i64_i32 v[24:25], s[42:43], v134, s72, v[102:103]
	v_lshl_add_u64 v[24:25], v[24:25], 0, v[104:105]
	v_mad_i64_i32 v[28:29], s[42:43], v135, s72, v[102:103]
	v_cvt_pk_bf16_f32 v35, v26, v27
	flat_load_dwordx4 v[24:27], v[24:25]
	v_lshl_add_u64 v[28:29], v[28:29], 0, v[104:105]
	v_mad_i64_i32 v[80:81], s[42:43], v142, s72, v[102:103]
	flat_load_dwordx4 v[28:31], v[28:29]
	v_lshl_add_u64 v[80:81], v[80:81], 0, v[104:105]
	v_mad_i64_i32 v[96:97], s[42:43], v143, s72, v[102:103]
	flat_load_dwordx4 v[80:83], v[80:81]
	v_lshl_add_u64 v[96:97], v[96:97], 0, v[104:105]
	flat_load_dwordx4 v[96:99], v[96:97]
	v_cndmask_b32_e64 v147, 0, v79, s[62:63]
	v_cndmask_b32_e64 v146, 0, v78, s[62:63]
	v_cndmask_b32_e64 v149, 0, v21, s[60:61]
	v_cndmask_b32_e64 v148, 0, v20, s[60:61]
	s_add_i32 s48, s20, s27
	s_lshl_b32 s20, s91, 7
	s_add_u32 s44, s10, s20
	s_addc_u32 s45, s11, 0
	s_waitcnt vmcnt(0) lgkmcnt(0)
	v_lshlrev_b32_e32 v134, 16, v24
	v_lshlrev_b32_e32 v142, 16, v25
	v_and_b32_e32 v135, 0xffff0000, v24
	v_and_b32_e32 v143, 0xffff0000, v25
	v_cndmask_b32_e64 v25, 0, v77, s[62:63]
	v_cndmask_b32_e64 v24, 0, v76, s[62:63]
	v_pk_fma_f32 v[142:143], v[146:147], v[142:143], v[74:75]
	v_pk_fma_f32 v[24:25], v[24:25], v[134:135], v[72:73]
	v_lshlrev_b32_e32 v134, 16, v29
	v_lshlrev_b32_e32 v146, 16, v28
	v_and_b32_e32 v135, 0xffff0000, v29
	v_and_b32_e32 v147, 0xffff0000, v28
	v_cndmask_b32_e64 v29, 0, v23, s[60:61]
	v_cndmask_b32_e64 v28, 0, v22, s[60:61]
	v_pk_fma_f32 v[24:25], v[148:149], v[146:147], v[24:25]
	v_pk_fma_f32 v[28:29], v[28:29], v[134:135], v[142:143]
	v_lshlrev_b32_e32 v134, 16, v80
	v_lshlrev_b32_e32 v142, 16, v81
	v_and_b32_e32 v135, 0xffff0000, v80
	v_and_b32_e32 v143, 0xffff0000, v81
	v_cndmask_b32_e64 v81, 0, v93, s[58:59]
	v_cndmask_b32_e64 v80, 0, v92, s[58:59]
	v_cndmask_b32_e64 v147, 0, v95, s[58:59]
	v_cndmask_b32_e64 v146, 0, v94, s[58:59]
	v_pk_fma_f32 v[28:29], v[146:147], v[142:143], v[28:29]
	v_pk_fma_f32 v[24:25], v[80:81], v[134:135], v[24:25]
	v_lshlrev_b32_e32 v80, 16, v97
	v_lshlrev_b32_e32 v134, 16, v96
	v_and_b32_e32 v81, 0xffff0000, v97
	v_and_b32_e32 v135, 0xffff0000, v96
	v_pk_fma_f32 v[24:25], v[114:115], v[134:135], v[24:25]
	v_pk_fma_f32 v[80:81], v[106:107], v[80:81], v[28:29]
	v_cvt_pk_bf16_f32 v28, v24, v25
	v_cvt_pk_bf16_f32 v29, v80, v81
	ds_write2_b32 v125, v80, v81 offset0:34 offset1:35
	ds_write2_b32 v125, v24, v25 offset0:32 offset1:33
	v_lshlrev_b32_e32 v24, 16, v26
	v_lshlrev_b32_e32 v80, 16, v27
	v_and_b32_e32 v25, 0xffff0000, v26
	v_and_b32_e32 v81, 0xffff0000, v27
	v_cndmask_b32_e64 v27, 0, v69, s[62:63]
	v_cndmask_b32_e64 v26, 0, v68, s[62:63]
	v_cndmask_b32_e64 v97, 0, v71, s[62:63]
	v_cndmask_b32_e64 v96, 0, v70, s[62:63]
	v_pk_fma_f32 v[80:81], v[96:97], v[80:81], v[42:43]
	v_pk_fma_f32 v[24:25], v[26:27], v[24:25], v[40:41]
	v_lshlrev_b32_e32 v26, 16, v31
	v_lshlrev_b32_e32 v96, 16, v30
	v_and_b32_e32 v27, 0xffff0000, v31
	v_and_b32_e32 v97, 0xffff0000, v30
	v_cndmask_b32_e64 v31, 0, v39, s[60:61]
	v_cndmask_b32_e64 v30, 0, v38, s[60:61]
	v_cndmask_b32_e64 v135, 0, v37, s[60:61]
	v_cndmask_b32_e64 v134, 0, v36, s[60:61]
	v_pk_fma_f32 v[24:25], v[134:135], v[96:97], v[24:25]
	v_pk_fma_f32 v[26:27], v[30:31], v[26:27], v[80:81]
	v_lshlrev_b32_e32 v30, 16, v82
	v_lshlrev_b32_e32 v80, 16, v83
	v_and_b32_e32 v31, 0xffff0000, v82
	v_and_b32_e32 v81, 0xffff0000, v83
	v_cndmask_b32_e64 v83, 0, v85, s[58:59]
	v_cndmask_b32_e64 v82, 0, v84, s[58:59]
	v_cndmask_b32_e64 v97, 0, v87, s[58:59]
	v_cndmask_b32_e64 v96, 0, v86, s[58:59]
	v_pk_fma_f32 v[26:27], v[96:97], v[80:81], v[26:27]
	v_pk_fma_f32 v[24:25], v[82:83], v[30:31], v[24:25]
	v_lshlrev_b32_e32 v30, 16, v99
	v_lshlrev_b32_e32 v80, 16, v98
	v_and_b32_e32 v31, 0xffff0000, v99
	v_and_b32_e32 v81, 0xffff0000, v98
	v_pk_fma_f32 v[24:25], v[118:119], v[80:81], v[24:25]
	v_pk_fma_f32 v[26:27], v[116:117], v[30:31], v[26:27]
	v_cvt_pk_bf16_f32 v30, v24, v25
	ds_write2_b32 v125, v26, v27 offset0:38 offset1:39
	ds_write2_b32 v125, v24, v25 offset0:36 offset1:37
	v_mad_i64_i32 v[24:25], s[42:43], v130, s72, v[102:103]
	v_lshl_add_u64 v[24:25], v[24:25], 0, v[104:105]
	v_mad_i64_i32 v[80:81], s[42:43], v131, s72, v[102:103]
	v_cvt_pk_bf16_f32 v31, v26, v27
	flat_load_dwordx4 v[24:27], v[24:25]
	v_lshl_add_u64 v[80:81], v[80:81], 0, v[104:105]
	v_mad_i64_i32 v[96:97], s[42:43], v132, s72, v[102:103]
	flat_load_dwordx4 v[80:83], v[80:81]
	v_lshl_add_u64 v[96:97], v[96:97], 0, v[104:105]
	v_mad_i64_i32 v[130:131], s[42:43], v133, s72, v[102:103]
	flat_load_dwordx4 v[96:99], v[96:97]
	v_lshl_add_u64 v[130:131], v[130:131], 0, v[104:105]
	flat_load_dwordx4 v[130:133], v[130:131]
	v_cndmask_b32_e64 v147, 0, v79, s[56:57]
	v_cndmask_b32_e64 v146, 0, v78, s[56:57]
	v_cndmask_b32_e64 v149, 0, v21, s[54:55]
	v_cndmask_b32_e64 v148, 0, v20, s[54:55]
	v_cndmask_b32_e64 v79, 0, v79, s[46:47]
	v_cndmask_b32_e64 v78, 0, v78, s[46:47]
	v_cndmask_b32_e64 v21, 0, v21, s[40:41]
	v_cndmask_b32_e64 v20, 0, v20, s[40:41]
	s_waitcnt vmcnt(0) lgkmcnt(0)
; __device__ __forceinline__ void ld8bf(const bf16_t* p, float (&o)[8]) { unpack8(*(const u32x4*)p, o); }
; __device__ __forceinline__ bf16x8 pack_frag(const float (&v)[8]) { return __builtin_bit_cast(bf16x8, pack8(v)); }
; __device__ __forceinline__ void w_lru_m1(const Args& a, int l, unsigned char* ws, const bf16_t* proj, bf16_t* y, LAS unsigned char* wl, int b, int ck_, int h, int lane) {
;     ...
;         for (int tb = 0; tb < 4; ++tb) { const int tok = 16 * tb + lo, t = 64 * ck_ + tok; float s[8];
; #pragma unroll
;             for (int j = 0; j < 8; ++j) s[j] = bs[j];
; #pragma unroll
;             for (int k = 0; k < 4; ++k) { const int tt = t - 3 + k; float x[8];
;                 ld8bf(proj + (size_t)(b * SEQ + (tt >= 0 ? tt : 0)) * NIN + C_LX + ch0, x);
; #pragma unroll
;                 for (int j = 0; j < 8; ++j) s[j] += (tt >= 0 ? w[k][j] : 0.f) * x[j]; }
;             Xf[tb][kk] = pack_frag(s);
; #pragma unroll
;             for (int j = 0; j < 8; ++j) xcf[tok * 65 + 32 * kk + 8 * fq + j] = s[j]; }
	v_lshlrev_b32_e32 v134, 16, v24
	v_lshlrev_b32_e32 v142, 16, v25
	v_and_b32_e32 v135, 0xffff0000, v24
	v_and_b32_e32 v143, 0xffff0000, v25
	v_cndmask_b32_e64 v25, 0, v77, s[56:57]
	v_cndmask_b32_e64 v24, 0, v76, s[56:57]
	v_pk_fma_f32 v[142:143], v[146:147], v[142:143], v[74:75]
	v_pk_fma_f32 v[24:25], v[24:25], v[134:135], v[72:73]
	v_lshlrev_b32_e32 v134, 16, v81
	v_lshlrev_b32_e32 v146, 16, v80
	v_and_b32_e32 v135, 0xffff0000, v81
	v_and_b32_e32 v147, 0xffff0000, v80
	v_cndmask_b32_e64 v81, 0, v23, s[54:55]
	v_cndmask_b32_e64 v80, 0, v22, s[54:55]
	v_pk_fma_f32 v[24:25], v[148:149], v[146:147], v[24:25]
	v_pk_fma_f32 v[80:81], v[80:81], v[134:135], v[142:143]
	v_lshlrev_b32_e32 v134, 16, v96
	v_lshlrev_b32_e32 v142, 16, v97
	v_and_b32_e32 v135, 0xffff0000, v96
	v_and_b32_e32 v143, 0xffff0000, v97
	v_cndmask_b32_e64 v97, 0, v93, s[52:53]
	v_cndmask_b32_e64 v96, 0, v92, s[52:53]
	v_cndmask_b32_e64 v147, 0, v95, s[52:53]
	v_cndmask_b32_e64 v146, 0, v94, s[52:53]
	v_pk_fma_f32 v[80:81], v[146:147], v[142:143], v[80:81]
	v_pk_fma_f32 v[24:25], v[96:97], v[134:135], v[24:25]
	v_lshlrev_b32_e32 v96, 16, v131
	v_lshlrev_b32_e32 v134, 16, v130
	v_and_b32_e32 v97, 0xffff0000, v131
	v_and_b32_e32 v135, 0xffff0000, v130
	v_pk_fma_f32 v[130:131], v[114:115], v[134:135], v[24:25]
	v_pk_fma_f32 v[80:81], v[106:107], v[96:97], v[80:81]
	v_cvt_pk_bf16_f32 v24, v130, v131
	v_cvt_pk_bf16_f32 v25, v80, v81
	ds_write2_b32 v124, v80, v81 offset0:34 offset1:35
	ds_write2_b32 v124, v130, v131 offset0:32 offset1:33
	v_lshlrev_b32_e32 v80, 16, v26
	v_lshlrev_b32_e32 v96, 16, v27
	v_and_b32_e32 v81, 0xffff0000, v26
	v_and_b32_e32 v97, 0xffff0000, v27
	v_cndmask_b32_e64 v27, 0, v69, s[56:57]
	v_cndmask_b32_e64 v26, 0, v68, s[56:57]
	v_cndmask_b32_e64 v131, 0, v71, s[56:57]
	v_cndmask_b32_e64 v130, 0, v70, s[56:57]
	v_pk_fma_f32 v[96:97], v[130:131], v[96:97], v[42:43]
	v_pk_fma_f32 v[26:27], v[26:27], v[80:81], v[40:41]
	v_lshlrev_b32_e32 v80, 16, v83
	v_lshlrev_b32_e32 v130, 16, v82
	v_and_b32_e32 v81, 0xffff0000, v83
	v_and_b32_e32 v131, 0xffff0000, v82
	v_cndmask_b32_e64 v83, 0, v39, s[54:55]
	v_cndmask_b32_e64 v82, 0, v38, s[54:55]
	v_cndmask_b32_e64 v135, 0, v37, s[54:55]
	v_cndmask_b32_e64 v134, 0, v36, s[54:55]
	v_pk_fma_f32 v[26:27], v[134:135], v[130:131], v[26:27]
	v_pk_fma_f32 v[80:81], v[82:83], v[80:81], v[96:97]
	v_lshlrev_b32_e32 v82, 16, v98
	v_lshlrev_b32_e32 v96, 16, v99
	v_and_b32_e32 v83, 0xffff0000, v98
	v_and_b32_e32 v97, 0xffff0000, v99
	v_cndmask_b32_e64 v99, 0, v85, s[52:53]
	v_cndmask_b32_e64 v98, 0, v84, s[52:53]
	v_cndmask_b32_e64 v131, 0, v87, s[52:53]
	v_cndmask_b32_e64 v130, 0, v86, s[52:53]
	v_pk_fma_f32 v[80:81], v[130:131], v[96:97], v[80:81]
	v_pk_fma_f32 v[26:27], v[98:99], v[82:83], v[26:27]
	v_lshlrev_b32_e32 v82, 16, v133
	v_and_b32_e32 v83, 0xffff0000, v133
	v_lshlrev_b32_e32 v96, 16, v132
	v_and_b32_e32 v97, 0xffff0000, v132
	v_pk_fma_f32 v[80:81], v[116:117], v[82:83], v[80:81]
	v_pk_fma_f32 v[96:97], v[118:119], v[96:97], v[26:27]
	v_cvt_pk_bf16_f32 v27, v80, v81
	ds_write2_b32 v124, v80, v81 offset0:38 offset1:39
	ds_write2_b32 v124, v96, v97 offset0:36 offset1:37
	v_mad_i64_i32 v[80:81], s[42:43], v126, s72, v[102:103]
	v_lshl_add_u64 v[80:81], v[80:81], 0, v[104:105]
	flat_load_dwordx4 v[130:133], v[80:81]
	v_mad_i64_i32 v[80:81], s[42:43], v127, s72, v[102:103]
	v_lshl_add_u64 v[80:81], v[80:81], 0, v[104:105]
	flat_load_dwordx4 v[124:127], v[80:81]
	v_mad_i64_i32 v[80:81], s[42:43], v128, s72, v[102:103]
	v_lshl_add_u64 v[80:81], v[80:81], 0, v[104:105]
	v_cvt_pk_bf16_f32 v26, v96, v97
	flat_load_dwordx4 v[96:99], v[80:81]
	v_mad_i64_i32 v[80:81], s[42:43], v129, s72, v[102:103]
	v_lshl_add_u64 v[80:81], v[80:81], 0, v[104:105]
	flat_load_dwordx4 v[80:83], v[80:81]
	v_cndmask_b32_e64 v77, 0, v77, s[46:47]
	v_cndmask_b32_e64 v76, 0, v76, s[46:47]
	v_cndmask_b32_e64 v23, 0, v23, s[40:41]
	v_cndmask_b32_e64 v22, 0, v22, s[40:41]
	v_cndmask_b32_e64 v69, 0, v69, s[46:47]
	v_cndmask_b32_e64 v68, 0, v68, s[46:47]
	v_cndmask_b32_e64 v71, 0, v71, s[46:47]
	v_cndmask_b32_e64 v70, 0, v70, s[46:47]
	v_cndmask_b32_e64 v39, 0, v39, s[40:41]
	v_cndmask_b32_e64 v38, 0, v38, s[40:41]
	v_cndmask_b32_e64 v37, 0, v37, s[40:41]
	v_cndmask_b32_e64 v36, 0, v36, s[40:41]
	s_add_u32 s46, s71, s20
	s_addc_u32 s47, s64, 0
	s_ashr_i32 s91, s90, 31
	s_lshl_b64 s[42:43], s[90:91], 9
	s_or_b32 s42, s42, s21
	s_waitcnt vmcnt(0) lgkmcnt(0)
; __device__ __forceinline__ void ld8bf(const bf16_t* p, float (&o)[8]) { unpack8(*(const u32x4*)p, o); }
; __device__ __forceinline__ bf16x8 pack_frag(const float (&v)[8]) { return __builtin_bit_cast(bf16x8, pack8(v)); }
; __device__ __forceinline__ void w_lru_m1(const Args& a, int l, unsigned char* ws, const bf16_t* proj, bf16_t* y, LAS unsigned char* wl, int b, int ck_, int h, int lane) {
;     ...
;         for (int tb = 0; tb < 4; ++tb) { const int tok = 16 * tb + lo, t = 64 * ck_ + tok; float s[8];
; #pragma unroll
;             for (int j = 0; j < 8; ++j) s[j] = bs[j];
; #pragma unroll
;             for (int k = 0; k < 4; ++k) { const int tt = t - 3 + k; float x[8];
;                 ld8bf(proj + (size_t)(b * SEQ + (tt >= 0 ? tt : 0)) * NIN + C_LX + ch0, x);
; #pragma unroll
;                 for (int j = 0; j < 8; ++j) s[j] += (tt >= 0 ? w[k][j] : 0.f) * x[j]; }
;             Xf[tb][kk] = pack_frag(s);
; #pragma unroll
;             for (int j = 0; j < 8; ++j) xcf[tok * 65 + 32 * kk + 8 * fq + j] = s[j]; }
;     ...
;     for (int jb = 0; jb < 4; ++jb) {
;         bf16x8 WaF[2], WxF[2]; f32x4 pba, pbx, plam;
; #pragma unroll
;         for (int kk = 0; kk < 2; ++kk) { WaF[kk] = nWa[kk]; WxF[kk] = nWx[kk]; }
;         pba = nba; pbx = nbx; plam = nlam;
;         if (jb < 3) {
; #pragma unroll
;             for (int kk = 0; kk < 2; ++kk) { nWa[kk] = *(const bf16x8*)(waT + (16 * (jb + 1) + lo) * 64 + 32 * kk + 8 * fq); nWx[kk] = *(const bf16x8*)(wxT + (16 * (jb + 1) + lo) * 64 + 32 * kk + 8 * fq); }
;             nba = *(const f32x4*)(ba + 16 * (jb + 1) + 4 * fq); nbx = *(const f32x4*)(bx + 16 * (jb + 1) + 4 * fq); nlam = *(const f32x4*)(lam + 16 * (jb + 1) + 4 * fq);
;         }
;         const int j0 = 16 * jb + 4 * fq;
;         float bav[4], bxv[4], sp[4], hc[4], Pc[4];
; #pragma unroll
;         for (int r = 0; r < 4; ++r) { bav[r] = pba[r]; bxv[r] = pbx[r]; sp[r] = log1pf(__expf(-plam[r])); hc[r] = 0.f; Pc[r] = 1.f; }
	v_lshlrev_b32_e32 v102, 16, v130
	v_lshlrev_b32_e32 v104, 16, v131
	v_and_b32_e32 v103, 0xffff0000, v130
	v_and_b32_e32 v105, 0xffff0000, v131
	v_pk_fma_f32 v[74:75], v[78:79], v[104:105], v[74:75]
	v_pk_fma_f32 v[72:73], v[76:77], v[102:103], v[72:73]
	v_lshlrev_b32_e32 v76, 16, v125
	v_lshlrev_b32_e32 v78, 16, v124
	v_and_b32_e32 v77, 0xffff0000, v125
	v_and_b32_e32 v79, 0xffff0000, v124
	v_pk_fma_f32 v[20:21], v[20:21], v[78:79], v[72:73]
	v_pk_fma_f32 v[22:23], v[22:23], v[76:77], v[74:75]
	v_lshlrev_b32_e32 v72, 16, v96
	v_lshlrev_b32_e32 v74, 16, v97
	v_and_b32_e32 v73, 0xffff0000, v96
	v_and_b32_e32 v75, 0xffff0000, v97
	v_cndmask_b32_e32 v77, 0, v93, vcc
	v_cndmask_b32_e32 v76, 0, v92, vcc
	v_cndmask_b32_e32 v79, 0, v95, vcc
	v_cndmask_b32_e32 v78, 0, v94, vcc
	v_pk_fma_f32 v[22:23], v[78:79], v[74:75], v[22:23]
	v_pk_fma_f32 v[20:21], v[76:77], v[72:73], v[20:21]
	v_lshlrev_b32_e32 v72, 16, v81
	v_and_b32_e32 v73, 0xffff0000, v81
	v_lshlrev_b32_e32 v74, 16, v80
	v_and_b32_e32 v75, 0xffff0000, v80
	v_pk_fma_f32 v[22:23], v[106:107], v[72:73], v[22:23]
	v_pk_fma_f32 v[74:75], v[114:115], v[74:75], v[20:21]
	v_cvt_pk_bf16_f32 v21, v22, v23
	ds_write2_b32 v120, v22, v23 offset0:34 offset1:35
	ds_write2_b32 v120, v74, v75 offset0:32 offset1:33
	v_lshlrev_b32_e32 v22, 16, v132
	v_lshlrev_b32_e32 v72, 16, v133
	v_and_b32_e32 v23, 0xffff0000, v132
	v_and_b32_e32 v73, 0xffff0000, v133
	v_pk_fma_f32 v[42:43], v[70:71], v[72:73], v[42:43]
	v_pk_fma_f32 v[22:23], v[68:69], v[22:23], v[40:41]
	v_lshlrev_b32_e32 v40, 16, v127
	v_lshlrev_b32_e32 v68, 16, v126
	v_and_b32_e32 v41, 0xffff0000, v127
	v_and_b32_e32 v69, 0xffff0000, v126
	v_pk_fma_f32 v[22:23], v[36:37], v[68:69], v[22:23]
	v_pk_fma_f32 v[36:37], v[38:39], v[40:41], v[42:43]
	v_lshlrev_b32_e32 v38, 16, v98
	v_lshlrev_b32_e32 v40, 16, v99
	v_and_b32_e32 v39, 0xffff0000, v98
	v_and_b32_e32 v41, 0xffff0000, v99
	v_cndmask_b32_e32 v43, 0, v85, vcc
	v_cndmask_b32_e32 v42, 0, v84, vcc
	v_cndmask_b32_e32 v69, 0, v87, vcc
	v_cndmask_b32_e32 v68, 0, v86, vcc
	v_pk_fma_f32 v[36:37], v[68:69], v[40:41], v[36:37]
	v_pk_fma_f32 v[22:23], v[42:43], v[38:39], v[22:23]
	v_lshlrev_b32_e32 v38, 16, v83
	v_and_b32_e32 v39, 0xffff0000, v83
	v_lshlrev_b32_e32 v40, 16, v82
	v_and_b32_e32 v41, 0xffff0000, v82
	v_pk_fma_f32 v[36:37], v[116:117], v[38:39], v[36:37]
	v_pk_fma_f32 v[40:41], v[118:119], v[40:41], v[22:23]
	v_cvt_pk_bf16_f32 v23, v36, v37
	ds_write2_b32 v120, v36, v37 offset0:38 offset1:39
	ds_write2_b32 v120, v40, v41 offset0:36 offset1:37
	v_lshlrev_b32_e32 v36, 2, v122
	v_lshl_add_u64 v[118:119], s[92:93], 0, v[100:101]
	v_lshl_add_u64 v[120:121], s[34:35], 0, v[100:101]
	v_and_b32_e32 v143, 0xc0, v36
	v_lshl_add_u64 v[36:37], v[118:119], 0, v[2:3]
	v_lshl_add_u64 v[38:39], v[120:121], 0, v[2:3]
	v_mul_f32_e32 v2, 0xbfb8aa3b, v88
	v_exp_f32_e32 v2, v2
	s_waitcnt lgkmcnt(0)
	v_cvt_pk_bf16_f32 v20, v74, v75
	v_cvt_pk_bf16_f32 v22, v40, v41
	v_add_f32_e32 v88, 1.0, v2
	v_add_f32_e32 v92, -1.0, v88
	v_sub_f32_e32 v93, v92, v88
	v_add_f32_e32 v93, 1.0, v93
	v_sub_f32_e32 v92, v2, v92
	v_add_f32_e32 v94, v92, v93
	v_frexp_mant_f32_e32 v92, v88
	v_cmp_gt_f32_e64 s[40:41], s77, v92
	v_cvt_f64_f32_e32 v[92:93], v88
	v_frexp_exp_i32_f64_e32 v92, v[92:93]
	v_subbrev_co_u32_e64 v100, s[40:41], 0, v92, s[40:41]
	v_sub_u32_e32 v92, 0, v100
	v_ldexp_f32 v88, v88, v92
	v_ldexp_f32 v92, v94, v92
	v_add_f32_e32 v94, -1.0, v88
	v_add_f32_e32 v93, 1.0, v94
	v_sub_f32_e32 v93, v88, v93
	v_add_f32_e32 v95, v92, v93
	v_add_f32_e32 v93, 1.0, v88
	v_add_f32_e32 v96, -1.0, v93
	v_sub_f32_e32 v88, v88, v96
	v_add_f32_e32 v88, v92, v88
	v_add_f32_e32 v101, v93, v88
	v_rcp_f32_e32 v102, v101
	v_sub_f32_e32 v92, v101, v93
	v_add_f32_e32 v93, v94, v95
	v_sub_f32_e32 v88, v88, v92
	v_mul_f32_e32 v104, v93, v102
	v_sub_f32_e32 v92, v93, v94
	v_mul_f32_e32 v94, v101, v104
	v_fma_f32 v96, v104, v101, -v94
	v_fmac_f32_e32 v96, v104, v88
	v_sub_f32_e32 v103, v95, v92
	v_add_f32_e32 v92, v94, v96
	v_sub_f32_e32 v95, v93, v92
	v_pk_add_f32 v[98:99], v[92:93], v[94:95] neg_lo:[0,1] neg_hi:[0,1]
	v_mov_b32_e32 v97, v92
	v_pk_add_f32 v[92:93], v[98:99], v[96:97] neg_lo:[0,1] neg_hi:[0,1]
	v_cmp_neq_f32_e64 s[40:41], s22, v2
	v_add_f32_e32 v93, v103, v93
	v_add_f32_e32 v92, v92, v93
	v_add_f32_e32 v93, v95, v92
	v_mul_f32_e32 v103, v102, v93
	v_mul_f32_e32 v94, v101, v103
	v_fma_f32 v96, v103, v101, -v94
	v_fmac_f32_e32 v96, v103, v88
	v_sub_f32_e32 v88, v95, v93
	v_add_f32_e32 v88, v92, v88
	v_add_f32_e32 v92, v94, v96
	v_sub_f32_e32 v95, v93, v92
	v_pk_add_f32 v[98:99], v[92:93], v[94:95] neg_lo:[0,1] neg_hi:[0,1]
	v_mov_b32_e32 v97, v92
	v_pk_add_f32 v[92:93], v[98:99], v[96:97] neg_lo:[0,1] neg_hi:[0,1]
	global_load_dwordx4 v[68:71], v[36:37], off offset:2048
	global_load_dwordx4 v[72:75], v[38:39], off offset:2048
	global_load_dwordx4 v[76:79], v[36:37], off offset:2112
	global_load_dwordx4 v[80:83], v[38:39], off offset:2112
	global_load_dwordx4 v[40:43], v[108:109], off offset:64
	s_nop 0
	global_load_dwordx4 v[36:39], v[110:111], off offset:64
	global_load_dwordx4 v[84:87], v[112:113], off offset:64
	v_add_f32_e32 v88, v88, v93
	v_add_f32_e32 v88, v92, v88
	v_add_f32_e32 v93, v104, v103
	v_add_f32_e32 v88, v95, v88
	v_sub_f32_e32 v92, v93, v104
	v_mul_f32_e32 v88, v102, v88
	v_sub_f32_e32 v92, v103, v92
	v_add_f32_e32 v88, v92, v88
	v_add_f32_e32 v94, v93, v88
	v_mul_f32_e32 v96, v94, v94
	v_fmamk_f32 v92, v96, 0x3e9b6dac, v201
	v_fmaak_f32 v169, v96, v92, 0x3f2aaada
	v_cvt_f32_i32_e32 v92, v100
	v_sub_f32_e32 v93, v94, v93
	v_sub_f32_e32 v88, v88, v93
	v_mul_f32_e32 v93, v94, v96
	v_pk_mul_f32 v[96:97], v[92:93], v[168:169]
; __device__ __forceinline__ void w_lru_m1(const Args& a, int l, unsigned char* ws, const bf16_t* proj, bf16_t* y, LAS unsigned char* wl, int b, int ck_, int h, int lane) {
;     ...
;         for (int r = 0; r < 4; ++r) { bav[r] = pba[r]; bxv[r] = pbx[r]; sp[r] = log1pf(__expf(-plam[r])); hc[r] = 0.f; Pc[r] = 1.f; }
	v_ldexp_f32 v95, v94, 1
	v_fma_f32 v94, v92, s94, -v96
	v_fmac_f32_e32 v94, 0xb102e308, v92
	v_pk_add_f32 v[92:93], v[96:97], v[94:95]
	v_ldexp_f32 v88, v88, 1
	v_sub_f32_e32 v95, v93, v95
	v_sub_f32_e32 v95, v97, v95
	v_add_f32_e32 v99, v88, v95
	v_mov_b32_e32 v98, v96
	v_pk_add_f32 v[96:97], v[92:93], v[96:97] neg_lo:[0,1] neg_hi:[0,1]
	v_pk_add_f32 v[100:101], v[92:93], v[98:99]
	v_mov_b32_e32 v95, v92
	v_mov_b32_e32 v97, v101
	v_pk_add_f32 v[102:103], v[94:95], v[96:97] neg_lo:[0,1] neg_hi:[0,1]
	v_pk_add_f32 v[94:95], v[94:95], v[96:97]
	v_mov_b32_e32 v98, v99
	v_pk_add_f32 v[96:97], v[94:95], v[92:93] op_sel:[1,0] op_sel_hi:[0,1] neg_lo:[0,1] neg_hi:[0,1]
	v_pk_add_f32 v[104:105], v[100:101], v[96:97] op_sel_hi:[1,0] neg_lo:[0,1] neg_hi:[0,1]
	v_mov_b32_e32 v100, v101
	v_mov_b32_e32 v101, v95
	v_pk_mov_b32 v[96:97], v[92:93], v[96:97] op_sel:[1,0]
	v_mov_b32_e32 v99, v92
	v_pk_add_f32 v[96:97], v[100:101], v[96:97] neg_lo:[0,1] neg_hi:[0,1]
	v_mov_b32_e32 v104, v102
	v_pk_add_f32 v[92:93], v[98:99], v[96:97] neg_lo:[0,1] neg_hi:[0,1]
	v_mov_b32_e32 v103, v95
	v_pk_add_f32 v[96:97], v[104:105], v[92:93]
	v_mov_b32_e32 v104, 1.0
	v_pk_add_f32 v[98:99], v[96:97], v[96:97] op_sel:[0,1] op_sel_hi:[1,0]
	v_mov_b32_e32 v105, 1.0
	v_pk_add_f32 v[94:95], v[94:95], v[98:99] op_sel:[1,0] op_sel_hi:[0,1]
	v_mov_b32_e32 v97, v94
	v_pk_add_f32 v[100:101], v[96:97], v[102:103] neg_lo:[0,1] neg_hi:[0,1]
	v_mov_b32_e32 v93, v98
	v_sub_f32_e32 v88, v96, v100
	v_pk_add_f32 v[92:93], v[92:93], v[100:101] neg_lo:[0,1] neg_hi:[0,1]
	v_sub_f32_e32 v88, v102, v88
	v_add_f32_e32 v88, v92, v88
	v_add_f32_e32 v88, v88, v93
	v_add_f32_e32 v88, v94, v88
	v_cndmask_b32_e64 v88, v208, v88, s[40:41]
	v_cmp_ngt_f32_e64 s[40:41], -1.0, v2
	v_cmp_eq_u32_e32 vcc, 0, v136
	s_nop 0
	v_cndmask_b32_e64 v88, v205, v88, s[40:41]
	v_cmp_neq_f32_e64 s[40:41], -1.0, v2
	s_nop 1
	v_cndmask_b32_e64 v88, v206, v88, s[40:41]
	v_cmp_lt_f32_e64 s[40:41], |v2|, s95
	s_nop 1
	v_cndmask_b32_e64 v145, v88, v2, s[40:41]
	v_mul_f32_e32 v2, 0xbfb8aa3b, v89
	v_exp_f32_e32 v2, v2
	s_nop 0
	v_add_f32_e32 v92, 1.0, v2
	v_add_f32_e32 v88, -1.0, v92
	v_sub_f32_e32 v89, v88, v92
	v_add_f32_e32 v89, 1.0, v89
	v_sub_f32_e32 v88, v2, v88
	v_add_f32_e32 v93, v88, v89
	v_frexp_mant_f32_e32 v88, v92
	v_cmp_gt_f32_e64 s[40:41], s77, v88
	v_cvt_f64_f32_e32 v[88:89], v92
	v_frexp_exp_i32_f64_e32 v88, v[88:89]
	v_subbrev_co_u32_e64 v98, s[40:41], 0, v88, s[40:41]
	v_sub_u32_e32 v88, 0, v98
	v_ldexp_f32 v89, v92, v88
	v_add_f32_e32 v92, -1.0, v89
	v_add_f32_e32 v94, 1.0, v89
	v_ldexp_f32 v88, v93, v88
	v_add_f32_e32 v93, 1.0, v92
	v_add_f32_e32 v95, -1.0, v94
	v_sub_f32_e32 v93, v89, v93
	v_sub_f32_e32 v89, v89, v95
	v_add_f32_e32 v93, v88, v93
	v_add_f32_e32 v88, v88, v89
	v_add_f32_e32 v99, v94, v88
	v_rcp_f32_e32 v101, v99
	v_sub_f32_e32 v89, v99, v94
	v_sub_f32_e32 v100, v88, v89
	v_add_f32_e32 v89, v92, v93
	v_mul_f32_e32 v103, v89, v101
	v_sub_f32_e32 v88, v89, v92
	v_mul_f32_e32 v92, v99, v103
	v_fma_f32 v94, v103, v99, -v92
	v_fmac_f32_e32 v94, v103, v100
	v_sub_f32_e32 v102, v93, v88
	v_add_f32_e32 v88, v92, v94
	v_sub_f32_e32 v93, v89, v88
	v_pk_add_f32 v[96:97], v[88:89], v[92:93] neg_lo:[0,1] neg_hi:[0,1]
	v_mov_b32_e32 v95, v88
	v_pk_add_f32 v[88:89], v[96:97], v[94:95] neg_lo:[0,1] neg_hi:[0,1]
	v_cmp_neq_f32_e64 s[40:41], s22, v2
	v_add_f32_e32 v89, v102, v89
	v_add_f32_e32 v88, v88, v89
	v_add_f32_e32 v89, v93, v88
	v_mul_f32_e32 v102, v101, v89
	v_mul_f32_e32 v92, v99, v102
	v_fma_f32 v94, v102, v99, -v92
	v_fmac_f32_e32 v94, v102, v100
	v_sub_f32_e32 v93, v93, v89
	v_add_f32_e32 v99, v88, v93
	v_add_f32_e32 v88, v92, v94
	v_sub_f32_e32 v93, v89, v88
	v_pk_add_f32 v[96:97], v[88:89], v[92:93] neg_lo:[0,1] neg_hi:[0,1]
	v_mov_b32_e32 v95, v88
	v_pk_add_f32 v[88:89], v[96:97], v[94:95] neg_lo:[0,1] neg_hi:[0,1]
	s_nop 0
	v_add_f32_e32 v89, v99, v89
	v_add_f32_e32 v88, v88, v89
	v_add_f32_e32 v89, v103, v102
	v_add_f32_e32 v88, v93, v88
	v_sub_f32_e32 v92, v89, v103
	v_mul_f32_e32 v88, v101, v88
	v_sub_f32_e32 v92, v102, v92
	v_add_f32_e32 v92, v92, v88
	v_add_f32_e32 v94, v89, v92
	v_mul_f32_e32 v95, v94, v94
	v_fmamk_f32 v88, v95, 0x3e9b6dac, v201
	v_fmaak_f32 v169, v95, v88, 0x3f2aaada
	v_cvt_f32_i32_e32 v88, v98
	v_sub_f32_e32 v89, v94, v89
	v_sub_f32_e32 v89, v92, v89
	v_ldexp_f32 v96, v89, 1
	v_mul_f32_e32 v89, v94, v95
	v_ldexp_f32 v93, v94, 1
	v_pk_mul_f32 v[94:95], v[88:89], v[168:169]
	s_nop 0
	v_fma_f32 v92, v88, s94, -v94
	v_fmac_f32_e32 v92, 0xb102e308, v88
	v_pk_add_f32 v[88:89], v[94:95], v[92:93]
	s_nop 0
	v_sub_f32_e32 v93, v89, v93
	v_sub_f32_e32 v93, v95, v93
	v_add_f32_e32 v97, v96, v93
	v_mov_b32_e32 v96, v94
	v_pk_add_f32 v[94:95], v[88:89], v[94:95] neg_lo:[0,1] neg_hi:[0,1]
	v_pk_add_f32 v[98:99], v[88:89], v[96:97]
	v_mov_b32_e32 v93, v88
	v_mov_b32_e32 v95, v99
	v_pk_add_f32 v[100:101], v[92:93], v[94:95] neg_lo:[0,1] neg_hi:[0,1]
	v_pk_add_f32 v[92:93], v[92:93], v[94:95]
	v_mov_b32_e32 v96, v97
	v_pk_add_f32 v[94:95], v[92:93], v[88:89] op_sel:[1,0] op_sel_hi:[0,1] neg_lo:[0,1] neg_hi:[0,1]
	v_pk_add_f32 v[102:103], v[98:99], v[94:95] op_sel_hi:[1,0] neg_lo:[0,1] neg_hi:[0,1]
	v_mov_b32_e32 v98, v99
	v_mov_b32_e32 v99, v93
	v_pk_mov_b32 v[94:95], v[88:89], v[94:95] op_sel:[1,0]
	v_mov_b32_e32 v97, v88
	v_pk_add_f32 v[94:95], v[98:99], v[94:95] neg_lo:[0,1] neg_hi:[0,1]
	v_mov_b32_e32 v102, v100
	v_pk_add_f32 v[88:89], v[96:97], v[94:95] neg_lo:[0,1] neg_hi:[0,1]
	v_mov_b32_e32 v101, v93
	v_pk_add_f32 v[94:95], v[102:103], v[88:89]
	s_nop 0
	v_pk_add_f32 v[96:97], v[94:95], v[94:95] op_sel:[0,1] op_sel_hi:[1,0]
	s_nop 0
	v_pk_add_f32 v[92:93], v[92:93], v[96:97] op_sel:[1,0] op_sel_hi:[0,1]
; __device__ __forceinline__ void w_lru_m1(const Args& a, int l, unsigned char* ws, const bf16_t* proj, bf16_t* y, LAS unsigned char* wl, int b, int ck_, int h, int lane) {
;     ...
;         for (int r = 0; r < 4; ++r) { bav[r] = pba[r]; bxv[r] = pbx[r]; sp[r] = log1pf(__expf(-plam[r])); hc[r] = 0.f; Pc[r] = 1.f; }
	v_mov_b32_e32 v95, v92
	v_pk_add_f32 v[98:99], v[94:95], v[100:101] neg_lo:[0,1] neg_hi:[0,1]
	v_mov_b32_e32 v89, v96
	v_sub_f32_e32 v93, v94, v98
	v_pk_add_f32 v[88:89], v[88:89], v[98:99] neg_lo:[0,1] neg_hi:[0,1]
	v_sub_f32_e32 v93, v100, v93
	v_add_f32_e32 v88, v88, v93
	v_add_f32_e32 v88, v88, v89
	v_add_f32_e32 v88, v92, v88
	v_cndmask_b32_e64 v88, v208, v88, s[40:41]
	v_cmp_ngt_f32_e64 s[40:41], -1.0, v2
	s_nop 1
	v_cndmask_b32_e64 v88, v205, v88, s[40:41]
	v_cmp_neq_f32_e64 s[40:41], -1.0, v2
	s_nop 1
	v_cndmask_b32_e64 v88, v206, v88, s[40:41]
	v_cmp_lt_f32_e64 s[40:41], |v2|, s95
	s_nop 1
	v_cndmask_b32_e64 v147, v88, v2, s[40:41]
	v_mul_f32_e32 v2, 0xbfb8aa3b, v90
	v_exp_f32_e32 v2, v2
	s_nop 0
	v_add_f32_e32 v90, 1.0, v2
	v_add_f32_e32 v88, -1.0, v90
	v_sub_f32_e32 v89, v88, v90
	v_add_f32_e32 v89, 1.0, v89
	v_sub_f32_e32 v88, v2, v88
	v_add_f32_e32 v92, v88, v89
	v_frexp_mant_f32_e32 v88, v90
	v_cmp_gt_f32_e64 s[40:41], s77, v88
	v_cvt_f64_f32_e32 v[88:89], v90
	v_frexp_exp_i32_f64_e32 v88, v[88:89]
	v_subbrev_co_u32_e64 v98, s[40:41], 0, v88, s[40:41]
	v_sub_u32_e32 v88, 0, v98
	v_ldexp_f32 v89, v90, v88
	v_add_f32_e32 v90, -1.0, v89
	v_add_f32_e32 v93, 1.0, v89
	v_ldexp_f32 v88, v92, v88
	v_add_f32_e32 v92, 1.0, v90
	v_add_f32_e32 v94, -1.0, v93
	v_sub_f32_e32 v92, v89, v92
	v_sub_f32_e32 v89, v89, v94
	v_add_f32_e32 v92, v88, v92
	v_add_f32_e32 v88, v88, v89
	v_add_f32_e32 v99, v93, v88
	v_rcp_f32_e32 v101, v99
	v_sub_f32_e32 v89, v99, v93
	v_sub_f32_e32 v100, v88, v89
	v_add_f32_e32 v89, v90, v92
	v_sub_f32_e32 v88, v89, v90
	v_mul_f32_e32 v102, v89, v101
	v_sub_f32_e32 v90, v92, v88
	v_mul_f32_e32 v92, v99, v102
	v_fma_f32 v94, v102, v99, -v92
	v_fmac_f32_e32 v94, v102, v100
	v_add_f32_e32 v88, v92, v94
	v_sub_f32_e32 v93, v89, v88
	v_pk_add_f32 v[96:97], v[88:89], v[92:93] neg_lo:[0,1] neg_hi:[0,1]
	v_mov_b32_e32 v95, v88
	v_pk_add_f32 v[88:89], v[96:97], v[94:95] neg_lo:[0,1] neg_hi:[0,1]
	v_cmp_neq_f32_e64 s[40:41], s22, v2
	v_add_f32_e32 v89, v90, v89
	v_add_f32_e32 v88, v88, v89
	v_add_f32_e32 v89, v93, v88
	v_mul_f32_e32 v90, v101, v89
	v_mul_f32_e32 v92, v99, v90
	v_fma_f32 v94, v90, v99, -v92
	v_fmac_f32_e32 v94, v90, v100
	v_sub_f32_e32 v93, v93, v89
	v_add_f32_e32 v99, v88, v93
	v_add_f32_e32 v88, v92, v94
	v_sub_f32_e32 v93, v89, v88
	v_pk_add_f32 v[96:97], v[88:89], v[92:93] neg_lo:[0,1] neg_hi:[0,1]
	v_mov_b32_e32 v95, v88
	v_pk_add_f32 v[88:89], v[96:97], v[94:95] neg_lo:[0,1] neg_hi:[0,1]
	s_nop 0
	v_add_f32_e32 v89, v99, v89
	v_add_f32_e32 v88, v88, v89
	v_add_f32_e32 v89, v102, v90
	v_add_f32_e32 v88, v93, v88
	v_sub_f32_e32 v92, v89, v102
	v_mul_f32_e32 v88, v101, v88
	v_sub_f32_e32 v90, v90, v92
	v_add_f32_e32 v90, v90, v88
	v_add_f32_e32 v92, v89, v90
	v_mul_f32_e32 v94, v92, v92
	v_fmamk_f32 v88, v94, 0x3e9b6dac, v201
	v_fmaak_f32 v169, v94, v88, 0x3f2aaada
	v_cvt_f32_i32_e32 v88, v98
	v_sub_f32_e32 v89, v92, v89
	v_sub_f32_e32 v89, v90, v89
	v_ldexp_f32 v90, v89, 1
	v_mul_f32_e32 v89, v92, v94
	v_pk_mul_f32 v[94:95], v[88:89], v[168:169]
	v_ldexp_f32 v93, v92, 1
	v_fma_f32 v92, v88, s94, -v94
	v_fmac_f32_e32 v92, 0xb102e308, v88
	v_pk_add_f32 v[88:89], v[94:95], v[92:93]
	v_mov_b32_e32 v96, v94
	v_sub_f32_e32 v93, v89, v93
	v_sub_f32_e32 v93, v95, v93
	v_add_f32_e32 v97, v90, v93
	v_pk_add_f32 v[94:95], v[88:89], v[94:95] neg_lo:[0,1] neg_hi:[0,1]
	v_pk_add_f32 v[98:99], v[88:89], v[96:97]
	v_mov_b32_e32 v93, v88
	v_mov_b32_e32 v95, v99
	v_pk_add_f32 v[100:101], v[92:93], v[94:95] neg_lo:[0,1] neg_hi:[0,1]
	v_pk_add_f32 v[92:93], v[92:93], v[94:95]
	v_mov_b32_e32 v96, v97
	v_pk_add_f32 v[94:95], v[92:93], v[88:89] op_sel:[1,0] op_sel_hi:[0,1] neg_lo:[0,1] neg_hi:[0,1]
	v_pk_add_f32 v[102:103], v[98:99], v[94:95] op_sel_hi:[1,0] neg_lo:[0,1] neg_hi:[0,1]
	v_mov_b32_e32 v98, v99
	v_mov_b32_e32 v99, v93
	v_pk_mov_b32 v[94:95], v[88:89], v[94:95] op_sel:[1,0]
	v_mov_b32_e32 v97, v88
	v_pk_add_f32 v[94:95], v[98:99], v[94:95] neg_lo:[0,1] neg_hi:[0,1]
	v_mov_b32_e32 v102, v100
	v_pk_add_f32 v[88:89], v[96:97], v[94:95] neg_lo:[0,1] neg_hi:[0,1]
	v_mov_b32_e32 v101, v93
	v_pk_add_f32 v[94:95], v[102:103], v[88:89]
	v_mov_b32_e32 v103, 1.0
	v_pk_add_f32 v[96:97], v[94:95], v[94:95] op_sel:[0,1] op_sel_hi:[1,0]
	s_nop 0
	v_pk_add_f32 v[92:93], v[92:93], v[96:97] op_sel:[1,0] op_sel_hi:[0,1]
	v_mov_b32_e32 v95, v92
	v_pk_add_f32 v[98:99], v[94:95], v[100:101] neg_lo:[0,1] neg_hi:[0,1]
	v_mov_b32_e32 v89, v96
	v_sub_f32_e32 v90, v94, v98
	v_pk_add_f32 v[88:89], v[88:89], v[98:99] neg_lo:[0,1] neg_hi:[0,1]
	v_sub_f32_e32 v90, v100, v90
	v_add_f32_e32 v88, v88, v90
	v_add_f32_e32 v88, v88, v89
	v_add_f32_e32 v88, v92, v88
	v_cndmask_b32_e64 v88, v208, v88, s[40:41]
	v_cmp_ngt_f32_e64 s[40:41], -1.0, v2
	s_nop 1
	v_cndmask_b32_e64 v88, v205, v88, s[40:41]
	v_cmp_neq_f32_e64 s[40:41], -1.0, v2
	s_nop 1
	v_cndmask_b32_e64 v88, v206, v88, s[40:41]
	v_cmp_lt_f32_e64 s[40:41], |v2|, s95
	s_nop 1
	v_cndmask_b32_e64 v2, v88, v2, s[40:41]
	v_mul_f32_e32 v88, 0xbfb8aa3b, v91
	v_exp_f32_e32 v102, v88
	s_nop 0
	v_add_f32_e32 v90, 1.0, v102
	v_add_f32_e32 v88, -1.0, v90
	v_sub_f32_e32 v89, v88, v90
	v_add_f32_e32 v89, 1.0, v89
	v_sub_f32_e32 v88, v102, v88
	v_add_f32_e32 v91, v88, v89
	v_frexp_mant_f32_e32 v88, v90
	v_cmp_gt_f32_e64 s[40:41], s77, v88
	v_cvt_f64_f32_e32 v[88:89], v90
	v_frexp_exp_i32_f64_e32 v88, v[88:89]
	v_subbrev_co_u32_e64 v96, s[40:41], 0, v88, s[40:41]
	v_sub_u32_e32 v88, 0, v96
	v_ldexp_f32 v89, v90, v88
	v_add_f32_e32 v90, -1.0, v89
	v_add_f32_e32 v92, 1.0, v89
	v_ldexp_f32 v88, v91, v88
	v_add_f32_e32 v91, 1.0, v90
	v_add_f32_e32 v93, -1.0, v92
	v_sub_f32_e32 v91, v89, v91
	v_sub_f32_e32 v89, v89, v93
; __device__ __forceinline__ float sigmoidf_(float x) { return __builtin_amdgcn_rcpf(1.0f + __expf(-x)); }
; __device__ __forceinline__ void w_lru_m1(const Args& a, int l, unsigned char* ws, const bf16_t* proj, bf16_t* y, LAS unsigned char* wl, int b, int ck_, int h, int lane) {
;     ...
;         for (int r = 0; r < 4; ++r) { bav[r] = pba[r]; bxv[r] = pbx[r]; sp[r] = log1pf(__expf(-plam[r])); hc[r] = 0.f; Pc[r] = 1.f; }
; #pragma unroll
;         for (int tb = 0; tb < 4; ++tb) { const int tok = 16 * tb + lo;
;             f32x4 ga = {0.f, 0.f, 0.f, 0.f}, gx = {0.f, 0.f, 0.f, 0.f};
; #pragma unroll
;             for (int kk = 0; kk < 2; ++kk) { ga = __builtin_amdgcn_mfma_f32_16x16x32_bf16(WaF[kk], Xf[tb][kk], ga, 0, 0, 0); gx = __builtin_amdgcn_mfma_f32_16x16x32_bf16(WxF[kk], Xf[tb][kk], gx, 0, 0, 0); }
;             float hv[4], pv[4];
; #pragma unroll
;             for (int r = 0; r < 4; ++r) {
;                 const float rg = sigmoidf_(ga[r] + bav[r]), ig = sigmoidf_(gx[r] + bxv[r]);
;                 const float la = -8.0f * rg * sp[r]; float A = __expf(la);
;                 float U = __builtin_amdgcn_sqrtf(1.0f - A * A) * (ig * xcf[tok * 65 + j0 + r]);
;                 { const float As = dpp_shr1<1>(A), Us = dpp_shr0<1>(U); U = A * Us + U; A = A * As; }
;                 { const float As = dpp_shr1<2>(A), Us = dpp_shr0<2>(U); U = A * Us + U; A = A * As; }
;                 { const float As = dpp_shr1<4>(A), Us = dpp_shr0<4>(U); U = A * Us + U; A = A * As; }
;                 { const float As = dpp_shr1<8>(A), Us = dpp_shr0<8>(U); U = A * Us + U; A = A * As; }
	v_add_f32_e32 v91, v88, v91
	v_add_f32_e32 v88, v88, v89
	v_add_f32_e32 v97, v92, v88
	v_rcp_f32_e32 v99, v97
	v_sub_f32_e32 v89, v97, v92
	v_sub_f32_e32 v98, v88, v89
	v_add_f32_e32 v89, v90, v91
	v_mul_f32_e32 v101, v89, v99
	v_sub_f32_e32 v88, v89, v90
	v_mul_f32_e32 v90, v97, v101
	v_fma_f32 v92, v101, v97, -v90
	v_fmac_f32_e32 v92, v101, v98
	v_sub_f32_e32 v100, v91, v88
	v_add_f32_e32 v88, v90, v92
	v_sub_f32_e32 v91, v89, v88
	v_pk_add_f32 v[94:95], v[88:89], v[90:91] neg_lo:[0,1] neg_hi:[0,1]
	v_mov_b32_e32 v93, v88
	v_pk_add_f32 v[88:89], v[94:95], v[92:93] neg_lo:[0,1] neg_hi:[0,1]
	v_cmp_neq_f32_e64 s[40:41], s22, v102
	v_add_f32_e32 v89, v100, v89
	v_add_f32_e32 v88, v88, v89
	v_add_f32_e32 v89, v91, v88
	v_mul_f32_e32 v100, v99, v89
	v_mul_f32_e32 v90, v97, v100
	v_fma_f32 v92, v100, v97, -v90
	v_fmac_f32_e32 v92, v100, v98
	v_sub_f32_e32 v91, v91, v89
	v_add_f32_e32 v97, v88, v91
	v_add_f32_e32 v88, v90, v92
	v_sub_f32_e32 v91, v89, v88
	v_pk_add_f32 v[94:95], v[88:89], v[90:91] neg_lo:[0,1] neg_hi:[0,1]
	v_mov_b32_e32 v93, v88
	v_pk_add_f32 v[88:89], v[94:95], v[92:93] neg_lo:[0,1] neg_hi:[0,1]
	s_nop 0
	v_add_f32_e32 v89, v97, v89
	v_add_f32_e32 v88, v88, v89
	v_add_f32_e32 v89, v101, v100
	v_add_f32_e32 v88, v91, v88
	v_sub_f32_e32 v90, v89, v101
	v_mul_f32_e32 v88, v99, v88
	v_sub_f32_e32 v90, v100, v90
	v_add_f32_e32 v90, v90, v88
	v_add_f32_e32 v92, v89, v90
	v_mul_f32_e32 v93, v92, v92
	v_fmamk_f32 v88, v93, 0x3e9b6dac, v201
	v_fmaak_f32 v169, v93, v88, 0x3f2aaada
	v_cvt_f32_i32_e32 v88, v96
	v_sub_f32_e32 v89, v92, v89
	v_sub_f32_e32 v89, v90, v89
	v_ldexp_f32 v94, v89, 1
	v_mul_f32_e32 v89, v92, v93
	v_ldexp_f32 v91, v92, 1
	v_pk_mul_f32 v[92:93], v[88:89], v[168:169]
	s_nop 0
	v_fma_f32 v90, v88, s94, -v92
	v_fmac_f32_e32 v90, 0xb102e308, v88
	v_pk_add_f32 v[88:89], v[92:93], v[90:91]
	s_nop 0
	v_sub_f32_e32 v91, v89, v91
	v_sub_f32_e32 v91, v93, v91
	v_add_f32_e32 v95, v94, v91
	v_mov_b32_e32 v94, v92
	v_pk_add_f32 v[92:93], v[88:89], v[92:93] neg_lo:[0,1] neg_hi:[0,1]
	v_pk_add_f32 v[96:97], v[88:89], v[94:95]
	v_mov_b32_e32 v91, v88
	v_mov_b32_e32 v93, v97
	v_pk_add_f32 v[98:99], v[90:91], v[92:93] neg_lo:[0,1] neg_hi:[0,1]
	v_pk_add_f32 v[90:91], v[90:91], v[92:93]
	v_mov_b32_e32 v94, v95
	v_pk_add_f32 v[92:93], v[90:91], v[88:89] op_sel:[1,0] op_sel_hi:[0,1] neg_lo:[0,1] neg_hi:[0,1]
	v_pk_add_f32 v[100:101], v[96:97], v[92:93] op_sel_hi:[1,0] neg_lo:[0,1] neg_hi:[0,1]
	v_mov_b32_e32 v96, v97
	v_mov_b32_e32 v97, v91
	v_pk_mov_b32 v[92:93], v[88:89], v[92:93] op_sel:[1,0]
	v_mov_b32_e32 v95, v88
	v_pk_add_f32 v[92:93], v[96:97], v[92:93] neg_lo:[0,1] neg_hi:[0,1]
	v_mov_b32_e32 v100, v98
	v_pk_add_f32 v[88:89], v[94:95], v[92:93] neg_lo:[0,1] neg_hi:[0,1]
	v_mov_b32_e32 v99, v91
	v_pk_add_f32 v[92:93], v[100:101], v[88:89]
	v_mov_b32_e32 v100, 1.0
	v_pk_add_f32 v[94:95], v[92:93], v[92:93] op_sel:[0,1] op_sel_hi:[1,0]
	v_mov_b32_e32 v101, 1.0
	v_pk_add_f32 v[90:91], v[90:91], v[94:95] op_sel:[1,0] op_sel_hi:[0,1]
	v_mov_b32_e32 v93, v90
	v_pk_add_f32 v[96:97], v[92:93], v[98:99] neg_lo:[0,1] neg_hi:[0,1]
	v_mov_b32_e32 v89, v94
	v_sub_f32_e32 v91, v92, v96
	v_pk_add_f32 v[88:89], v[88:89], v[96:97] neg_lo:[0,1] neg_hi:[0,1]
	v_sub_f32_e32 v91, v98, v91
	v_add_f32_e32 v88, v88, v91
	v_add_f32_e32 v88, v88, v89
	v_add_f32_e32 v88, v90, v88
	v_cndmask_b32_e64 v88, v208, v88, s[40:41]
	v_cmp_ngt_f32_e64 s[40:41], -1.0, v102
	v_mfma_f32_16x16x32_bf16 v[92:95], v[56:59], v[16:19], 0
	v_mov_b32_e32 v98, 1.0
	v_cndmask_b32_e64 v88, v205, v88, s[40:41]
	v_cmp_neq_f32_e64 s[40:41], -1.0, v102
	v_mfma_f32_16x16x32_bf16 v[92:95], v[64:67], v[32:35], v[92:95]
	v_mov_b32_e32 v99, 1.0
	v_cndmask_b32_e64 v88, v206, v88, s[40:41]
	v_cmp_lt_f32_e64 s[40:41], |v102|, s95
	s_nop 1
	v_cndmask_b32_e64 v146, v88, v102, s[40:41]
	v_and_b32_e32 v88, -16, v122
	v_add_u32_e32 v142, s6, v88
	v_lshlrev_b64 v[88:89], 1, v[0:1]
	v_lshl_add_u64 v[114:115], s[44:45], 0, v[88:89]
	v_lshl_add_u64 v[116:117], s[46:47], 0, v[88:89]
	v_mfma_f32_16x16x32_bf16 v[88:91], v[52:55], v[16:19], 0
	v_mad_u32_u24 v122, v136, s76, v142
	ds_read2_b32 v[124:125], v122 offset1:1
	ds_read2_b32 v[128:129], v122 offset0:2 offset1:3
	v_mfma_f32_16x16x32_bf16 v[88:91], v[60:63], v[32:35], v[88:91]
	v_mov_b32_e32 v102, 1.0
	v_add_u32_e32 v148, v142, v123
	v_add_u32_e32 v150, v142, v141
	s_nop 4
	v_add_f32_e32 v88, v48, v88
	v_add_f32_e32 v89, v49, v89
	v_mul_f32_e32 v88, 0xbfb8aa3b, v88
	v_mul_f32_e32 v89, 0xbfb8aa3b, v89
	v_exp_f32_e32 v88, v88
	v_exp_f32_e32 v89, v89
	v_add_f32_e32 v90, v50, v90
	v_mul_f32_e32 v90, 0xbfb8aa3b, v90
	v_add_f32_e32 v88, 1.0, v88
	v_add_f32_e32 v89, 1.0, v89
	v_rcp_f32_e32 v96, v88
	v_rcp_f32_e32 v97, v89
	v_add_f32_e32 v88, v44, v92
	v_add_f32_e32 v89, v45, v93
	v_mul_f32_e32 v92, 0xc1000000, v96
	v_mul_f32_e32 v93, 0xc1000000, v97
	v_mul_f32_e32 v88, 0xbfb8aa3b, v88
	v_mul_f32_e32 v92, v145, v92
	v_mul_f32_e32 v89, 0xbfb8aa3b, v89
	v_mul_f32_e32 v93, v147, v93
	v_exp_f32_e32 v88, v88
	v_mul_f32_e32 v92, 0x3fb8aa3b, v92
	v_exp_f32_e32 v89, v89
	v_mul_f32_e32 v93, 0x3fb8aa3b, v93
	v_exp_f32_e32 v92, v92
	v_exp_f32_e32 v93, v93
	v_add_f32_e32 v88, 1.0, v88
	v_add_f32_e32 v89, 1.0, v89
	v_rcp_f32_e32 v88, v88
	v_fma_f32 v96, -v92, v92, 1.0
	v_rcp_f32_e32 v89, v89
	v_fma_f32 v97, -v93, v93, 1.0
	v_sqrt_f32_e32 v96, v96
	v_sqrt_f32_e32 v97, v97
	s_waitcnt lgkmcnt(0)
; __device__ __forceinline__ unsigned pk2(float lo, float hi) { const f32x2_t v = {lo, hi}; const bf16x2_t b = __builtin_convertvector(v, bf16x2_t); return __builtin_bit_cast(unsigned, b); }
; __device__ __forceinline__ float sigmoidf_(float x) { return __builtin_amdgcn_rcpf(1.0f + __expf(-x)); }
; __device__ __forceinline__ float bcast15(float v, int lane) { return bperm_f((lane & 48) | 15, v); }
; __device__ __forceinline__ void w_lru_m1(const Args& a, int l, unsigned char* ws, const bf16_t* proj, bf16_t* y, LAS unsigned char* wl, int b, int ck_, int h, int lane) {
;     ...
;             for (int r = 0; r < 4; ++r) {
;                 const float rg = sigmoidf_(ga[r] + bav[r]), ig = sigmoidf_(gx[r] + bxv[r]);
;                 const float la = -8.0f * rg * sp[r]; float A = __expf(la);
;                 float U = __builtin_amdgcn_sqrtf(1.0f - A * A) * (ig * xcf[tok * 65 + j0 + r]);
;                 { const float As = dpp_shr1<1>(A), Us = dpp_shr0<1>(U); U = A * Us + U; A = A * As; }
;                 { const float As = dpp_shr1<2>(A), Us = dpp_shr0<2>(U); U = A * Us + U; A = A * As; }
;                 { const float As = dpp_shr1<4>(A), Us = dpp_shr0<4>(U); U = A * Us + U; A = A * As; }
;                 { const float As = dpp_shr1<8>(A), Us = dpp_shr0<8>(U); U = A * Us + U; A = A * As; }
;                 const float hh = U + A * hc[r], PP = A * Pc[r];
;                 hc[r] = bcast15(hh, lane); Pc[r] = bcast15(PP, lane); hv[r] = hh; pv[r] = PP; }
;             *(unsigned long long*)(y + (size_t)(row0 + tok) * DM + 64 * h + j0) = (unsigned long long)pk2(hv[0], hv[1]) | ((unsigned long long)pk2(hv[2], hv[3]) << 32);
;             *(unsigned long long*)((bf16_t*)(ws + WS_P) + (size_t)(row0 + tok) * 512 + 64 * h + j0) = (unsigned long long)pk2(pv[0], pv[1]) | ((unsigned long long)pk2(pv[2], pv[3]) << 32);
	v_pk_mul_f32 v[88:89], v[124:125], v[88:89]
	v_mov_b32_dpp v98, v92 row_shr:1 row_mask:0xf bank_mask:0xf
	v_mov_b32_dpp v99, v93 row_shr:1 row_mask:0xf bank_mask:0xf
	v_pk_mul_f32 v[88:89], v[88:89], v[96:97]
	v_pk_mul_f32 v[98:99], v[92:93], v[98:99]
	v_exp_f32_e32 v90, v90
	v_mov_b32_dpp v96, v88 row_shr:1 row_mask:0xf bank_mask:0xf bound_ctrl:1
	v_mov_b32_dpp v97, v89 row_shr:1 row_mask:0xf bank_mask:0xf bound_ctrl:1
	v_pk_fma_f32 v[88:89], v[92:93], v[96:97], v[88:89]
	v_mov_b32_dpp v100, v98 row_shr:2 row_mask:0xf bank_mask:0xf
	v_mov_b32_dpp v101, v99 row_shr:2 row_mask:0xf bank_mask:0xf
	v_mov_b32_dpp v92, v88 row_shr:2 row_mask:0xf bank_mask:0xf bound_ctrl:1
	v_mov_b32_dpp v93, v89 row_shr:2 row_mask:0xf bank_mask:0xf bound_ctrl:1
	v_pk_fma_f32 v[88:89], v[98:99], v[92:93], v[88:89]
	v_pk_mul_f32 v[100:101], v[98:99], v[100:101]
	v_add_f32_e32 v90, 1.0, v90
	v_mov_b32_dpp v92, v88 row_shr:4 row_mask:0xf bank_mask:0xf bound_ctrl:1
	v_mov_b32_dpp v93, v89 row_shr:4 row_mask:0xf bank_mask:0xf bound_ctrl:1
	v_mov_b32_dpp v102, v100 row_shr:4 row_mask:0xf bank_mask:0xf
	v_mov_b32_dpp v103, v101 row_shr:4 row_mask:0xf bank_mask:0xf
	v_pk_fma_f32 v[88:89], v[100:101], v[92:93], v[88:89]
	v_pk_mul_f32 v[102:103], v[100:101], v[102:103]
	v_add_f32_e32 v91, v51, v91
	v_mov_b32_dpp v92, v88 row_shr:8 row_mask:0xf bank_mask:0xf bound_ctrl:1
	v_mov_b32_dpp v93, v89 row_shr:8 row_mask:0xf bank_mask:0xf bound_ctrl:1
	v_pk_fma_f32 v[88:89], v[102:103], v[92:93], v[88:89]
	v_rcp_f32_e32 v92, v90
	v_mul_f32_e32 v91, 0xbfb8aa3b, v91
	v_exp_f32_e32 v91, v91
	v_add_f32_e32 v90, v46, v94
	v_mul_f32_e32 v92, 0xc1000000, v92
	v_mul_f32_e32 v92, v2, v92
	v_mul_f32_e32 v92, 0x3fb8aa3b, v92
	v_exp_f32_e32 v92, v92
	v_add_f32_e32 v91, 1.0, v91
	v_mul_f32_e32 v90, 0xbfb8aa3b, v90
	v_exp_f32_e32 v90, v90
	v_fma_f32 v93, -v92, v92, 1.0
	v_sqrt_f32_e32 v94, v93
	v_rcp_f32_e32 v93, v91
	v_add_f32_e32 v91, v47, v95
	v_mul_f32_e32 v91, 0xbfb8aa3b, v91
	v_exp_f32_e32 v91, v91
	v_mul_f32_e32 v93, 0xc1000000, v93
	v_mul_f32_e32 v93, v146, v93
	v_mul_f32_e32 v93, 0x3fb8aa3b, v93
	v_exp_f32_e32 v93, v93
	v_add_f32_e32 v90, 1.0, v90
	v_add_f32_e32 v91, 1.0, v91
	v_rcp_f32_e32 v90, v90
	v_rcp_f32_e32 v91, v91
	v_fma_f32 v95, -v93, v93, 1.0
	v_sqrt_f32_e32 v95, v95
	v_mov_b32_e32 v96, 1.0
	v_pk_mul_f32 v[90:91], v[90:91], v[128:129]
	v_mov_b32_e32 v97, 1.0
	v_pk_mul_f32 v[90:91], v[94:95], v[90:91]
	v_mov_b32_dpp v96, v92 row_shr:1 row_mask:0xf bank_mask:0xf
	v_mov_b32_dpp v97, v93 row_shr:1 row_mask:0xf bank_mask:0xf
	v_mov_b32_dpp v94, v90 row_shr:1 row_mask:0xf bank_mask:0xf bound_ctrl:1
	v_mov_b32_dpp v95, v91 row_shr:1 row_mask:0xf bank_mask:0xf bound_ctrl:1
	v_pk_mul_f32 v[96:97], v[92:93], v[96:97]
	v_mov_b32_e32 v100, 1.0
	v_mov_b32_e32 v101, 1.0
	v_pk_fma_f32 v[90:91], v[92:93], v[94:95], v[90:91]
	v_mov_b32_dpp v104, v102 row_shr:8 row_mask:0xf bank_mask:0xf
	v_mov_b32_dpp v105, v103 row_shr:8 row_mask:0xf bank_mask:0xf
	v_mov_b32_dpp v100, v96 row_shr:2 row_mask:0xf bank_mask:0xf
	v_mov_b32_dpp v101, v97 row_shr:2 row_mask:0xf bank_mask:0xf
	v_mov_b32_dpp v92, v90 row_shr:2 row_mask:0xf bank_mask:0xf bound_ctrl:1
	v_mov_b32_dpp v93, v91 row_shr:2 row_mask:0xf bank_mask:0xf bound_ctrl:1
	v_pk_mul_f32 v[106:107], v[102:103], v[104:105]
	v_pk_mul_f32 v[100:101], v[96:97], v[100:101]
	v_mov_b32_e32 v102, 1.0
	v_mov_b32_e32 v103, 1.0
	v_pk_fma_f32 v[90:91], v[96:97], v[92:93], v[90:91]
	v_mov_b32_dpp v102, v100 row_shr:4 row_mask:0xf bank_mask:0xf
	v_mov_b32_dpp v103, v101 row_shr:4 row_mask:0xf bank_mask:0xf
	v_mov_b32_dpp v92, v90 row_shr:4 row_mask:0xf bank_mask:0xf bound_ctrl:1
	v_mov_b32_dpp v93, v91 row_shr:4 row_mask:0xf bank_mask:0xf bound_ctrl:1
	v_pk_mul_f32 v[102:103], v[100:101], v[102:103]
	v_mov_b32_e32 v124, 1.0
	v_mov_b32_e32 v125, 1.0
	v_pk_fma_f32 v[90:91], v[100:101], v[92:93], v[90:91]
	v_mov_b32_dpp v124, v102 row_shr:8 row_mask:0xf bank_mask:0xf
	v_mov_b32_dpp v125, v103 row_shr:8 row_mask:0xf bank_mask:0xf
	v_mov_b32_dpp v92, v90 row_shr:8 row_mask:0xf bank_mask:0xf bound_ctrl:1
	v_mov_b32_dpp v93, v91 row_shr:8 row_mask:0xf bank_mask:0xf bound_ctrl:1
	v_pk_mul_f32 v[126:127], v[102:103], v[124:125]
	v_pk_fma_f32 v[90:91], v[102:103], v[92:93], v[90:91]
	v_pk_fma_f32 v[88:89], v[106:107], 0, v[88:89] op_sel_hi:[1,0,1]
	v_pk_fma_f32 v[90:91], v[126:127], 0, v[90:91] op_sel_hi:[1,0,1]
	ds_bpermute_b32 v98, v143, v88 offset:60
	ds_bpermute_b32 v99, v143, v89 offset:60
	ds_bpermute_b32 v96, v143, v90 offset:60
	v_cvt_pk_bf16_f32 v88, v88, v89
	v_cvt_pk_bf16_f32 v89, v90, v91
	v_or_b32_e32 v90, s48, v136
	ds_bpermute_b32 v97, v143, v91 offset:60
	v_ashrrev_i32_e32 v91, 31, v90
	v_lshlrev_b64 v[92:93], 11, v[90:91]
	v_lshl_add_u64 v[100:101], v[114:115], 0, v[92:93]
	v_lshlrev_b64 v[90:91], 10, v[90:91]
	global_store_dwordx2 v[100:101], v[88:89], off
	v_cvt_pk_bf16_f32 v88, v106, v107
	v_cvt_pk_bf16_f32 v89, v126, v127
	v_lshl_add_u64 v[102:103], v[116:117], 0, v[90:91]
	global_store_dwordx2 v[102:103], v[88:89], off
	v_mfma_f32_16x16x32_bf16 v[88:91], v[52:55], v[12:15], 0
	ds_bpermute_b32 v124, v143, v126 offset:60
	ds_bpermute_b32 v125, v143, v127 offset:60
	ds_bpermute_b32 v104, v143, v106 offset:60
	v_mfma_f32_16x16x32_bf16 v[126:129], v[56:59], v[12:15], 0
	ds_bpermute_b32 v105, v143, v107 offset:60
	v_mfma_f32_16x16x32_bf16 v[92:95], v[60:63], v[28:31], v[88:91]
	v_mfma_f32_16x16x32_bf16 v[88:91], v[64:67], v[28:31], v[126:129]
	s_nop 6
	v_add_f32_e32 v92, v48, v92
	v_mul_f32_e32 v92, 0xbfb8aa3b, v92
	v_exp_f32_e32 v92, v92
	v_add_f32_e32 v88, v44, v88
	v_mul_f32_e32 v88, 0xbfb8aa3b, v88
	v_exp_f32_e32 v88, v88
	v_add_f32_e32 v92, 1.0, v92
; __device__ __forceinline__ float sigmoidf_(float x) { return __builtin_amdgcn_rcpf(1.0f + __expf(-x)); }
; __device__ __forceinline__ float bcast15(float v, int lane) { return bperm_f((lane & 48) | 15, v); }
; __device__ __forceinline__ void w_lru_m1(const Args& a, int l, unsigned char* ws, const bf16_t* proj, bf16_t* y, LAS unsigned char* wl, int b, int ck_, int h, int lane) {
;     ...
;         for (int tb = 0; tb < 4; ++tb) { const int tok = 16 * tb + lo;
;             f32x4 ga = {0.f, 0.f, 0.f, 0.f}, gx = {0.f, 0.f, 0.f, 0.f};
; #pragma unroll
;             for (int kk = 0; kk < 2; ++kk) { ga = __builtin_amdgcn_mfma_f32_16x16x32_bf16(WaF[kk], Xf[tb][kk], ga, 0, 0, 0); gx = __builtin_amdgcn_mfma_f32_16x16x32_bf16(WxF[kk], Xf[tb][kk], gx, 0, 0, 0); }
;             float hv[4], pv[4];
; #pragma unroll
;             for (int r = 0; r < 4; ++r) {
;                 const float rg = sigmoidf_(ga[r] + bav[r]), ig = sigmoidf_(gx[r] + bxv[r]);
;                 const float la = -8.0f * rg * sp[r]; float A = __expf(la);
;                 float U = __builtin_amdgcn_sqrtf(1.0f - A * A) * (ig * xcf[tok * 65 + j0 + r]);
;                 { const float As = dpp_shr1<1>(A), Us = dpp_shr0<1>(U); U = A * Us + U; A = A * As; }
;                 { const float As = dpp_shr1<2>(A), Us = dpp_shr0<2>(U); U = A * Us + U; A = A * As; }
;                 { const float As = dpp_shr1<4>(A), Us = dpp_shr0<4>(U); U = A * Us + U; A = A * As; }
;                 { const float As = dpp_shr1<8>(A), Us = dpp_shr0<8>(U); U = A * Us + U; A = A * As; }
;                 const float hh = U + A * hc[r], PP = A * Pc[r];
;                 hc[r] = bcast15(hh, lane); Pc[r] = bcast15(PP, lane); hv[r] = hh; pv[r] = PP; }
	v_rcp_f32_e32 v92, v92
	v_add_f32_e32 v89, v45, v89
	v_add_f32_e32 v88, 1.0, v88
	v_rcp_f32_e32 v106, v88
	v_mul_f32_e32 v88, 0xc1000000, v92
	v_add_f32_e32 v92, v49, v93
	v_mul_f32_e32 v92, 0xbfb8aa3b, v92
	v_exp_f32_e32 v92, v92
	v_mul_f32_e32 v89, 0xbfb8aa3b, v89
	v_exp_f32_e32 v89, v89
	v_mul_f32_e32 v88, v145, v88
	v_add_f32_e32 v92, 1.0, v92
	v_rcp_f32_e32 v92, v92
	v_add_f32_e32 v89, 1.0, v89
	v_rcp_f32_e32 v107, v89
	v_mul_f32_e32 v88, 0x3fb8aa3b, v88
	v_mul_f32_e32 v89, 0xc1000000, v92
	v_mul_f32_e32 v89, v147, v89
	v_mul_f32_e32 v89, 0x3fb8aa3b, v89
	v_exp_f32_e32 v122, v88
	v_exp_f32_e32 v123, v89
	v_add_f32_e32 v94, v50, v94
	v_add_f32_e32 v95, v51, v95
	v_fma_f32 v88, -v122, v122, 1.0
	v_fma_f32 v89, -v123, v123, 1.0
	v_sqrt_f32_e32 v126, v88
	v_mov_b32_e32 v88, 1.0
	v_sqrt_f32_e32 v127, v89
	v_mov_b32_e32 v89, 1.0
	v_mov_b32_dpp v88, v122 row_shr:1 row_mask:0xf bank_mask:0xf
	v_mul_f32_e32 v94, 0xbfb8aa3b, v94
	v_mov_b32_dpp v89, v123 row_shr:1 row_mask:0xf bank_mask:0xf
	v_pk_mul_f32 v[128:129], v[122:123], v[88:89]
	v_mov_b32_e32 v88, 1.0
	v_mov_b32_e32 v89, 1.0
	v_mul_f32_e32 v95, 0xbfb8aa3b, v95
	v_mov_b32_dpp v88, v128 row_shr:2 row_mask:0xf bank_mask:0xf
	v_mov_b32_dpp v89, v129 row_shr:2 row_mask:0xf bank_mask:0xf
	v_pk_mul_f32 v[130:131], v[128:129], v[88:89]
	v_mov_b32_e32 v88, 1.0
	v_mov_b32_e32 v89, 1.0
	v_exp_f32_e32 v94, v94
	v_mov_b32_dpp v88, v130 row_shr:4 row_mask:0xf bank_mask:0xf
	v_mov_b32_dpp v89, v131 row_shr:4 row_mask:0xf bank_mask:0xf
	v_pk_mul_f32 v[132:133], v[130:131], v[88:89]
	v_mov_b32_e32 v88, 1.0
	v_mov_b32_e32 v89, 1.0
	v_exp_f32_e32 v95, v95
	v_mov_b32_dpp v88, v132 row_shr:8 row_mask:0xf bank_mask:0xf
	v_mov_b32_dpp v89, v133 row_shr:8 row_mask:0xf bank_mask:0xf
	v_pk_mul_f32 v[134:135], v[132:133], v[88:89]
	v_add_f32_e32 v90, v46, v90
	s_waitcnt lgkmcnt(0)
	v_pk_mul_f32 v[92:93], v[134:135], v[104:105]
	ds_read2_b32 v[104:105], v148 offset1:1
	v_add_f32_e32 v91, v47, v91
	v_mul_f32_e32 v90, 0xbfb8aa3b, v90
	v_mul_f32_e32 v91, 0xbfb8aa3b, v91
	v_add_f32_e32 v94, 1.0, v94
	s_waitcnt lgkmcnt(0)
	v_pk_mul_f32 v[104:105], v[104:105], v[106:107]
	v_exp_f32_e32 v90, v90
	v_pk_mul_f32 v[104:105], v[104:105], v[126:127]
	v_add_f32_e32 v95, 1.0, v95
	v_exp_f32_e32 v91, v91
	v_mov_b32_dpp v106, v104 row_shr:1 row_mask:0xf bank_mask:0xf bound_ctrl:1
	v_mov_b32_dpp v107, v105 row_shr:1 row_mask:0xf bank_mask:0xf bound_ctrl:1
	v_pk_fma_f32 v[104:105], v[122:123], v[106:107], v[104:105]
	v_rcp_f32_e32 v94, v94
	v_rcp_f32_e32 v95, v95
	v_mov_b32_dpp v106, v104 row_shr:2 row_mask:0xf bank_mask:0xf bound_ctrl:1
	v_mov_b32_dpp v107, v105 row_shr:2 row_mask:0xf bank_mask:0xf bound_ctrl:1
	v_pk_fma_f32 v[104:105], v[128:129], v[106:107], v[104:105]
	v_add_f32_e32 v90, 1.0, v90
	v_add_f32_e32 v91, 1.0, v91
	v_mov_b32_dpp v106, v104 row_shr:4 row_mask:0xf bank_mask:0xf bound_ctrl:1
	v_mov_b32_dpp v107, v105 row_shr:4 row_mask:0xf bank_mask:0xf bound_ctrl:1
	v_pk_fma_f32 v[104:105], v[130:131], v[106:107], v[104:105]
	ds_bpermute_b32 v88, v143, v92 offset:60
	ds_bpermute_b32 v89, v143, v93 offset:60
	v_mov_b32_dpp v106, v104 row_shr:8 row_mask:0xf bank_mask:0xf bound_ctrl:1
	v_mov_b32_dpp v107, v105 row_shr:8 row_mask:0xf bank_mask:0xf bound_ctrl:1
	v_pk_fma_f32 v[104:105], v[132:133], v[106:107], v[104:105]
	v_rcp_f32_e32 v106, v90
	v_mul_f32_e32 v90, 0xc1000000, v94
	v_rcp_f32_e32 v107, v91
	v_mul_f32_e32 v91, 0xc1000000, v95
	v_mul_f32_e32 v90, v2, v90
	v_mul_f32_e32 v91, v146, v91
	v_mul_f32_e32 v90, 0x3fb8aa3b, v90
	v_mul_f32_e32 v91, 0x3fb8aa3b, v91
	v_exp_f32_e32 v94, v90
	v_exp_f32_e32 v95, v91
	v_pk_fma_f32 v[104:105], v[134:135], v[98:99], v[104:105]
	ds_read2_b32 v[134:135], v148 offset0:2 offset1:3
	v_fma_f32 v90, -v94, v94, 1.0
	v_fma_f32 v91, -v95, v95, 1.0
	v_sqrt_f32_e32 v122, v90
	v_sqrt_f32_e32 v123, v91
	s_waitcnt lgkmcnt(0)
	v_pk_mul_f32 v[106:107], v[106:107], v[134:135]
	v_mov_b32_e32 v90, 1.0
	v_mov_b32_e32 v91, 1.0
	v_pk_mul_f32 v[106:107], v[122:123], v[106:107]
	v_mov_b32_dpp v90, v94 row_shr:1 row_mask:0xf bank_mask:0xf
	v_mov_b32_dpp v91, v95 row_shr:1 row_mask:0xf bank_mask:0xf
	v_mov_b32_dpp v122, v106 row_shr:1 row_mask:0xf bank_mask:0xf bound_ctrl:1
	v_mov_b32_dpp v123, v107 row_shr:1 row_mask:0xf bank_mask:0xf bound_ctrl:1
	v_pk_mul_f32 v[126:127], v[94:95], v[90:91]
	v_mov_b32_e32 v90, 1.0
	v_mov_b32_e32 v91, 1.0
	v_pk_fma_f32 v[94:95], v[94:95], v[122:123], v[106:107]
	v_mov_b32_dpp v90, v126 row_shr:2 row_mask:0xf bank_mask:0xf
	v_mov_b32_dpp v91, v127 row_shr:2 row_mask:0xf bank_mask:0xf
	v_mov_b32_dpp v106, v94 row_shr:2 row_mask:0xf bank_mask:0xf bound_ctrl:1
	v_mov_b32_dpp v107, v95 row_shr:2 row_mask:0xf bank_mask:0xf bound_ctrl:1
	v_pk_mul_f32 v[128:129], v[126:127], v[90:91]
	v_mov_b32_e32 v90, 1.0
	v_mov_b32_e32 v91, 1.0
	v_pk_fma_f32 v[94:95], v[126:127], v[106:107], v[94:95]
	v_mov_b32_dpp v90, v128 row_shr:4 row_mask:0xf bank_mask:0xf
	v_mov_b32_dpp v91, v129 row_shr:4 row_mask:0xf bank_mask:0xf
	v_mov_b32_dpp v106, v94 row_shr:4 row_mask:0xf bank_mask:0xf bound_ctrl:1
	v_mov_b32_dpp v107, v95 row_shr:4 row_mask:0xf bank_mask:0xf bound_ctrl:1
	v_pk_mul_f32 v[130:131], v[128:129], v[90:91]
	v_mov_b32_e32 v90, 1.0
	v_mov_b32_e32 v91, 1.0
	v_pk_fma_f32 v[94:95], v[128:129], v[106:107], v[94:95]
	v_mov_b32_dpp v90, v130 row_shr:8 row_mask:0xf bank_mask:0xf
	v_mov_b32_dpp v91, v131 row_shr:8 row_mask:0xf bank_mask:0xf
	v_mov_b32_dpp v106, v94 row_shr:8 row_mask:0xf bank_mask:0xf bound_ctrl:1
	v_mov_b32_dpp v107, v95 row_shr:8 row_mask:0xf bank_mask:0xf bound_ctrl:1
	v_pk_mul_f32 v[132:133], v[130:131], v[90:91]
	v_pk_fma_f32 v[94:95], v[130:131], v[106:107], v[94:95]
; __device__ __forceinline__ unsigned pk2(float lo, float hi) { const f32x2_t v = {lo, hi}; const bf16x2_t b = __builtin_convertvector(v, bf16x2_t); return __builtin_bit_cast(unsigned, b); }
; __device__ __forceinline__ float sigmoidf_(float x) { return __builtin_amdgcn_rcpf(1.0f + __expf(-x)); }
; __device__ __forceinline__ float bcast15(float v, int lane) { return bperm_f((lane & 48) | 15, v); }
; __device__ __forceinline__ void w_lru_m1(const Args& a, int l, unsigned char* ws, const bf16_t* proj, bf16_t* y, LAS unsigned char* wl, int b, int ck_, int h, int lane) {
;     ...
;         for (int tb = 0; tb < 4; ++tb) { const int tok = 16 * tb + lo;
;             f32x4 ga = {0.f, 0.f, 0.f, 0.f}, gx = {0.f, 0.f, 0.f, 0.f};
; #pragma unroll
;             for (int kk = 0; kk < 2; ++kk) { ga = __builtin_amdgcn_mfma_f32_16x16x32_bf16(WaF[kk], Xf[tb][kk], ga, 0, 0, 0); gx = __builtin_amdgcn_mfma_f32_16x16x32_bf16(WxF[kk], Xf[tb][kk], gx, 0, 0, 0); }
;             float hv[4], pv[4];
; #pragma unroll
;             for (int r = 0; r < 4; ++r) {
;                 const float rg = sigmoidf_(ga[r] + bav[r]), ig = sigmoidf_(gx[r] + bxv[r]);
;                 const float la = -8.0f * rg * sp[r]; float A = __expf(la);
;                 float U = __builtin_amdgcn_sqrtf(1.0f - A * A) * (ig * xcf[tok * 65 + j0 + r]);
;                 { const float As = dpp_shr1<1>(A), Us = dpp_shr0<1>(U); U = A * Us + U; A = A * As; }
;                 { const float As = dpp_shr1<2>(A), Us = dpp_shr0<2>(U); U = A * Us + U; A = A * As; }
;                 { const float As = dpp_shr1<4>(A), Us = dpp_shr0<4>(U); U = A * Us + U; A = A * As; }
;                 { const float As = dpp_shr1<8>(A), Us = dpp_shr0<8>(U); U = A * Us + U; A = A * As; }
;                 const float hh = U + A * hc[r], PP = A * Pc[r];
;                 hc[r] = bcast15(hh, lane); Pc[r] = bcast15(PP, lane); hv[r] = hh; pv[r] = PP; }
;             *(unsigned long long*)(y + (size_t)(row0 + tok) * DM + 64 * h + j0) = (unsigned long long)pk2(hv[0], hv[1]) | ((unsigned long long)pk2(hv[2], hv[3]) << 32);
;             *(unsigned long long*)((bf16_t*)(ws + WS_P) + (size_t)(row0 + tok) * 512 + 64 * h + j0) = (unsigned long long)pk2(pv[0], pv[1]) | ((unsigned long long)pk2(pv[2], pv[3]) << 32);
	ds_bpermute_b32 v98, v143, v104 offset:60
	v_pk_fma_f32 v[94:95], v[132:133], v[96:97], v[94:95]
	ds_bpermute_b32 v96, v143, v94 offset:60
	v_cvt_pk_bf16_f32 v107, v94, v95
	v_or_b32_e32 v94, s48, v140
	ds_bpermute_b32 v97, v143, v95 offset:60
	v_ashrrev_i32_e32 v95, 31, v94
	ds_bpermute_b32 v99, v143, v105 offset:60
	v_cvt_pk_bf16_f32 v106, v104, v105
	v_lshlrev_b64 v[104:105], 11, v[94:95]
	v_pk_mul_f32 v[124:125], v[132:133], v[124:125]
	v_lshl_add_u64 v[104:105], v[114:115], 0, v[104:105]
	v_lshlrev_b64 v[94:95], 10, v[94:95]
	global_store_dwordx2 v[104:105], v[106:107], off
	v_cvt_pk_bf16_f32 v92, v92, v93
	v_cvt_pk_bf16_f32 v93, v124, v125
	v_lshl_add_u64 v[106:107], v[116:117], 0, v[94:95]
	global_store_dwordx2 v[106:107], v[92:93], off
	v_mfma_f32_16x16x32_bf16 v[92:95], v[52:55], v[8:11], 0
	ds_bpermute_b32 v90, v143, v124 offset:60
	ds_bpermute_b32 v91, v143, v125 offset:60
	v_mfma_f32_16x16x32_bf16 v[126:129], v[60:63], v[24:27], v[92:95]
	v_mfma_f32_16x16x32_bf16 v[122:125], v[56:59], v[8:11], 0
	v_mfma_f32_16x16x32_bf16 v[122:125], v[64:67], v[24:27], v[122:125]
	s_nop 5
	v_add_f32_e32 v92, v48, v126
	v_mul_f32_e32 v92, 0xbfb8aa3b, v92
	v_exp_f32_e32 v92, v92
	v_mfma_f32_16x16x32_bf16 v[52:55], v[52:55], v[4:7], 0
	v_add_f32_e32 v92, 1.0, v92
	v_rcp_f32_e32 v93, v92
	v_add_f32_e32 v92, v44, v122
	v_mov_b32_e32 v122, 1.0
	v_mul_f32_e32 v92, 0xbfb8aa3b, v92
	v_mul_f32_e32 v93, 0xc1000000, v93
	v_mul_f32_e32 v93, v145, v93
	v_mul_f32_e32 v93, 0x3fb8aa3b, v93
	v_exp_f32_e32 v94, v93
	v_exp_f32_e32 v92, v92
	v_fma_f32 v93, -v94, v94, 1.0
	v_sqrt_f32_e32 v126, v93
	v_add_f32_e32 v93, v49, v127
	v_mul_f32_e32 v93, 0xbfb8aa3b, v93
	v_exp_f32_e32 v93, v93
	v_mov_b32_dpp v122, v94 row_shr:1 row_mask:0xf bank_mask:0xf
	v_add_f32_e32 v92, 1.0, v92
	v_rcp_f32_e32 v92, v92
	v_add_f32_e32 v93, 1.0, v93
	v_rcp_f32_e32 v95, v93
	v_add_f32_e32 v93, v45, v123
	v_mul_f32_e32 v93, 0xbfb8aa3b, v93
	v_exp_f32_e32 v93, v93
	v_mul_f32_e32 v95, 0xc1000000, v95
	v_mul_f32_e32 v95, v147, v95
	v_mul_f32_e32 v95, 0x3fb8aa3b, v95
	v_exp_f32_e32 v95, v95
	v_add_f32_e32 v93, 1.0, v93
	v_rcp_f32_e32 v93, v93
	v_fma_f32 v123, -v95, v95, 1.0
	v_sqrt_f32_e32 v127, v123
	v_mov_b32_e32 v123, 1.0
	s_nop 1
	v_mov_b32_dpp v123, v95 row_shr:1 row_mask:0xf bank_mask:0xf
	v_pk_mul_f32 v[130:131], v[94:95], v[122:123]
	v_mov_b32_e32 v122, 1.0
	v_mov_b32_e32 v123, 1.0
	s_nop 0
	v_mov_b32_dpp v122, v130 row_shr:2 row_mask:0xf bank_mask:0xf
	v_mov_b32_dpp v123, v131 row_shr:2 row_mask:0xf bank_mask:0xf
	v_pk_mul_f32 v[132:133], v[130:131], v[122:123]
	v_mov_b32_e32 v122, 1.0
	v_mov_b32_e32 v123, 1.0
	s_nop 0
	v_mov_b32_dpp v122, v132 row_shr:4 row_mask:0xf bank_mask:0xf
	v_mov_b32_dpp v123, v133 row_shr:4 row_mask:0xf bank_mask:0xf
	v_pk_mul_f32 v[134:135], v[132:133], v[122:123]
	v_mov_b32_e32 v122, 1.0
	v_mov_b32_e32 v123, 1.0
	s_nop 0
	v_mov_b32_dpp v122, v134 row_shr:8 row_mask:0xf bank_mask:0xf
	v_mov_b32_dpp v123, v135 row_shr:8 row_mask:0xf bank_mask:0xf
	v_pk_mul_f32 v[140:141], v[134:135], v[122:123]
	s_nop 0
	v_pk_mul_f32 v[148:149], v[140:141], v[88:89]
	ds_read2_b32 v[88:89], v150 offset1:1
	ds_bpermute_b32 v122, v143, v148 offset:60
	ds_bpermute_b32 v123, v143, v149 offset:60
	s_waitcnt lgkmcnt(0)
	v_pk_mul_f32 v[88:89], v[88:89], v[92:93]
	s_nop 0
	v_pk_mul_f32 v[88:89], v[88:89], v[126:127]
	s_nop 1
	v_mov_b32_dpp v92, v88 row_shr:1 row_mask:0xf bank_mask:0xf bound_ctrl:1
	v_mov_b32_dpp v93, v89 row_shr:1 row_mask:0xf bank_mask:0xf bound_ctrl:1
	v_pk_fma_f32 v[88:89], v[94:95], v[92:93], v[88:89]
	s_nop 1
	v_mov_b32_dpp v92, v88 row_shr:2 row_mask:0xf bank_mask:0xf bound_ctrl:1
	v_mov_b32_dpp v93, v89 row_shr:2 row_mask:0xf bank_mask:0xf bound_ctrl:1
	v_pk_fma_f32 v[88:89], v[130:131], v[92:93], v[88:89]
	s_nop 1
	v_mov_b32_dpp v92, v88 row_shr:4 row_mask:0xf bank_mask:0xf bound_ctrl:1
	v_mov_b32_dpp v93, v89 row_shr:4 row_mask:0xf bank_mask:0xf bound_ctrl:1
	v_pk_fma_f32 v[88:89], v[132:133], v[92:93], v[88:89]
	s_nop 1
	v_mov_b32_dpp v92, v88 row_shr:8 row_mask:0xf bank_mask:0xf bound_ctrl:1
	v_mov_b32_dpp v93, v89 row_shr:8 row_mask:0xf bank_mask:0xf bound_ctrl:1
	v_pk_fma_f32 v[88:89], v[134:135], v[92:93], v[88:89]
	v_mov_b32_e32 v92, 1.0
	v_pk_fma_f32 v[98:99], v[140:141], v[98:99], v[88:89]
	v_add_f32_e32 v88, v50, v128
	v_mul_f32_e32 v88, 0xbfb8aa3b, v88
	v_exp_f32_e32 v88, v88
	ds_read2_b32 v[140:141], v150 offset0:2 offset1:3
	ds_bpermute_b32 v94, v143, v98 offset:60
	ds_bpermute_b32 v95, v143, v99 offset:60
	v_add_f32_e32 v88, 1.0, v88
	v_rcp_f32_e32 v89, v88
	v_add_f32_e32 v88, v46, v124
	v_mul_f32_e32 v88, 0xbfb8aa3b, v88
	v_exp_f32_e32 v88, v88
	v_mul_f32_e32 v89, 0xc1000000, v89
	v_mul_f32_e32 v89, v2, v89
	v_mul_f32_e32 v89, 0x3fb8aa3b, v89
	v_exp_f32_e32 v124, v89
	v_add_f32_e32 v88, 1.0, v88
	v_rcp_f32_e32 v88, v88
	v_cvt_pk_bf16_f32 v98, v98, v99
	v_fma_f32 v89, -v124, v124, 1.0
	v_sqrt_f32_e32 v126, v89
	v_add_f32_e32 v89, v51, v129
	v_mul_f32_e32 v89, 0xbfb8aa3b, v89
	v_exp_f32_e32 v89, v89
	v_mov_b32_dpp v92, v124 row_shr:1 row_mask:0xf bank_mask:0xf
	v_add_f32_e32 v89, 1.0, v89
	v_rcp_f32_e32 v93, v89
	v_add_f32_e32 v89, v47, v125
	v_mul_f32_e32 v89, 0xbfb8aa3b, v89
	v_exp_f32_e32 v89, v89
	v_mul_f32_e32 v93, 0xc1000000, v93
	v_mul_f32_e32 v93, v146, v93
	v_mul_f32_e32 v93, 0x3fb8aa3b, v93
	v_exp_f32_e32 v125, v93
	v_add_f32_e32 v89, 1.0, v89
	v_rcp_f32_e32 v89, v89
	v_fma_f32 v93, -v125, v125, 1.0
	v_sqrt_f32_e32 v127, v93
	s_waitcnt lgkmcnt(0)
; __device__ __forceinline__ unsigned pk2(float lo, float hi) { const f32x2_t v = {lo, hi}; const bf16x2_t b = __builtin_convertvector(v, bf16x2_t); return __builtin_bit_cast(unsigned, b); }
; __device__ __forceinline__ float sigmoidf_(float x) { return __builtin_amdgcn_rcpf(1.0f + __expf(-x)); }
; __device__ __forceinline__ float bcast15(float v, int lane) { return bperm_f((lane & 48) | 15, v); }
; __device__ __forceinline__ void w_lru_m1(const Args& a, int l, unsigned char* ws, const bf16_t* proj, bf16_t* y, LAS unsigned char* wl, int b, int ck_, int h, int lane) {
;     ...
;         for (int tb = 0; tb < 4; ++tb) { const int tok = 16 * tb + lo;
;             f32x4 ga = {0.f, 0.f, 0.f, 0.f}, gx = {0.f, 0.f, 0.f, 0.f};
; #pragma unroll
;             for (int kk = 0; kk < 2; ++kk) { ga = __builtin_amdgcn_mfma_f32_16x16x32_bf16(WaF[kk], Xf[tb][kk], ga, 0, 0, 0); gx = __builtin_amdgcn_mfma_f32_16x16x32_bf16(WxF[kk], Xf[tb][kk], gx, 0, 0, 0); }
;             float hv[4], pv[4];
; #pragma unroll
;             for (int r = 0; r < 4; ++r) {
;                 const float rg = sigmoidf_(ga[r] + bav[r]), ig = sigmoidf_(gx[r] + bxv[r]);
;                 const float la = -8.0f * rg * sp[r]; float A = __expf(la);
;                 float U = __builtin_amdgcn_sqrtf(1.0f - A * A) * (ig * xcf[tok * 65 + j0 + r]);
;                 { const float As = dpp_shr1<1>(A), Us = dpp_shr0<1>(U); U = A * Us + U; A = A * As; }
;                 { const float As = dpp_shr1<2>(A), Us = dpp_shr0<2>(U); U = A * Us + U; A = A * As; }
;                 { const float As = dpp_shr1<4>(A), Us = dpp_shr0<4>(U); U = A * Us + U; A = A * As; }
;                 { const float As = dpp_shr1<8>(A), Us = dpp_shr0<8>(U); U = A * Us + U; A = A * As; }
;                 const float hh = U + A * hc[r], PP = A * Pc[r];
;                 hc[r] = bcast15(hh, lane); Pc[r] = bcast15(PP, lane); hv[r] = hh; pv[r] = PP; }
;             *(unsigned long long*)(y + (size_t)(row0 + tok) * DM + 64 * h + j0) = (unsigned long long)pk2(hv[0], hv[1]) | ((unsigned long long)pk2(hv[2], hv[3]) << 32);
;             *(unsigned long long*)((bf16_t*)(ws + WS_P) + (size_t)(row0 + tok) * 512 + 64 * h + j0) = (unsigned long long)pk2(pv[0], pv[1]) | ((unsigned long long)pk2(pv[2], pv[3]) << 32);
	v_pk_mul_f32 v[88:89], v[88:89], v[140:141]
	v_mov_b32_e32 v93, 1.0
	v_pk_mul_f32 v[88:89], v[126:127], v[88:89]
	s_nop 0
	v_mov_b32_dpp v93, v125 row_shr:1 row_mask:0xf bank_mask:0xf
	v_mov_b32_dpp v126, v88 row_shr:1 row_mask:0xf bank_mask:0xf bound_ctrl:1
	v_mov_b32_dpp v127, v89 row_shr:1 row_mask:0xf bank_mask:0xf bound_ctrl:1
	v_pk_mul_f32 v[128:129], v[124:125], v[92:93]
	v_mov_b32_e32 v92, 1.0
	v_mov_b32_e32 v93, 1.0
	v_pk_fma_f32 v[88:89], v[124:125], v[126:127], v[88:89]
	v_mov_b32_dpp v92, v128 row_shr:2 row_mask:0xf bank_mask:0xf
	v_mov_b32_dpp v93, v129 row_shr:2 row_mask:0xf bank_mask:0xf
	v_mov_b32_dpp v124, v88 row_shr:2 row_mask:0xf bank_mask:0xf bound_ctrl:1
	v_mov_b32_dpp v125, v89 row_shr:2 row_mask:0xf bank_mask:0xf bound_ctrl:1
	v_pk_mul_f32 v[130:131], v[128:129], v[92:93]
	v_mov_b32_e32 v92, 1.0
	v_mov_b32_e32 v93, 1.0
	v_pk_fma_f32 v[88:89], v[128:129], v[124:125], v[88:89]
	v_mov_b32_dpp v92, v130 row_shr:4 row_mask:0xf bank_mask:0xf
	v_mov_b32_dpp v93, v131 row_shr:4 row_mask:0xf bank_mask:0xf
	v_mov_b32_dpp v124, v88 row_shr:4 row_mask:0xf bank_mask:0xf bound_ctrl:1
	v_mov_b32_dpp v125, v89 row_shr:4 row_mask:0xf bank_mask:0xf bound_ctrl:1
	v_pk_mul_f32 v[132:133], v[130:131], v[92:93]
	v_mov_b32_e32 v92, 1.0
	v_mov_b32_e32 v93, 1.0
	v_pk_fma_f32 v[88:89], v[130:131], v[124:125], v[88:89]
	v_mov_b32_dpp v92, v132 row_shr:8 row_mask:0xf bank_mask:0xf
	v_mov_b32_dpp v93, v133 row_shr:8 row_mask:0xf bank_mask:0xf
	v_mov_b32_dpp v124, v88 row_shr:8 row_mask:0xf bank_mask:0xf bound_ctrl:1
	v_mov_b32_dpp v125, v89 row_shr:8 row_mask:0xf bank_mask:0xf bound_ctrl:1
	v_pk_mul_f32 v[134:135], v[132:133], v[92:93]
	v_pk_fma_f32 v[88:89], v[132:133], v[124:125], v[88:89]
	v_or_b32_e32 v124, s48, v139
	v_pk_fma_f32 v[96:97], v[134:135], v[96:97], v[88:89]
	v_ashrrev_i32_e32 v125, 31, v124
	v_pk_mul_f32 v[90:91], v[134:135], v[90:91]
	ds_bpermute_b32 v88, v143, v96 offset:60
	ds_bpermute_b32 v89, v143, v97 offset:60
	v_cvt_pk_bf16_f32 v99, v96, v97
	v_lshlrev_b64 v[96:97], 11, v[124:125]
	ds_bpermute_b32 v92, v143, v90 offset:60
	ds_bpermute_b32 v93, v143, v91 offset:60
	v_lshl_add_u64 v[96:97], v[114:115], 0, v[96:97]
	v_cvt_pk_bf16_f32 v127, v90, v91
	v_lshlrev_b64 v[90:91], 10, v[124:125]
	global_store_dwordx2 v[96:97], v[98:99], off
	v_cvt_pk_bf16_f32 v126, v148, v149
	v_lshl_add_u64 v[98:99], v[116:117], 0, v[90:91]
	global_store_dwordx2 v[98:99], v[126:127], off
	v_mfma_f32_16x16x32_bf16 v[124:127], v[56:59], v[4:7], 0
	v_mfma_f32_16x16x32_bf16 v[56:59], v[60:63], v[20:23], v[52:55]
	v_mfma_f32_16x16x32_bf16 v[52:55], v[64:67], v[20:23], v[124:127]
	s_nop 5
	v_add_u32_e32 v124, v142, v138
	v_add_f32_e32 v48, v48, v56
	v_add_f32_e32 v49, v49, v57
	v_mul_f32_e32 v48, 0xbfb8aa3b, v48
	v_mul_f32_e32 v49, 0xbfb8aa3b, v49
	v_exp_f32_e32 v48, v48
	v_exp_f32_e32 v49, v49
	v_add_f32_e32 v44, v44, v52
	v_add_f32_e32 v45, v45, v53
	v_mul_f32_e32 v44, 0xbfb8aa3b, v44
	v_mul_f32_e32 v45, 0xbfb8aa3b, v45
	v_add_f32_e32 v48, 1.0, v48
	v_exp_f32_e32 v44, v44
	v_add_f32_e32 v49, 1.0, v49
	v_exp_f32_e32 v45, v45
	v_rcp_f32_e32 v56, v48
	v_rcp_f32_e32 v52, v49
	v_add_f32_e32 v44, 1.0, v44
	v_add_f32_e32 v45, 1.0, v45
	v_rcp_f32_e32 v48, v44
	v_mul_f32_e32 v44, 0xc1000000, v56
	v_rcp_f32_e32 v49, v45
	v_mul_f32_e32 v45, 0xc1000000, v52
	v_mul_f32_e32 v44, v145, v44
	v_mul_f32_e32 v45, v147, v45
	v_mul_f32_e32 v44, 0x3fb8aa3b, v44
	v_mul_f32_e32 v45, 0x3fb8aa3b, v45
	v_exp_f32_e32 v56, v44
	v_exp_f32_e32 v57, v45
	v_add_f32_e32 v50, v50, v58
	v_mul_f32_e32 v50, 0xbfb8aa3b, v50
	v_fma_f32 v44, -v56, v56, 1.0
	v_fma_f32 v45, -v57, v57, 1.0
	v_sqrt_f32_e32 v60, v44
	v_mov_b32_e32 v44, 1.0
	v_sqrt_f32_e32 v61, v45
	v_mov_b32_e32 v45, 1.0
	v_exp_f32_e32 v50, v50
	v_mov_b32_dpp v44, v56 row_shr:1 row_mask:0xf bank_mask:0xf
	v_mov_b32_dpp v45, v57 row_shr:1 row_mask:0xf bank_mask:0xf
	v_pk_mul_f32 v[62:63], v[56:57], v[44:45]
	v_mov_b32_e32 v44, 1.0
	v_mov_b32_e32 v45, 1.0
	v_add_f32_e32 v46, v46, v54
	v_mov_b32_dpp v44, v62 row_shr:2 row_mask:0xf bank_mask:0xf
	v_mov_b32_dpp v45, v63 row_shr:2 row_mask:0xf bank_mask:0xf
	v_mul_f32_e32 v46, 0xbfb8aa3b, v46
	v_pk_mul_f32 v[64:65], v[62:63], v[44:45]
	v_mov_b32_e32 v44, 1.0
	v_mov_b32_e32 v45, 1.0
	v_add_f32_e32 v50, 1.0, v50
	v_exp_f32_e32 v46, v46
	v_mov_b32_dpp v44, v64 row_shr:4 row_mask:0xf bank_mask:0xf
	v_mov_b32_dpp v45, v65 row_shr:4 row_mask:0xf bank_mask:0xf
	v_rcp_f32_e32 v50, v50
	v_pk_mul_f32 v[66:67], v[64:65], v[44:45]
	v_mov_b32_e32 v44, 1.0
	v_mov_b32_e32 v45, 1.0
	v_add_f32_e32 v46, 1.0, v46
	v_mov_b32_dpp v44, v66 row_shr:8 row_mask:0xf bank_mask:0xf
	v_mov_b32_dpp v45, v67 row_shr:8 row_mask:0xf bank_mask:0xf
	v_pk_mul_f32 v[90:91], v[66:67], v[44:45]
	v_rcp_f32_e32 v54, v46
	v_pk_mul_f32 v[52:53], v[90:91], v[122:123]
	ds_read2_b32 v[122:123], v124 offset1:1
	v_mul_f32_e32 v46, 0xc1000000, v50
	v_mul_f32_e32 v2, v2, v46
	v_mul_f32_e32 v2, 0x3fb8aa3b, v2
	v_exp_f32_e32 v50, v2
	s_waitcnt lgkmcnt(0)
; __device__ __forceinline__ unsigned pk2(float lo, float hi) { const f32x2_t v = {lo, hi}; const bf16x2_t b = __builtin_convertvector(v, bf16x2_t); return __builtin_bit_cast(unsigned, b); }
; __device__ __forceinline__ float bcast15(float v, int lane) { return bperm_f((lane & 48) | 15, v); }
; __device__ __forceinline__ void w_lru_m1(const Args& a, int l, unsigned char* ws, const bf16_t* proj, bf16_t* y, LAS unsigned char* wl, int b, int ck_, int h, int lane) {
;     ...
;                 { const float As = dpp_shr1<1>(A), Us = dpp_shr0<1>(U); U = A * Us + U; A = A * As; }
;                 { const float As = dpp_shr1<2>(A), Us = dpp_shr0<2>(U); U = A * Us + U; A = A * As; }
;                 { const float As = dpp_shr1<4>(A), Us = dpp_shr0<4>(U); U = A * Us + U; A = A * As; }
;                 { const float As = dpp_shr1<8>(A), Us = dpp_shr0<8>(U); U = A * Us + U; A = A * As; }
;                 const float hh = U + A * hc[r], PP = A * Pc[r];
;                 hc[r] = bcast15(hh, lane); Pc[r] = bcast15(PP, lane); hv[r] = hh; pv[r] = PP; }
;             *(unsigned long long*)(y + (size_t)(row0 + tok) * DM + 64 * h + j0) = (unsigned long long)pk2(hv[0], hv[1]) | ((unsigned long long)pk2(hv[2], hv[3]) << 32);
;             *(unsigned long long*)((bf16_t*)(ws + WS_P) + (size_t)(row0 + tok) * 512 + 64 * h + j0) = (unsigned long long)pk2(pv[0], pv[1]) | ((unsigned long long)pk2(pv[2], pv[3]) << 32);
;         }
;         if (lo == 0) { const size_t so = (size_t)(b * NCH + ck_) * 512 + 64 * h + j0;
; #pragma unroll
;             for (int r = 0; r < 4; ++r) { ((float*)(ws + WS_LRUA))[so + r] = Pc[r]; ((float*)(ws + WS_LRUH))[so + r] = hc[r]; } }
	v_pk_mul_f32 v[48:49], v[122:123], v[48:49]
	v_add_f32_e32 v47, v47, v55
	v_pk_mul_f32 v[48:49], v[48:49], v[60:61]
	v_fma_f32 v2, -v50, v50, 1.0
	v_mul_f32_e32 v47, 0xbfb8aa3b, v47
	v_mov_b32_dpp v60, v48 row_shr:1 row_mask:0xf bank_mask:0xf bound_ctrl:1
	v_mov_b32_dpp v61, v49 row_shr:1 row_mask:0xf bank_mask:0xf bound_ctrl:1
	v_pk_fma_f32 v[48:49], v[56:57], v[60:61], v[48:49]
	v_sqrt_f32_e32 v60, v2
	v_add_f32_e32 v2, v51, v59
	v_mul_f32_e32 v2, 0xbfb8aa3b, v2
	v_exp_f32_e32 v2, v2
	v_exp_f32_e32 v47, v47
	v_mov_b32_e32 v46, 1.0
	v_mov_b32_dpp v56, v48 row_shr:2 row_mask:0xf bank_mask:0xf bound_ctrl:1
	v_add_f32_e32 v2, 1.0, v2
	v_rcp_f32_e32 v2, v2
	v_add_f32_e32 v47, 1.0, v47
	v_rcp_f32_e32 v55, v47
	v_mov_b32_e32 v47, 1.0
	v_mul_f32_e32 v2, 0xc1000000, v2
	v_mul_f32_e32 v2, v146, v2
	v_mul_f32_e32 v2, 0x3fb8aa3b, v2
	v_exp_f32_e32 v51, v2
	v_mov_b32_dpp v57, v49 row_shr:2 row_mask:0xf bank_mask:0xf bound_ctrl:1
	v_mov_b32_dpp v46, v50 row_shr:1 row_mask:0xf bank_mask:0xf
	v_pk_fma_f32 v[48:49], v[62:63], v[56:57], v[48:49]
	v_mov_b32_dpp v47, v51 row_shr:1 row_mask:0xf bank_mask:0xf
	v_pk_mul_f32 v[62:63], v[50:51], v[46:47]
	v_mov_b32_e32 v46, 1.0
	v_mov_b32_e32 v47, 1.0
	v_mov_b32_dpp v56, v48 row_shr:4 row_mask:0xf bank_mask:0xf bound_ctrl:1
	v_mov_b32_dpp v57, v49 row_shr:4 row_mask:0xf bank_mask:0xf bound_ctrl:1
	v_mov_b32_dpp v46, v62 row_shr:2 row_mask:0xf bank_mask:0xf
	v_mov_b32_dpp v47, v63 row_shr:2 row_mask:0xf bank_mask:0xf
	v_pk_fma_f32 v[48:49], v[64:65], v[56:57], v[48:49]
	v_pk_mul_f32 v[64:65], v[62:63], v[46:47]
	v_mov_b32_e32 v46, 1.0
	v_mov_b32_e32 v47, 1.0
	v_mov_b32_dpp v56, v48 row_shr:8 row_mask:0xf bank_mask:0xf bound_ctrl:1
	v_mov_b32_dpp v57, v49 row_shr:8 row_mask:0xf bank_mask:0xf bound_ctrl:1
	v_mov_b32_dpp v46, v64 row_shr:4 row_mask:0xf bank_mask:0xf
	v_mov_b32_dpp v47, v65 row_shr:4 row_mask:0xf bank_mask:0xf
	v_pk_fma_f32 v[48:49], v[66:67], v[56:57], v[48:49]
	v_pk_mul_f32 v[66:67], v[64:65], v[46:47]
	v_mov_b32_e32 v46, 1.0
	v_mov_b32_e32 v47, 1.0
	v_pk_fma_f32 v[56:57], v[90:91], v[94:95], v[48:49]
	v_mov_b32_dpp v46, v66 row_shr:8 row_mask:0xf bank_mask:0xf
	v_mov_b32_dpp v47, v67 row_shr:8 row_mask:0xf bank_mask:0xf
	v_pk_mul_f32 v[90:91], v[66:67], v[46:47]
	v_fma_f32 v2, -v51, v51, 1.0
	v_pk_mul_f32 v[58:59], v[90:91], v[92:93]
	ds_read2_b32 v[92:93], v124 offset0:2 offset1:3
	v_sqrt_f32_e32 v61, v2
	ds_bpermute_b32 v44, v143, v52 offset:60
	ds_bpermute_b32 v48, v143, v56 offset:60
	ds_bpermute_b32 v49, v143, v57 offset:60
	s_waitcnt lgkmcnt(0)
	v_pk_mul_f32 v[54:55], v[54:55], v[92:93]
	ds_bpermute_b32 v45, v143, v53 offset:60
	v_pk_mul_f32 v[54:55], v[60:61], v[54:55]
	ds_bpermute_b32 v46, v143, v58 offset:60
	ds_bpermute_b32 v47, v143, v59 offset:60
	v_mov_b32_dpp v60, v54 row_shr:1 row_mask:0xf bank_mask:0xf bound_ctrl:1
	v_mov_b32_dpp v61, v55 row_shr:1 row_mask:0xf bank_mask:0xf bound_ctrl:1
	v_pk_fma_f32 v[50:51], v[50:51], v[60:61], v[54:55]
	v_cvt_pk_bf16_f32 v56, v56, v57
	v_cvt_pk_bf16_f32 v52, v52, v53
	v_mov_b32_dpp v54, v50 row_shr:2 row_mask:0xf bank_mask:0xf bound_ctrl:1
	v_mov_b32_dpp v55, v51 row_shr:2 row_mask:0xf bank_mask:0xf bound_ctrl:1
	v_pk_fma_f32 v[50:51], v[62:63], v[54:55], v[50:51]
	v_cvt_pk_bf16_f32 v53, v58, v59
	s_nop 0
	v_mov_b32_dpp v54, v50 row_shr:4 row_mask:0xf bank_mask:0xf bound_ctrl:1
	v_mov_b32_dpp v55, v51 row_shr:4 row_mask:0xf bank_mask:0xf bound_ctrl:1
	v_pk_fma_f32 v[50:51], v[64:65], v[54:55], v[50:51]
	s_nop 1
	v_mov_b32_dpp v54, v50 row_shr:8 row_mask:0xf bank_mask:0xf bound_ctrl:1
	v_mov_b32_dpp v55, v51 row_shr:8 row_mask:0xf bank_mask:0xf bound_ctrl:1
	v_pk_fma_f32 v[50:51], v[66:67], v[54:55], v[50:51]
	s_nop 0
	v_pk_fma_f32 v[54:55], v[90:91], v[88:89], v[50:51]
	ds_bpermute_b32 v50, v143, v54 offset:60
	ds_bpermute_b32 v51, v143, v55 offset:60
	v_cvt_pk_bf16_f32 v57, v54, v55
	v_or_b32_e32 v54, s48, v137
	v_ashrrev_i32_e32 v55, 31, v54
	v_lshlrev_b64 v[60:61], 11, v[54:55]
	v_lshlrev_b64 v[54:55], 10, v[54:55]
	v_lshl_add_u64 v[114:115], v[114:115], 0, v[60:61]
	v_lshl_add_u64 v[116:117], v[116:117], 0, v[54:55]
	global_store_dwordx2 v[114:115], v[56:57], off
	global_store_dwordx2 v[116:117], v[52:53], off
	s_and_saveexec_b64 s[34:35], vcc
	s_cbranch_execz .LBB0_523
	v_lshl_add_u64 v[52:53], s[42:43], 0, v[0:1]
	v_lshlrev_b64 v[52:53], 2, v[52:53]
	v_lshl_add_u64 v[54:55], s[84:85], 0, v[52:53]
	v_lshl_add_u64 v[52:53], s[86:87], 0, v[52:53]
	s_waitcnt lgkmcnt(0)
	global_store_dwordx4 v[54:55], v[44:47], off
	global_store_dwordx4 v[52:53], v[48:51], off
; __device__ __forceinline__ void w_lru_m1(const Args& a, int l, unsigned char* ws, const bf16_t* proj, bf16_t* y, LAS unsigned char* wl, int b, int ck_, int h, int lane) {
;     ...
;     for (int jb = 0; jb < 4; ++jb) {
;         bf16x8 WaF[2], WxF[2]; f32x4 pba, pbx, plam;
; #pragma unroll
;         for (int kk = 0; kk < 2; ++kk) { WaF[kk] = nWa[kk]; WxF[kk] = nWx[kk]; }
;         pba = nba; pbx = nbx; plam = nlam;
;         if (jb < 3) {
; #pragma unroll
;             for (int kk = 0; kk < 2; ++kk) { nWa[kk] = *(const bf16x8*)(waT + (16 * (jb + 1) + lo) * 64 + 32 * kk + 8 * fq); nWx[kk] = *(const bf16x8*)(wxT + (16 * (jb + 1) + lo) * 64 + 32 * kk + 8 * fq); }
;             nba = *(const f32x4*)(ba + 16 * (jb + 1) + 4 * fq); nbx = *(const f32x4*)(bx + 16 * (jb + 1) + 4 * fq); nlam = *(const f32x4*)(lam + 16 * (jb + 1) + 4 * fq);
;         }
;         const int j0 = 16 * jb + 4 * fq;
;         float bav[4], bxv[4], sp[4], hc[4], Pc[4];
; #pragma unroll
;         for (int r = 0; r < 4; ++r) { bav[r] = pba[r]; bxv[r] = pbx[r]; sp[r] = log1pf(__expf(-plam[r])); hc[r] = 0.f; Pc[r] = 1.f; }
.LBB0_523:
	s_or_b64 exec, exec, s[34:35]
	v_lshlrev_b32_e32 v146, 6, v136
	v_lshl_or_b32 v2, v146, 1, v209
	s_waitcnt lgkmcnt(0)
	v_lshl_add_u64 v[44:45], v[118:119], 0, v[2:3]
	v_lshl_add_u64 v[46:47], v[120:121], 0, v[2:3]
	s_waitcnt vmcnt(8)
	v_mul_f32_e32 v2, 0xbfb8aa3b, v84
	v_exp_f32_e32 v2, v2
	v_mul_u32_u24_e32 v92, 0x104, v136
	v_add_u32_e32 v145, v142, v92
	global_load_dwordx4 v[64:67], v[44:45], off
	global_load_dwordx4 v[60:63], v[46:47], off
	global_load_dwordx4 v[56:59], v[44:45], off offset:64
	global_load_dwordx4 v[52:55], v[46:47], off offset:64
	global_load_dwordx4 v[48:51], v[108:109], off offset:128
	s_nop 0
	global_load_dwordx4 v[44:47], v[110:111], off offset:128
	global_load_dwordx4 v[88:91], v[112:113], off offset:128
	v_add_f32_e32 v84, 1.0, v2
	v_add_f32_e32 v93, -1.0, v84
	v_sub_f32_e32 v94, v93, v84
	v_add_f32_e32 v94, 1.0, v94
	v_sub_f32_e32 v93, v2, v93
	v_add_f32_e32 v93, v93, v94
	v_frexp_mant_f32_e32 v94, v84
	v_cmp_gt_f32_e64 s[40:41], s77, v94
	v_cvt_f64_f32_e32 v[94:95], v84
	v_frexp_exp_i32_f64_e32 v94, v[94:95]
	v_subbrev_co_u32_e64 v128, s[40:41], 0, v94, s[40:41]
	v_sub_u32_e32 v94, 0, v128
	v_ldexp_f32 v84, v84, v94
	v_ldexp_f32 v93, v93, v94
	v_add_f32_e32 v94, -1.0, v84
	v_add_f32_e32 v95, 1.0, v94
	v_sub_f32_e32 v95, v84, v95
	v_add_f32_e32 v122, v93, v95
	v_add_f32_e32 v95, 1.0, v84
	v_add_f32_e32 v123, -1.0, v95
	v_sub_f32_e32 v84, v84, v123
	v_add_f32_e32 v84, v93, v84
	v_add_f32_e32 v93, v95, v84
	v_rcp_f32_e32 v129, v93
	v_sub_f32_e32 v95, v93, v95
	v_sub_f32_e32 v84, v84, v95
	v_add_f32_e32 v95, v94, v122
	v_sub_f32_e32 v94, v95, v94
	v_mul_f32_e32 v131, v95, v129
	v_sub_f32_e32 v130, v122, v94
	v_mul_f32_e32 v122, v93, v131
	v_fma_f32 v124, v131, v93, -v122
	v_fmac_f32_e32 v124, v131, v84
	v_add_f32_e32 v94, v122, v124
	v_sub_f32_e32 v123, v95, v94
	v_pk_add_f32 v[126:127], v[94:95], v[122:123] neg_lo:[0,1] neg_hi:[0,1]
	v_mov_b32_e32 v125, v94
	v_pk_add_f32 v[94:95], v[126:127], v[124:125] neg_lo:[0,1] neg_hi:[0,1]
	v_cmp_neq_f32_e64 s[40:41], s22, v2
	v_add_f32_e32 v95, v130, v95
	v_add_f32_e32 v94, v94, v95
	v_add_f32_e32 v95, v123, v94
	v_mul_f32_e32 v130, v129, v95
	v_mul_f32_e32 v122, v93, v130
	v_fma_f32 v124, v130, v93, -v122
	v_fmac_f32_e32 v124, v130, v84
	v_sub_f32_e32 v84, v123, v95
	v_add_f32_e32 v84, v94, v84
	v_add_f32_e32 v94, v122, v124
	v_sub_f32_e32 v123, v95, v94
	v_pk_add_f32 v[126:127], v[94:95], v[122:123] neg_lo:[0,1] neg_hi:[0,1]
	v_mov_b32_e32 v125, v94
	v_pk_add_f32 v[94:95], v[126:127], v[124:125] neg_lo:[0,1] neg_hi:[0,1]
	v_add_f32_e32 v93, v131, v130
	v_add_f32_e32 v84, v84, v95
	v_add_f32_e32 v84, v94, v84
	v_add_f32_e32 v84, v123, v84
	v_sub_f32_e32 v94, v93, v131
	v_mul_f32_e32 v84, v129, v84
	v_sub_f32_e32 v94, v130, v94
	v_add_f32_e32 v84, v94, v84
	v_add_f32_e32 v95, v93, v84
	v_mul_f32_e32 v122, v95, v95
	v_fmamk_f32 v94, v122, 0x3e9b6dac, v201
	v_fmaak_f32 v169, v122, v94, 0x3f2aaada
	v_cvt_f32_i32_e32 v94, v128
	v_sub_f32_e32 v93, v95, v93
	v_ldexp_f32 v123, v95, 1
	v_mul_f32_e32 v95, v95, v122
	v_pk_mul_f32 v[124:125], v[94:95], v[168:169]
	v_sub_f32_e32 v84, v84, v93
	v_fma_f32 v122, v94, s94, -v124
	v_fmac_f32_e32 v122, 0xb102e308, v94
	v_pk_add_f32 v[94:95], v[124:125], v[122:123]
	v_ldexp_f32 v84, v84, 1
	v_sub_f32_e32 v93, v95, v123
	v_sub_f32_e32 v93, v125, v93
	v_add_f32_e32 v127, v84, v93
	v_mov_b32_e32 v126, v124
	v_pk_add_f32 v[124:125], v[94:95], v[124:125] neg_lo:[0,1] neg_hi:[0,1]
	v_pk_add_f32 v[128:129], v[94:95], v[126:127]
	v_mov_b32_e32 v123, v94
	v_mov_b32_e32 v125, v129
	v_pk_add_f32 v[130:131], v[122:123], v[124:125] neg_lo:[0,1] neg_hi:[0,1]
	v_pk_add_f32 v[122:123], v[122:123], v[124:125]
	v_mov_b32_e32 v126, v127
	v_pk_add_f32 v[124:125], v[122:123], v[94:95] op_sel:[1,0] op_sel_hi:[0,1] neg_lo:[0,1] neg_hi:[0,1]
	v_pk_add_f32 v[132:133], v[128:129], v[124:125] op_sel_hi:[1,0] neg_lo:[0,1] neg_hi:[0,1]
	v_mov_b32_e32 v128, v129
	v_mov_b32_e32 v129, v123
	v_pk_mov_b32 v[124:125], v[94:95], v[124:125] op_sel:[1,0]
	v_mov_b32_e32 v127, v94
	v_pk_add_f32 v[124:125], v[128:129], v[124:125] neg_lo:[0,1] neg_hi:[0,1]
	v_mov_b32_e32 v132, v130
	v_pk_add_f32 v[94:95], v[126:127], v[124:125] neg_lo:[0,1] neg_hi:[0,1]
	v_mov_b32_e32 v131, v123
	v_pk_add_f32 v[124:125], v[132:133], v[94:95]
	v_mov_b32_e32 v132, 1.0
	v_pk_add_f32 v[126:127], v[124:125], v[124:125] op_sel:[0,1] op_sel_hi:[1,0]
	v_mov_b32_e32 v133, 1.0
	v_pk_add_f32 v[122:123], v[122:123], v[126:127] op_sel:[1,0] op_sel_hi:[0,1]
	v_mov_b32_e32 v125, v122
	v_pk_add_f32 v[128:129], v[124:125], v[130:131] neg_lo:[0,1] neg_hi:[0,1]
	v_mov_b32_e32 v95, v126
	v_sub_f32_e32 v84, v124, v128
	v_pk_add_f32 v[94:95], v[94:95], v[128:129] neg_lo:[0,1] neg_hi:[0,1]
	v_sub_f32_e32 v84, v130, v84
	v_add_f32_e32 v84, v94, v84
	v_add_f32_e32 v84, v84, v95
	v_add_f32_e32 v84, v122, v84
	v_cndmask_b32_e64 v84, v208, v84, s[40:41]
	v_cmp_ngt_f32_e64 s[40:41], -1.0, v2
	v_or_b32_e32 v1, 60, v143
	ds_read2_b32 v[136:137], v145 offset0:18 offset1:19
	v_cndmask_b32_e64 v84, v205, v84, s[40:41]
	v_cmp_neq_f32_e64 s[40:41], -1.0, v2
	s_nop 1
	v_cndmask_b32_e64 v84, v206, v84, s[40:41]
	v_cmp_lt_f32_e64 s[40:41], |v2|, s95
	s_nop 1
	v_cndmask_b32_e64 v147, v84, v2, s[40:41]
	v_mul_f32_e32 v2, 0xbfb8aa3b, v85
	v_exp_f32_e32 v2, v2
	s_nop 0
	v_add_f32_e32 v93, 1.0, v2
	v_add_f32_e32 v84, -1.0, v93
	v_sub_f32_e32 v85, v84, v93
	v_add_f32_e32 v85, 1.0, v85
	v_sub_f32_e32 v84, v2, v84
	v_add_f32_e32 v94, v84, v85
	v_frexp_mant_f32_e32 v84, v93
	v_cmp_gt_f32_e64 s[40:41], s77, v84
	v_cvt_f64_f32_e32 v[84:85], v93
	v_frexp_exp_i32_f64_e32 v84, v[84:85]
	v_subbrev_co_u32_e64 v126, s[40:41], 0, v84, s[40:41]
; __device__ __forceinline__ void w_lru_m1(const Args& a, int l, unsigned char* ws, const bf16_t* proj, bf16_t* y, LAS unsigned char* wl, int b, int ck_, int h, int lane) {
;     ...
;         for (int r = 0; r < 4; ++r) { bav[r] = pba[r]; bxv[r] = pbx[r]; sp[r] = log1pf(__expf(-plam[r])); hc[r] = 0.f; Pc[r] = 1.f; }
	v_sub_u32_e32 v84, 0, v126
	v_ldexp_f32 v85, v93, v84
	v_add_f32_e32 v93, -1.0, v85
	v_add_f32_e32 v95, 1.0, v85
	v_ldexp_f32 v84, v94, v84
	v_add_f32_e32 v94, 1.0, v93
	v_add_f32_e32 v122, -1.0, v95
	v_sub_f32_e32 v94, v85, v94
	v_sub_f32_e32 v85, v85, v122
	v_add_f32_e32 v94, v84, v94
	v_add_f32_e32 v84, v84, v85
	v_add_f32_e32 v127, v95, v84
	v_rcp_f32_e32 v129, v127
	v_sub_f32_e32 v85, v127, v95
	v_sub_f32_e32 v128, v84, v85
	v_add_f32_e32 v85, v93, v94
	v_sub_f32_e32 v84, v85, v93
	v_mul_f32_e32 v130, v85, v129
	v_sub_f32_e32 v93, v94, v84
	v_mul_f32_e32 v94, v127, v130
	v_fma_f32 v122, v130, v127, -v94
	v_fmac_f32_e32 v122, v130, v128
	v_add_f32_e32 v84, v94, v122
	v_sub_f32_e32 v95, v85, v84
	v_pk_add_f32 v[124:125], v[84:85], v[94:95] neg_lo:[0,1] neg_hi:[0,1]
	v_mov_b32_e32 v123, v84
	v_pk_add_f32 v[84:85], v[124:125], v[122:123] neg_lo:[0,1] neg_hi:[0,1]
	v_cmp_neq_f32_e64 s[40:41], s22, v2
	v_add_f32_e32 v85, v93, v85
	v_add_f32_e32 v84, v84, v85
	v_add_f32_e32 v85, v95, v84
	v_mul_f32_e32 v93, v129, v85
	v_mul_f32_e32 v94, v127, v93
	v_fma_f32 v122, v93, v127, -v94
	v_fmac_f32_e32 v122, v93, v128
	v_sub_f32_e32 v95, v95, v85
	v_add_f32_e32 v127, v84, v95
	v_add_f32_e32 v84, v94, v122
	v_sub_f32_e32 v95, v85, v84
	v_pk_add_f32 v[124:125], v[84:85], v[94:95] neg_lo:[0,1] neg_hi:[0,1]
	v_mov_b32_e32 v123, v84
	v_pk_add_f32 v[84:85], v[124:125], v[122:123] neg_lo:[0,1] neg_hi:[0,1]
	s_nop 0
	v_add_f32_e32 v85, v127, v85
	v_add_f32_e32 v84, v84, v85
	v_add_f32_e32 v85, v130, v93
	v_add_f32_e32 v84, v95, v84
	v_sub_f32_e32 v94, v85, v130
	v_mul_f32_e32 v84, v129, v84
	v_sub_f32_e32 v93, v93, v94
	v_add_f32_e32 v93, v93, v84
	v_add_f32_e32 v94, v85, v93
	v_mul_f32_e32 v122, v94, v94
	v_fmamk_f32 v84, v122, 0x3e9b6dac, v201
	v_fmaak_f32 v169, v122, v84, 0x3f2aaada
	v_cvt_f32_i32_e32 v84, v126
	v_sub_f32_e32 v85, v94, v85
	v_sub_f32_e32 v85, v93, v85
	v_ldexp_f32 v93, v85, 1
	v_mul_f32_e32 v85, v94, v122
	v_pk_mul_f32 v[122:123], v[84:85], v[168:169]
	v_ldexp_f32 v95, v94, 1
	v_fma_f32 v94, v84, s94, -v122
	v_fmac_f32_e32 v94, 0xb102e308, v84
	v_pk_add_f32 v[84:85], v[122:123], v[94:95]
	v_mov_b32_e32 v124, v122
	v_sub_f32_e32 v95, v85, v95
	v_sub_f32_e32 v95, v123, v95
	v_add_f32_e32 v125, v93, v95
	v_pk_add_f32 v[122:123], v[84:85], v[122:123] neg_lo:[0,1] neg_hi:[0,1]
	v_pk_add_f32 v[126:127], v[84:85], v[124:125]
	v_mov_b32_e32 v95, v84
	v_mov_b32_e32 v123, v127
	v_pk_add_f32 v[128:129], v[94:95], v[122:123] neg_lo:[0,1] neg_hi:[0,1]
	v_pk_add_f32 v[94:95], v[94:95], v[122:123]
	v_mov_b32_e32 v124, v125
	v_pk_add_f32 v[122:123], v[94:95], v[84:85] op_sel:[1,0] op_sel_hi:[0,1] neg_lo:[0,1] neg_hi:[0,1]
	v_pk_add_f32 v[130:131], v[126:127], v[122:123] op_sel_hi:[1,0] neg_lo:[0,1] neg_hi:[0,1]
	v_mov_b32_e32 v126, v127
	v_mov_b32_e32 v127, v95
	v_pk_mov_b32 v[122:123], v[84:85], v[122:123] op_sel:[1,0]
	v_mov_b32_e32 v125, v84
	v_pk_add_f32 v[122:123], v[126:127], v[122:123] neg_lo:[0,1] neg_hi:[0,1]
	v_mov_b32_e32 v130, v128
	v_pk_add_f32 v[84:85], v[124:125], v[122:123] neg_lo:[0,1] neg_hi:[0,1]
	v_mov_b32_e32 v129, v95
	v_pk_add_f32 v[122:123], v[130:131], v[84:85]
	s_nop 0
	v_pk_add_f32 v[124:125], v[122:123], v[122:123] op_sel:[0,1] op_sel_hi:[1,0]
	s_nop 0
	v_pk_add_f32 v[94:95], v[94:95], v[124:125] op_sel:[1,0] op_sel_hi:[0,1]
	v_mov_b32_e32 v123, v94
	v_pk_add_f32 v[126:127], v[122:123], v[128:129] neg_lo:[0,1] neg_hi:[0,1]
	v_mov_b32_e32 v85, v124
	v_sub_f32_e32 v93, v122, v126
	v_pk_add_f32 v[84:85], v[84:85], v[126:127] neg_lo:[0,1] neg_hi:[0,1]
	v_sub_f32_e32 v93, v128, v93
	v_add_f32_e32 v84, v84, v93
	v_add_f32_e32 v84, v84, v85
	v_add_f32_e32 v84, v94, v84
	v_cndmask_b32_e64 v84, v208, v84, s[40:41]
	v_cmp_ngt_f32_e64 s[40:41], -1.0, v2
	s_nop 1
	v_cndmask_b32_e64 v84, v205, v84, s[40:41]
	v_cmp_neq_f32_e64 s[40:41], -1.0, v2
	s_nop 1
	v_cndmask_b32_e64 v84, v206, v84, s[40:41]
	v_cmp_lt_f32_e64 s[40:41], |v2|, s95
	s_nop 1
	v_cndmask_b32_e64 v149, v84, v2, s[40:41]
	v_mul_f32_e32 v2, 0xbfb8aa3b, v86
	v_exp_f32_e32 v2, v2
	s_nop 0
	v_add_f32_e32 v86, 1.0, v2
	v_add_f32_e32 v84, -1.0, v86
	v_sub_f32_e32 v85, v84, v86
	v_add_f32_e32 v85, 1.0, v85
	v_sub_f32_e32 v84, v2, v84
	v_add_f32_e32 v93, v84, v85
	v_frexp_mant_f32_e32 v84, v86
	v_cmp_gt_f32_e64 s[40:41], s77, v84
	v_cvt_f64_f32_e32 v[84:85], v86
	v_frexp_exp_i32_f64_e32 v84, v[84:85]
	v_subbrev_co_u32_e64 v126, s[40:41], 0, v84, s[40:41]
	v_sub_u32_e32 v84, 0, v126
	v_ldexp_f32 v85, v86, v84
	v_add_f32_e32 v86, -1.0, v85
	v_add_f32_e32 v94, 1.0, v85
	v_ldexp_f32 v84, v93, v84
	v_add_f32_e32 v93, 1.0, v86
	v_add_f32_e32 v95, -1.0, v94
	v_sub_f32_e32 v93, v85, v93
	v_sub_f32_e32 v85, v85, v95
	v_add_f32_e32 v93, v84, v93
	v_add_f32_e32 v84, v84, v85
	v_add_f32_e32 v127, v94, v84
	v_rcp_f32_e32 v129, v127
	v_sub_f32_e32 v85, v127, v94
	v_sub_f32_e32 v128, v84, v85
	v_add_f32_e32 v85, v86, v93
	v_sub_f32_e32 v84, v85, v86
	v_sub_f32_e32 v86, v93, v84
	v_mul_f32_e32 v93, v85, v129
	v_mul_f32_e32 v94, v127, v93
	v_fma_f32 v122, v93, v127, -v94
	v_fmac_f32_e32 v122, v93, v128
	v_add_f32_e32 v84, v94, v122
	v_sub_f32_e32 v95, v85, v84
	v_pk_add_f32 v[124:125], v[84:85], v[94:95] neg_lo:[0,1] neg_hi:[0,1]
	v_mov_b32_e32 v123, v84
	v_pk_add_f32 v[84:85], v[124:125], v[122:123] neg_lo:[0,1] neg_hi:[0,1]
	v_cmp_neq_f32_e64 s[40:41], s22, v2
	v_add_f32_e32 v85, v86, v85
	v_add_f32_e32 v84, v84, v85
	v_add_f32_e32 v85, v95, v84
	v_mul_f32_e32 v86, v129, v85
	v_mul_f32_e32 v94, v127, v86
	v_fma_f32 v122, v86, v127, -v94
	v_fmac_f32_e32 v122, v86, v128
	v_sub_f32_e32 v95, v95, v85
	v_add_f32_e32 v127, v84, v95
	v_add_f32_e32 v84, v94, v122
	v_sub_f32_e32 v95, v85, v84
; __device__ __forceinline__ void w_lru_m1(const Args& a, int l, unsigned char* ws, const bf16_t* proj, bf16_t* y, LAS unsigned char* wl, int b, int ck_, int h, int lane) {
;     ...
;         for (int r = 0; r < 4; ++r) { bav[r] = pba[r]; bxv[r] = pbx[r]; sp[r] = log1pf(__expf(-plam[r])); hc[r] = 0.f; Pc[r] = 1.f; }
	v_pk_add_f32 v[124:125], v[84:85], v[94:95] neg_lo:[0,1] neg_hi:[0,1]
	v_mov_b32_e32 v123, v84
	v_pk_add_f32 v[84:85], v[124:125], v[122:123] neg_lo:[0,1] neg_hi:[0,1]
	s_nop 0
	v_add_f32_e32 v85, v127, v85
	v_add_f32_e32 v84, v84, v85
	v_add_f32_e32 v85, v93, v86
	v_add_f32_e32 v84, v95, v84
	v_sub_f32_e32 v93, v85, v93
	v_mul_f32_e32 v84, v129, v84
	v_sub_f32_e32 v86, v86, v93
	v_add_f32_e32 v86, v86, v84
	v_add_f32_e32 v93, v85, v86
	v_mul_f32_e32 v94, v93, v93
	v_fmamk_f32 v84, v94, 0x3e9b6dac, v201
	v_fmaak_f32 v169, v94, v84, 0x3f2aaada
	v_cvt_f32_i32_e32 v84, v126
	v_sub_f32_e32 v85, v93, v85
	v_sub_f32_e32 v85, v86, v85
	v_ldexp_f32 v86, v85, 1
	v_mul_f32_e32 v85, v93, v94
	v_pk_mul_f32 v[122:123], v[84:85], v[168:169]
	v_ldexp_f32 v95, v93, 1
	v_fma_f32 v94, v84, s94, -v122
	v_fmac_f32_e32 v94, 0xb102e308, v84
	v_pk_add_f32 v[84:85], v[122:123], v[94:95]
	v_mov_b32_e32 v124, v122
	v_sub_f32_e32 v93, v85, v95
	v_sub_f32_e32 v93, v123, v93
	v_add_f32_e32 v125, v86, v93
	v_pk_add_f32 v[122:123], v[84:85], v[122:123] neg_lo:[0,1] neg_hi:[0,1]
	v_pk_add_f32 v[126:127], v[84:85], v[124:125]
	v_mov_b32_e32 v95, v84
	v_mov_b32_e32 v123, v127
	v_pk_add_f32 v[128:129], v[94:95], v[122:123] neg_lo:[0,1] neg_hi:[0,1]
	v_pk_add_f32 v[94:95], v[94:95], v[122:123]
	v_mov_b32_e32 v124, v125
	v_pk_add_f32 v[122:123], v[94:95], v[84:85] op_sel:[1,0] op_sel_hi:[0,1] neg_lo:[0,1] neg_hi:[0,1]
	v_pk_add_f32 v[130:131], v[126:127], v[122:123] op_sel_hi:[1,0] neg_lo:[0,1] neg_hi:[0,1]
	v_mov_b32_e32 v126, v127
	v_mov_b32_e32 v127, v95
	v_pk_mov_b32 v[122:123], v[84:85], v[122:123] op_sel:[1,0]
	v_mov_b32_e32 v125, v84
	v_pk_add_f32 v[122:123], v[126:127], v[122:123] neg_lo:[0,1] neg_hi:[0,1]
	v_mov_b32_e32 v130, v128
	v_pk_add_f32 v[84:85], v[124:125], v[122:123] neg_lo:[0,1] neg_hi:[0,1]
	v_mov_b32_e32 v129, v95
	v_pk_add_f32 v[122:123], v[130:131], v[84:85]
	v_mov_b32_e32 v130, 1.0
	v_pk_add_f32 v[124:125], v[122:123], v[122:123] op_sel:[0,1] op_sel_hi:[1,0]
	v_mov_b32_e32 v131, 1.0
	v_pk_add_f32 v[94:95], v[94:95], v[124:125] op_sel:[1,0] op_sel_hi:[0,1]
	v_mov_b32_e32 v123, v94
	v_pk_add_f32 v[126:127], v[122:123], v[128:129] neg_lo:[0,1] neg_hi:[0,1]
	v_mov_b32_e32 v85, v124
	v_sub_f32_e32 v86, v122, v126
	v_pk_add_f32 v[84:85], v[84:85], v[126:127] neg_lo:[0,1] neg_hi:[0,1]
	v_sub_f32_e32 v86, v128, v86
	v_add_f32_e32 v84, v84, v86
	v_add_f32_e32 v84, v84, v85
	v_add_f32_e32 v84, v94, v84
	v_cndmask_b32_e64 v84, v208, v84, s[40:41]
	v_cmp_ngt_f32_e64 s[40:41], -1.0, v2
	s_nop 1
	v_cndmask_b32_e64 v84, v205, v84, s[40:41]
	v_cmp_neq_f32_e64 s[40:41], -1.0, v2
	s_nop 1
	v_cndmask_b32_e64 v84, v206, v84, s[40:41]
	v_cmp_lt_f32_e64 s[40:41], |v2|, s95
	s_nop 1
	v_cndmask_b32_e64 v2, v84, v2, s[40:41]
	v_mul_f32_e32 v84, 0xbfb8aa3b, v87
	v_exp_f32_e32 v93, v84
	s_nop 0
	v_add_f32_e32 v86, 1.0, v93
	v_add_f32_e32 v84, -1.0, v86
	v_sub_f32_e32 v85, v84, v86
	v_add_f32_e32 v85, 1.0, v85
	v_sub_f32_e32 v84, v93, v84
	v_add_f32_e32 v87, v84, v85
	v_frexp_mant_f32_e32 v84, v86
	v_cmp_gt_f32_e64 s[40:41], s77, v84
	v_cvt_f64_f32_e32 v[84:85], v86
	v_frexp_exp_i32_f64_e32 v84, v[84:85]
	v_subbrev_co_u32_e64 v124, s[40:41], 0, v84, s[40:41]
	v_sub_u32_e32 v84, 0, v124
	v_ldexp_f32 v85, v86, v84
	v_add_f32_e32 v86, -1.0, v85
	v_add_f32_e32 v94, 1.0, v85
	v_ldexp_f32 v84, v87, v84
	v_add_f32_e32 v87, 1.0, v86
	v_add_f32_e32 v95, -1.0, v94
	v_sub_f32_e32 v87, v85, v87
	v_sub_f32_e32 v85, v85, v95
	v_add_f32_e32 v87, v84, v87
	v_add_f32_e32 v84, v84, v85
	v_add_f32_e32 v125, v94, v84
	v_rcp_f32_e32 v127, v125
	v_sub_f32_e32 v85, v125, v94
	v_sub_f32_e32 v126, v84, v85
	v_add_f32_e32 v85, v86, v87
	v_mul_f32_e32 v129, v85, v127
	v_sub_f32_e32 v84, v85, v86
	v_mul_f32_e32 v86, v125, v129
	v_fma_f32 v94, v129, v125, -v86
	v_fmac_f32_e32 v94, v129, v126
	v_sub_f32_e32 v128, v87, v84
	v_add_f32_e32 v84, v86, v94
	v_sub_f32_e32 v87, v85, v84
	v_pk_add_f32 v[122:123], v[84:85], v[86:87] neg_lo:[0,1] neg_hi:[0,1]
	v_mov_b32_e32 v95, v84
	v_pk_add_f32 v[84:85], v[122:123], v[94:95] neg_lo:[0,1] neg_hi:[0,1]
	v_cmp_neq_f32_e64 s[40:41], s22, v93
	v_add_f32_e32 v85, v128, v85
	v_add_f32_e32 v84, v84, v85
	v_add_f32_e32 v85, v87, v84
	v_mul_f32_e32 v128, v127, v85
	v_mul_f32_e32 v86, v125, v128
	v_fma_f32 v94, v128, v125, -v86
	v_fmac_f32_e32 v94, v128, v126
	v_sub_f32_e32 v87, v87, v85
	v_add_f32_e32 v125, v84, v87
	v_add_f32_e32 v84, v86, v94
	v_sub_f32_e32 v87, v85, v84
	v_pk_add_f32 v[122:123], v[84:85], v[86:87] neg_lo:[0,1] neg_hi:[0,1]
	v_mov_b32_e32 v95, v84
	v_pk_add_f32 v[84:85], v[122:123], v[94:95] neg_lo:[0,1] neg_hi:[0,1]
	s_nop 0
	v_add_f32_e32 v85, v125, v85
	v_add_f32_e32 v84, v84, v85
	v_add_f32_e32 v85, v129, v128
	v_add_f32_e32 v84, v87, v84
	v_sub_f32_e32 v86, v85, v129
	v_mul_f32_e32 v84, v127, v84
	v_sub_f32_e32 v86, v128, v86
	v_add_f32_e32 v86, v86, v84
	v_add_f32_e32 v94, v85, v86
	v_mul_f32_e32 v95, v94, v94
	v_fmamk_f32 v84, v95, 0x3e9b6dac, v201
	v_fmaak_f32 v169, v95, v84, 0x3f2aaada
	v_cvt_f32_i32_e32 v84, v124
	v_sub_f32_e32 v85, v94, v85
	v_sub_f32_e32 v85, v86, v85
	v_ldexp_f32 v122, v85, 1
	v_mul_f32_e32 v85, v94, v95
	v_ldexp_f32 v87, v94, 1
	v_pk_mul_f32 v[94:95], v[84:85], v[168:169]
	s_nop 0
	v_fma_f32 v86, v84, s94, -v94
	v_fmac_f32_e32 v86, 0xb102e308, v84
	v_pk_add_f32 v[84:85], v[94:95], v[86:87]
	s_nop 0
	v_sub_f32_e32 v87, v85, v87
	v_sub_f32_e32 v87, v95, v87
	v_add_f32_e32 v123, v122, v87
	v_mov_b32_e32 v122, v94
	v_pk_add_f32 v[94:95], v[84:85], v[94:95] neg_lo:[0,1] neg_hi:[0,1]
	v_pk_add_f32 v[124:125], v[84:85], v[122:123]
	v_mov_b32_e32 v87, v84
	v_mov_b32_e32 v95, v125
	v_pk_add_f32 v[126:127], v[86:87], v[94:95] neg_lo:[0,1] neg_hi:[0,1]
; __device__ __forceinline__ float sigmoidf_(float x) { return __builtin_amdgcn_rcpf(1.0f + __expf(-x)); }
; __device__ __forceinline__ float bcast15(float v, int lane) { return bperm_f((lane & 48) | 15, v); }
; __device__ __forceinline__ void w_lru_m1(const Args& a, int l, unsigned char* ws, const bf16_t* proj, bf16_t* y, LAS unsigned char* wl, int b, int ck_, int h, int lane) {
;     ...
;         for (int r = 0; r < 4; ++r) { bav[r] = pba[r]; bxv[r] = pbx[r]; sp[r] = log1pf(__expf(-plam[r])); hc[r] = 0.f; Pc[r] = 1.f; }
; #pragma unroll
;         for (int tb = 0; tb < 4; ++tb) { const int tok = 16 * tb + lo;
;             f32x4 ga = {0.f, 0.f, 0.f, 0.f}, gx = {0.f, 0.f, 0.f, 0.f};
; #pragma unroll
;             for (int kk = 0; kk < 2; ++kk) { ga = __builtin_amdgcn_mfma_f32_16x16x32_bf16(WaF[kk], Xf[tb][kk], ga, 0, 0, 0); gx = __builtin_amdgcn_mfma_f32_16x16x32_bf16(WxF[kk], Xf[tb][kk], gx, 0, 0, 0); }
;             float hv[4], pv[4];
; #pragma unroll
;             for (int r = 0; r < 4; ++r) {
;                 const float rg = sigmoidf_(ga[r] + bav[r]), ig = sigmoidf_(gx[r] + bxv[r]);
;                 const float la = -8.0f * rg * sp[r]; float A = __expf(la);
;                 float U = __builtin_amdgcn_sqrtf(1.0f - A * A) * (ig * xcf[tok * 65 + j0 + r]);
;                 { const float As = dpp_shr1<1>(A), Us = dpp_shr0<1>(U); U = A * Us + U; A = A * As; }
;                 { const float As = dpp_shr1<2>(A), Us = dpp_shr0<2>(U); U = A * Us + U; A = A * As; }
;                 { const float As = dpp_shr1<4>(A), Us = dpp_shr0<4>(U); U = A * Us + U; A = A * As; }
;                 { const float As = dpp_shr1<8>(A), Us = dpp_shr0<8>(U); U = A * Us + U; A = A * As; }
;                 const float hh = U + A * hc[r], PP = A * Pc[r];
;                 hc[r] = bcast15(hh, lane); Pc[r] = bcast15(PP, lane); hv[r] = hh; pv[r] = PP; }
	v_pk_add_f32 v[86:87], v[86:87], v[94:95]
	v_mov_b32_e32 v122, v123
	v_pk_add_f32 v[94:95], v[86:87], v[84:85] op_sel:[1,0] op_sel_hi:[0,1] neg_lo:[0,1] neg_hi:[0,1]
	v_pk_add_f32 v[128:129], v[124:125], v[94:95] op_sel_hi:[1,0] neg_lo:[0,1] neg_hi:[0,1]
	v_mov_b32_e32 v124, v125
	v_mov_b32_e32 v125, v87
	v_pk_mov_b32 v[94:95], v[84:85], v[94:95] op_sel:[1,0]
	v_mov_b32_e32 v123, v84
	v_pk_add_f32 v[94:95], v[124:125], v[94:95] neg_lo:[0,1] neg_hi:[0,1]
	v_mov_b32_e32 v128, v126
	v_pk_add_f32 v[84:85], v[122:123], v[94:95] neg_lo:[0,1] neg_hi:[0,1]
	v_mov_b32_e32 v127, v87
	v_pk_add_f32 v[94:95], v[128:129], v[84:85]
	v_mov_b32_e32 v128, 1.0
	v_pk_add_f32 v[122:123], v[94:95], v[94:95] op_sel:[0,1] op_sel_hi:[1,0]
	v_mov_b32_e32 v129, 1.0
	v_pk_add_f32 v[86:87], v[86:87], v[122:123] op_sel:[1,0] op_sel_hi:[0,1]
	v_mov_b32_e32 v95, v86
	v_pk_add_f32 v[124:125], v[94:95], v[126:127] neg_lo:[0,1] neg_hi:[0,1]
	v_mov_b32_e32 v85, v122
	v_sub_f32_e32 v87, v94, v124
	v_pk_add_f32 v[84:85], v[84:85], v[124:125] neg_lo:[0,1] neg_hi:[0,1]
	v_sub_f32_e32 v87, v126, v87
	v_add_f32_e32 v84, v84, v87
	v_add_f32_e32 v84, v84, v85
	v_add_f32_e32 v84, v86, v84
	v_cndmask_b32_e64 v84, v208, v84, s[40:41]
	v_cmp_ngt_f32_e64 s[40:41], -1.0, v93
	v_mfma_f32_16x16x32_bf16 v[122:125], v[72:75], v[16:19], 0
	s_nop 0
	v_cndmask_b32_e64 v84, v205, v84, s[40:41]
	v_cmp_neq_f32_e64 s[40:41], -1.0, v93
	v_mfma_f32_16x16x32_bf16 v[124:127], v[80:83], v[32:35], v[122:125]
	s_nop 0
	v_cndmask_b32_e64 v84, v206, v84, s[40:41]
	v_cmp_lt_f32_e64 s[40:41], |v93|, s95
	s_nop 1
	v_cndmask_b32_e64 v148, v84, v93, s[40:41]
	v_mfma_f32_16x16x32_bf16 v[84:87], v[68:71], v[16:19], 0
	v_mfma_f32_16x16x32_bf16 v[84:87], v[76:79], v[32:35], v[84:87]
	s_nop 7
	v_add_f32_e32 v84, v40, v84
	v_mul_f32_e32 v84, 0xbfb8aa3b, v84
	v_exp_f32_e32 v84, v84
	v_add_f32_e32 v85, v41, v85
	v_mul_f32_e32 v85, 0xbfb8aa3b, v85
	v_exp_f32_e32 v85, v85
	v_add_f32_e32 v84, 1.0, v84
	v_rcp_f32_e32 v93, v84
	v_add_f32_e32 v84, v36, v124
	v_add_f32_e32 v85, 1.0, v85
	v_mul_f32_e32 v84, 0xbfb8aa3b, v84
	v_mul_f32_e32 v93, 0xc1000000, v93
	v_mul_f32_e32 v93, v147, v93
	v_mul_f32_e32 v93, 0x3fb8aa3b, v93
	v_exp_f32_e32 v94, v93
	v_exp_f32_e32 v84, v84
	v_mov_b32_e32 v124, 1.0
	v_add_f32_e32 v86, v42, v86
	v_fma_f32 v93, -v94, v94, 1.0
	v_sqrt_f32_e32 v122, v93
	v_rcp_f32_e32 v93, v85
	v_add_f32_e32 v85, v37, v125
	v_mul_f32_e32 v85, 0xbfb8aa3b, v85
	v_exp_f32_e32 v85, v85
	v_mul_f32_e32 v93, 0xc1000000, v93
	v_mul_f32_e32 v93, v149, v93
	v_mul_f32_e32 v93, 0x3fb8aa3b, v93
	v_exp_f32_e32 v95, v93
	v_add_f32_e32 v84, 1.0, v84
	v_add_f32_e32 v85, 1.0, v85
	v_rcp_f32_e32 v84, v84
	v_fma_f32 v93, -v95, v95, 1.0
	v_sqrt_f32_e32 v123, v93
	ds_read2_b32 v[92:93], v145 offset0:16 offset1:17
	v_rcp_f32_e32 v85, v85
	v_mov_b32_e32 v125, 1.0
	v_mov_b32_dpp v124, v94 row_shr:1 row_mask:0xf bank_mask:0xf
	v_mul_f32_e32 v86, 0xbfb8aa3b, v86
	s_waitcnt lgkmcnt(0)
	v_pk_mul_f32 v[84:85], v[92:93], v[84:85]
	v_mov_b32_dpp v125, v95 row_shr:1 row_mask:0xf bank_mask:0xf
	v_pk_mul_f32 v[84:85], v[84:85], v[122:123]
	v_pk_mul_f32 v[124:125], v[94:95], v[124:125]
	v_exp_f32_e32 v86, v86
	v_mov_b32_dpp v92, v84 row_shr:1 row_mask:0xf bank_mask:0xf bound_ctrl:1
	v_mov_b32_dpp v93, v85 row_shr:1 row_mask:0xf bank_mask:0xf bound_ctrl:1
	v_pk_fma_f32 v[84:85], v[94:95], v[92:93], v[84:85]
	v_mov_b32_dpp v128, v124 row_shr:2 row_mask:0xf bank_mask:0xf
	v_mov_b32_dpp v129, v125 row_shr:2 row_mask:0xf bank_mask:0xf
	v_mov_b32_dpp v92, v84 row_shr:2 row_mask:0xf bank_mask:0xf bound_ctrl:1
	v_mov_b32_dpp v93, v85 row_shr:2 row_mask:0xf bank_mask:0xf bound_ctrl:1
	v_pk_fma_f32 v[84:85], v[124:125], v[92:93], v[84:85]
	v_pk_mul_f32 v[128:129], v[124:125], v[128:129]
	v_add_f32_e32 v86, 1.0, v86
	v_mov_b32_dpp v92, v84 row_shr:4 row_mask:0xf bank_mask:0xf bound_ctrl:1
	v_mov_b32_dpp v93, v85 row_shr:4 row_mask:0xf bank_mask:0xf bound_ctrl:1
	v_mov_b32_dpp v130, v128 row_shr:4 row_mask:0xf bank_mask:0xf
	v_mov_b32_dpp v131, v129 row_shr:4 row_mask:0xf bank_mask:0xf
	v_pk_fma_f32 v[84:85], v[128:129], v[92:93], v[84:85]
	v_pk_mul_f32 v[130:131], v[128:129], v[130:131]
	v_add_f32_e32 v87, v43, v87
	v_mov_b32_dpp v92, v84 row_shr:8 row_mask:0xf bank_mask:0xf bound_ctrl:1
	v_mov_b32_dpp v93, v85 row_shr:8 row_mask:0xf bank_mask:0xf bound_ctrl:1
	v_pk_fma_f32 v[84:85], v[130:131], v[92:93], v[84:85]
	v_rcp_f32_e32 v92, v86
	v_mul_f32_e32 v87, 0xbfb8aa3b, v87
	v_exp_f32_e32 v87, v87
	v_add_f32_e32 v86, v38, v126
	v_mul_f32_e32 v92, 0xc1000000, v92
	v_mul_f32_e32 v92, v2, v92
	v_mul_f32_e32 v92, 0x3fb8aa3b, v92
	v_exp_f32_e32 v92, v92
	v_add_f32_e32 v87, 1.0, v87
	v_mul_f32_e32 v86, 0xbfb8aa3b, v86
	v_exp_f32_e32 v86, v86
	v_fma_f32 v93, -v92, v92, 1.0
	v_sqrt_f32_e32 v94, v93
	v_rcp_f32_e32 v93, v87
	v_add_f32_e32 v87, v39, v127
	v_mul_f32_e32 v87, 0xbfb8aa3b, v87
	v_exp_f32_e32 v87, v87
	v_mul_f32_e32 v93, 0xc1000000, v93
	v_mul_f32_e32 v93, v148, v93
	v_mul_f32_e32 v93, 0x3fb8aa3b, v93
	v_exp_f32_e32 v93, v93
	v_add_f32_e32 v86, 1.0, v86
	v_add_f32_e32 v87, 1.0, v87
	v_rcp_f32_e32 v86, v86
	v_rcp_f32_e32 v87, v87
	v_fma_f32 v95, -v93, v93, 1.0
	v_sqrt_f32_e32 v95, v95
	v_mov_b32_e32 v122, 1.0
	v_pk_mul_f32 v[86:87], v[86:87], v[136:137]
	v_mov_b32_e32 v123, 1.0
	v_pk_mul_f32 v[86:87], v[94:95], v[86:87]
	v_mov_b32_dpp v122, v92 row_shr:1 row_mask:0xf bank_mask:0xf
	v_mov_b32_dpp v123, v93 row_shr:1 row_mask:0xf bank_mask:0xf
	v_mov_b32_dpp v94, v86 row_shr:1 row_mask:0xf bank_mask:0xf bound_ctrl:1
	v_mov_b32_dpp v95, v87 row_shr:1 row_mask:0xf bank_mask:0xf bound_ctrl:1
	v_pk_mul_f32 v[122:123], v[92:93], v[122:123]
	v_mov_b32_e32 v126, 1.0
; __device__ __forceinline__ unsigned pk2(float lo, float hi) { const f32x2_t v = {lo, hi}; const bf16x2_t b = __builtin_convertvector(v, bf16x2_t); return __builtin_bit_cast(unsigned, b); }
; __device__ __forceinline__ float sigmoidf_(float x) { return __builtin_amdgcn_rcpf(1.0f + __expf(-x)); }
; __device__ __forceinline__ float bcast15(float v, int lane) { return bperm_f((lane & 48) | 15, v); }
; __device__ __forceinline__ void w_lru_m1(const Args& a, int l, unsigned char* ws, const bf16_t* proj, bf16_t* y, LAS unsigned char* wl, int b, int ck_, int h, int lane) {
;     ...
;         for (int tb = 0; tb < 4; ++tb) { const int tok = 16 * tb + lo;
;             f32x4 ga = {0.f, 0.f, 0.f, 0.f}, gx = {0.f, 0.f, 0.f, 0.f};
; #pragma unroll
;             for (int kk = 0; kk < 2; ++kk) { ga = __builtin_amdgcn_mfma_f32_16x16x32_bf16(WaF[kk], Xf[tb][kk], ga, 0, 0, 0); gx = __builtin_amdgcn_mfma_f32_16x16x32_bf16(WxF[kk], Xf[tb][kk], gx, 0, 0, 0); }
;             float hv[4], pv[4];
; #pragma unroll
;             for (int r = 0; r < 4; ++r) {
;                 const float rg = sigmoidf_(ga[r] + bav[r]), ig = sigmoidf_(gx[r] + bxv[r]);
;                 const float la = -8.0f * rg * sp[r]; float A = __expf(la);
;                 float U = __builtin_amdgcn_sqrtf(1.0f - A * A) * (ig * xcf[tok * 65 + j0 + r]);
;                 { const float As = dpp_shr1<1>(A), Us = dpp_shr0<1>(U); U = A * Us + U; A = A * As; }
;                 { const float As = dpp_shr1<2>(A), Us = dpp_shr0<2>(U); U = A * Us + U; A = A * As; }
;                 { const float As = dpp_shr1<4>(A), Us = dpp_shr0<4>(U); U = A * Us + U; A = A * As; }
;                 { const float As = dpp_shr1<8>(A), Us = dpp_shr0<8>(U); U = A * Us + U; A = A * As; }
;                 const float hh = U + A * hc[r], PP = A * Pc[r];
;                 hc[r] = bcast15(hh, lane); Pc[r] = bcast15(PP, lane); hv[r] = hh; pv[r] = PP; }
;             *(unsigned long long*)(y + (size_t)(row0 + tok) * DM + 64 * h + j0) = (unsigned long long)pk2(hv[0], hv[1]) | ((unsigned long long)pk2(hv[2], hv[3]) << 32);
;             *(unsigned long long*)((bf16_t*)(ws + WS_P) + (size_t)(row0 + tok) * 512 + 64 * h + j0) = (unsigned long long)pk2(pv[0], pv[1]) | ((unsigned long long)pk2(pv[2], pv[3]) << 32);
	v_mov_b32_e32 v127, 1.0
	v_pk_fma_f32 v[86:87], v[92:93], v[94:95], v[86:87]
	v_mov_b32_dpp v126, v122 row_shr:2 row_mask:0xf bank_mask:0xf
	v_mov_b32_dpp v127, v123 row_shr:2 row_mask:0xf bank_mask:0xf
	v_mov_b32_dpp v92, v86 row_shr:2 row_mask:0xf bank_mask:0xf bound_ctrl:1
	v_mov_b32_dpp v93, v87 row_shr:2 row_mask:0xf bank_mask:0xf bound_ctrl:1
	v_pk_mul_f32 v[126:127], v[122:123], v[126:127]
	v_mov_b32_e32 v128, 1.0
	v_mov_b32_e32 v129, 1.0
	v_pk_fma_f32 v[86:87], v[122:123], v[92:93], v[86:87]
	v_mov_b32_dpp v132, v130 row_shr:8 row_mask:0xf bank_mask:0xf
	v_mov_b32_dpp v133, v131 row_shr:8 row_mask:0xf bank_mask:0xf
	v_mov_b32_dpp v128, v126 row_shr:4 row_mask:0xf bank_mask:0xf
	v_mov_b32_dpp v129, v127 row_shr:4 row_mask:0xf bank_mask:0xf
	v_mov_b32_dpp v92, v86 row_shr:4 row_mask:0xf bank_mask:0xf bound_ctrl:1
	v_mov_b32_dpp v93, v87 row_shr:4 row_mask:0xf bank_mask:0xf bound_ctrl:1
	v_pk_mul_f32 v[134:135], v[130:131], v[132:133]
	v_pk_mul_f32 v[128:129], v[126:127], v[128:129]
	v_mov_b32_e32 v130, 1.0
	v_mov_b32_e32 v131, 1.0
	v_pk_fma_f32 v[86:87], v[126:127], v[92:93], v[86:87]
	v_mov_b32_dpp v130, v128 row_shr:8 row_mask:0xf bank_mask:0xf
	v_mov_b32_dpp v131, v129 row_shr:8 row_mask:0xf bank_mask:0xf
	v_mov_b32_dpp v92, v86 row_shr:8 row_mask:0xf bank_mask:0xf bound_ctrl:1
	v_mov_b32_dpp v93, v87 row_shr:8 row_mask:0xf bank_mask:0xf bound_ctrl:1
	v_pk_mul_f32 v[130:131], v[128:129], v[130:131]
	v_pk_fma_f32 v[86:87], v[128:129], v[92:93], v[86:87]
	v_pk_fma_f32 v[84:85], v[134:135], 0, v[84:85] op_sel_hi:[1,0,1]
	v_pk_fma_f32 v[86:87], v[130:131], 0, v[86:87] op_sel_hi:[1,0,1]
	ds_bpermute_b32 v124, v1, v84
	ds_bpermute_b32 v125, v1, v85
	v_cvt_pk_bf16_f32 v84, v84, v85
	v_cvt_pk_bf16_f32 v85, v86, v87
	global_store_dwordx2 v[100:101], v[84:85], off offset:32
	v_cvt_pk_bf16_f32 v84, v134, v135
	v_cvt_pk_bf16_f32 v85, v130, v131
	ds_bpermute_b32 v122, v1, v86
	ds_bpermute_b32 v123, v1, v87
	global_store_dwordx2 v[102:103], v[84:85], off offset:32
	v_mfma_f32_16x16x32_bf16 v[84:87], v[68:71], v[12:15], 0
	ds_bpermute_b32 v132, v1, v130
	ds_bpermute_b32 v133, v1, v131
	ds_bpermute_b32 v150, v1, v134
	v_mfma_f32_16x16x32_bf16 v[126:129], v[72:75], v[12:15], 0
	ds_bpermute_b32 v151, v1, v135
	v_mfma_f32_16x16x32_bf16 v[92:95], v[76:79], v[28:31], v[84:87]
	v_mfma_f32_16x16x32_bf16 v[84:87], v[80:83], v[28:31], v[126:129]
	s_nop 6
	v_add_f32_e32 v92, v40, v92
	v_mul_f32_e32 v92, 0xbfb8aa3b, v92
	v_exp_f32_e32 v92, v92
	v_add_f32_e32 v84, v36, v84
	v_mul_f32_e32 v84, 0xbfb8aa3b, v84
	v_exp_f32_e32 v84, v84
	v_add_f32_e32 v92, 1.0, v92
	v_rcp_f32_e32 v92, v92
	v_add_f32_e32 v85, v37, v85
	v_add_f32_e32 v84, 1.0, v84
	v_rcp_f32_e32 v126, v84
	v_mul_f32_e32 v84, 0xc1000000, v92
	v_add_f32_e32 v92, v41, v93
	v_mul_f32_e32 v92, 0xbfb8aa3b, v92
	v_exp_f32_e32 v92, v92
	v_mul_f32_e32 v85, 0xbfb8aa3b, v85
	v_exp_f32_e32 v85, v85
	v_mul_f32_e32 v84, v147, v84
	v_add_f32_e32 v92, 1.0, v92
	v_rcp_f32_e32 v92, v92
	v_add_f32_e32 v85, 1.0, v85
	v_rcp_f32_e32 v127, v85
	v_mul_f32_e32 v84, 0x3fb8aa3b, v84
	v_mul_f32_e32 v85, 0xc1000000, v92
	v_mul_f32_e32 v85, v149, v85
	v_mul_f32_e32 v85, 0x3fb8aa3b, v85
	v_exp_f32_e32 v128, v84
	v_exp_f32_e32 v129, v85
	v_add_f32_e32 v94, v42, v94
	v_add_f32_e32 v95, v43, v95
	v_fma_f32 v84, -v128, v128, 1.0
	v_fma_f32 v85, -v129, v129, 1.0
	v_sqrt_f32_e32 v130, v84
	v_mov_b32_e32 v84, 1.0
	v_sqrt_f32_e32 v131, v85
	v_mov_b32_e32 v85, 1.0
	v_mov_b32_dpp v84, v128 row_shr:1 row_mask:0xf bank_mask:0xf
	v_mul_f32_e32 v94, 0xbfb8aa3b, v94
	v_mov_b32_dpp v85, v129 row_shr:1 row_mask:0xf bank_mask:0xf
	v_pk_mul_f32 v[134:135], v[128:129], v[84:85]
	v_mov_b32_e32 v84, 1.0
	v_mov_b32_e32 v85, 1.0
	v_mul_f32_e32 v95, 0xbfb8aa3b, v95
	v_mov_b32_dpp v84, v134 row_shr:2 row_mask:0xf bank_mask:0xf
	v_mov_b32_dpp v85, v135 row_shr:2 row_mask:0xf bank_mask:0xf
	v_pk_mul_f32 v[136:137], v[134:135], v[84:85]
	v_mov_b32_e32 v84, 1.0
	v_mov_b32_e32 v85, 1.0
	v_exp_f32_e32 v94, v94
	v_mov_b32_dpp v84, v136 row_shr:4 row_mask:0xf bank_mask:0xf
	v_mov_b32_dpp v85, v137 row_shr:4 row_mask:0xf bank_mask:0xf
	v_pk_mul_f32 v[138:139], v[136:137], v[84:85]
	v_mov_b32_e32 v84, 1.0
	v_mov_b32_e32 v85, 1.0
	v_exp_f32_e32 v95, v95
	v_mov_b32_dpp v84, v138 row_shr:8 row_mask:0xf bank_mask:0xf
	v_mov_b32_dpp v85, v139 row_shr:8 row_mask:0xf bank_mask:0xf
	v_pk_mul_f32 v[140:141], v[138:139], v[84:85]
	v_add_u32_e32 v85, 0x1080, v145
	ds_read2_b32 v[142:143], v85 offset1:1
	v_add_f32_e32 v86, v38, v86
	v_add_f32_e32 v87, v39, v87
	v_mul_f32_e32 v86, 0xbfb8aa3b, v86
	v_mul_f32_e32 v87, 0xbfb8aa3b, v87
	s_waitcnt lgkmcnt(0)
; __device__ __forceinline__ unsigned pk2(float lo, float hi) { const f32x2_t v = {lo, hi}; const bf16x2_t b = __builtin_convertvector(v, bf16x2_t); return __builtin_bit_cast(unsigned, b); }
; __device__ __forceinline__ float sigmoidf_(float x) { return __builtin_amdgcn_rcpf(1.0f + __expf(-x)); }
; __device__ __forceinline__ float bcast15(float v, int lane) { return bperm_f((lane & 48) | 15, v); }
; __device__ __forceinline__ void w_lru_m1(const Args& a, int l, unsigned char* ws, const bf16_t* proj, bf16_t* y, LAS unsigned char* wl, int b, int ck_, int h, int lane) {
;     ...
;         for (int tb = 0; tb < 4; ++tb) { const int tok = 16 * tb + lo;
;             f32x4 ga = {0.f, 0.f, 0.f, 0.f}, gx = {0.f, 0.f, 0.f, 0.f};
; #pragma unroll
;             for (int kk = 0; kk < 2; ++kk) { ga = __builtin_amdgcn_mfma_f32_16x16x32_bf16(WaF[kk], Xf[tb][kk], ga, 0, 0, 0); gx = __builtin_amdgcn_mfma_f32_16x16x32_bf16(WxF[kk], Xf[tb][kk], gx, 0, 0, 0); }
;             float hv[4], pv[4];
; #pragma unroll
;             for (int r = 0; r < 4; ++r) {
;                 const float rg = sigmoidf_(ga[r] + bav[r]), ig = sigmoidf_(gx[r] + bxv[r]);
;                 const float la = -8.0f * rg * sp[r]; float A = __expf(la);
;                 float U = __builtin_amdgcn_sqrtf(1.0f - A * A) * (ig * xcf[tok * 65 + j0 + r]);
;                 { const float As = dpp_shr1<1>(A), Us = dpp_shr0<1>(U); U = A * Us + U; A = A * As; }
;                 { const float As = dpp_shr1<2>(A), Us = dpp_shr0<2>(U); U = A * Us + U; A = A * As; }
;                 { const float As = dpp_shr1<4>(A), Us = dpp_shr0<4>(U); U = A * Us + U; A = A * As; }
;                 { const float As = dpp_shr1<8>(A), Us = dpp_shr0<8>(U); U = A * Us + U; A = A * As; }
;                 const float hh = U + A * hc[r], PP = A * Pc[r];
;                 hc[r] = bcast15(hh, lane); Pc[r] = bcast15(PP, lane); hv[r] = hh; pv[r] = PP; }
;             *(unsigned long long*)(y + (size_t)(row0 + tok) * DM + 64 * h + j0) = (unsigned long long)pk2(hv[0], hv[1]) | ((unsigned long long)pk2(hv[2], hv[3]) << 32);
;             *(unsigned long long*)((bf16_t*)(ws + WS_P) + (size_t)(row0 + tok) * 512 + 64 * h + j0) = (unsigned long long)pk2(pv[0], pv[1]) | ((unsigned long long)pk2(pv[2], pv[3]) << 32);
	v_pk_mul_f32 v[126:127], v[142:143], v[126:127]
	v_add_f32_e32 v94, 1.0, v94
	v_pk_mul_f32 v[126:127], v[126:127], v[130:131]
	v_exp_f32_e32 v86, v86
	v_add_f32_e32 v95, 1.0, v95
	v_mov_b32_dpp v130, v126 row_shr:1 row_mask:0xf bank_mask:0xf bound_ctrl:1
	v_mov_b32_dpp v131, v127 row_shr:1 row_mask:0xf bank_mask:0xf bound_ctrl:1
	v_pk_fma_f32 v[126:127], v[128:129], v[130:131], v[126:127]
	v_exp_f32_e32 v87, v87
	v_rcp_f32_e32 v94, v94
	v_mov_b32_dpp v128, v126 row_shr:2 row_mask:0xf bank_mask:0xf bound_ctrl:1
	v_mov_b32_dpp v129, v127 row_shr:2 row_mask:0xf bank_mask:0xf bound_ctrl:1
	v_pk_fma_f32 v[126:127], v[134:135], v[128:129], v[126:127]
	v_rcp_f32_e32 v95, v95
	v_add_f32_e32 v86, 1.0, v86
	v_mov_b32_dpp v128, v126 row_shr:4 row_mask:0xf bank_mask:0xf bound_ctrl:1
	v_mov_b32_dpp v129, v127 row_shr:4 row_mask:0xf bank_mask:0xf bound_ctrl:1
	v_pk_fma_f32 v[126:127], v[136:137], v[128:129], v[126:127]
	v_add_f32_e32 v87, 1.0, v87
	v_pk_mul_f32 v[92:93], v[140:141], v[150:151]
	v_mov_b32_dpp v128, v126 row_shr:8 row_mask:0xf bank_mask:0xf bound_ctrl:1
	v_mov_b32_dpp v129, v127 row_shr:8 row_mask:0xf bank_mask:0xf bound_ctrl:1
	v_pk_fma_f32 v[126:127], v[138:139], v[128:129], v[126:127]
	v_rcp_f32_e32 v128, v86
	v_mul_f32_e32 v86, 0xc1000000, v94
	v_rcp_f32_e32 v129, v87
	v_mul_f32_e32 v87, 0xc1000000, v95
	v_mul_f32_e32 v86, v2, v86
	v_mul_f32_e32 v87, v148, v87
	v_mul_f32_e32 v86, 0x3fb8aa3b, v86
	v_mul_f32_e32 v87, 0x3fb8aa3b, v87
	v_exp_f32_e32 v94, v86
	v_exp_f32_e32 v95, v87
	v_pk_fma_f32 v[126:127], v[140:141], v[124:125], v[126:127]
	ds_bpermute_b32 v84, v1, v92
	v_fma_f32 v86, -v94, v94, 1.0
	v_fma_f32 v87, -v95, v95, 1.0
	v_sqrt_f32_e32 v130, v86
	v_mov_b32_e32 v86, 1.0
	v_sqrt_f32_e32 v131, v87
	v_mov_b32_e32 v87, 1.0
	v_mov_b32_dpp v86, v94 row_shr:1 row_mask:0xf bank_mask:0xf
	ds_bpermute_b32 v124, v1, v126
	v_mov_b32_dpp v87, v95 row_shr:1 row_mask:0xf bank_mask:0xf
	v_pk_mul_f32 v[134:135], v[94:95], v[86:87]
	v_mov_b32_e32 v86, 1.0
	v_mov_b32_e32 v87, 1.0
	ds_bpermute_b32 v125, v1, v127
	v_mov_b32_dpp v86, v134 row_shr:2 row_mask:0xf bank_mask:0xf
	v_mov_b32_dpp v87, v135 row_shr:2 row_mask:0xf bank_mask:0xf
	v_pk_mul_f32 v[136:137], v[134:135], v[86:87]
	v_mov_b32_e32 v86, 1.0
	v_mov_b32_e32 v87, 1.0
	ds_bpermute_b32 v85, v1, v93
	v_mov_b32_dpp v86, v136 row_shr:4 row_mask:0xf bank_mask:0xf
	v_mov_b32_dpp v87, v137 row_shr:4 row_mask:0xf bank_mask:0xf
	v_pk_mul_f32 v[138:139], v[136:137], v[86:87]
	v_mov_b32_e32 v86, 1.0
	v_mov_b32_e32 v87, 1.0
	v_cvt_pk_bf16_f32 v126, v126, v127
	v_mov_b32_dpp v86, v138 row_shr:8 row_mask:0xf bank_mask:0xf
	v_mov_b32_dpp v87, v139 row_shr:8 row_mask:0xf bank_mask:0xf
	v_pk_mul_f32 v[140:141], v[138:139], v[86:87]
	v_add_u32_e32 v87, 0x1088, v145
	ds_read2_b32 v[142:143], v87 offset1:1
	v_pk_mul_f32 v[132:133], v[140:141], v[132:133]
	v_cvt_pk_bf16_f32 v92, v92, v93
	v_cvt_pk_bf16_f32 v93, v132, v133
	ds_bpermute_b32 v86, v1, v132
	s_waitcnt lgkmcnt(0)
	v_pk_mul_f32 v[128:129], v[128:129], v[142:143]
	ds_bpermute_b32 v87, v1, v133
	v_pk_mul_f32 v[128:129], v[130:131], v[128:129]
	s_nop 1
	v_mov_b32_dpp v130, v128 row_shr:1 row_mask:0xf bank_mask:0xf bound_ctrl:1
	v_mov_b32_dpp v131, v129 row_shr:1 row_mask:0xf bank_mask:0xf bound_ctrl:1
	v_pk_fma_f32 v[94:95], v[94:95], v[130:131], v[128:129]
	s_nop 1
	v_mov_b32_dpp v128, v94 row_shr:2 row_mask:0xf bank_mask:0xf bound_ctrl:1
	v_mov_b32_dpp v129, v95 row_shr:2 row_mask:0xf bank_mask:0xf bound_ctrl:1
	v_pk_fma_f32 v[94:95], v[134:135], v[128:129], v[94:95]
	s_nop 1
	v_mov_b32_dpp v128, v94 row_shr:4 row_mask:0xf bank_mask:0xf bound_ctrl:1
	v_mov_b32_dpp v129, v95 row_shr:4 row_mask:0xf bank_mask:0xf bound_ctrl:1
	v_pk_fma_f32 v[94:95], v[136:137], v[128:129], v[94:95]
	s_nop 1
	v_mov_b32_dpp v128, v94 row_shr:8 row_mask:0xf bank_mask:0xf bound_ctrl:1
	v_mov_b32_dpp v129, v95 row_shr:8 row_mask:0xf bank_mask:0xf bound_ctrl:1
	v_pk_fma_f32 v[94:95], v[138:139], v[128:129], v[94:95]
	s_nop 0
	v_pk_fma_f32 v[94:95], v[140:141], v[122:123], v[94:95]
	ds_bpermute_b32 v122, v1, v94
	v_cvt_pk_bf16_f32 v127, v94, v95
	ds_bpermute_b32 v123, v1, v95
	global_store_dwordx2 v[104:105], v[126:127], off offset:32
	global_store_dwordx2 v[106:107], v[92:93], off offset:32
	v_mfma_f32_16x16x32_bf16 v[92:95], v[68:71], v[8:11], 0
	v_mfma_f32_16x16x32_bf16 v[130:133], v[76:79], v[24:27], v[92:95]
	v_mfma_f32_16x16x32_bf16 v[126:129], v[72:75], v[8:11], 0
	v_mfma_f32_16x16x32_bf16 v[134:137], v[80:83], v[24:27], v[126:129]
	s_nop 5
	v_add_f32_e32 v92, v40, v130
	v_mul_f32_e32 v92, 0xbfb8aa3b, v92
	v_exp_f32_e32 v92, v92
	v_mov_b32_e32 v126, 1.0
	v_mfma_f32_16x16x32_bf16 v[68:71], v[68:71], v[4:7], 0
	v_add_f32_e32 v92, 1.0, v92
	v_rcp_f32_e32 v93, v92
	v_add_f32_e32 v92, v36, v134
	v_mul_f32_e32 v92, 0xbfb8aa3b, v92
	v_exp_f32_e32 v92, v92
	v_mul_f32_e32 v93, 0xc1000000, v93
	v_mul_f32_e32 v93, v147, v93
	v_mul_f32_e32 v93, 0x3fb8aa3b, v93
	v_exp_f32_e32 v94, v93
	v_add_f32_e32 v92, 1.0, v92
	v_rcp_f32_e32 v92, v92
	v_fma_f32 v93, -v94, v94, 1.0
	v_sqrt_f32_e32 v130, v93
	v_add_f32_e32 v93, v41, v131
	v_mul_f32_e32 v93, 0xbfb8aa3b, v93
	v_exp_f32_e32 v93, v93
	v_mov_b32_dpp v126, v94 row_shr:1 row_mask:0xf bank_mask:0xf
	v_add_f32_e32 v93, 1.0, v93
	v_rcp_f32_e32 v95, v93
	v_add_f32_e32 v93, v37, v135
	v_mul_f32_e32 v93, 0xbfb8aa3b, v93
	v_exp_f32_e32 v93, v93
	v_mul_f32_e32 v95, 0xc1000000, v95
	v_mul_f32_e32 v95, v149, v95
	v_mul_f32_e32 v95, 0x3fb8aa3b, v95
	v_exp_f32_e32 v95, v95
	v_add_f32_e32 v93, 1.0, v93
	v_rcp_f32_e32 v93, v93
	v_fma_f32 v127, -v95, v95, 1.0
	v_sqrt_f32_e32 v131, v127
	v_mov_b32_e32 v127, 1.0
	s_nop 1
	v_mov_b32_dpp v127, v95 row_shr:1 row_mask:0xf bank_mask:0xf
	v_pk_mul_f32 v[134:135], v[94:95], v[126:127]
	v_mov_b32_e32 v126, 1.0
	v_mov_b32_e32 v127, 1.0
	s_nop 0
	v_mov_b32_dpp v126, v134 row_shr:2 row_mask:0xf bank_mask:0xf
	v_mov_b32_dpp v127, v135 row_shr:2 row_mask:0xf bank_mask:0xf
	v_pk_mul_f32 v[138:139], v[134:135], v[126:127]
	v_mov_b32_e32 v126, 1.0
	v_mov_b32_e32 v127, 1.0
	s_nop 0
	v_mov_b32_dpp v126, v138 row_shr:4 row_mask:0xf bank_mask:0xf
	v_mov_b32_dpp v127, v139 row_shr:4 row_mask:0xf bank_mask:0xf
	v_pk_mul_f32 v[140:141], v[138:139], v[126:127]
	v_mov_b32_e32 v126, 1.0
	v_mov_b32_e32 v127, 1.0
	s_nop 0
	v_mov_b32_dpp v126, v140 row_shr:8 row_mask:0xf bank_mask:0xf
	v_mov_b32_dpp v127, v141 row_shr:8 row_mask:0xf bank_mask:0xf
	v_pk_mul_f32 v[142:143], v[140:141], v[126:127]
	s_nop 0
	v_pk_mul_f32 v[128:129], v[142:143], v[84:85]
	v_add_u32_e32 v84, 0x20c0, v145
	ds_read2_b32 v[84:85], v84 offset1:1
	ds_bpermute_b32 v126, v1, v128
	ds_bpermute_b32 v127, v1, v129
	s_waitcnt lgkmcnt(0)
; __device__ __forceinline__ unsigned pk2(float lo, float hi) { const f32x2_t v = {lo, hi}; const bf16x2_t b = __builtin_convertvector(v, bf16x2_t); return __builtin_bit_cast(unsigned, b); }
; __device__ __forceinline__ float sigmoidf_(float x) { return __builtin_amdgcn_rcpf(1.0f + __expf(-x)); }
; __device__ __forceinline__ float bcast15(float v, int lane) { return bperm_f((lane & 48) | 15, v); }
; __device__ __forceinline__ void w_lru_m1(const Args& a, int l, unsigned char* ws, const bf16_t* proj, bf16_t* y, LAS unsigned char* wl, int b, int ck_, int h, int lane) {
;     ...
;         for (int tb = 0; tb < 4; ++tb) { const int tok = 16 * tb + lo;
;             f32x4 ga = {0.f, 0.f, 0.f, 0.f}, gx = {0.f, 0.f, 0.f, 0.f};
; #pragma unroll
;             for (int kk = 0; kk < 2; ++kk) { ga = __builtin_amdgcn_mfma_f32_16x16x32_bf16(WaF[kk], Xf[tb][kk], ga, 0, 0, 0); gx = __builtin_amdgcn_mfma_f32_16x16x32_bf16(WxF[kk], Xf[tb][kk], gx, 0, 0, 0); }
;             float hv[4], pv[4];
; #pragma unroll
;             for (int r = 0; r < 4; ++r) {
;                 const float rg = sigmoidf_(ga[r] + bav[r]), ig = sigmoidf_(gx[r] + bxv[r]);
;                 const float la = -8.0f * rg * sp[r]; float A = __expf(la);
;                 float U = __builtin_amdgcn_sqrtf(1.0f - A * A) * (ig * xcf[tok * 65 + j0 + r]);
;                 { const float As = dpp_shr1<1>(A), Us = dpp_shr0<1>(U); U = A * Us + U; A = A * As; }
;                 { const float As = dpp_shr1<2>(A), Us = dpp_shr0<2>(U); U = A * Us + U; A = A * As; }
;                 { const float As = dpp_shr1<4>(A), Us = dpp_shr0<4>(U); U = A * Us + U; A = A * As; }
;                 { const float As = dpp_shr1<8>(A), Us = dpp_shr0<8>(U); U = A * Us + U; A = A * As; }
;                 const float hh = U + A * hc[r], PP = A * Pc[r];
;                 hc[r] = bcast15(hh, lane); Pc[r] = bcast15(PP, lane); hv[r] = hh; pv[r] = PP; }
;             *(unsigned long long*)(y + (size_t)(row0 + tok) * DM + 64 * h + j0) = (unsigned long long)pk2(hv[0], hv[1]) | ((unsigned long long)pk2(hv[2], hv[3]) << 32);
	v_pk_mul_f32 v[84:85], v[84:85], v[92:93]
	s_nop 0
	v_pk_mul_f32 v[84:85], v[84:85], v[130:131]
	s_nop 1
	v_mov_b32_dpp v92, v84 row_shr:1 row_mask:0xf bank_mask:0xf bound_ctrl:1
	v_mov_b32_dpp v93, v85 row_shr:1 row_mask:0xf bank_mask:0xf bound_ctrl:1
	v_pk_fma_f32 v[84:85], v[94:95], v[92:93], v[84:85]
	s_nop 1
	v_mov_b32_dpp v92, v84 row_shr:2 row_mask:0xf bank_mask:0xf bound_ctrl:1
	v_mov_b32_dpp v93, v85 row_shr:2 row_mask:0xf bank_mask:0xf bound_ctrl:1
	v_pk_fma_f32 v[84:85], v[134:135], v[92:93], v[84:85]
	s_nop 1
	v_mov_b32_dpp v92, v84 row_shr:4 row_mask:0xf bank_mask:0xf bound_ctrl:1
	v_mov_b32_dpp v93, v85 row_shr:4 row_mask:0xf bank_mask:0xf bound_ctrl:1
	v_pk_fma_f32 v[84:85], v[138:139], v[92:93], v[84:85]
	s_nop 1
	v_mov_b32_dpp v92, v84 row_shr:8 row_mask:0xf bank_mask:0xf bound_ctrl:1
	v_mov_b32_dpp v93, v85 row_shr:8 row_mask:0xf bank_mask:0xf bound_ctrl:1
	v_pk_fma_f32 v[84:85], v[140:141], v[92:93], v[84:85]
	v_mov_b32_e32 v92, 1.0
	v_pk_fma_f32 v[124:125], v[142:143], v[124:125], v[84:85]
	v_add_f32_e32 v84, v42, v132
	v_mul_f32_e32 v84, 0xbfb8aa3b, v84
	v_exp_f32_e32 v84, v84
	ds_bpermute_b32 v94, v1, v124
	ds_bpermute_b32 v95, v1, v125
	v_cvt_pk_bf16_f32 v124, v124, v125
	v_add_f32_e32 v84, 1.0, v84
	v_rcp_f32_e32 v85, v84
	v_add_f32_e32 v84, v38, v136
	v_mul_f32_e32 v84, 0xbfb8aa3b, v84
	v_exp_f32_e32 v84, v84
	v_mul_f32_e32 v85, 0xc1000000, v85
	v_mul_f32_e32 v85, v2, v85
	v_mul_f32_e32 v85, 0x3fb8aa3b, v85
	v_exp_f32_e32 v130, v85
	v_add_f32_e32 v84, 1.0, v84
	v_rcp_f32_e32 v84, v84
	v_fma_f32 v85, -v130, v130, 1.0
	v_sqrt_f32_e32 v132, v85
	v_add_f32_e32 v85, v43, v133
	v_mul_f32_e32 v85, 0xbfb8aa3b, v85
	v_exp_f32_e32 v85, v85
	v_mov_b32_dpp v92, v130 row_shr:1 row_mask:0xf bank_mask:0xf
	v_add_f32_e32 v85, 1.0, v85
	v_rcp_f32_e32 v93, v85
	v_add_f32_e32 v85, v39, v137
	v_mul_f32_e32 v85, 0xbfb8aa3b, v85
	v_exp_f32_e32 v85, v85
	v_mul_f32_e32 v93, 0xc1000000, v93
	v_mul_f32_e32 v93, v148, v93
	v_mul_f32_e32 v93, 0x3fb8aa3b, v93
	v_exp_f32_e32 v131, v93
	v_add_f32_e32 v85, 1.0, v85
	v_rcp_f32_e32 v85, v85
	v_fma_f32 v93, -v131, v131, 1.0
	v_sqrt_f32_e32 v133, v93
	v_mov_b32_e32 v93, 1.0
	s_nop 1
	v_mov_b32_dpp v93, v131 row_shr:1 row_mask:0xf bank_mask:0xf
	v_pk_mul_f32 v[134:135], v[130:131], v[92:93]
	v_mov_b32_e32 v92, 1.0
	v_mov_b32_e32 v93, 1.0
	s_nop 0
	v_mov_b32_dpp v92, v134 row_shr:2 row_mask:0xf bank_mask:0xf
	v_mov_b32_dpp v93, v135 row_shr:2 row_mask:0xf bank_mask:0xf
	v_pk_mul_f32 v[136:137], v[134:135], v[92:93]
	v_mov_b32_e32 v92, 1.0
	v_mov_b32_e32 v93, 1.0
	s_nop 0
	v_mov_b32_dpp v92, v136 row_shr:4 row_mask:0xf bank_mask:0xf
	v_mov_b32_dpp v93, v137 row_shr:4 row_mask:0xf bank_mask:0xf
	v_pk_mul_f32 v[138:139], v[136:137], v[92:93]
	v_mov_b32_e32 v92, 1.0
	v_mov_b32_e32 v93, 1.0
	s_nop 0
	v_mov_b32_dpp v92, v138 row_shr:8 row_mask:0xf bank_mask:0xf
	v_mov_b32_dpp v93, v139 row_shr:8 row_mask:0xf bank_mask:0xf
	v_pk_mul_f32 v[140:141], v[138:139], v[92:93]
	v_add_u32_e32 v93, 0x20c8, v145
	ds_read2_b32 v[142:143], v93 offset1:1
	v_pk_mul_f32 v[86:87], v[140:141], v[86:87]
	ds_bpermute_b32 v92, v1, v86
	ds_bpermute_b32 v93, v1, v87
	s_waitcnt lgkmcnt(0)
	v_pk_mul_f32 v[84:85], v[84:85], v[142:143]
	s_nop 0
	v_pk_mul_f32 v[84:85], v[132:133], v[84:85]
	s_nop 1
	v_mov_b32_dpp v132, v84 row_shr:1 row_mask:0xf bank_mask:0xf bound_ctrl:1
	v_mov_b32_dpp v133, v85 row_shr:1 row_mask:0xf bank_mask:0xf bound_ctrl:1
	v_pk_fma_f32 v[84:85], v[130:131], v[132:133], v[84:85]
	s_nop 1
	v_mov_b32_dpp v130, v84 row_shr:2 row_mask:0xf bank_mask:0xf bound_ctrl:1
	v_mov_b32_dpp v131, v85 row_shr:2 row_mask:0xf bank_mask:0xf bound_ctrl:1
	v_pk_fma_f32 v[84:85], v[134:135], v[130:131], v[84:85]
	s_nop 1
	v_mov_b32_dpp v130, v84 row_shr:4 row_mask:0xf bank_mask:0xf bound_ctrl:1
	v_mov_b32_dpp v131, v85 row_shr:4 row_mask:0xf bank_mask:0xf bound_ctrl:1
	v_pk_fma_f32 v[84:85], v[136:137], v[130:131], v[84:85]
	s_nop 1
	v_mov_b32_dpp v130, v84 row_shr:8 row_mask:0xf bank_mask:0xf bound_ctrl:1
	v_mov_b32_dpp v131, v85 row_shr:8 row_mask:0xf bank_mask:0xf bound_ctrl:1
	v_pk_fma_f32 v[84:85], v[138:139], v[130:131], v[84:85]
	s_nop 0
	v_pk_fma_f32 v[122:123], v[140:141], v[122:123], v[84:85]
	ds_bpermute_b32 v84, v1, v122
	ds_bpermute_b32 v85, v1, v123
	v_cvt_pk_bf16_f32 v125, v122, v123
	v_cvt_pk_bf16_f32 v122, v128, v129
	v_cvt_pk_bf16_f32 v123, v86, v87
	global_store_dwordx2 v[96:97], v[124:125], off offset:32
	global_store_dwordx2 v[98:99], v[122:123], off offset:32
	v_mfma_f32_16x16x32_bf16 v[122:125], v[72:75], v[4:7], 0
	v_mfma_f32_16x16x32_bf16 v[72:75], v[76:79], v[20:23], v[68:71]
	v_mfma_f32_16x16x32_bf16 v[68:71], v[80:83], v[20:23], v[122:125]
	s_nop 6
	v_add_f32_e32 v40, v40, v72
	v_add_f32_e32 v41, v41, v73
	v_add_f32_e32 v42, v42, v74
	v_mul_f32_e32 v40, 0xbfb8aa3b, v40
	v_mul_f32_e32 v41, 0xbfb8aa3b, v41
	v_mul_f32_e32 v42, 0xbfb8aa3b, v42
	v_exp_f32_e32 v40, v40
	v_exp_f32_e32 v41, v41
	v_exp_f32_e32 v42, v42
	v_add_f32_e32 v36, v36, v68
	v_add_f32_e32 v37, v37, v69
	v_add_f32_e32 v38, v38, v70
	v_mul_f32_e32 v36, 0xbfb8aa3b, v36
	v_mul_f32_e32 v37, 0xbfb8aa3b, v37
	v_mul_f32_e32 v38, 0xbfb8aa3b, v38
	v_add_f32_e32 v40, 1.0, v40
	v_exp_f32_e32 v36, v36
	v_add_f32_e32 v41, 1.0, v41
	v_exp_f32_e32 v37, v37
	v_add_f32_e32 v42, 1.0, v42
	v_exp_f32_e32 v38, v38
	v_rcp_f32_e32 v72, v40
	v_rcp_f32_e32 v68, v41
	v_rcp_f32_e32 v42, v42
	v_add_f32_e32 v36, 1.0, v36
	v_add_f32_e32 v37, 1.0, v37
	v_add_f32_e32 v38, 1.0, v38
	v_rcp_f32_e32 v40, v36
	v_mul_f32_e32 v36, 0xc1000000, v72
	v_rcp_f32_e32 v41, v37
	v_mul_f32_e32 v37, 0xc1000000, v68
	v_rcp_f32_e32 v70, v38
	v_mul_f32_e32 v38, 0xc1000000, v42
; __device__ __forceinline__ unsigned pk2(float lo, float hi) { const f32x2_t v = {lo, hi}; const bf16x2_t b = __builtin_convertvector(v, bf16x2_t); return __builtin_bit_cast(unsigned, b); }
; __device__ __forceinline__ float sigmoidf_(float x) { return __builtin_amdgcn_rcpf(1.0f + __expf(-x)); }
; __device__ __forceinline__ float bcast15(float v, int lane) { return bperm_f((lane & 48) | 15, v); }
; __device__ __forceinline__ void w_lru_m1(const Args& a, int l, unsigned char* ws, const bf16_t* proj, bf16_t* y, LAS unsigned char* wl, int b, int ck_, int h, int lane) {
;     ...
;             for (int r = 0; r < 4; ++r) {
;                 const float rg = sigmoidf_(ga[r] + bav[r]), ig = sigmoidf_(gx[r] + bxv[r]);
;                 const float la = -8.0f * rg * sp[r]; float A = __expf(la);
;                 float U = __builtin_amdgcn_sqrtf(1.0f - A * A) * (ig * xcf[tok * 65 + j0 + r]);
;                 { const float As = dpp_shr1<1>(A), Us = dpp_shr0<1>(U); U = A * Us + U; A = A * As; }
;                 { const float As = dpp_shr1<2>(A), Us = dpp_shr0<2>(U); U = A * Us + U; A = A * As; }
;                 { const float As = dpp_shr1<4>(A), Us = dpp_shr0<4>(U); U = A * Us + U; A = A * As; }
;                 { const float As = dpp_shr1<8>(A), Us = dpp_shr0<8>(U); U = A * Us + U; A = A * As; }
;                 const float hh = U + A * hc[r], PP = A * Pc[r];
;                 hc[r] = bcast15(hh, lane); Pc[r] = bcast15(PP, lane); hv[r] = hh; pv[r] = PP; }
;             *(unsigned long long*)(y + (size_t)(row0 + tok) * DM + 64 * h + j0) = (unsigned long long)pk2(hv[0], hv[1]) | ((unsigned long long)pk2(hv[2], hv[3]) << 32);
;             *(unsigned long long*)((bf16_t*)(ws + WS_P) + (size_t)(row0 + tok) * 512 + 64 * h + j0) = (unsigned long long)pk2(pv[0], pv[1]) | ((unsigned long long)pk2(pv[2], pv[3]) << 32);
;         }
;         if (lo == 0) { const size_t so = (size_t)(b * NCH + ck_) * 512 + 64 * h + j0;
; #pragma unroll
;             for (int r = 0; r < 4; ++r) { ((float*)(ws + WS_LRUA))[so + r] = Pc[r]; ((float*)(ws + WS_LRUH))[so + r] = hc[r]; } }
	v_mul_f32_e32 v36, v147, v36
	v_mul_f32_e32 v37, v149, v37
	v_mul_f32_e32 v2, v2, v38
	v_mul_f32_e32 v36, 0x3fb8aa3b, v36
	v_mul_f32_e32 v37, 0x3fb8aa3b, v37
	v_mul_f32_e32 v2, 0x3fb8aa3b, v2
	v_exp_f32_e32 v72, v36
	v_exp_f32_e32 v73, v37
	v_exp_f32_e32 v42, v2
	v_add_f32_e32 v39, v39, v71
	v_fma_f32 v36, -v72, v72, 1.0
	v_fma_f32 v37, -v73, v73, 1.0
	v_fma_f32 v2, -v42, v42, 1.0
	v_sqrt_f32_e32 v76, v36
	v_mov_b32_e32 v36, 1.0
	v_sqrt_f32_e32 v77, v37
	v_mov_b32_e32 v37, 1.0
	v_sqrt_f32_e32 v74, v2
	v_add_f32_e32 v2, v43, v75
	v_mov_b32_dpp v36, v72 row_shr:1 row_mask:0xf bank_mask:0xf
	v_mov_b32_dpp v37, v73 row_shr:1 row_mask:0xf bank_mask:0xf
	v_mul_f32_e32 v2, 0xbfb8aa3b, v2
	v_pk_mul_f32 v[78:79], v[72:73], v[36:37]
	v_mov_b32_e32 v36, 1.0
	v_mov_b32_e32 v37, 1.0
	v_exp_f32_e32 v2, v2
	v_mov_b32_dpp v36, v78 row_shr:2 row_mask:0xf bank_mask:0xf
	v_mov_b32_dpp v37, v79 row_shr:2 row_mask:0xf bank_mask:0xf
	v_pk_mul_f32 v[80:81], v[78:79], v[36:37]
	v_mov_b32_e32 v36, 1.0
	v_mov_b32_e32 v37, 1.0
	v_add_f32_e32 v2, 1.0, v2
	v_mov_b32_dpp v36, v80 row_shr:4 row_mask:0xf bank_mask:0xf
	v_mov_b32_dpp v37, v81 row_shr:4 row_mask:0xf bank_mask:0xf
	v_pk_mul_f32 v[82:83], v[80:81], v[36:37]
	v_mov_b32_e32 v36, 1.0
	v_mov_b32_e32 v37, 1.0
	v_rcp_f32_e32 v2, v2
	v_mov_b32_dpp v36, v82 row_shr:8 row_mask:0xf bank_mask:0xf
	v_mov_b32_dpp v37, v83 row_shr:8 row_mask:0xf bank_mask:0xf
	v_pk_mul_f32 v[86:87], v[82:83], v[36:37]
	v_add_u32_e32 v37, 0x3100, v145
	ds_read2_b32 v[122:123], v37 offset1:1
	v_mul_f32_e32 v39, 0xbfb8aa3b, v39
	v_mul_f32_e32 v2, 0xc1000000, v2
	v_exp_f32_e32 v39, v39
	v_mul_f32_e32 v2, v148, v2
	v_mul_f32_e32 v2, 0x3fb8aa3b, v2
	s_waitcnt lgkmcnt(0)
	v_pk_mul_f32 v[40:41], v[122:123], v[40:41]
	v_exp_f32_e32 v43, v2
	v_pk_mul_f32 v[40:41], v[40:41], v[76:77]
	v_add_f32_e32 v39, 1.0, v39
	v_mov_b32_e32 v38, 1.0
	v_mov_b32_dpp v76, v40 row_shr:1 row_mask:0xf bank_mask:0xf bound_ctrl:1
	v_mov_b32_dpp v77, v41 row_shr:1 row_mask:0xf bank_mask:0xf bound_ctrl:1
	v_pk_fma_f32 v[40:41], v[72:73], v[76:77], v[40:41]
	v_rcp_f32_e32 v71, v39
	v_mov_b32_e32 v39, 1.0
	v_mov_b32_dpp v72, v40 row_shr:2 row_mask:0xf bank_mask:0xf bound_ctrl:1
	v_mov_b32_dpp v73, v41 row_shr:2 row_mask:0xf bank_mask:0xf bound_ctrl:1
	v_mov_b32_dpp v38, v42 row_shr:1 row_mask:0xf bank_mask:0xf
	v_mov_b32_dpp v39, v43 row_shr:1 row_mask:0xf bank_mask:0xf
	v_pk_fma_f32 v[40:41], v[78:79], v[72:73], v[40:41]
	v_pk_mul_f32 v[78:79], v[42:43], v[38:39]
	v_mov_b32_e32 v38, 1.0
	v_mov_b32_e32 v39, 1.0
	v_mov_b32_dpp v72, v40 row_shr:4 row_mask:0xf bank_mask:0xf bound_ctrl:1
	v_mov_b32_dpp v73, v41 row_shr:4 row_mask:0xf bank_mask:0xf bound_ctrl:1
	v_mov_b32_dpp v38, v78 row_shr:2 row_mask:0xf bank_mask:0xf
	v_mov_b32_dpp v39, v79 row_shr:2 row_mask:0xf bank_mask:0xf
	v_pk_fma_f32 v[40:41], v[80:81], v[72:73], v[40:41]
	v_pk_mul_f32 v[80:81], v[78:79], v[38:39]
	v_mov_b32_e32 v38, 1.0
	v_mov_b32_e32 v39, 1.0
	v_mov_b32_dpp v72, v40 row_shr:8 row_mask:0xf bank_mask:0xf bound_ctrl:1
	v_mov_b32_dpp v73, v41 row_shr:8 row_mask:0xf bank_mask:0xf bound_ctrl:1
	v_mov_b32_dpp v38, v80 row_shr:4 row_mask:0xf bank_mask:0xf
	v_mov_b32_dpp v39, v81 row_shr:4 row_mask:0xf bank_mask:0xf
	v_pk_fma_f32 v[40:41], v[82:83], v[72:73], v[40:41]
	v_pk_mul_f32 v[82:83], v[80:81], v[38:39]
	v_mov_b32_e32 v38, 1.0
	v_mov_b32_e32 v39, 1.0
	v_fma_f32 v2, -v43, v43, 1.0
	v_mov_b32_dpp v38, v82 row_shr:8 row_mask:0xf bank_mask:0xf
	v_mov_b32_dpp v39, v83 row_shr:8 row_mask:0xf bank_mask:0xf
	v_pk_mul_f32 v[68:69], v[86:87], v[126:127]
	v_pk_fma_f32 v[72:73], v[86:87], v[94:95], v[40:41]
	v_sqrt_f32_e32 v75, v2
	v_pk_mul_f32 v[86:87], v[82:83], v[38:39]
	v_add_u32_e32 v2, 0x3108, v145
	v_pk_mul_f32 v[76:77], v[86:87], v[92:93]
	ds_read2_b32 v[92:93], v2 offset1:1
	ds_bpermute_b32 v36, v1, v68
	ds_bpermute_b32 v40, v1, v72
	ds_bpermute_b32 v41, v1, v73
	ds_bpermute_b32 v37, v1, v69
	s_waitcnt lgkmcnt(0)
	v_pk_mul_f32 v[70:71], v[70:71], v[92:93]
	ds_bpermute_b32 v38, v1, v76
	v_pk_mul_f32 v[70:71], v[74:75], v[70:71]
	ds_bpermute_b32 v39, v1, v77
	v_cvt_pk_bf16_f32 v72, v72, v73
	v_mov_b32_dpp v74, v70 row_shr:1 row_mask:0xf bank_mask:0xf bound_ctrl:1
	v_mov_b32_dpp v75, v71 row_shr:1 row_mask:0xf bank_mask:0xf bound_ctrl:1
	v_pk_fma_f32 v[42:43], v[42:43], v[74:75], v[70:71]
	v_cvt_pk_bf16_f32 v68, v68, v69
	v_cvt_pk_bf16_f32 v69, v76, v77
	v_mov_b32_dpp v70, v42 row_shr:2 row_mask:0xf bank_mask:0xf bound_ctrl:1
	v_mov_b32_dpp v71, v43 row_shr:2 row_mask:0xf bank_mask:0xf bound_ctrl:1
	v_pk_fma_f32 v[42:43], v[78:79], v[70:71], v[42:43]
	s_nop 1
	v_mov_b32_dpp v70, v42 row_shr:4 row_mask:0xf bank_mask:0xf bound_ctrl:1
	v_mov_b32_dpp v71, v43 row_shr:4 row_mask:0xf bank_mask:0xf bound_ctrl:1
	v_pk_fma_f32 v[42:43], v[80:81], v[70:71], v[42:43]
	s_nop 1
	v_mov_b32_dpp v70, v42 row_shr:8 row_mask:0xf bank_mask:0xf bound_ctrl:1
	v_mov_b32_dpp v71, v43 row_shr:8 row_mask:0xf bank_mask:0xf bound_ctrl:1
	v_pk_fma_f32 v[42:43], v[82:83], v[70:71], v[42:43]
	s_nop 0
	v_pk_fma_f32 v[70:71], v[86:87], v[84:85], v[42:43]
	ds_bpermute_b32 v42, v1, v70
	ds_bpermute_b32 v43, v1, v71
	v_cvt_pk_bf16_f32 v73, v70, v71
	global_store_dwordx2 v[114:115], v[72:73], off offset:32
	global_store_dwordx2 v[116:117], v[68:69], off offset:32
	s_and_saveexec_b64 s[34:35], vcc
	s_cbranch_execz .LBB0_525
	v_add_u32_e32 v68, 16, v0
	v_ashrrev_i32_e32 v69, 31, v68
	v_lshl_add_u64 v[68:69], s[42:43], 0, v[68:69]
	v_lshlrev_b64 v[68:69], 2, v[68:69]
	v_lshl_add_u64 v[70:71], s[84:85], 0, v[68:69]
	v_lshl_add_u64 v[68:69], s[86:87], 0, v[68:69]
	s_waitcnt lgkmcnt(0)
	global_store_dwordx4 v[70:71], v[36:39], off
	global_store_dwordx4 v[68:69], v[40:43], off
; __device__ __forceinline__ void w_lru_m1(const Args& a, int l, unsigned char* ws, const bf16_t* proj, bf16_t* y, LAS unsigned char* wl, int b, int ck_, int h, int lane) {
;     ...
;         if (jb < 3) {
; #pragma unroll
;             for (int kk = 0; kk < 2; ++kk) { nWa[kk] = *(const bf16x8*)(waT + (16 * (jb + 1) + lo) * 64 + 32 * kk + 8 * fq); nWx[kk] = *(const bf16x8*)(wxT + (16 * (jb + 1) + lo) * 64 + 32 * kk + 8 * fq); }
;             nba = *(const f32x4*)(ba + 16 * (jb + 1) + 4 * fq); nbx = *(const f32x4*)(bx + 16 * (jb + 1) + 4 * fq); nlam = *(const f32x4*)(lam + 16 * (jb + 1) + 4 * fq);
;         }
;         const int j0 = 16 * jb + 4 * fq;
;         float bav[4], bxv[4], sp[4], hc[4], Pc[4];
; #pragma unroll
;         for (int r = 0; r < 4; ++r) { bav[r] = pba[r]; bxv[r] = pbx[r]; sp[r] = log1pf(__expf(-plam[r])); hc[r] = 0.f; Pc[r] = 1.f; }
.LBB0_525:
	s_or_b64 exec, exec, s[34:35]
	v_lshl_or_b32 v2, v146, 1, v210
	v_lshl_add_u64 v[36:37], v[118:119], 0, v[2:3]
	s_waitcnt lgkmcnt(0)
	v_lshl_add_u64 v[38:39], v[120:121], 0, v[2:3]
	s_waitcnt vmcnt(8)
	v_mul_f32_e32 v2, 0xbfb8aa3b, v88
	v_exp_f32_e32 v2, v2
	global_load_dwordx4 v[68:71], v[36:37], off
	global_load_dwordx4 v[72:75], v[38:39], off
	global_load_dwordx4 v[76:79], v[36:37], off offset:64
	global_load_dwordx4 v[80:83], v[38:39], off offset:64
	global_load_dwordx4 v[40:43], v[108:109], off offset:192
	s_nop 0
	global_load_dwordx4 v[36:39], v[110:111], off offset:192
	global_load_dwordx4 v[84:87], v[112:113], off offset:192
	ds_read2_b32 v[124:125], v145 offset0:32 offset1:33
	ds_read2_b32 v[128:129], v145 offset0:34 offset1:35
	v_add_f32_e32 v88, 1.0, v2
	v_add_f32_e32 v92, -1.0, v88
	v_sub_f32_e32 v93, v92, v88
	v_add_f32_e32 v93, 1.0, v93
	v_sub_f32_e32 v92, v2, v92
	v_add_f32_e32 v94, v92, v93
	v_frexp_mant_f32_e32 v92, v88
	v_cmp_gt_f32_e64 s[40:41], s77, v92
	v_cvt_f64_f32_e32 v[92:93], v88
	v_frexp_exp_i32_f64_e32 v92, v[92:93]
	v_subbrev_co_u32_e64 v112, s[40:41], 0, v92, s[40:41]
	v_sub_u32_e32 v92, 0, v112
	v_ldexp_f32 v88, v88, v92
	v_ldexp_f32 v92, v94, v92
	v_add_f32_e32 v94, -1.0, v88
	v_add_f32_e32 v93, 1.0, v94
	v_sub_f32_e32 v93, v88, v93
	v_add_f32_e32 v95, v92, v93
	v_add_f32_e32 v93, 1.0, v88
	v_add_f32_e32 v108, -1.0, v93
	v_sub_f32_e32 v88, v88, v108
	v_add_f32_e32 v88, v92, v88
	v_add_f32_e32 v113, v93, v88
	v_rcp_f32_e32 v118, v113
	v_sub_f32_e32 v92, v113, v93
	v_add_f32_e32 v93, v94, v95
	v_sub_f32_e32 v88, v88, v92
	v_mul_f32_e32 v120, v93, v118
	v_sub_f32_e32 v92, v93, v94
	v_mul_f32_e32 v94, v113, v120
	v_fma_f32 v108, v120, v113, -v94
	v_fmac_f32_e32 v108, v120, v88
	v_sub_f32_e32 v119, v95, v92
	v_add_f32_e32 v92, v94, v108
	v_sub_f32_e32 v95, v93, v92
	v_pk_add_f32 v[110:111], v[92:93], v[94:95] neg_lo:[0,1] neg_hi:[0,1]
	v_mov_b32_e32 v109, v92
	v_pk_add_f32 v[92:93], v[110:111], v[108:109] neg_lo:[0,1] neg_hi:[0,1]
	v_cmp_neq_f32_e64 s[40:41], s22, v2
	v_add_f32_e32 v93, v119, v93
	v_add_f32_e32 v92, v92, v93
	v_add_f32_e32 v93, v95, v92
	v_mul_f32_e32 v119, v118, v93
	v_mul_f32_e32 v94, v113, v119
	v_fma_f32 v108, v119, v113, -v94
	v_fmac_f32_e32 v108, v119, v88
	v_sub_f32_e32 v88, v95, v93
	v_add_f32_e32 v88, v92, v88
	v_add_f32_e32 v92, v94, v108
	v_sub_f32_e32 v95, v93, v92
	v_pk_add_f32 v[110:111], v[92:93], v[94:95] neg_lo:[0,1] neg_hi:[0,1]
	v_mov_b32_e32 v109, v92
	v_pk_add_f32 v[92:93], v[110:111], v[108:109] neg_lo:[0,1] neg_hi:[0,1]
	s_nop 0
	v_add_f32_e32 v88, v88, v93
	v_add_f32_e32 v88, v92, v88
	v_add_f32_e32 v93, v120, v119
	v_add_f32_e32 v88, v95, v88
	v_sub_f32_e32 v92, v93, v120
	v_mul_f32_e32 v88, v118, v88
	v_sub_f32_e32 v92, v119, v92
	v_add_f32_e32 v88, v92, v88
	v_add_f32_e32 v94, v93, v88
	v_mul_f32_e32 v108, v94, v94
	v_fmamk_f32 v92, v108, 0x3e9b6dac, v201
	v_fmaak_f32 v169, v108, v92, 0x3f2aaada
	v_cvt_f32_i32_e32 v92, v112
	v_sub_f32_e32 v93, v94, v93
	v_sub_f32_e32 v88, v88, v93
	v_mul_f32_e32 v93, v94, v108
	v_pk_mul_f32 v[108:109], v[92:93], v[168:169]
	v_ldexp_f32 v95, v94, 1
	v_fma_f32 v94, v92, s94, -v108
	v_fmac_f32_e32 v94, 0xb102e308, v92
	v_pk_add_f32 v[92:93], v[108:109], v[94:95]
	v_ldexp_f32 v88, v88, 1
	v_sub_f32_e32 v95, v93, v95
	v_sub_f32_e32 v95, v109, v95
	v_add_f32_e32 v111, v88, v95
	v_mov_b32_e32 v110, v108
	v_pk_add_f32 v[108:109], v[92:93], v[108:109] neg_lo:[0,1] neg_hi:[0,1]
	v_pk_add_f32 v[112:113], v[92:93], v[110:111]
	v_mov_b32_e32 v95, v92
	v_mov_b32_e32 v109, v113
	v_pk_add_f32 v[118:119], v[94:95], v[108:109] neg_lo:[0,1] neg_hi:[0,1]
	v_pk_add_f32 v[94:95], v[94:95], v[108:109]
	v_mov_b32_e32 v110, v111
	v_pk_add_f32 v[108:109], v[94:95], v[92:93] op_sel:[1,0] op_sel_hi:[0,1] neg_lo:[0,1] neg_hi:[0,1]
	v_pk_add_f32 v[120:121], v[112:113], v[108:109] op_sel_hi:[1,0] neg_lo:[0,1] neg_hi:[0,1]
	v_mov_b32_e32 v112, v113
	v_mov_b32_e32 v113, v95
	v_pk_mov_b32 v[108:109], v[92:93], v[108:109] op_sel:[1,0]
	v_mov_b32_e32 v111, v92
	v_pk_add_f32 v[108:109], v[112:113], v[108:109] neg_lo:[0,1] neg_hi:[0,1]
	v_mov_b32_e32 v120, v118
	v_pk_add_f32 v[92:93], v[110:111], v[108:109] neg_lo:[0,1] neg_hi:[0,1]
	v_mov_b32_e32 v119, v95
	v_pk_add_f32 v[108:109], v[120:121], v[92:93]
	s_nop 0
	v_pk_add_f32 v[110:111], v[108:109], v[108:109] op_sel:[0,1] op_sel_hi:[1,0]
	s_nop 0
	v_pk_add_f32 v[94:95], v[94:95], v[110:111] op_sel:[1,0] op_sel_hi:[0,1]
	v_mov_b32_e32 v109, v94
	v_pk_add_f32 v[112:113], v[108:109], v[118:119] neg_lo:[0,1] neg_hi:[0,1]
	v_mov_b32_e32 v93, v110
	v_sub_f32_e32 v88, v108, v112
	v_pk_add_f32 v[92:93], v[92:93], v[112:113] neg_lo:[0,1] neg_hi:[0,1]
	v_sub_f32_e32 v88, v118, v88
	v_add_f32_e32 v88, v92, v88
	v_add_f32_e32 v88, v88, v93
	v_add_f32_e32 v88, v94, v88
	v_cndmask_b32_e64 v88, v208, v88, s[40:41]
	v_cmp_ngt_f32_e64 s[40:41], -1.0, v2
	s_nop 1
	v_cndmask_b32_e64 v88, v205, v88, s[40:41]
	v_cmp_neq_f32_e64 s[40:41], -1.0, v2
	s_nop 1
	v_cndmask_b32_e64 v88, v206, v88, s[40:41]
	v_cmp_lt_f32_e64 s[40:41], |v2|, s95
	s_nop 1
	v_cndmask_b32_e64 v2, v88, v2, s[40:41]
	v_mul_f32_e32 v88, 0xbfb8aa3b, v89
	v_exp_f32_e32 v120, v88
	s_nop 0
	v_add_f32_e32 v92, 1.0, v120
	v_add_f32_e32 v88, -1.0, v92
	v_sub_f32_e32 v89, v88, v92
	v_add_f32_e32 v89, 1.0, v89
	v_sub_f32_e32 v88, v120, v88
	v_add_f32_e32 v93, v88, v89
	v_frexp_mant_f32_e32 v88, v92
	v_cmp_gt_f32_e64 s[40:41], s77, v88
	v_cvt_f64_f32_e32 v[88:89], v92
	v_frexp_exp_i32_f64_e32 v88, v[88:89]
	v_subbrev_co_u32_e64 v110, s[40:41], 0, v88, s[40:41]
	v_sub_u32_e32 v88, 0, v110
	v_ldexp_f32 v89, v92, v88
	v_add_f32_e32 v92, -1.0, v89
	v_add_f32_e32 v94, 1.0, v89
; __device__ __forceinline__ void w_lru_m1(const Args& a, int l, unsigned char* ws, const bf16_t* proj, bf16_t* y, LAS unsigned char* wl, int b, int ck_, int h, int lane) {
;     ...
;         for (int r = 0; r < 4; ++r) { bav[r] = pba[r]; bxv[r] = pbx[r]; sp[r] = log1pf(__expf(-plam[r])); hc[r] = 0.f; Pc[r] = 1.f; }
	v_ldexp_f32 v88, v93, v88
	v_add_f32_e32 v93, 1.0, v92
	v_add_f32_e32 v95, -1.0, v94
	v_sub_f32_e32 v93, v89, v93
	v_sub_f32_e32 v89, v89, v95
	v_add_f32_e32 v93, v88, v93
	v_add_f32_e32 v88, v88, v89
	v_add_f32_e32 v111, v94, v88
	v_rcp_f32_e32 v113, v111
	v_sub_f32_e32 v89, v111, v94
	v_sub_f32_e32 v112, v88, v89
	v_add_f32_e32 v89, v92, v93
	v_mul_f32_e32 v119, v89, v113
	v_sub_f32_e32 v88, v89, v92
	v_mul_f32_e32 v92, v111, v119
	v_fma_f32 v94, v119, v111, -v92
	v_fmac_f32_e32 v94, v119, v112
	v_sub_f32_e32 v118, v93, v88
	v_add_f32_e32 v88, v92, v94
	v_sub_f32_e32 v93, v89, v88
	v_pk_add_f32 v[108:109], v[88:89], v[92:93] neg_lo:[0,1] neg_hi:[0,1]
	v_mov_b32_e32 v95, v88
	v_pk_add_f32 v[88:89], v[108:109], v[94:95] neg_lo:[0,1] neg_hi:[0,1]
	v_cmp_neq_f32_e64 s[40:41], s22, v120
	v_add_f32_e32 v89, v118, v89
	v_add_f32_e32 v88, v88, v89
	v_add_f32_e32 v89, v93, v88
	v_mul_f32_e32 v118, v113, v89
	v_mul_f32_e32 v92, v111, v118
	v_fma_f32 v94, v118, v111, -v92
	v_fmac_f32_e32 v94, v118, v112
	v_sub_f32_e32 v93, v93, v89
	v_add_f32_e32 v111, v88, v93
	v_add_f32_e32 v88, v92, v94
	v_sub_f32_e32 v93, v89, v88
	v_pk_add_f32 v[108:109], v[88:89], v[92:93] neg_lo:[0,1] neg_hi:[0,1]
	v_mov_b32_e32 v95, v88
	v_pk_add_f32 v[88:89], v[108:109], v[94:95] neg_lo:[0,1] neg_hi:[0,1]
	s_nop 0
	v_add_f32_e32 v89, v111, v89
	v_add_f32_e32 v88, v88, v89
	v_add_f32_e32 v89, v119, v118
	v_add_f32_e32 v88, v93, v88
	v_sub_f32_e32 v92, v89, v119
	v_mul_f32_e32 v88, v113, v88
	v_sub_f32_e32 v92, v118, v92
	v_add_f32_e32 v92, v92, v88
	v_add_f32_e32 v94, v89, v92
	v_mul_f32_e32 v95, v94, v94
	v_fmamk_f32 v88, v95, 0x3e9b6dac, v201
	v_fmaak_f32 v169, v95, v88, 0x3f2aaada
	v_cvt_f32_i32_e32 v88, v110
	v_sub_f32_e32 v89, v94, v89
	v_sub_f32_e32 v89, v92, v89
	v_ldexp_f32 v108, v89, 1
	v_mul_f32_e32 v89, v94, v95
	v_ldexp_f32 v93, v94, 1
	v_pk_mul_f32 v[94:95], v[88:89], v[168:169]
	s_nop 0
	v_fma_f32 v92, v88, s94, -v94
	v_fmac_f32_e32 v92, 0xb102e308, v88
	v_pk_add_f32 v[88:89], v[94:95], v[92:93]
	s_nop 0
	v_sub_f32_e32 v93, v89, v93
	v_sub_f32_e32 v93, v95, v93
	v_add_f32_e32 v109, v108, v93
	v_mov_b32_e32 v108, v94
	v_pk_add_f32 v[94:95], v[88:89], v[94:95] neg_lo:[0,1] neg_hi:[0,1]
	v_pk_add_f32 v[110:111], v[88:89], v[108:109]
	v_mov_b32_e32 v93, v88
	v_mov_b32_e32 v95, v111
	v_pk_add_f32 v[112:113], v[92:93], v[94:95] neg_lo:[0,1] neg_hi:[0,1]
	v_pk_add_f32 v[92:93], v[92:93], v[94:95]
	v_mov_b32_e32 v108, v109
	v_pk_add_f32 v[94:95], v[92:93], v[88:89] op_sel:[1,0] op_sel_hi:[0,1] neg_lo:[0,1] neg_hi:[0,1]
	v_pk_add_f32 v[118:119], v[110:111], v[94:95] op_sel_hi:[1,0] neg_lo:[0,1] neg_hi:[0,1]
	v_mov_b32_e32 v110, v111
	v_mov_b32_e32 v111, v93
	v_pk_mov_b32 v[94:95], v[88:89], v[94:95] op_sel:[1,0]
	v_mov_b32_e32 v109, v88
	v_pk_add_f32 v[94:95], v[110:111], v[94:95] neg_lo:[0,1] neg_hi:[0,1]
	v_mov_b32_e32 v118, v112
	v_pk_add_f32 v[88:89], v[108:109], v[94:95] neg_lo:[0,1] neg_hi:[0,1]
	v_mov_b32_e32 v113, v93
	v_pk_add_f32 v[94:95], v[118:119], v[88:89]
	s_nop 0
	v_pk_add_f32 v[108:109], v[94:95], v[94:95] op_sel:[0,1] op_sel_hi:[1,0]
	s_nop 0
	v_pk_add_f32 v[92:93], v[92:93], v[108:109] op_sel:[1,0] op_sel_hi:[0,1]
	v_mov_b32_e32 v95, v92
	v_pk_add_f32 v[110:111], v[94:95], v[112:113] neg_lo:[0,1] neg_hi:[0,1]
	v_mov_b32_e32 v89, v108
	v_sub_f32_e32 v93, v94, v110
	v_pk_add_f32 v[88:89], v[88:89], v[110:111] neg_lo:[0,1] neg_hi:[0,1]
	v_sub_f32_e32 v93, v112, v93
	v_add_f32_e32 v88, v88, v93
	v_add_f32_e32 v88, v88, v89
	v_add_f32_e32 v88, v92, v88
	v_cndmask_b32_e64 v88, v208, v88, s[40:41]
	v_cmp_ngt_f32_e64 s[40:41], -1.0, v120
	s_nop 1
	v_cndmask_b32_e64 v88, v205, v88, s[40:41]
	v_cmp_neq_f32_e64 s[40:41], -1.0, v120
	s_nop 1
	v_cndmask_b32_e64 v88, v206, v88, s[40:41]
	v_cmp_lt_f32_e64 s[40:41], |v120|, s95
	s_nop 1
	v_cndmask_b32_e64 v134, v88, v120, s[40:41]
	v_mul_f32_e32 v88, 0xbfb8aa3b, v90
	v_exp_f32_e32 v90, v88
	s_nop 0
	v_add_f32_e32 v92, 1.0, v90
	v_add_f32_e32 v88, -1.0, v92
	v_sub_f32_e32 v89, v88, v92
	v_add_f32_e32 v89, 1.0, v89
	v_sub_f32_e32 v88, v90, v88
	v_add_f32_e32 v93, v88, v89
	v_frexp_mant_f32_e32 v88, v92
	v_cmp_gt_f32_e64 s[40:41], s77, v88
	v_cvt_f64_f32_e32 v[88:89], v92
	v_frexp_exp_i32_f64_e32 v88, v[88:89]
	v_subbrev_co_u32_e64 v110, s[40:41], 0, v88, s[40:41]
	v_sub_u32_e32 v88, 0, v110
	v_ldexp_f32 v89, v92, v88
	v_add_f32_e32 v92, -1.0, v89
	v_add_f32_e32 v94, 1.0, v89
	v_ldexp_f32 v88, v93, v88
	v_add_f32_e32 v93, 1.0, v92
	v_add_f32_e32 v95, -1.0, v94
	v_sub_f32_e32 v93, v89, v93
	v_sub_f32_e32 v89, v89, v95
	v_add_f32_e32 v93, v88, v93
	v_add_f32_e32 v88, v88, v89
	v_add_f32_e32 v111, v94, v88
	v_rcp_f32_e32 v113, v111
	v_sub_f32_e32 v89, v111, v94
	v_sub_f32_e32 v112, v88, v89
	v_add_f32_e32 v89, v92, v93
	v_mul_f32_e32 v119, v89, v113
	v_sub_f32_e32 v88, v89, v92
	v_mul_f32_e32 v92, v111, v119
	v_fma_f32 v94, v119, v111, -v92
	v_fmac_f32_e32 v94, v119, v112
	v_sub_f32_e32 v118, v93, v88
	v_add_f32_e32 v88, v92, v94
	v_sub_f32_e32 v93, v89, v88
	v_pk_add_f32 v[108:109], v[88:89], v[92:93] neg_lo:[0,1] neg_hi:[0,1]
	v_mov_b32_e32 v95, v88
	v_pk_add_f32 v[88:89], v[108:109], v[94:95] neg_lo:[0,1] neg_hi:[0,1]
	v_cmp_neq_f32_e64 s[40:41], s22, v90
	v_add_f32_e32 v89, v118, v89
	v_add_f32_e32 v88, v88, v89
	v_add_f32_e32 v89, v93, v88
	v_mul_f32_e32 v118, v113, v89
	v_mul_f32_e32 v92, v111, v118
	v_fma_f32 v94, v118, v111, -v92
	v_fmac_f32_e32 v94, v118, v112
	v_sub_f32_e32 v93, v93, v89
	v_add_f32_e32 v111, v88, v93
	v_add_f32_e32 v88, v92, v94
	v_sub_f32_e32 v93, v89, v88
	v_pk_add_f32 v[108:109], v[88:89], v[92:93] neg_lo:[0,1] neg_hi:[0,1]
	v_mov_b32_e32 v95, v88
	v_pk_add_f32 v[88:89], v[108:109], v[94:95] neg_lo:[0,1] neg_hi:[0,1]
; __device__ __forceinline__ void w_lru_m1(const Args& a, int l, unsigned char* ws, const bf16_t* proj, bf16_t* y, LAS unsigned char* wl, int b, int ck_, int h, int lane) {
;     ...
;         for (int r = 0; r < 4; ++r) { bav[r] = pba[r]; bxv[r] = pbx[r]; sp[r] = log1pf(__expf(-plam[r])); hc[r] = 0.f; Pc[r] = 1.f; }
	s_nop 0
	v_add_f32_e32 v89, v111, v89
	v_add_f32_e32 v88, v88, v89
	v_add_f32_e32 v89, v119, v118
	v_add_f32_e32 v88, v93, v88
	v_sub_f32_e32 v92, v89, v119
	v_mul_f32_e32 v88, v113, v88
	v_sub_f32_e32 v92, v118, v92
	v_add_f32_e32 v92, v92, v88
	v_add_f32_e32 v94, v89, v92
	v_mul_f32_e32 v95, v94, v94
	v_fmamk_f32 v88, v95, 0x3e9b6dac, v201
	v_fmaak_f32 v169, v95, v88, 0x3f2aaada
	v_cvt_f32_i32_e32 v88, v110
	v_sub_f32_e32 v89, v94, v89
	v_sub_f32_e32 v89, v92, v89
	v_ldexp_f32 v108, v89, 1
	v_mul_f32_e32 v89, v94, v95
	v_ldexp_f32 v93, v94, 1
	v_pk_mul_f32 v[94:95], v[88:89], v[168:169]
	s_nop 0
	v_fma_f32 v92, v88, s94, -v94
	v_fmac_f32_e32 v92, 0xb102e308, v88
	v_pk_add_f32 v[88:89], v[94:95], v[92:93]
	s_nop 0
	v_sub_f32_e32 v93, v89, v93
	v_sub_f32_e32 v93, v95, v93
	v_add_f32_e32 v109, v108, v93
	v_mov_b32_e32 v108, v94
	v_pk_add_f32 v[94:95], v[88:89], v[94:95] neg_lo:[0,1] neg_hi:[0,1]
	v_pk_add_f32 v[110:111], v[88:89], v[108:109]
	v_mov_b32_e32 v93, v88
	v_mov_b32_e32 v95, v111
	v_pk_add_f32 v[112:113], v[92:93], v[94:95] neg_lo:[0,1] neg_hi:[0,1]
	v_pk_add_f32 v[92:93], v[92:93], v[94:95]
	v_mov_b32_e32 v108, v109
	v_pk_add_f32 v[94:95], v[92:93], v[88:89] op_sel:[1,0] op_sel_hi:[0,1] neg_lo:[0,1] neg_hi:[0,1]
	v_pk_add_f32 v[118:119], v[110:111], v[94:95] op_sel_hi:[1,0] neg_lo:[0,1] neg_hi:[0,1]
	v_mov_b32_e32 v110, v111
	v_mov_b32_e32 v111, v93
	v_pk_mov_b32 v[94:95], v[88:89], v[94:95] op_sel:[1,0]
	v_mov_b32_e32 v109, v88
	v_pk_add_f32 v[94:95], v[110:111], v[94:95] neg_lo:[0,1] neg_hi:[0,1]
	v_mov_b32_e32 v118, v112
	v_pk_add_f32 v[88:89], v[108:109], v[94:95] neg_lo:[0,1] neg_hi:[0,1]
	v_mov_b32_e32 v113, v93
	v_pk_add_f32 v[94:95], v[118:119], v[88:89]
	s_nop 0
	v_pk_add_f32 v[108:109], v[94:95], v[94:95] op_sel:[0,1] op_sel_hi:[1,0]
	s_nop 0
	v_pk_add_f32 v[92:93], v[92:93], v[108:109] op_sel:[1,0] op_sel_hi:[0,1]
	v_mov_b32_e32 v95, v92
	v_pk_add_f32 v[110:111], v[94:95], v[112:113] neg_lo:[0,1] neg_hi:[0,1]
	v_mov_b32_e32 v89, v108
	v_sub_f32_e32 v93, v94, v110
	v_pk_add_f32 v[88:89], v[88:89], v[110:111] neg_lo:[0,1] neg_hi:[0,1]
	v_sub_f32_e32 v93, v112, v93
	v_add_f32_e32 v88, v88, v93
	v_add_f32_e32 v88, v88, v89
	v_add_f32_e32 v88, v92, v88
	v_cndmask_b32_e64 v88, v208, v88, s[40:41]
	v_cmp_ngt_f32_e64 s[40:41], -1.0, v90
	s_nop 1
	v_cndmask_b32_e64 v88, v205, v88, s[40:41]
	v_cmp_neq_f32_e64 s[40:41], -1.0, v90
	s_nop 1
	v_cndmask_b32_e64 v88, v206, v88, s[40:41]
	v_cmp_lt_f32_e64 s[40:41], |v90|, s95
	s_nop 1
	v_cndmask_b32_e64 v135, v88, v90, s[40:41]
	v_mul_f32_e32 v88, 0xbfb8aa3b, v91
	v_exp_f32_e32 v118, v88
	s_nop 0
	v_add_f32_e32 v90, 1.0, v118
	v_add_f32_e32 v88, -1.0, v90
	v_sub_f32_e32 v89, v88, v90
	v_add_f32_e32 v89, 1.0, v89
	v_sub_f32_e32 v88, v118, v88
	v_add_f32_e32 v91, v88, v89
	v_frexp_mant_f32_e32 v88, v90
	v_cmp_gt_f32_e64 s[40:41], s77, v88
	v_cvt_f64_f32_e32 v[88:89], v90
	v_frexp_exp_i32_f64_e32 v88, v[88:89]
	v_subbrev_co_u32_e64 v108, s[40:41], 0, v88, s[40:41]
	v_sub_u32_e32 v88, 0, v108
	v_ldexp_f32 v89, v90, v88
	v_add_f32_e32 v90, -1.0, v89
	v_add_f32_e32 v92, 1.0, v89
	v_ldexp_f32 v88, v91, v88
	v_add_f32_e32 v91, 1.0, v90
	v_add_f32_e32 v93, -1.0, v92
	v_sub_f32_e32 v91, v89, v91
	v_sub_f32_e32 v89, v89, v93
	v_add_f32_e32 v91, v88, v91
	v_add_f32_e32 v88, v88, v89
	v_add_f32_e32 v109, v92, v88
	v_rcp_f32_e32 v111, v109
	v_sub_f32_e32 v89, v109, v92
	v_sub_f32_e32 v110, v88, v89
	v_add_f32_e32 v89, v90, v91
	v_mul_f32_e32 v113, v89, v111
	v_sub_f32_e32 v88, v89, v90
	v_mul_f32_e32 v90, v109, v113
	v_fma_f32 v92, v113, v109, -v90
	v_fmac_f32_e32 v92, v113, v110
	v_sub_f32_e32 v112, v91, v88
	v_add_f32_e32 v88, v90, v92
	v_sub_f32_e32 v91, v89, v88
	v_pk_add_f32 v[94:95], v[88:89], v[90:91] neg_lo:[0,1] neg_hi:[0,1]
	v_mov_b32_e32 v93, v88
	v_pk_add_f32 v[88:89], v[94:95], v[92:93] neg_lo:[0,1] neg_hi:[0,1]
	v_cmp_neq_f32_e64 s[40:41], s22, v118
	v_add_f32_e32 v89, v112, v89
	v_add_f32_e32 v88, v88, v89
	v_add_f32_e32 v89, v91, v88
	v_mul_f32_e32 v112, v111, v89
	v_mul_f32_e32 v90, v109, v112
	v_fma_f32 v92, v112, v109, -v90
	v_fmac_f32_e32 v92, v112, v110
	v_sub_f32_e32 v91, v91, v89
	v_add_f32_e32 v109, v88, v91
	v_add_f32_e32 v88, v90, v92
	v_sub_f32_e32 v91, v89, v88
	v_pk_add_f32 v[94:95], v[88:89], v[90:91] neg_lo:[0,1] neg_hi:[0,1]
	v_mov_b32_e32 v93, v88
	v_pk_add_f32 v[88:89], v[94:95], v[92:93] neg_lo:[0,1] neg_hi:[0,1]
	s_nop 0
	v_add_f32_e32 v89, v109, v89
	v_add_f32_e32 v88, v88, v89
	v_add_f32_e32 v89, v113, v112
	v_add_f32_e32 v88, v91, v88
	v_sub_f32_e32 v90, v89, v113
	v_mul_f32_e32 v88, v111, v88
	v_sub_f32_e32 v90, v112, v90
	v_add_f32_e32 v90, v90, v88
	v_add_f32_e32 v92, v89, v90
	v_mul_f32_e32 v93, v92, v92
	v_fmamk_f32 v88, v93, 0x3e9b6dac, v201
	v_fmaak_f32 v169, v93, v88, 0x3f2aaada
	v_cvt_f32_i32_e32 v88, v108
	v_sub_f32_e32 v89, v92, v89
	v_sub_f32_e32 v89, v90, v89
	v_ldexp_f32 v94, v89, 1
	v_mul_f32_e32 v89, v92, v93
	v_ldexp_f32 v91, v92, 1
	v_pk_mul_f32 v[92:93], v[88:89], v[168:169]
	s_nop 0
	v_fma_f32 v90, v88, s94, -v92
	v_fmac_f32_e32 v90, 0xb102e308, v88
	v_pk_add_f32 v[88:89], v[92:93], v[90:91]
	s_nop 0
	v_sub_f32_e32 v91, v89, v91
	v_sub_f32_e32 v91, v93, v91
	v_add_f32_e32 v95, v94, v91
	v_mov_b32_e32 v94, v92
	v_pk_add_f32 v[92:93], v[88:89], v[92:93] neg_lo:[0,1] neg_hi:[0,1]
	v_pk_add_f32 v[108:109], v[88:89], v[94:95]
	v_mov_b32_e32 v91, v88
	v_mov_b32_e32 v93, v109
	v_pk_add_f32 v[110:111], v[90:91], v[92:93] neg_lo:[0,1] neg_hi:[0,1]
	v_pk_add_f32 v[90:91], v[90:91], v[92:93]
	v_mov_b32_e32 v94, v95
	v_pk_add_f32 v[92:93], v[90:91], v[88:89] op_sel:[1,0] op_sel_hi:[0,1] neg_lo:[0,1] neg_hi:[0,1]
; __device__ __forceinline__ float sigmoidf_(float x) { return __builtin_amdgcn_rcpf(1.0f + __expf(-x)); }
; __device__ __forceinline__ void w_lru_m1(const Args& a, int l, unsigned char* ws, const bf16_t* proj, bf16_t* y, LAS unsigned char* wl, int b, int ck_, int h, int lane) {
;     ...
;         for (int r = 0; r < 4; ++r) { bav[r] = pba[r]; bxv[r] = pbx[r]; sp[r] = log1pf(__expf(-plam[r])); hc[r] = 0.f; Pc[r] = 1.f; }
; #pragma unroll
;         for (int tb = 0; tb < 4; ++tb) { const int tok = 16 * tb + lo;
;             f32x4 ga = {0.f, 0.f, 0.f, 0.f}, gx = {0.f, 0.f, 0.f, 0.f};
; #pragma unroll
;             for (int kk = 0; kk < 2; ++kk) { ga = __builtin_amdgcn_mfma_f32_16x16x32_bf16(WaF[kk], Xf[tb][kk], ga, 0, 0, 0); gx = __builtin_amdgcn_mfma_f32_16x16x32_bf16(WxF[kk], Xf[tb][kk], gx, 0, 0, 0); }
;             float hv[4], pv[4];
; #pragma unroll
;             for (int r = 0; r < 4; ++r) {
;                 const float rg = sigmoidf_(ga[r] + bav[r]), ig = sigmoidf_(gx[r] + bxv[r]);
;                 const float la = -8.0f * rg * sp[r]; float A = __expf(la);
;                 float U = __builtin_amdgcn_sqrtf(1.0f - A * A) * (ig * xcf[tok * 65 + j0 + r]);
;                 { const float As = dpp_shr1<1>(A), Us = dpp_shr0<1>(U); U = A * Us + U; A = A * As; }
;                 { const float As = dpp_shr1<2>(A), Us = dpp_shr0<2>(U); U = A * Us + U; A = A * As; }
;                 { const float As = dpp_shr1<4>(A), Us = dpp_shr0<4>(U); U = A * Us + U; A = A * As; }
;                 { const float As = dpp_shr1<8>(A), Us = dpp_shr0<8>(U); U = A * Us + U; A = A * As; }
	v_pk_add_f32 v[112:113], v[108:109], v[92:93] op_sel_hi:[1,0] neg_lo:[0,1] neg_hi:[0,1]
	v_mov_b32_e32 v108, v109
	v_mov_b32_e32 v109, v91
	v_pk_mov_b32 v[92:93], v[88:89], v[92:93] op_sel:[1,0]
	v_mov_b32_e32 v95, v88
	v_pk_add_f32 v[92:93], v[108:109], v[92:93] neg_lo:[0,1] neg_hi:[0,1]
	v_mov_b32_e32 v112, v110
	v_pk_add_f32 v[88:89], v[94:95], v[92:93] neg_lo:[0,1] neg_hi:[0,1]
	v_mov_b32_e32 v111, v91
	v_pk_add_f32 v[92:93], v[112:113], v[88:89]
	s_nop 0
	v_pk_add_f32 v[94:95], v[92:93], v[92:93] op_sel:[0,1] op_sel_hi:[1,0]
	s_nop 0
	v_pk_add_f32 v[90:91], v[90:91], v[94:95] op_sel:[1,0] op_sel_hi:[0,1]
	v_mov_b32_e32 v93, v90
	v_pk_add_f32 v[108:109], v[92:93], v[110:111] neg_lo:[0,1] neg_hi:[0,1]
	v_mov_b32_e32 v89, v94
	v_sub_f32_e32 v91, v92, v108
	v_pk_add_f32 v[88:89], v[88:89], v[108:109] neg_lo:[0,1] neg_hi:[0,1]
	v_sub_f32_e32 v91, v110, v91
	v_add_f32_e32 v88, v88, v91
	v_add_f32_e32 v88, v88, v89
	v_add_f32_e32 v88, v90, v88
	v_cndmask_b32_e64 v88, v208, v88, s[40:41]
	v_cmp_ngt_f32_e64 s[40:41], -1.0, v118
	v_mfma_f32_16x16x32_bf16 v[92:95], v[60:63], v[16:19], 0
	s_nop 0
	v_cndmask_b32_e64 v88, v205, v88, s[40:41]
	v_cmp_neq_f32_e64 s[40:41], -1.0, v118
	v_mfma_f32_16x16x32_bf16 v[110:113], v[52:55], v[32:35], v[92:95]
	s_nop 0
	v_cndmask_b32_e64 v88, v206, v88, s[40:41]
	v_cmp_lt_f32_e64 s[40:41], |v118|, s95
	s_nop 1
	v_cndmask_b32_e64 v136, v88, v118, s[40:41]
	v_mfma_f32_16x16x32_bf16 v[88:91], v[64:67], v[16:19], 0
	s_nop 0
	v_add_f32_e32 v92, v44, v110
	v_add_f32_e32 v93, v45, v111
	v_mul_f32_e32 v92, 0xbfb8aa3b, v92
	v_mfma_f32_16x16x32_bf16 v[88:91], v[56:59], v[32:35], v[88:91]
	v_mul_f32_e32 v93, 0xbfb8aa3b, v93
	v_exp_f32_e32 v92, v92
	v_exp_f32_e32 v93, v93
	v_add_f32_e32 v92, 1.0, v92
	v_add_f32_e32 v93, 1.0, v93
	s_nop 2
	v_add_f32_e32 v88, v48, v88
	v_add_f32_e32 v89, v49, v89
	v_mul_f32_e32 v88, 0xbfb8aa3b, v88
	v_mul_f32_e32 v89, 0xbfb8aa3b, v89
	v_exp_f32_e32 v88, v88
	v_exp_f32_e32 v89, v89
	v_rcp_f32_e32 v92, v92
	v_rcp_f32_e32 v93, v93
	v_add_f32_e32 v88, 1.0, v88
	v_add_f32_e32 v89, 1.0, v89
	v_rcp_f32_e32 v88, v88
	v_rcp_f32_e32 v89, v89
	s_waitcnt lgkmcnt(0)
	v_pk_mul_f32 v[92:93], v[124:125], v[92:93]
	v_add_f32_e32 v90, v50, v90
	v_mul_f32_e32 v88, 0xc1000000, v88
	v_mul_f32_e32 v89, 0xc1000000, v89
	v_mul_f32_e32 v88, v2, v88
	v_mul_f32_e32 v89, v134, v89
	v_mul_f32_e32 v88, 0x3fb8aa3b, v88
	v_mul_f32_e32 v89, 0x3fb8aa3b, v89
	v_exp_f32_e32 v108, v88
	v_exp_f32_e32 v109, v89
	v_add_f32_e32 v91, v51, v91
	v_mul_f32_e32 v90, 0xbfb8aa3b, v90
	v_fma_f32 v88, -v108, v108, 1.0
	v_fma_f32 v89, -v109, v109, 1.0
	v_sqrt_f32_e32 v110, v88
	v_sqrt_f32_e32 v111, v89
	v_mov_b32_e32 v88, 1.0
	v_mov_b32_e32 v89, 1.0
	v_mul_f32_e32 v91, 0xbfb8aa3b, v91
	v_pk_mul_f32 v[92:93], v[92:93], v[110:111]
	v_mov_b32_dpp v88, v108 row_shr:1 row_mask:0xf bank_mask:0xf
	v_mov_b32_dpp v89, v109 row_shr:1 row_mask:0xf bank_mask:0xf
	v_mov_b32_dpp v110, v92 row_shr:1 row_mask:0xf bank_mask:0xf bound_ctrl:1
	v_mov_b32_dpp v111, v93 row_shr:1 row_mask:0xf bank_mask:0xf bound_ctrl:1
	v_pk_fma_f32 v[92:93], v[108:109], v[110:111], v[92:93]
	v_pk_mul_f32 v[118:119], v[108:109], v[88:89]
	v_mov_b32_e32 v88, 1.0
	v_mov_b32_e32 v89, 1.0
	v_mov_b32_dpp v108, v92 row_shr:2 row_mask:0xf bank_mask:0xf bound_ctrl:1
	v_mov_b32_dpp v109, v93 row_shr:2 row_mask:0xf bank_mask:0xf bound_ctrl:1
	v_exp_f32_e32 v90, v90
	v_exp_f32_e32 v91, v91
	v_mov_b32_dpp v88, v118 row_shr:2 row_mask:0xf bank_mask:0xf
	v_mov_b32_dpp v89, v119 row_shr:2 row_mask:0xf bank_mask:0xf
	v_pk_fma_f32 v[92:93], v[118:119], v[108:109], v[92:93]
	v_pk_mul_f32 v[120:121], v[118:119], v[88:89]
	v_mov_b32_e32 v88, 1.0
	v_mov_b32_e32 v89, 1.0
	v_mov_b32_dpp v108, v92 row_shr:4 row_mask:0xf bank_mask:0xf bound_ctrl:1
	v_mov_b32_dpp v109, v93 row_shr:4 row_mask:0xf bank_mask:0xf bound_ctrl:1
	v_mov_b32_dpp v88, v120 row_shr:4 row_mask:0xf bank_mask:0xf
	v_mov_b32_dpp v89, v121 row_shr:4 row_mask:0xf bank_mask:0xf
	v_pk_fma_f32 v[92:93], v[120:121], v[108:109], v[92:93]
	v_pk_mul_f32 v[122:123], v[120:121], v[88:89]
	v_add_f32_e32 v90, 1.0, v90
	v_mov_b32_dpp v108, v92 row_shr:8 row_mask:0xf bank_mask:0xf bound_ctrl:1
	v_mov_b32_dpp v109, v93 row_shr:8 row_mask:0xf bank_mask:0xf bound_ctrl:1
	v_add_f32_e32 v91, 1.0, v91
	v_pk_fma_f32 v[92:93], v[122:123], v[108:109], v[92:93]
	v_rcp_f32_e32 v90, v90
	v_add_f32_e32 v108, v46, v112
	v_rcp_f32_e32 v91, v91
	v_add_f32_e32 v109, v47, v113
	v_mul_f32_e32 v108, 0xbfb8aa3b, v108
	v_mul_f32_e32 v109, 0xbfb8aa3b, v109
	v_exp_f32_e32 v108, v108
	v_exp_f32_e32 v109, v109
	v_mul_f32_e32 v90, 0xc1000000, v90
	v_mul_f32_e32 v91, 0xc1000000, v91
	v_mul_f32_e32 v90, v135, v90
	v_mul_f32_e32 v91, v136, v91
	v_add_f32_e32 v108, 1.0, v108
	v_mul_f32_e32 v90, 0x3fb8aa3b, v90
	v_add_f32_e32 v109, 1.0, v109
	v_mul_f32_e32 v91, 0x3fb8aa3b, v91
	v_rcp_f32_e32 v112, v108
	v_exp_f32_e32 v108, v90
	v_rcp_f32_e32 v113, v109
	v_exp_f32_e32 v109, v91
	v_mov_b32_e32 v88, 1.0
	v_fma_f32 v90, -v108, v108, 1.0
	v_sqrt_f32_e32 v118, v90
	v_fma_f32 v91, -v109, v109, 1.0
	v_sqrt_f32_e32 v119, v91
	v_pk_mul_f32 v[112:113], v[112:113], v[128:129]
	v_mov_b32_e32 v89, 1.0
	v_mov_b32_e32 v90, 1.0
	v_mov_b32_e32 v91, 1.0
	v_pk_mul_f32 v[112:113], v[118:119], v[112:113]
	v_mov_b32_dpp v88, v122 row_shr:8 row_mask:0xf bank_mask:0xf
	v_mov_b32_dpp v89, v123 row_shr:8 row_mask:0xf bank_mask:0xf
	v_mov_b32_dpp v90, v108 row_shr:1 row_mask:0xf bank_mask:0xf
	v_mov_b32_dpp v91, v109 row_shr:1 row_mask:0xf bank_mask:0xf
	v_mov_b32_dpp v118, v112 row_shr:1 row_mask:0xf bank_mask:0xf bound_ctrl:1
	v_mov_b32_dpp v119, v113 row_shr:1 row_mask:0xf bank_mask:0xf bound_ctrl:1
; __device__ __forceinline__ unsigned pk2(float lo, float hi) { const f32x2_t v = {lo, hi}; const bf16x2_t b = __builtin_convertvector(v, bf16x2_t); return __builtin_bit_cast(unsigned, b); }
; __device__ __forceinline__ float sigmoidf_(float x) { return __builtin_amdgcn_rcpf(1.0f + __expf(-x)); }
; __device__ __forceinline__ float bcast15(float v, int lane) { return bperm_f((lane & 48) | 15, v); }
; __device__ __forceinline__ void w_lru_m1(const Args& a, int l, unsigned char* ws, const bf16_t* proj, bf16_t* y, LAS unsigned char* wl, int b, int ck_, int h, int lane) {
;     ...
;         for (int tb = 0; tb < 4; ++tb) { const int tok = 16 * tb + lo;
;             f32x4 ga = {0.f, 0.f, 0.f, 0.f}, gx = {0.f, 0.f, 0.f, 0.f};
; #pragma unroll
;             for (int kk = 0; kk < 2; ++kk) { ga = __builtin_amdgcn_mfma_f32_16x16x32_bf16(WaF[kk], Xf[tb][kk], ga, 0, 0, 0); gx = __builtin_amdgcn_mfma_f32_16x16x32_bf16(WxF[kk], Xf[tb][kk], gx, 0, 0, 0); }
;             float hv[4], pv[4];
; #pragma unroll
;             for (int r = 0; r < 4; ++r) {
;                 const float rg = sigmoidf_(ga[r] + bav[r]), ig = sigmoidf_(gx[r] + bxv[r]);
;                 const float la = -8.0f * rg * sp[r]; float A = __expf(la);
;                 float U = __builtin_amdgcn_sqrtf(1.0f - A * A) * (ig * xcf[tok * 65 + j0 + r]);
;                 { const float As = dpp_shr1<1>(A), Us = dpp_shr0<1>(U); U = A * Us + U; A = A * As; }
;                 { const float As = dpp_shr1<2>(A), Us = dpp_shr0<2>(U); U = A * Us + U; A = A * As; }
;                 { const float As = dpp_shr1<4>(A), Us = dpp_shr0<4>(U); U = A * Us + U; A = A * As; }
;                 { const float As = dpp_shr1<8>(A), Us = dpp_shr0<8>(U); U = A * Us + U; A = A * As; }
;                 const float hh = U + A * hc[r], PP = A * Pc[r];
;                 hc[r] = bcast15(hh, lane); Pc[r] = bcast15(PP, lane); hv[r] = hh; pv[r] = PP; }
;             *(unsigned long long*)(y + (size_t)(row0 + tok) * DM + 64 * h + j0) = (unsigned long long)pk2(hv[0], hv[1]) | ((unsigned long long)pk2(hv[2], hv[3]) << 32);
	v_pk_mul_f32 v[94:95], v[122:123], v[88:89]
	v_pk_mul_f32 v[122:123], v[108:109], v[90:91]
	v_mov_b32_e32 v90, 1.0
	v_mov_b32_e32 v91, 1.0
	v_pk_fma_f32 v[108:109], v[108:109], v[118:119], v[112:113]
	v_mov_b32_dpp v90, v122 row_shr:2 row_mask:0xf bank_mask:0xf
	v_mov_b32_dpp v91, v123 row_shr:2 row_mask:0xf bank_mask:0xf
	v_mov_b32_dpp v112, v108 row_shr:2 row_mask:0xf bank_mask:0xf bound_ctrl:1
	v_mov_b32_dpp v113, v109 row_shr:2 row_mask:0xf bank_mask:0xf bound_ctrl:1
	v_pk_mul_f32 v[124:125], v[122:123], v[90:91]
	v_mov_b32_e32 v90, 1.0
	v_mov_b32_e32 v91, 1.0
	v_pk_fma_f32 v[108:109], v[122:123], v[112:113], v[108:109]
	v_mov_b32_dpp v90, v124 row_shr:4 row_mask:0xf bank_mask:0xf
	v_mov_b32_dpp v91, v125 row_shr:4 row_mask:0xf bank_mask:0xf
	v_mov_b32_dpp v112, v108 row_shr:4 row_mask:0xf bank_mask:0xf bound_ctrl:1
	v_mov_b32_dpp v113, v109 row_shr:4 row_mask:0xf bank_mask:0xf bound_ctrl:1
	v_pk_mul_f32 v[126:127], v[124:125], v[90:91]
	v_mov_b32_e32 v90, 1.0
	v_mov_b32_e32 v91, 1.0
	v_pk_fma_f32 v[108:109], v[124:125], v[112:113], v[108:109]
	v_mov_b32_dpp v90, v126 row_shr:8 row_mask:0xf bank_mask:0xf
	v_mov_b32_dpp v91, v127 row_shr:8 row_mask:0xf bank_mask:0xf
	v_mov_b32_dpp v112, v108 row_shr:8 row_mask:0xf bank_mask:0xf bound_ctrl:1
	v_mov_b32_dpp v113, v109 row_shr:8 row_mask:0xf bank_mask:0xf bound_ctrl:1
	v_pk_mul_f32 v[120:121], v[126:127], v[90:91]
	v_pk_fma_f32 v[108:109], v[126:127], v[112:113], v[108:109]
	v_pk_fma_f32 v[110:111], v[94:95], 0, v[92:93] op_sel_hi:[1,0,1]
	v_pk_fma_f32 v[112:113], v[120:121], 0, v[108:109] op_sel_hi:[1,0,1]
	ds_bpermute_b32 v92, v1, v110
	ds_bpermute_b32 v93, v1, v111
	v_cvt_pk_bf16_f32 v110, v110, v111
	v_cvt_pk_bf16_f32 v111, v112, v113
	ds_bpermute_b32 v108, v1, v112
	ds_bpermute_b32 v109, v1, v113
	global_store_dwordx2 v[100:101], v[110:111], off offset:64
	v_mfma_f32_16x16x32_bf16 v[110:113], v[64:67], v[12:15], 0
	ds_bpermute_b32 v88, v1, v94
	ds_bpermute_b32 v89, v1, v95
	v_cvt_pk_bf16_f32 v94, v94, v95
	v_mfma_f32_16x16x32_bf16 v[122:125], v[56:59], v[28:31], v[110:113]
	v_cvt_pk_bf16_f32 v95, v120, v121
	global_store_dwordx2 v[102:103], v[94:95], off offset:64
	ds_bpermute_b32 v90, v1, v120
	ds_bpermute_b32 v91, v1, v121
	v_mfma_f32_16x16x32_bf16 v[118:121], v[60:63], v[12:15], 0
	s_nop 2
	v_add_f32_e32 v94, v48, v122
	v_mul_f32_e32 v94, 0xbfb8aa3b, v94
	v_exp_f32_e32 v94, v94
	v_mfma_f32_16x16x32_bf16 v[118:121], v[52:55], v[28:31], v[118:121]
	v_mov_b32_e32 v112, 1.0
	v_add_f32_e32 v94, 1.0, v94
	v_rcp_f32_e32 v95, v94
	s_nop 0
	v_mul_f32_e32 v95, 0xc1000000, v95
	v_mul_f32_e32 v95, v2, v95
	v_mul_f32_e32 v95, 0x3fb8aa3b, v95
	v_exp_f32_e32 v110, v95
	v_add_f32_e32 v94, v44, v118
	v_mul_f32_e32 v94, 0xbfb8aa3b, v94
	v_exp_f32_e32 v94, v94
	v_fma_f32 v95, -v110, v110, 1.0
	v_sqrt_f32_e32 v118, v95
	v_add_f32_e32 v95, v49, v123
	v_mul_f32_e32 v95, 0xbfb8aa3b, v95
	v_exp_f32_e32 v95, v95
	v_mov_b32_dpp v112, v110 row_shr:1 row_mask:0xf bank_mask:0xf
	v_add_f32_e32 v94, 1.0, v94
	v_rcp_f32_e32 v94, v94
	v_add_f32_e32 v95, 1.0, v95
	v_rcp_f32_e32 v111, v95
	v_add_f32_e32 v95, v45, v119
	v_mul_f32_e32 v95, 0xbfb8aa3b, v95
	v_exp_f32_e32 v95, v95
	v_mul_f32_e32 v111, 0xc1000000, v111
	v_mul_f32_e32 v111, v134, v111
	v_mul_f32_e32 v111, 0x3fb8aa3b, v111
	v_exp_f32_e32 v111, v111
	v_add_f32_e32 v95, 1.0, v95
	v_rcp_f32_e32 v95, v95
	v_fma_f32 v113, -v111, v111, 1.0
	v_sqrt_f32_e32 v119, v113
	v_mov_b32_e32 v113, 1.0
	s_nop 1
	v_mov_b32_dpp v113, v111 row_shr:1 row_mask:0xf bank_mask:0xf
	v_pk_mul_f32 v[122:123], v[110:111], v[112:113]
	v_mov_b32_e32 v112, 1.0
	v_mov_b32_e32 v113, 1.0
	s_nop 0
	v_mov_b32_dpp v112, v122 row_shr:2 row_mask:0xf bank_mask:0xf
	v_mov_b32_dpp v113, v123 row_shr:2 row_mask:0xf bank_mask:0xf
	v_pk_mul_f32 v[126:127], v[122:123], v[112:113]
	v_mov_b32_e32 v112, 1.0
	v_mov_b32_e32 v113, 1.0
	s_nop 0
	v_mov_b32_dpp v112, v126 row_shr:4 row_mask:0xf bank_mask:0xf
	v_mov_b32_dpp v113, v127 row_shr:4 row_mask:0xf bank_mask:0xf
	v_pk_mul_f32 v[128:129], v[126:127], v[112:113]
	v_mov_b32_e32 v112, 1.0
	v_mov_b32_e32 v113, 1.0
	s_nop 0
	v_mov_b32_dpp v112, v128 row_shr:8 row_mask:0xf bank_mask:0xf
	v_mov_b32_dpp v113, v129 row_shr:8 row_mask:0xf bank_mask:0xf
	v_pk_mul_f32 v[130:131], v[128:129], v[112:113]
	v_add_u32_e32 v113, 0x10c0, v145
	ds_read2_b32 v[132:133], v113 offset1:1
	s_waitcnt lgkmcnt(0)
; __device__ __forceinline__ unsigned pk2(float lo, float hi) { const f32x2_t v = {lo, hi}; const bf16x2_t b = __builtin_convertvector(v, bf16x2_t); return __builtin_bit_cast(unsigned, b); }
; __device__ __forceinline__ float sigmoidf_(float x) { return __builtin_amdgcn_rcpf(1.0f + __expf(-x)); }
; __device__ __forceinline__ float bcast15(float v, int lane) { return bperm_f((lane & 48) | 15, v); }
; __device__ __forceinline__ void w_lru_m1(const Args& a, int l, unsigned char* ws, const bf16_t* proj, bf16_t* y, LAS unsigned char* wl, int b, int ck_, int h, int lane) {
;     ...
;         for (int tb = 0; tb < 4; ++tb) { const int tok = 16 * tb + lo;
;             f32x4 ga = {0.f, 0.f, 0.f, 0.f}, gx = {0.f, 0.f, 0.f, 0.f};
; #pragma unroll
;             for (int kk = 0; kk < 2; ++kk) { ga = __builtin_amdgcn_mfma_f32_16x16x32_bf16(WaF[kk], Xf[tb][kk], ga, 0, 0, 0); gx = __builtin_amdgcn_mfma_f32_16x16x32_bf16(WxF[kk], Xf[tb][kk], gx, 0, 0, 0); }
;             float hv[4], pv[4];
; #pragma unroll
;             for (int r = 0; r < 4; ++r) {
;                 const float rg = sigmoidf_(ga[r] + bav[r]), ig = sigmoidf_(gx[r] + bxv[r]);
;                 const float la = -8.0f * rg * sp[r]; float A = __expf(la);
;                 float U = __builtin_amdgcn_sqrtf(1.0f - A * A) * (ig * xcf[tok * 65 + j0 + r]);
;                 { const float As = dpp_shr1<1>(A), Us = dpp_shr0<1>(U); U = A * Us + U; A = A * As; }
;                 { const float As = dpp_shr1<2>(A), Us = dpp_shr0<2>(U); U = A * Us + U; A = A * As; }
;                 { const float As = dpp_shr1<4>(A), Us = dpp_shr0<4>(U); U = A * Us + U; A = A * As; }
;                 { const float As = dpp_shr1<8>(A), Us = dpp_shr0<8>(U); U = A * Us + U; A = A * As; }
;                 const float hh = U + A * hc[r], PP = A * Pc[r];
;                 hc[r] = bcast15(hh, lane); Pc[r] = bcast15(PP, lane); hv[r] = hh; pv[r] = PP; }
;             *(unsigned long long*)(y + (size_t)(row0 + tok) * DM + 64 * h + j0) = (unsigned long long)pk2(hv[0], hv[1]) | ((unsigned long long)pk2(hv[2], hv[3]) << 32);
	v_pk_mul_f32 v[88:89], v[130:131], v[88:89]
	ds_bpermute_b32 v112, v1, v88
	ds_bpermute_b32 v113, v1, v89
	v_cvt_pk_bf16_f32 v88, v88, v89
	v_pk_mul_f32 v[94:95], v[132:133], v[94:95]
	s_nop 0
	v_pk_mul_f32 v[94:95], v[94:95], v[118:119]
	s_nop 1
	v_mov_b32_dpp v118, v94 row_shr:1 row_mask:0xf bank_mask:0xf bound_ctrl:1
	v_mov_b32_dpp v119, v95 row_shr:1 row_mask:0xf bank_mask:0xf bound_ctrl:1
	v_pk_fma_f32 v[94:95], v[110:111], v[118:119], v[94:95]
	s_nop 1
	v_mov_b32_dpp v110, v94 row_shr:2 row_mask:0xf bank_mask:0xf bound_ctrl:1
	v_mov_b32_dpp v111, v95 row_shr:2 row_mask:0xf bank_mask:0xf bound_ctrl:1
	v_pk_fma_f32 v[94:95], v[122:123], v[110:111], v[94:95]
	v_mov_b32_e32 v122, 1.0
	v_mov_b32_e32 v123, 1.0
	v_mov_b32_dpp v110, v94 row_shr:4 row_mask:0xf bank_mask:0xf bound_ctrl:1
	v_mov_b32_dpp v111, v95 row_shr:4 row_mask:0xf bank_mask:0xf bound_ctrl:1
	v_pk_fma_f32 v[94:95], v[126:127], v[110:111], v[94:95]
	s_nop 1
	v_mov_b32_dpp v110, v94 row_shr:8 row_mask:0xf bank_mask:0xf bound_ctrl:1
	v_mov_b32_dpp v111, v95 row_shr:8 row_mask:0xf bank_mask:0xf bound_ctrl:1
	v_pk_fma_f32 v[94:95], v[128:129], v[110:111], v[94:95]
	s_nop 0
	v_pk_fma_f32 v[92:93], v[130:131], v[92:93], v[94:95]
	v_add_f32_e32 v94, v50, v124
	v_mul_f32_e32 v94, 0xbfb8aa3b, v94
	v_exp_f32_e32 v94, v94
	ds_bpermute_b32 v110, v1, v92
	ds_bpermute_b32 v111, v1, v93
	v_cvt_pk_bf16_f32 v92, v92, v93
	v_add_f32_e32 v94, 1.0, v94
	v_rcp_f32_e32 v95, v94
	v_add_f32_e32 v94, v46, v120
	v_mul_f32_e32 v94, 0xbfb8aa3b, v94
	v_exp_f32_e32 v94, v94
	v_mul_f32_e32 v95, 0xc1000000, v95
	v_mul_f32_e32 v95, v135, v95
	v_mul_f32_e32 v95, 0x3fb8aa3b, v95
	v_exp_f32_e32 v118, v95
	v_add_f32_e32 v94, 1.0, v94
	v_rcp_f32_e32 v94, v94
	v_fma_f32 v95, -v118, v118, 1.0
	v_sqrt_f32_e32 v120, v95
	v_add_f32_e32 v95, v51, v125
	v_mul_f32_e32 v95, 0xbfb8aa3b, v95
	v_exp_f32_e32 v95, v95
	v_mov_b32_dpp v122, v118 row_shr:1 row_mask:0xf bank_mask:0xf
	v_add_f32_e32 v95, 1.0, v95
	v_rcp_f32_e32 v119, v95
	v_add_f32_e32 v95, v47, v121
	v_mul_f32_e32 v95, 0xbfb8aa3b, v95
	v_exp_f32_e32 v95, v95
	v_mul_f32_e32 v119, 0xc1000000, v119
	v_mul_f32_e32 v119, v136, v119
	v_mul_f32_e32 v119, 0x3fb8aa3b, v119
	v_exp_f32_e32 v119, v119
	v_add_f32_e32 v95, 1.0, v95
	v_rcp_f32_e32 v95, v95
	v_mov_b32_dpp v123, v119 row_shr:1 row_mask:0xf bank_mask:0xf
	v_pk_mul_f32 v[124:125], v[118:119], v[122:123]
	v_mov_b32_e32 v122, 1.0
	v_mov_b32_e32 v123, 1.0
	v_fma_f32 v121, -v119, v119, 1.0
	v_mov_b32_dpp v122, v124 row_shr:2 row_mask:0xf bank_mask:0xf
	v_mov_b32_dpp v123, v125 row_shr:2 row_mask:0xf bank_mask:0xf
	v_pk_mul_f32 v[126:127], v[124:125], v[122:123]
	v_mov_b32_e32 v122, 1.0
	v_mov_b32_e32 v123, 1.0
	v_sqrt_f32_e32 v121, v121
	v_mov_b32_dpp v122, v126 row_shr:4 row_mask:0xf bank_mask:0xf
	v_mov_b32_dpp v123, v127 row_shr:4 row_mask:0xf bank_mask:0xf
	v_pk_mul_f32 v[128:129], v[126:127], v[122:123]
	v_mov_b32_e32 v122, 1.0
	v_mov_b32_e32 v123, 1.0
	s_nop 0
	v_mov_b32_dpp v122, v128 row_shr:8 row_mask:0xf bank_mask:0xf
	v_mov_b32_dpp v123, v129 row_shr:8 row_mask:0xf bank_mask:0xf
	v_pk_mul_f32 v[130:131], v[128:129], v[122:123]
	v_add_u32_e32 v123, 0x10c8, v145
	ds_read2_b32 v[132:133], v123 offset1:1
	v_pk_mul_f32 v[90:91], v[130:131], v[90:91]
	ds_bpermute_b32 v122, v1, v90
	v_cvt_pk_bf16_f32 v89, v90, v91
	ds_bpermute_b32 v123, v1, v91
	s_waitcnt lgkmcnt(0)
	v_pk_mul_f32 v[94:95], v[94:95], v[132:133]
	s_nop 0
	v_pk_mul_f32 v[94:95], v[120:121], v[94:95]
	s_nop 1
	v_mov_b32_dpp v120, v94 row_shr:1 row_mask:0xf bank_mask:0xf bound_ctrl:1
	v_mov_b32_dpp v121, v95 row_shr:1 row_mask:0xf bank_mask:0xf bound_ctrl:1
	v_pk_fma_f32 v[94:95], v[118:119], v[120:121], v[94:95]
	s_nop 1
	v_mov_b32_dpp v118, v94 row_shr:2 row_mask:0xf bank_mask:0xf bound_ctrl:1
	v_mov_b32_dpp v119, v95 row_shr:2 row_mask:0xf bank_mask:0xf bound_ctrl:1
	v_pk_fma_f32 v[94:95], v[124:125], v[118:119], v[94:95]
	s_nop 1
	v_mov_b32_dpp v118, v94 row_shr:4 row_mask:0xf bank_mask:0xf bound_ctrl:1
	v_mov_b32_dpp v119, v95 row_shr:4 row_mask:0xf bank_mask:0xf bound_ctrl:1
	v_pk_fma_f32 v[94:95], v[126:127], v[118:119], v[94:95]
	s_nop 1
	v_mov_b32_dpp v118, v94 row_shr:8 row_mask:0xf bank_mask:0xf bound_ctrl:1
	v_mov_b32_dpp v119, v95 row_shr:8 row_mask:0xf bank_mask:0xf bound_ctrl:1
	v_pk_fma_f32 v[94:95], v[128:129], v[118:119], v[94:95]
	v_mfma_f32_16x16x32_bf16 v[118:121], v[60:63], v[8:11], 0
	v_fma_f32 v94, v130, v108, v94
	v_fma_f32 v95, v131, v109, v95
	ds_bpermute_b32 v108, v1, v94
	v_cvt_pk_bf16_f32 v93, v94, v95
	global_store_dwordx2 v[104:105], v[92:93], off offset:64
	global_store_dwordx2 v[106:107], v[88:89], off offset:64
	v_mfma_f32_16x16x32_bf16 v[88:91], v[64:67], v[8:11], 0
	ds_bpermute_b32 v109, v1, v95
	v_mfma_f32_16x16x32_bf16 v[92:95], v[56:59], v[24:27], v[88:91]
	v_mfma_f32_16x16x32_bf16 v[88:91], v[52:55], v[24:27], v[118:121]
	v_mfma_f32_16x16x32_bf16 v[64:67], v[64:67], v[4:7], 0
	s_nop 5
	v_add_f32_e32 v92, v48, v92
	v_mul_f32_e32 v92, 0xbfb8aa3b, v92
	v_exp_f32_e32 v92, v92
	v_add_f32_e32 v88, v44, v88
	v_mul_f32_e32 v88, 0xbfb8aa3b, v88
	v_exp_f32_e32 v88, v88
	v_add_f32_e32 v92, 1.0, v92
	v_rcp_f32_e32 v92, v92
	v_add_f32_e32 v89, v45, v89
	v_add_f32_e32 v88, 1.0, v88
	v_rcp_f32_e32 v118, v88
	v_mul_f32_e32 v88, 0xc1000000, v92
	v_add_f32_e32 v92, v49, v93
	v_mul_f32_e32 v92, 0xbfb8aa3b, v92
	v_exp_f32_e32 v92, v92
	v_mul_f32_e32 v89, 0xbfb8aa3b, v89
	v_exp_f32_e32 v89, v89
	v_mul_f32_e32 v88, v2, v88
	v_add_f32_e32 v92, 1.0, v92
	v_rcp_f32_e32 v92, v92
	v_add_f32_e32 v89, 1.0, v89
	v_rcp_f32_e32 v119, v89
	v_mul_f32_e32 v88, 0x3fb8aa3b, v88
	v_mul_f32_e32 v89, 0xc1000000, v92
	v_mul_f32_e32 v89, v134, v89
; __device__ __forceinline__ float sigmoidf_(float x) { return __builtin_amdgcn_rcpf(1.0f + __expf(-x)); }
; __device__ __forceinline__ void w_lru_m1(const Args& a, int l, unsigned char* ws, const bf16_t* proj, bf16_t* y, LAS unsigned char* wl, int b, int ck_, int h, int lane) {
;     ...
;         for (int tb = 0; tb < 4; ++tb) { const int tok = 16 * tb + lo;
;             f32x4 ga = {0.f, 0.f, 0.f, 0.f}, gx = {0.f, 0.f, 0.f, 0.f};
; #pragma unroll
;             for (int kk = 0; kk < 2; ++kk) { ga = __builtin_amdgcn_mfma_f32_16x16x32_bf16(WaF[kk], Xf[tb][kk], ga, 0, 0, 0); gx = __builtin_amdgcn_mfma_f32_16x16x32_bf16(WxF[kk], Xf[tb][kk], gx, 0, 0, 0); }
;             float hv[4], pv[4];
; #pragma unroll
;             for (int r = 0; r < 4; ++r) {
;                 const float rg = sigmoidf_(ga[r] + bav[r]), ig = sigmoidf_(gx[r] + bxv[r]);
;                 const float la = -8.0f * rg * sp[r]; float A = __expf(la);
;                 float U = __builtin_amdgcn_sqrtf(1.0f - A * A) * (ig * xcf[tok * 65 + j0 + r]);
;                 { const float As = dpp_shr1<1>(A), Us = dpp_shr0<1>(U); U = A * Us + U; A = A * As; }
;                 { const float As = dpp_shr1<2>(A), Us = dpp_shr0<2>(U); U = A * Us + U; A = A * As; }
;                 { const float As = dpp_shr1<4>(A), Us = dpp_shr0<4>(U); U = A * Us + U; A = A * As; }
;                 { const float As = dpp_shr1<8>(A), Us = dpp_shr0<8>(U); U = A * Us + U; A = A * As; }
;                 const float hh = U + A * hc[r], PP = A * Pc[r];
	v_mul_f32_e32 v89, 0x3fb8aa3b, v89
	v_exp_f32_e32 v120, v88
	v_exp_f32_e32 v121, v89
	v_mfma_f32_16x16x32_bf16 v[60:63], v[60:63], v[4:7], 0
	v_add_f32_e32 v94, v50, v94
	v_fma_f32 v88, -v120, v120, 1.0
	v_fma_f32 v89, -v121, v121, 1.0
	v_sqrt_f32_e32 v124, v88
	v_mov_b32_e32 v88, 1.0
	v_sqrt_f32_e32 v125, v89
	v_mov_b32_e32 v89, 1.0
	v_mov_b32_dpp v88, v120 row_shr:1 row_mask:0xf bank_mask:0xf
	v_mfma_f32_16x16x32_bf16 v[56:59], v[56:59], v[20:23], v[64:67]
	v_mov_b32_dpp v89, v121 row_shr:1 row_mask:0xf bank_mask:0xf
	v_pk_mul_f32 v[126:127], v[120:121], v[88:89]
	v_mov_b32_e32 v88, 1.0
	v_mov_b32_e32 v89, 1.0
	v_add_f32_e32 v95, v51, v95
	v_mov_b32_dpp v88, v126 row_shr:2 row_mask:0xf bank_mask:0xf
	v_mov_b32_dpp v89, v127 row_shr:2 row_mask:0xf bank_mask:0xf
	v_pk_mul_f32 v[128:129], v[126:127], v[88:89]
	v_mov_b32_e32 v88, 1.0
	v_mov_b32_e32 v89, 1.0
	v_mul_f32_e32 v94, 0xbfb8aa3b, v94
	v_mov_b32_dpp v88, v128 row_shr:4 row_mask:0xf bank_mask:0xf
	v_mov_b32_dpp v89, v129 row_shr:4 row_mask:0xf bank_mask:0xf
	v_pk_mul_f32 v[130:131], v[128:129], v[88:89]
	v_mov_b32_e32 v88, 1.0
	v_mov_b32_e32 v89, 1.0
	v_mul_f32_e32 v95, 0xbfb8aa3b, v95
	v_mov_b32_dpp v88, v130 row_shr:8 row_mask:0xf bank_mask:0xf
	v_mov_b32_dpp v89, v131 row_shr:8 row_mask:0xf bank_mask:0xf
	v_pk_mul_f32 v[132:133], v[130:131], v[88:89]
	v_add_u32_e32 v89, 0x2100, v145
	v_pk_mul_f32 v[92:93], v[132:133], v[112:113]
	ds_read2_b32 v[112:113], v89 offset1:1
	v_mfma_f32_16x16x32_bf16 v[60:63], v[52:55], v[20:23], v[60:63]
	v_add_f32_e32 v48, v48, v56
	v_exp_f32_e32 v94, v94
	v_exp_f32_e32 v95, v95
	s_waitcnt lgkmcnt(0)
	v_pk_mul_f32 v[112:113], v[112:113], v[118:119]
	v_mul_f32_e32 v48, 0xbfb8aa3b, v48
	v_pk_mul_f32 v[112:113], v[112:113], v[124:125]
	v_exp_f32_e32 v48, v48
	v_add_f32_e32 v90, v46, v90
	v_mov_b32_dpp v118, v112 row_shr:1 row_mask:0xf bank_mask:0xf bound_ctrl:1
	v_mov_b32_dpp v119, v113 row_shr:1 row_mask:0xf bank_mask:0xf bound_ctrl:1
	v_add_f32_e32 v91, v47, v91
	v_pk_fma_f32 v[112:113], v[120:121], v[118:119], v[112:113]
	v_mul_f32_e32 v90, 0xbfb8aa3b, v90
	v_mul_f32_e32 v91, 0xbfb8aa3b, v91
	v_add_f32_e32 v44, v44, v60
	v_mov_b32_dpp v118, v112 row_shr:2 row_mask:0xf bank_mask:0xf bound_ctrl:1
	v_mov_b32_dpp v119, v113 row_shr:2 row_mask:0xf bank_mask:0xf bound_ctrl:1
	v_add_f32_e32 v94, 1.0, v94
	v_exp_f32_e32 v90, v90
	v_add_f32_e32 v95, 1.0, v95
	v_exp_f32_e32 v91, v91
	v_mul_f32_e32 v44, 0xbfb8aa3b, v44
	v_pk_fma_f32 v[112:113], v[126:127], v[118:119], v[112:113]
	v_rcp_f32_e32 v94, v94
	v_rcp_f32_e32 v95, v95
	v_add_f32_e32 v48, 1.0, v48
	v_exp_f32_e32 v44, v44
	v_mov_b32_dpp v118, v112 row_shr:4 row_mask:0xf bank_mask:0xf bound_ctrl:1
	v_mov_b32_dpp v119, v113 row_shr:4 row_mask:0xf bank_mask:0xf bound_ctrl:1
	v_rcp_f32_e32 v52, v48
	v_pk_fma_f32 v[112:113], v[128:129], v[118:119], v[112:113]
	v_add_f32_e32 v90, 1.0, v90
	v_add_f32_e32 v91, 1.0, v91
	v_mov_b32_dpp v118, v112 row_shr:8 row_mask:0xf bank_mask:0xf bound_ctrl:1
	v_mov_b32_dpp v119, v113 row_shr:8 row_mask:0xf bank_mask:0xf bound_ctrl:1
	v_pk_fma_f32 v[112:113], v[130:131], v[118:119], v[112:113]
	v_rcp_f32_e32 v118, v90
	v_mul_f32_e32 v90, 0xc1000000, v94
	v_rcp_f32_e32 v119, v91
	v_mul_f32_e32 v91, 0xc1000000, v95
	v_add_f32_e32 v44, 1.0, v44
	v_mul_f32_e32 v90, v135, v90
	v_mul_f32_e32 v91, v136, v91
	v_rcp_f32_e32 v48, v44
	v_mul_f32_e32 v44, 0xc1000000, v52
	v_mul_f32_e32 v90, 0x3fb8aa3b, v90
	v_mul_f32_e32 v91, 0x3fb8aa3b, v91
	v_mul_f32_e32 v2, v2, v44
	v_exp_f32_e32 v94, v90
	v_exp_f32_e32 v95, v91
	v_mul_f32_e32 v2, 0x3fb8aa3b, v2
	v_exp_f32_e32 v54, v2
	v_fma_f32 v90, -v94, v94, 1.0
	v_fma_f32 v91, -v95, v95, 1.0
	v_sqrt_f32_e32 v120, v90
	v_mov_b32_e32 v90, 1.0
	v_sqrt_f32_e32 v121, v91
	v_mov_b32_e32 v91, 1.0
	v_fma_f32 v2, -v54, v54, 1.0
	v_mov_b32_dpp v90, v94 row_shr:1 row_mask:0xf bank_mask:0xf
	v_mov_b32_dpp v91, v95 row_shr:1 row_mask:0xf bank_mask:0xf
	v_sqrt_f32_e32 v56, v2
	v_add_f32_e32 v2, v49, v57
	v_pk_mul_f32 v[124:125], v[94:95], v[90:91]
	v_mov_b32_e32 v90, 1.0
	v_mov_b32_e32 v91, 1.0
	v_mul_f32_e32 v2, 0xbfb8aa3b, v2
	v_mov_b32_dpp v90, v124 row_shr:2 row_mask:0xf bank_mask:0xf
	v_mov_b32_dpp v91, v125 row_shr:2 row_mask:0xf bank_mask:0xf
	v_exp_f32_e32 v2, v2
	v_pk_mul_f32 v[126:127], v[124:125], v[90:91]
	v_mov_b32_e32 v90, 1.0
	v_mov_b32_e32 v91, 1.0
	v_add_f32_e32 v2, 1.0, v2
	v_mov_b32_dpp v90, v126 row_shr:4 row_mask:0xf bank_mask:0xf
	v_mov_b32_dpp v91, v127 row_shr:4 row_mask:0xf bank_mask:0xf
	v_pk_mul_f32 v[128:129], v[126:127], v[90:91]
	v_mov_b32_e32 v90, 1.0
	v_mov_b32_e32 v91, 1.0
	v_rcp_f32_e32 v2, v2
	v_mov_b32_dpp v90, v128 row_shr:8 row_mask:0xf bank_mask:0xf
	v_mov_b32_dpp v91, v129 row_shr:8 row_mask:0xf bank_mask:0xf
	v_pk_mul_f32 v[130:131], v[128:129], v[90:91]
	v_add_u32_e32 v91, 0x2108, v145
	v_pk_fma_f32 v[112:113], v[132:133], v[110:111], v[112:113]
	ds_read2_b32 v[132:133], v91 offset1:1
	v_add_f32_e32 v45, v45, v61
	v_mul_f32_e32 v45, 0xbfb8aa3b, v45
	v_mul_f32_e32 v2, 0xc1000000, v2
	v_exp_f32_e32 v45, v45
	v_mul_f32_e32 v2, v134, v2
	s_waitcnt lgkmcnt(0)
; __device__ __forceinline__ unsigned pk2(float lo, float hi) { const f32x2_t v = {lo, hi}; const bf16x2_t b = __builtin_convertvector(v, bf16x2_t); return __builtin_bit_cast(unsigned, b); }
; __device__ __forceinline__ float sigmoidf_(float x) { return __builtin_amdgcn_rcpf(1.0f + __expf(-x)); }
; __device__ __forceinline__ float bcast15(float v, int lane) { return bperm_f((lane & 48) | 15, v); }
; __device__ __forceinline__ void w_lru_m1(const Args& a, int l, unsigned char* ws, const bf16_t* proj, bf16_t* y, LAS unsigned char* wl, int b, int ck_, int h, int lane) {
;     ...
;             for (int r = 0; r < 4; ++r) {
;                 const float rg = sigmoidf_(ga[r] + bav[r]), ig = sigmoidf_(gx[r] + bxv[r]);
;                 const float la = -8.0f * rg * sp[r]; float A = __expf(la);
;                 float U = __builtin_amdgcn_sqrtf(1.0f - A * A) * (ig * xcf[tok * 65 + j0 + r]);
;                 { const float As = dpp_shr1<1>(A), Us = dpp_shr0<1>(U); U = A * Us + U; A = A * As; }
;                 { const float As = dpp_shr1<2>(A), Us = dpp_shr0<2>(U); U = A * Us + U; A = A * As; }
;                 { const float As = dpp_shr1<4>(A), Us = dpp_shr0<4>(U); U = A * Us + U; A = A * As; }
;                 { const float As = dpp_shr1<8>(A), Us = dpp_shr0<8>(U); U = A * Us + U; A = A * As; }
;                 const float hh = U + A * hc[r], PP = A * Pc[r];
;                 hc[r] = bcast15(hh, lane); Pc[r] = bcast15(PP, lane); hv[r] = hh; pv[r] = PP; }
;             *(unsigned long long*)(y + (size_t)(row0 + tok) * DM + 64 * h + j0) = (unsigned long long)pk2(hv[0], hv[1]) | ((unsigned long long)pk2(hv[2], hv[3]) << 32);
;             *(unsigned long long*)((bf16_t*)(ws + WS_P) + (size_t)(row0 + tok) * 512 + 64 * h + j0) = (unsigned long long)pk2(pv[0], pv[1]) | ((unsigned long long)pk2(pv[2], pv[3]) << 32);
	v_pk_mul_f32 v[118:119], v[118:119], v[132:133]
	v_mul_f32_e32 v2, 0x3fb8aa3b, v2
	v_pk_mul_f32 v[118:119], v[120:121], v[118:119]
	v_exp_f32_e32 v55, v2
	v_add_f32_e32 v45, 1.0, v45
	v_mov_b32_dpp v120, v118 row_shr:1 row_mask:0xf bank_mask:0xf bound_ctrl:1
	v_mov_b32_dpp v121, v119 row_shr:1 row_mask:0xf bank_mask:0xf bound_ctrl:1
	v_pk_fma_f32 v[94:95], v[94:95], v[120:121], v[118:119]
	v_mov_b32_e32 v44, 1.0
	v_rcp_f32_e32 v49, v45
	v_mov_b32_dpp v118, v94 row_shr:2 row_mask:0xf bank_mask:0xf bound_ctrl:1
	v_mov_b32_dpp v119, v95 row_shr:2 row_mask:0xf bank_mask:0xf bound_ctrl:1
	v_mov_b32_e32 v45, 1.0
	v_pk_fma_f32 v[94:95], v[124:125], v[118:119], v[94:95]
	v_mov_b32_dpp v44, v54 row_shr:1 row_mask:0xf bank_mask:0xf
	v_mov_b32_dpp v45, v55 row_shr:1 row_mask:0xf bank_mask:0xf
	v_mov_b32_dpp v118, v94 row_shr:4 row_mask:0xf bank_mask:0xf bound_ctrl:1
	v_mov_b32_dpp v119, v95 row_shr:4 row_mask:0xf bank_mask:0xf bound_ctrl:1
	v_pk_mul_f32 v[60:61], v[54:55], v[44:45]
	v_mov_b32_e32 v44, 1.0
	v_mov_b32_e32 v45, 1.0
	v_pk_fma_f32 v[94:95], v[126:127], v[118:119], v[94:95]
	v_mov_b32_dpp v44, v60 row_shr:2 row_mask:0xf bank_mask:0xf
	v_mov_b32_dpp v45, v61 row_shr:2 row_mask:0xf bank_mask:0xf
	ds_bpermute_b32 v88, v1, v92
	ds_bpermute_b32 v89, v1, v93
	v_mov_b32_dpp v118, v94 row_shr:8 row_mask:0xf bank_mask:0xf bound_ctrl:1
	v_mov_b32_dpp v119, v95 row_shr:8 row_mask:0xf bank_mask:0xf bound_ctrl:1
	v_pk_mul_f32 v[64:65], v[60:61], v[44:45]
	v_mov_b32_e32 v44, 1.0
	v_mov_b32_e32 v45, 1.0
	v_pk_fma_f32 v[94:95], v[128:129], v[118:119], v[94:95]
	v_mov_b32_dpp v44, v64 row_shr:4 row_mask:0xf bank_mask:0xf
	v_mov_b32_dpp v45, v65 row_shr:4 row_mask:0xf bank_mask:0xf
	v_pk_mul_f32 v[122:123], v[130:131], v[122:123]
	v_pk_fma_f32 v[108:109], v[130:131], v[108:109], v[94:95]
	v_pk_mul_f32 v[66:67], v[64:65], v[44:45]
	v_mov_b32_e32 v44, 1.0
	v_mov_b32_e32 v45, 1.0
	ds_bpermute_b32 v110, v1, v112
	ds_bpermute_b32 v111, v1, v113
	v_cvt_pk_bf16_f32 v112, v112, v113
	v_cvt_pk_bf16_f32 v113, v108, v109
	v_cvt_pk_bf16_f32 v92, v92, v93
	v_cvt_pk_bf16_f32 v93, v122, v123
	v_fma_f32 v2, -v55, v55, 1.0
	v_mov_b32_dpp v44, v66 row_shr:8 row_mask:0xf bank_mask:0xf
	v_mov_b32_dpp v45, v67 row_shr:8 row_mask:0xf bank_mask:0xf
	global_store_dwordx2 v[96:97], v[112:113], off offset:64
	global_store_dwordx2 v[98:99], v[92:93], off offset:64
	v_sqrt_f32_e32 v57, v2
	v_pk_mul_f32 v[92:93], v[66:67], v[44:45]
	v_add_u32_e32 v2, 0x3140, v145
	s_waitcnt lgkmcnt(0)
	v_pk_mul_f32 v[52:53], v[92:93], v[88:89]
	ds_read2_b32 v[88:89], v2 offset1:1
	v_add_f32_e32 v2, v50, v58
	v_mul_f32_e32 v2, 0xbfb8aa3b, v2
	v_exp_f32_e32 v2, v2
	v_add_f32_e32 v46, v46, v62
	v_add_f32_e32 v47, v47, v63
	v_mul_f32_e32 v46, 0xbfb8aa3b, v46
	v_add_f32_e32 v2, 1.0, v2
	v_rcp_f32_e32 v2, v2
	v_mul_f32_e32 v47, 0xbfb8aa3b, v47
	v_exp_f32_e32 v46, v46
	v_exp_f32_e32 v47, v47
	v_mul_f32_e32 v2, 0xc1000000, v2
	v_mul_f32_e32 v2, v135, v2
	v_mul_f32_e32 v2, 0x3fb8aa3b, v2
	v_exp_f32_e32 v50, v2
	s_waitcnt lgkmcnt(0)
	v_pk_mul_f32 v[48:49], v[88:89], v[48:49]
	v_add_f32_e32 v46, 1.0, v46
	v_pk_mul_f32 v[48:49], v[48:49], v[56:57]
	v_fma_f32 v2, -v50, v50, 1.0
	v_sqrt_f32_e32 v58, v2
	v_add_f32_e32 v2, v51, v59
	v_mul_f32_e32 v2, 0xbfb8aa3b, v2
	v_exp_f32_e32 v2, v2
	v_mov_b32_dpp v56, v48 row_shr:1 row_mask:0xf bank_mask:0xf bound_ctrl:1
	v_mov_b32_dpp v57, v49 row_shr:1 row_mask:0xf bank_mask:0xf bound_ctrl:1
	v_add_f32_e32 v47, 1.0, v47
	v_add_f32_e32 v2, 1.0, v2
	v_rcp_f32_e32 v2, v2
	v_pk_fma_f32 v[48:49], v[54:55], v[56:57], v[48:49]
	v_rcp_f32_e32 v56, v46
	v_mov_b32_e32 v46, 1.0
	v_mul_f32_e32 v2, 0xc1000000, v2
	v_mul_f32_e32 v2, v136, v2
	v_mul_f32_e32 v2, 0x3fb8aa3b, v2
	v_exp_f32_e32 v51, v2
	v_rcp_f32_e32 v57, v47
	v_mov_b32_e32 v47, 1.0
	v_mov_b32_dpp v54, v48 row_shr:2 row_mask:0xf bank_mask:0xf bound_ctrl:1
	v_mov_b32_dpp v55, v49 row_shr:2 row_mask:0xf bank_mask:0xf bound_ctrl:1
	v_mov_b32_dpp v46, v50 row_shr:1 row_mask:0xf bank_mask:0xf
	v_mov_b32_dpp v47, v51 row_shr:1 row_mask:0xf bank_mask:0xf
	v_pk_fma_f32 v[48:49], v[60:61], v[54:55], v[48:49]
	v_pk_mul_f32 v[62:63], v[50:51], v[46:47]
	v_mov_b32_e32 v46, 1.0
	v_mov_b32_e32 v47, 1.0
	v_mov_b32_dpp v54, v48 row_shr:4 row_mask:0xf bank_mask:0xf bound_ctrl:1
	v_mov_b32_dpp v55, v49 row_shr:4 row_mask:0xf bank_mask:0xf bound_ctrl:1
	v_mov_b32_dpp v46, v62 row_shr:2 row_mask:0xf bank_mask:0xf
	v_mov_b32_dpp v47, v63 row_shr:2 row_mask:0xf bank_mask:0xf
	ds_bpermute_b32 v90, v1, v122
	ds_bpermute_b32 v91, v1, v123
	v_pk_fma_f32 v[48:49], v[64:65], v[54:55], v[48:49]
	v_pk_mul_f32 v[64:65], v[62:63], v[46:47]
	v_mov_b32_e32 v46, 1.0
	v_mov_b32_e32 v47, 1.0
	v_mov_b32_dpp v54, v48 row_shr:8 row_mask:0xf bank_mask:0xf bound_ctrl:1
	v_mov_b32_dpp v55, v49 row_shr:8 row_mask:0xf bank_mask:0xf bound_ctrl:1
	v_mov_b32_dpp v46, v64 row_shr:4 row_mask:0xf bank_mask:0xf
	v_mov_b32_dpp v47, v65 row_shr:4 row_mask:0xf bank_mask:0xf
	v_pk_fma_f32 v[48:49], v[66:67], v[54:55], v[48:49]
	v_pk_mul_f32 v[66:67], v[64:65], v[46:47]
	v_mov_b32_e32 v46, 1.0
	v_mov_b32_e32 v47, 1.0
	v_fma_f32 v2, -v51, v51, 1.0
	v_mov_b32_dpp v46, v66 row_shr:8 row_mask:0xf bank_mask:0xf
	v_mov_b32_dpp v47, v67 row_shr:8 row_mask:0xf bank_mask:0xf
	v_sqrt_f32_e32 v59, v2
	v_pk_mul_f32 v[88:89], v[66:67], v[46:47]
	v_add_u32_e32 v2, 0x3148, v145
	s_waitcnt lgkmcnt(0)
	v_pk_mul_f32 v[60:61], v[88:89], v[90:91]
	ds_read2_b32 v[90:91], v2 offset1:1
	ds_bpermute_b32 v94, v1, v108
	ds_bpermute_b32 v95, v1, v109
	v_pk_fma_f32 v[54:55], v[92:93], v[110:111], v[48:49]
	ds_bpermute_b32 v44, v1, v52
	s_waitcnt lgkmcnt(0)
; __device__ __forceinline__ unsigned pk2(float lo, float hi) { const f32x2_t v = {lo, hi}; const bf16x2_t b = __builtin_convertvector(v, bf16x2_t); return __builtin_bit_cast(unsigned, b); }
; __device__ __forceinline__ float bcast15(float v, int lane) { return bperm_f((lane & 48) | 15, v); }
; __device__ __forceinline__ void w_lru_m1(const Args& a, int l, unsigned char* ws, const bf16_t* proj, bf16_t* y, LAS unsigned char* wl, int b, int ck_, int h, int lane) {
;     ...
;         for (int r = 0; r < 4; ++r) { bav[r] = pba[r]; bxv[r] = pbx[r]; sp[r] = log1pf(__expf(-plam[r])); hc[r] = 0.f; Pc[r] = 1.f; }
;     ...
;                 { const float As = dpp_shr1<1>(A), Us = dpp_shr0<1>(U); U = A * Us + U; A = A * As; }
;                 { const float As = dpp_shr1<2>(A), Us = dpp_shr0<2>(U); U = A * Us + U; A = A * As; }
;                 { const float As = dpp_shr1<4>(A), Us = dpp_shr0<4>(U); U = A * Us + U; A = A * As; }
;                 { const float As = dpp_shr1<8>(A), Us = dpp_shr0<8>(U); U = A * Us + U; A = A * As; }
;                 const float hh = U + A * hc[r], PP = A * Pc[r];
;                 hc[r] = bcast15(hh, lane); Pc[r] = bcast15(PP, lane); hv[r] = hh; pv[r] = PP; }
;             *(unsigned long long*)(y + (size_t)(row0 + tok) * DM + 64 * h + j0) = (unsigned long long)pk2(hv[0], hv[1]) | ((unsigned long long)pk2(hv[2], hv[3]) << 32);
;             *(unsigned long long*)((bf16_t*)(ws + WS_P) + (size_t)(row0 + tok) * 512 + 64 * h + j0) = (unsigned long long)pk2(pv[0], pv[1]) | ((unsigned long long)pk2(pv[2], pv[3]) << 32);
;         }
;         if (lo == 0) { const size_t so = (size_t)(b * NCH + ck_) * 512 + 64 * h + j0;
; #pragma unroll
;             for (int r = 0; r < 4; ++r) { ((float*)(ws + WS_LRUA))[so + r] = Pc[r]; ((float*)(ws + WS_LRUH))[so + r] = hc[r]; } }
	v_pk_mul_f32 v[56:57], v[56:57], v[90:91]
	ds_bpermute_b32 v48, v1, v54
	v_pk_mul_f32 v[56:57], v[58:59], v[56:57]
	ds_bpermute_b32 v49, v1, v55
	ds_bpermute_b32 v45, v1, v53
	v_mov_b32_dpp v58, v56 row_shr:1 row_mask:0xf bank_mask:0xf bound_ctrl:1
	v_mov_b32_dpp v59, v57 row_shr:1 row_mask:0xf bank_mask:0xf bound_ctrl:1
	v_pk_fma_f32 v[50:51], v[50:51], v[58:59], v[56:57]
	ds_bpermute_b32 v46, v1, v60
	ds_bpermute_b32 v47, v1, v61
	v_mov_b32_dpp v56, v50 row_shr:2 row_mask:0xf bank_mask:0xf bound_ctrl:1
	v_mov_b32_dpp v57, v51 row_shr:2 row_mask:0xf bank_mask:0xf bound_ctrl:1
	v_pk_fma_f32 v[50:51], v[62:63], v[56:57], v[50:51]
	v_cvt_pk_bf16_f32 v54, v54, v55
	v_cvt_pk_bf16_f32 v52, v52, v53
	v_mov_b32_dpp v56, v50 row_shr:4 row_mask:0xf bank_mask:0xf bound_ctrl:1
	v_mov_b32_dpp v57, v51 row_shr:4 row_mask:0xf bank_mask:0xf bound_ctrl:1
	v_pk_fma_f32 v[50:51], v[64:65], v[56:57], v[50:51]
	v_cvt_pk_bf16_f32 v53, v60, v61
	s_nop 0
	v_mov_b32_dpp v56, v50 row_shr:8 row_mask:0xf bank_mask:0xf bound_ctrl:1
	v_mov_b32_dpp v57, v51 row_shr:8 row_mask:0xf bank_mask:0xf bound_ctrl:1
	v_pk_fma_f32 v[50:51], v[66:67], v[56:57], v[50:51]
	s_nop 0
	v_pk_fma_f32 v[56:57], v[88:89], v[94:95], v[50:51]
	ds_bpermute_b32 v50, v1, v56
	ds_bpermute_b32 v51, v1, v57
	v_cvt_pk_bf16_f32 v55, v56, v57
	global_store_dwordx2 v[114:115], v[54:55], off offset:64
	global_store_dwordx2 v[116:117], v[52:53], off offset:64
	s_and_saveexec_b64 s[34:35], vcc
	s_cbranch_execz .LBB0_527
	v_add_u32_e32 v52, 32, v0
	v_ashrrev_i32_e32 v53, 31, v52
	v_lshl_add_u64 v[52:53], s[42:43], 0, v[52:53]
	v_lshlrev_b64 v[52:53], 2, v[52:53]
	v_lshl_add_u64 v[54:55], s[84:85], 0, v[52:53]
	v_lshl_add_u64 v[52:53], s[86:87], 0, v[52:53]
	s_waitcnt lgkmcnt(0)
	global_store_dwordx4 v[54:55], v[44:47], off
	global_store_dwordx4 v[52:53], v[48:51], off
.LBB0_527:
	s_or_b64 exec, exec, s[34:35]
	s_waitcnt vmcnt(8)
	v_mul_f32_e32 v2, 0xbfb8aa3b, v84
	v_exp_f32_e32 v2, v2
	ds_read2_b32 v[64:65], v145 offset0:50 offset1:51
	s_waitcnt lgkmcnt(0)
	v_add_f32_e32 v46, 1.0, v2
	v_add_f32_e32 v44, -1.0, v46
	v_sub_f32_e32 v45, v44, v46
	v_add_f32_e32 v45, 1.0, v45
	v_sub_f32_e32 v44, v2, v44
	v_add_f32_e32 v47, v44, v45
	v_frexp_mant_f32_e32 v44, v46
	v_cmp_gt_f32_e64 s[40:41], s77, v44
	v_cvt_f64_f32_e32 v[44:45], v46
	v_frexp_exp_i32_f64_e32 v44, v[44:45]
	v_subbrev_co_u32_e64 v52, s[40:41], 0, v44, s[40:41]
	v_sub_u32_e32 v44, 0, v52
	v_ldexp_f32 v45, v46, v44
	v_add_f32_e32 v46, -1.0, v45
	v_add_f32_e32 v48, 1.0, v45
	v_ldexp_f32 v44, v47, v44
	v_add_f32_e32 v47, 1.0, v46
	v_add_f32_e32 v49, -1.0, v48
	v_sub_f32_e32 v47, v45, v47
	v_sub_f32_e32 v45, v45, v49
	v_add_f32_e32 v47, v44, v47
	v_add_f32_e32 v44, v44, v45
	v_add_f32_e32 v53, v48, v44
	v_rcp_f32_e32 v55, v53
	v_sub_f32_e32 v45, v53, v48
	v_sub_f32_e32 v54, v44, v45
	v_add_f32_e32 v45, v46, v47
	v_mul_f32_e32 v57, v45, v55
	v_sub_f32_e32 v44, v45, v46
	v_mul_f32_e32 v46, v53, v57
	v_fma_f32 v48, v57, v53, -v46
	v_fmac_f32_e32 v48, v57, v54
	v_sub_f32_e32 v56, v47, v44
	v_add_f32_e32 v44, v46, v48
	v_sub_f32_e32 v47, v45, v44
	v_pk_add_f32 v[50:51], v[44:45], v[46:47] neg_lo:[0,1] neg_hi:[0,1]
	v_mov_b32_e32 v49, v44
	v_pk_add_f32 v[44:45], v[50:51], v[48:49] neg_lo:[0,1] neg_hi:[0,1]
	v_cmp_neq_f32_e64 s[40:41], s22, v2
	v_add_f32_e32 v45, v56, v45
	v_add_f32_e32 v44, v44, v45
	v_add_f32_e32 v45, v47, v44
	v_mul_f32_e32 v56, v55, v45
	v_mul_f32_e32 v46, v53, v56
	v_fma_f32 v48, v56, v53, -v46
	v_fmac_f32_e32 v48, v56, v54
	v_sub_f32_e32 v47, v47, v45
	v_add_f32_e32 v53, v44, v47
	v_add_f32_e32 v44, v46, v48
	v_sub_f32_e32 v47, v45, v44
	v_pk_add_f32 v[50:51], v[44:45], v[46:47] neg_lo:[0,1] neg_hi:[0,1]
	v_mov_b32_e32 v49, v44
	v_pk_add_f32 v[44:45], v[50:51], v[48:49] neg_lo:[0,1] neg_hi:[0,1]
	s_nop 0
	v_add_f32_e32 v45, v53, v45
	v_add_f32_e32 v44, v44, v45
	v_add_f32_e32 v45, v57, v56
	v_add_f32_e32 v44, v47, v44
	v_sub_f32_e32 v46, v45, v57
	v_mul_f32_e32 v44, v55, v44
	v_sub_f32_e32 v46, v56, v46
	v_add_f32_e32 v46, v46, v44
	v_add_f32_e32 v48, v45, v46
	v_mul_f32_e32 v49, v48, v48
	v_fmamk_f32 v44, v49, 0x3e9b6dac, v201
	v_fmaak_f32 v169, v49, v44, 0x3f2aaada
	v_cvt_f32_i32_e32 v44, v52
	v_sub_f32_e32 v45, v48, v45
	v_sub_f32_e32 v45, v46, v45
	v_ldexp_f32 v50, v45, 1
	v_mul_f32_e32 v45, v48, v49
	v_ldexp_f32 v47, v48, 1
	v_pk_mul_f32 v[48:49], v[44:45], v[168:169]
	s_nop 0
	v_fma_f32 v46, v44, s94, -v48
	v_fmac_f32_e32 v46, 0xb102e308, v44
	v_pk_add_f32 v[44:45], v[48:49], v[46:47]
	s_nop 0
	v_sub_f32_e32 v47, v45, v47
	v_sub_f32_e32 v47, v49, v47
	v_add_f32_e32 v51, v50, v47
	v_mov_b32_e32 v50, v48
	v_pk_add_f32 v[48:49], v[44:45], v[48:49] neg_lo:[0,1] neg_hi:[0,1]
	v_pk_add_f32 v[52:53], v[44:45], v[50:51]
	v_mov_b32_e32 v47, v44
	v_mov_b32_e32 v49, v53
	v_pk_add_f32 v[54:55], v[46:47], v[48:49] neg_lo:[0,1] neg_hi:[0,1]
	v_pk_add_f32 v[46:47], v[46:47], v[48:49]
	v_mov_b32_e32 v50, v51
	v_pk_add_f32 v[48:49], v[46:47], v[44:45] op_sel:[1,0] op_sel_hi:[0,1] neg_lo:[0,1] neg_hi:[0,1]
	v_pk_add_f32 v[56:57], v[52:53], v[48:49] op_sel_hi:[1,0] neg_lo:[0,1] neg_hi:[0,1]
	v_mov_b32_e32 v52, v53
	v_mov_b32_e32 v53, v47
	v_pk_mov_b32 v[48:49], v[44:45], v[48:49] op_sel:[1,0]
	v_mov_b32_e32 v51, v44
	v_pk_add_f32 v[48:49], v[52:53], v[48:49] neg_lo:[0,1] neg_hi:[0,1]
	v_mov_b32_e32 v56, v54
	v_pk_add_f32 v[44:45], v[50:51], v[48:49] neg_lo:[0,1] neg_hi:[0,1]
	v_mov_b32_e32 v55, v47
	v_pk_add_f32 v[48:49], v[56:57], v[44:45]
	s_nop 0
	v_pk_add_f32 v[50:51], v[48:49], v[48:49] op_sel:[0,1] op_sel_hi:[1,0]
	s_nop 0
	v_pk_add_f32 v[46:47], v[46:47], v[50:51] op_sel:[1,0] op_sel_hi:[0,1]
	v_mov_b32_e32 v49, v46
; __device__ __forceinline__ void w_lru_m1(const Args& a, int l, unsigned char* ws, const bf16_t* proj, bf16_t* y, LAS unsigned char* wl, int b, int ck_, int h, int lane) {
;     ...
;         for (int r = 0; r < 4; ++r) { bav[r] = pba[r]; bxv[r] = pbx[r]; sp[r] = log1pf(__expf(-plam[r])); hc[r] = 0.f; Pc[r] = 1.f; }
	v_pk_add_f32 v[52:53], v[48:49], v[54:55] neg_lo:[0,1] neg_hi:[0,1]
	v_mov_b32_e32 v45, v50
	v_sub_f32_e32 v47, v48, v52
	v_pk_add_f32 v[44:45], v[44:45], v[52:53] neg_lo:[0,1] neg_hi:[0,1]
	v_sub_f32_e32 v47, v54, v47
	v_add_f32_e32 v44, v44, v47
	v_add_f32_e32 v44, v44, v45
	v_add_f32_e32 v44, v46, v44
	v_cndmask_b32_e64 v44, v208, v44, s[40:41]
	v_cmp_ngt_f32_e64 s[40:41], -1.0, v2
	s_nop 1
	v_cndmask_b32_e64 v44, v205, v44, s[40:41]
	v_cmp_neq_f32_e64 s[40:41], -1.0, v2
	s_nop 1
	v_cndmask_b32_e64 v44, v206, v44, s[40:41]
	v_cmp_lt_f32_e64 s[40:41], |v2|, s95
	s_nop 1
	v_cndmask_b32_e64 v58, v44, v2, s[40:41]
	v_mul_f32_e32 v2, 0xbfb8aa3b, v85
	v_exp_f32_e32 v2, v2
	s_nop 0
	v_add_f32_e32 v46, 1.0, v2
	v_add_f32_e32 v44, -1.0, v46
	v_sub_f32_e32 v45, v44, v46
	v_add_f32_e32 v45, 1.0, v45
	v_sub_f32_e32 v44, v2, v44
	v_add_f32_e32 v47, v44, v45
	v_frexp_mant_f32_e32 v44, v46
	v_cmp_gt_f32_e64 s[40:41], s77, v44
	v_cvt_f64_f32_e32 v[44:45], v46
	v_frexp_exp_i32_f64_e32 v44, v[44:45]
	v_subbrev_co_u32_e64 v52, s[40:41], 0, v44, s[40:41]
	v_sub_u32_e32 v44, 0, v52
	v_ldexp_f32 v45, v46, v44
	v_add_f32_e32 v46, -1.0, v45
	v_add_f32_e32 v48, 1.0, v45
	v_ldexp_f32 v44, v47, v44
	v_add_f32_e32 v47, 1.0, v46
	v_add_f32_e32 v49, -1.0, v48
	v_sub_f32_e32 v47, v45, v47
	v_sub_f32_e32 v45, v45, v49
	v_add_f32_e32 v47, v44, v47
	v_add_f32_e32 v44, v44, v45
	v_add_f32_e32 v53, v48, v44
	v_rcp_f32_e32 v55, v53
	v_sub_f32_e32 v45, v53, v48
	v_sub_f32_e32 v54, v44, v45
	v_add_f32_e32 v45, v46, v47
	v_mul_f32_e32 v57, v45, v55
	v_sub_f32_e32 v44, v45, v46
	v_mul_f32_e32 v46, v53, v57
	v_fma_f32 v48, v57, v53, -v46
	v_fmac_f32_e32 v48, v57, v54
	v_sub_f32_e32 v56, v47, v44
	v_add_f32_e32 v44, v46, v48
	v_sub_f32_e32 v47, v45, v44
	v_pk_add_f32 v[50:51], v[44:45], v[46:47] neg_lo:[0,1] neg_hi:[0,1]
	v_mov_b32_e32 v49, v44
	v_pk_add_f32 v[44:45], v[50:51], v[48:49] neg_lo:[0,1] neg_hi:[0,1]
	v_cmp_neq_f32_e64 s[40:41], s22, v2
	v_add_f32_e32 v45, v56, v45
	v_add_f32_e32 v44, v44, v45
	v_add_f32_e32 v45, v47, v44
	v_mul_f32_e32 v56, v55, v45
	v_mul_f32_e32 v46, v53, v56
	v_fma_f32 v48, v56, v53, -v46
	v_fmac_f32_e32 v48, v56, v54
	v_sub_f32_e32 v47, v47, v45
	v_add_f32_e32 v53, v44, v47
	v_add_f32_e32 v44, v46, v48
	v_sub_f32_e32 v47, v45, v44
	v_pk_add_f32 v[50:51], v[44:45], v[46:47] neg_lo:[0,1] neg_hi:[0,1]
	v_mov_b32_e32 v49, v44
	v_pk_add_f32 v[44:45], v[50:51], v[48:49] neg_lo:[0,1] neg_hi:[0,1]
	s_nop 0
	v_add_f32_e32 v45, v53, v45
	v_add_f32_e32 v44, v44, v45
	v_add_f32_e32 v45, v57, v56
	v_add_f32_e32 v44, v47, v44
	v_sub_f32_e32 v46, v45, v57
	v_mul_f32_e32 v44, v55, v44
	v_sub_f32_e32 v46, v56, v46
	v_add_f32_e32 v46, v46, v44
	v_add_f32_e32 v48, v45, v46
	v_mul_f32_e32 v49, v48, v48
	v_fmamk_f32 v44, v49, 0x3e9b6dac, v201
	v_fmaak_f32 v169, v49, v44, 0x3f2aaada
	v_cvt_f32_i32_e32 v44, v52
	v_sub_f32_e32 v45, v48, v45
	v_sub_f32_e32 v45, v46, v45
	v_ldexp_f32 v50, v45, 1
	v_mul_f32_e32 v45, v48, v49
	v_ldexp_f32 v47, v48, 1
	v_pk_mul_f32 v[48:49], v[44:45], v[168:169]
	s_nop 0
	v_fma_f32 v46, v44, s94, -v48
	v_fmac_f32_e32 v46, 0xb102e308, v44
	v_pk_add_f32 v[44:45], v[48:49], v[46:47]
	s_nop 0
	v_sub_f32_e32 v47, v45, v47
	v_sub_f32_e32 v47, v49, v47
	v_add_f32_e32 v51, v50, v47
	v_mov_b32_e32 v50, v48
	v_pk_add_f32 v[48:49], v[44:45], v[48:49] neg_lo:[0,1] neg_hi:[0,1]
	v_pk_add_f32 v[52:53], v[44:45], v[50:51]
	v_mov_b32_e32 v47, v44
	v_mov_b32_e32 v49, v53
	v_pk_add_f32 v[54:55], v[46:47], v[48:49] neg_lo:[0,1] neg_hi:[0,1]
	v_pk_add_f32 v[46:47], v[46:47], v[48:49]
	v_mov_b32_e32 v50, v51
	v_pk_add_f32 v[48:49], v[46:47], v[44:45] op_sel:[1,0] op_sel_hi:[0,1] neg_lo:[0,1] neg_hi:[0,1]
	v_pk_add_f32 v[56:57], v[52:53], v[48:49] op_sel_hi:[1,0] neg_lo:[0,1] neg_hi:[0,1]
	v_mov_b32_e32 v52, v53
	v_mov_b32_e32 v53, v47
	v_pk_mov_b32 v[48:49], v[44:45], v[48:49] op_sel:[1,0]
	v_mov_b32_e32 v51, v44
	v_pk_add_f32 v[48:49], v[52:53], v[48:49] neg_lo:[0,1] neg_hi:[0,1]
	v_mov_b32_e32 v56, v54
	v_pk_add_f32 v[44:45], v[50:51], v[48:49] neg_lo:[0,1] neg_hi:[0,1]
	v_mov_b32_e32 v55, v47
	v_pk_add_f32 v[48:49], v[56:57], v[44:45]
	s_nop 0
	v_pk_add_f32 v[50:51], v[48:49], v[48:49] op_sel:[0,1] op_sel_hi:[1,0]
	s_nop 0
	v_pk_add_f32 v[46:47], v[46:47], v[50:51] op_sel:[1,0] op_sel_hi:[0,1]
	v_mov_b32_e32 v49, v46
	v_pk_add_f32 v[52:53], v[48:49], v[54:55] neg_lo:[0,1] neg_hi:[0,1]
	v_mov_b32_e32 v45, v50
	v_sub_f32_e32 v47, v48, v52
	v_pk_add_f32 v[44:45], v[44:45], v[52:53] neg_lo:[0,1] neg_hi:[0,1]
	v_sub_f32_e32 v47, v54, v47
	v_add_f32_e32 v44, v44, v47
	v_add_f32_e32 v44, v44, v45
	v_add_f32_e32 v44, v46, v44
	v_cndmask_b32_e64 v44, v208, v44, s[40:41]
	v_cmp_ngt_f32_e64 s[40:41], -1.0, v2
	s_nop 1
	v_cndmask_b32_e64 v44, v205, v44, s[40:41]
	v_cmp_neq_f32_e64 s[40:41], -1.0, v2
	s_nop 1
	v_cndmask_b32_e64 v44, v206, v44, s[40:41]
	v_cmp_lt_f32_e64 s[40:41], |v2|, s95
	s_nop 1
	v_cndmask_b32_e64 v60, v44, v2, s[40:41]
	v_mul_f32_e32 v2, 0xbfb8aa3b, v86
	v_exp_f32_e32 v2, v2
	s_nop 0
	v_add_f32_e32 v46, 1.0, v2
	v_add_f32_e32 v44, -1.0, v46
	v_sub_f32_e32 v45, v44, v46
	v_add_f32_e32 v45, 1.0, v45
	v_sub_f32_e32 v44, v2, v44
	v_add_f32_e32 v47, v44, v45
	v_frexp_mant_f32_e32 v44, v46
	v_cmp_gt_f32_e64 s[40:41], s77, v44
	v_cvt_f64_f32_e32 v[44:45], v46
	v_frexp_exp_i32_f64_e32 v44, v[44:45]
	v_subbrev_co_u32_e64 v52, s[40:41], 0, v44, s[40:41]
	v_sub_u32_e32 v44, 0, v52
	v_ldexp_f32 v45, v46, v44
	v_add_f32_e32 v46, -1.0, v45
	v_add_f32_e32 v48, 1.0, v45
	v_ldexp_f32 v44, v47, v44
	v_add_f32_e32 v47, 1.0, v46
	v_add_f32_e32 v49, -1.0, v48
	v_sub_f32_e32 v47, v45, v47
	v_sub_f32_e32 v45, v45, v49
	v_add_f32_e32 v47, v44, v47
	v_add_f32_e32 v44, v44, v45
; __device__ __forceinline__ void w_lru_m1(const Args& a, int l, unsigned char* ws, const bf16_t* proj, bf16_t* y, LAS unsigned char* wl, int b, int ck_, int h, int lane) {
;     ...
;         for (int r = 0; r < 4; ++r) { bav[r] = pba[r]; bxv[r] = pbx[r]; sp[r] = log1pf(__expf(-plam[r])); hc[r] = 0.f; Pc[r] = 1.f; }
	v_add_f32_e32 v53, v48, v44
	v_rcp_f32_e32 v55, v53
	v_sub_f32_e32 v45, v53, v48
	v_sub_f32_e32 v54, v44, v45
	v_add_f32_e32 v45, v46, v47
	v_mul_f32_e32 v57, v45, v55
	v_sub_f32_e32 v44, v45, v46
	v_mul_f32_e32 v46, v53, v57
	v_fma_f32 v48, v57, v53, -v46
	v_fmac_f32_e32 v48, v57, v54
	v_sub_f32_e32 v56, v47, v44
	v_add_f32_e32 v44, v46, v48
	v_sub_f32_e32 v47, v45, v44
	v_pk_add_f32 v[50:51], v[44:45], v[46:47] neg_lo:[0,1] neg_hi:[0,1]
	v_mov_b32_e32 v49, v44
	v_pk_add_f32 v[44:45], v[50:51], v[48:49] neg_lo:[0,1] neg_hi:[0,1]
	v_cmp_neq_f32_e64 s[40:41], s22, v2
	v_add_f32_e32 v45, v56, v45
	v_add_f32_e32 v44, v44, v45
	v_add_f32_e32 v45, v47, v44
	v_mul_f32_e32 v56, v55, v45
	v_mul_f32_e32 v46, v53, v56
	v_fma_f32 v48, v56, v53, -v46
	v_fmac_f32_e32 v48, v56, v54
	v_sub_f32_e32 v47, v47, v45
	v_add_f32_e32 v53, v44, v47
	v_add_f32_e32 v44, v46, v48
	v_sub_f32_e32 v47, v45, v44
	v_pk_add_f32 v[50:51], v[44:45], v[46:47] neg_lo:[0,1] neg_hi:[0,1]
	v_mov_b32_e32 v49, v44
	v_pk_add_f32 v[44:45], v[50:51], v[48:49] neg_lo:[0,1] neg_hi:[0,1]
	s_nop 0
	v_add_f32_e32 v45, v53, v45
	v_add_f32_e32 v44, v44, v45
	v_add_f32_e32 v45, v57, v56
	v_add_f32_e32 v44, v47, v44
	v_sub_f32_e32 v46, v45, v57
	v_mul_f32_e32 v44, v55, v44
	v_sub_f32_e32 v46, v56, v46
	v_add_f32_e32 v46, v46, v44
	v_add_f32_e32 v48, v45, v46
	v_mul_f32_e32 v49, v48, v48
	v_fmamk_f32 v44, v49, 0x3e9b6dac, v201
	v_fmaak_f32 v169, v49, v44, 0x3f2aaada
	v_cvt_f32_i32_e32 v44, v52
	v_sub_f32_e32 v45, v48, v45
	v_sub_f32_e32 v45, v46, v45
	v_ldexp_f32 v50, v45, 1
	v_mul_f32_e32 v45, v48, v49
	v_ldexp_f32 v47, v48, 1
	v_pk_mul_f32 v[48:49], v[44:45], v[168:169]
	s_nop 0
	v_fma_f32 v46, v44, s94, -v48
	v_fmac_f32_e32 v46, 0xb102e308, v44
	v_pk_add_f32 v[44:45], v[48:49], v[46:47]
	s_nop 0
	v_sub_f32_e32 v47, v45, v47
	v_sub_f32_e32 v47, v49, v47
	v_add_f32_e32 v51, v50, v47
	v_mov_b32_e32 v50, v48
	v_pk_add_f32 v[48:49], v[44:45], v[48:49] neg_lo:[0,1] neg_hi:[0,1]
	v_pk_add_f32 v[52:53], v[44:45], v[50:51]
	v_mov_b32_e32 v47, v44
	v_mov_b32_e32 v49, v53
	v_pk_add_f32 v[54:55], v[46:47], v[48:49] neg_lo:[0,1] neg_hi:[0,1]
	v_pk_add_f32 v[46:47], v[46:47], v[48:49]
	v_mov_b32_e32 v50, v51
	v_pk_add_f32 v[48:49], v[46:47], v[44:45] op_sel:[1,0] op_sel_hi:[0,1] neg_lo:[0,1] neg_hi:[0,1]
	v_pk_add_f32 v[56:57], v[52:53], v[48:49] op_sel_hi:[1,0] neg_lo:[0,1] neg_hi:[0,1]
	v_mov_b32_e32 v52, v53
	v_mov_b32_e32 v53, v47
	v_pk_mov_b32 v[48:49], v[44:45], v[48:49] op_sel:[1,0]
	v_mov_b32_e32 v51, v44
	v_pk_add_f32 v[48:49], v[52:53], v[48:49] neg_lo:[0,1] neg_hi:[0,1]
	v_mov_b32_e32 v56, v54
	v_pk_add_f32 v[44:45], v[50:51], v[48:49] neg_lo:[0,1] neg_hi:[0,1]
	v_mov_b32_e32 v55, v47
	v_pk_add_f32 v[48:49], v[56:57], v[44:45]
	s_nop 0
	v_pk_add_f32 v[50:51], v[48:49], v[48:49] op_sel:[0,1] op_sel_hi:[1,0]
	s_nop 0
	v_pk_add_f32 v[46:47], v[46:47], v[50:51] op_sel:[1,0] op_sel_hi:[0,1]
	v_mov_b32_e32 v49, v46
	v_pk_add_f32 v[52:53], v[48:49], v[54:55] neg_lo:[0,1] neg_hi:[0,1]
	v_mov_b32_e32 v45, v50
	v_sub_f32_e32 v47, v48, v52
	v_pk_add_f32 v[44:45], v[44:45], v[52:53] neg_lo:[0,1] neg_hi:[0,1]
	v_sub_f32_e32 v47, v54, v47
	v_add_f32_e32 v44, v44, v47
	v_add_f32_e32 v44, v44, v45
	v_add_f32_e32 v44, v46, v44
	v_cndmask_b32_e64 v44, v208, v44, s[40:41]
	v_cmp_ngt_f32_e64 s[40:41], -1.0, v2
	s_nop 1
	v_cndmask_b32_e64 v44, v205, v44, s[40:41]
	v_cmp_neq_f32_e64 s[40:41], -1.0, v2
	s_nop 1
	v_cndmask_b32_e64 v44, v206, v44, s[40:41]
	v_cmp_lt_f32_e64 s[40:41], |v2|, s95
	s_nop 1
	v_cndmask_b32_e64 v2, v44, v2, s[40:41]
	v_mul_f32_e32 v44, 0xbfb8aa3b, v87
	v_exp_f32_e32 v59, v44
	s_nop 0
	v_add_f32_e32 v46, 1.0, v59
	v_add_f32_e32 v44, -1.0, v46
	v_sub_f32_e32 v45, v44, v46
	v_add_f32_e32 v45, 1.0, v45
	v_sub_f32_e32 v44, v59, v44
	v_add_f32_e32 v47, v44, v45
	v_frexp_mant_f32_e32 v44, v46
	v_cmp_gt_f32_e64 s[40:41], s77, v44
	v_cvt_f64_f32_e32 v[44:45], v46
	v_frexp_exp_i32_f64_e32 v44, v[44:45]
	v_subbrev_co_u32_e64 v52, s[40:41], 0, v44, s[40:41]
	v_sub_u32_e32 v44, 0, v52
	v_ldexp_f32 v45, v46, v44
	v_add_f32_e32 v46, -1.0, v45
	v_add_f32_e32 v48, 1.0, v45
	v_ldexp_f32 v44, v47, v44
	v_add_f32_e32 v47, 1.0, v46
	v_add_f32_e32 v49, -1.0, v48
	v_sub_f32_e32 v47, v45, v47
	v_sub_f32_e32 v45, v45, v49
	v_add_f32_e32 v47, v44, v47
	v_add_f32_e32 v44, v44, v45
	v_add_f32_e32 v53, v48, v44
	v_rcp_f32_e32 v55, v53
	v_sub_f32_e32 v45, v53, v48
	v_sub_f32_e32 v54, v44, v45
	v_add_f32_e32 v45, v46, v47
	v_mul_f32_e32 v57, v45, v55
	v_sub_f32_e32 v44, v45, v46
	v_mul_f32_e32 v46, v53, v57
	v_fma_f32 v48, v57, v53, -v46
	v_fmac_f32_e32 v48, v57, v54
	v_sub_f32_e32 v56, v47, v44
	v_add_f32_e32 v44, v46, v48
	v_sub_f32_e32 v47, v45, v44
	v_pk_add_f32 v[50:51], v[44:45], v[46:47] neg_lo:[0,1] neg_hi:[0,1]
	v_mov_b32_e32 v49, v44
	v_pk_add_f32 v[44:45], v[50:51], v[48:49] neg_lo:[0,1] neg_hi:[0,1]
	v_cmp_neq_f32_e64 s[40:41], s22, v59
	v_add_f32_e32 v45, v56, v45
	v_add_f32_e32 v44, v44, v45
	v_add_f32_e32 v45, v47, v44
	v_mul_f32_e32 v56, v55, v45
	v_mul_f32_e32 v46, v53, v56
	v_fma_f32 v48, v56, v53, -v46
	v_fmac_f32_e32 v48, v56, v54
	v_sub_f32_e32 v47, v47, v45
	v_add_f32_e32 v53, v44, v47
	v_add_f32_e32 v44, v46, v48
	v_sub_f32_e32 v47, v45, v44
	v_pk_add_f32 v[50:51], v[44:45], v[46:47] neg_lo:[0,1] neg_hi:[0,1]
	v_mov_b32_e32 v49, v44
	v_pk_add_f32 v[44:45], v[50:51], v[48:49] neg_lo:[0,1] neg_hi:[0,1]
	s_nop 0
	v_add_f32_e32 v45, v53, v45
	v_add_f32_e32 v44, v44, v45
	v_add_f32_e32 v45, v57, v56
	v_add_f32_e32 v44, v47, v44
	v_sub_f32_e32 v46, v45, v57
	v_mul_f32_e32 v44, v55, v44
	v_sub_f32_e32 v46, v56, v46
	v_add_f32_e32 v46, v46, v44
	v_add_f32_e32 v48, v45, v46
	v_mul_f32_e32 v49, v48, v48
; __device__ __forceinline__ float sigmoidf_(float x) { return __builtin_amdgcn_rcpf(1.0f + __expf(-x)); }
; __device__ __forceinline__ void w_lru_m1(const Args& a, int l, unsigned char* ws, const bf16_t* proj, bf16_t* y, LAS unsigned char* wl, int b, int ck_, int h, int lane) {
;     ...
;         for (int r = 0; r < 4; ++r) { bav[r] = pba[r]; bxv[r] = pbx[r]; sp[r] = log1pf(__expf(-plam[r])); hc[r] = 0.f; Pc[r] = 1.f; }
; #pragma unroll
;         for (int tb = 0; tb < 4; ++tb) { const int tok = 16 * tb + lo;
;             f32x4 ga = {0.f, 0.f, 0.f, 0.f}, gx = {0.f, 0.f, 0.f, 0.f};
; #pragma unroll
;             for (int kk = 0; kk < 2; ++kk) { ga = __builtin_amdgcn_mfma_f32_16x16x32_bf16(WaF[kk], Xf[tb][kk], ga, 0, 0, 0); gx = __builtin_amdgcn_mfma_f32_16x16x32_bf16(WxF[kk], Xf[tb][kk], gx, 0, 0, 0); }
;             float hv[4], pv[4];
; #pragma unroll
;             for (int r = 0; r < 4; ++r) {
;                 const float rg = sigmoidf_(ga[r] + bav[r]), ig = sigmoidf_(gx[r] + bxv[r]);
;                 const float la = -8.0f * rg * sp[r]; float A = __expf(la);
;                 float U = __builtin_amdgcn_sqrtf(1.0f - A * A) * (ig * xcf[tok * 65 + j0 + r]);
;                 { const float As = dpp_shr1<1>(A), Us = dpp_shr0<1>(U); U = A * Us + U; A = A * As; }
;                 { const float As = dpp_shr1<2>(A), Us = dpp_shr0<2>(U); U = A * Us + U; A = A * As; }
;                 { const float As = dpp_shr1<4>(A), Us = dpp_shr0<4>(U); U = A * Us + U; A = A * As; }
;                 { const float As = dpp_shr1<8>(A), Us = dpp_shr0<8>(U); U = A * Us + U; A = A * As; }
;                 const float hh = U + A * hc[r], PP = A * Pc[r];
	v_fmamk_f32 v44, v49, 0x3e9b6dac, v201
	v_fmaak_f32 v169, v49, v44, 0x3f2aaada
	v_cvt_f32_i32_e32 v44, v52
	v_sub_f32_e32 v45, v48, v45
	v_sub_f32_e32 v45, v46, v45
	v_ldexp_f32 v50, v45, 1
	v_mul_f32_e32 v45, v48, v49
	v_ldexp_f32 v47, v48, 1
	v_pk_mul_f32 v[48:49], v[44:45], v[168:169]
	s_nop 0
	v_fma_f32 v46, v44, s94, -v48
	v_fmac_f32_e32 v46, 0xb102e308, v44
	v_pk_add_f32 v[44:45], v[48:49], v[46:47]
	s_nop 0
	v_sub_f32_e32 v47, v45, v47
	v_sub_f32_e32 v47, v49, v47
	v_add_f32_e32 v51, v50, v47
	v_mov_b32_e32 v50, v48
	v_pk_add_f32 v[48:49], v[44:45], v[48:49] neg_lo:[0,1] neg_hi:[0,1]
	v_pk_add_f32 v[52:53], v[44:45], v[50:51]
	v_mov_b32_e32 v47, v44
	v_mov_b32_e32 v49, v53
	v_pk_add_f32 v[54:55], v[46:47], v[48:49] neg_lo:[0,1] neg_hi:[0,1]
	v_pk_add_f32 v[46:47], v[46:47], v[48:49]
	v_mov_b32_e32 v50, v51
	v_pk_add_f32 v[48:49], v[46:47], v[44:45] op_sel:[1,0] op_sel_hi:[0,1] neg_lo:[0,1] neg_hi:[0,1]
	v_pk_add_f32 v[56:57], v[52:53], v[48:49] op_sel_hi:[1,0] neg_lo:[0,1] neg_hi:[0,1]
	v_mov_b32_e32 v52, v53
	v_mov_b32_e32 v53, v47
	v_pk_mov_b32 v[48:49], v[44:45], v[48:49] op_sel:[1,0]
	v_mov_b32_e32 v51, v44
	v_pk_add_f32 v[48:49], v[52:53], v[48:49] neg_lo:[0,1] neg_hi:[0,1]
	v_mov_b32_e32 v56, v54
	v_pk_add_f32 v[44:45], v[50:51], v[48:49] neg_lo:[0,1] neg_hi:[0,1]
	v_mov_b32_e32 v55, v47
	v_pk_add_f32 v[48:49], v[56:57], v[44:45]
	s_nop 0
	v_pk_add_f32 v[50:51], v[48:49], v[48:49] op_sel:[0,1] op_sel_hi:[1,0]
	s_nop 0
	v_pk_add_f32 v[46:47], v[46:47], v[50:51] op_sel:[1,0] op_sel_hi:[0,1]
	v_mov_b32_e32 v49, v46
	v_pk_add_f32 v[52:53], v[48:49], v[54:55] neg_lo:[0,1] neg_hi:[0,1]
	v_mov_b32_e32 v45, v50
	v_sub_f32_e32 v47, v48, v52
	v_pk_add_f32 v[44:45], v[44:45], v[52:53] neg_lo:[0,1] neg_hi:[0,1]
	v_sub_f32_e32 v47, v54, v47
	v_add_f32_e32 v44, v44, v47
	v_add_f32_e32 v44, v44, v45
	v_add_f32_e32 v44, v46, v44
	v_cndmask_b32_e64 v44, v208, v44, s[40:41]
	v_cmp_ngt_f32_e64 s[40:41], -1.0, v59
	ds_read2_b32 v[54:55], v145 offset0:48 offset1:49
	v_mov_b32_e32 v48, 1.0
	v_cndmask_b32_e64 v44, v205, v44, s[40:41]
	v_cmp_neq_f32_e64 s[40:41], -1.0, v59
	v_mov_b32_e32 v49, 1.0
	v_mov_b32_e32 v50, 1.0
	v_cndmask_b32_e64 v44, v206, v44, s[40:41]
	v_cmp_lt_f32_e64 s[40:41], |v59|, s95
	v_mov_b32_e32 v51, 1.0
	v_mov_b32_e32 v52, 1.0
	v_cndmask_b32_e64 v59, v44, v59, s[40:41]
	v_mfma_f32_16x16x32_bf16 v[44:47], v[68:71], v[16:19], 0
	v_mov_b32_e32 v53, 1.0
	v_mfma_f32_16x16x32_bf16 v[16:19], v[72:75], v[16:19], 0
	v_mfma_f32_16x16x32_bf16 v[44:47], v[76:79], v[32:35], v[44:47]
	v_mfma_f32_16x16x32_bf16 v[16:19], v[80:83], v[32:35], v[16:19]
	s_nop 6
	v_add_f32_e32 v32, v40, v44
	v_mul_f32_e32 v32, 0xbfb8aa3b, v32
	v_exp_f32_e32 v32, v32
	v_add_f32_e32 v16, v36, v16
	v_add_f32_e32 v17, v37, v17
	v_mul_f32_e32 v16, 0xbfb8aa3b, v16
	v_add_f32_e32 v32, 1.0, v32
	v_rcp_f32_e32 v32, v32
	v_mul_f32_e32 v17, 0xbfb8aa3b, v17
	v_exp_f32_e32 v16, v16
	v_exp_f32_e32 v17, v17
	v_mul_f32_e32 v32, 0xc1000000, v32
	v_mul_f32_e32 v32, v58, v32
	v_mul_f32_e32 v32, 0x3fb8aa3b, v32
	v_exp_f32_e32 v32, v32
	v_add_f32_e32 v16, 1.0, v16
	v_add_f32_e32 v17, 1.0, v17
	v_rcp_f32_e32 v16, v16
	v_fma_f32 v33, -v32, v32, 1.0
	v_sqrt_f32_e32 v34, v33
	v_add_f32_e32 v33, v41, v45
	v_mul_f32_e32 v33, 0xbfb8aa3b, v33
	v_exp_f32_e32 v33, v33
	v_rcp_f32_e32 v17, v17
	v_mov_b32_e32 v44, 1.0
	v_mov_b32_e32 v45, 1.0
	v_add_f32_e32 v33, 1.0, v33
	v_rcp_f32_e32 v33, v33
	s_waitcnt lgkmcnt(0)
	v_pk_mul_f32 v[16:17], v[54:55], v[16:17]
	v_mov_b32_dpp v44, v32 row_shr:1 row_mask:0xf bank_mask:0xf
	v_add_f32_e32 v18, v38, v18
	v_mul_f32_e32 v33, 0xc1000000, v33
	v_mul_f32_e32 v33, v60, v33
	v_mul_f32_e32 v33, 0x3fb8aa3b, v33
	v_exp_f32_e32 v33, v33
	v_add_f32_e32 v19, v39, v19
	v_mul_f32_e32 v18, 0xbfb8aa3b, v18
	v_mul_f32_e32 v19, 0xbfb8aa3b, v19
	v_fma_f32 v35, -v33, v33, 1.0
	v_sqrt_f32_e32 v35, v35
	v_mov_b32_dpp v45, v33 row_shr:1 row_mask:0xf bank_mask:0xf
	v_pk_mul_f32 v[44:45], v[32:33], v[44:45]
	v_exp_f32_e32 v18, v18
	v_pk_mul_f32 v[16:17], v[16:17], v[34:35]
	v_mov_b32_dpp v48, v44 row_shr:2 row_mask:0xf bank_mask:0xf
	v_mov_b32_dpp v49, v45 row_shr:2 row_mask:0xf bank_mask:0xf
	v_mov_b32_dpp v34, v16 row_shr:1 row_mask:0xf bank_mask:0xf bound_ctrl:1
	v_mov_b32_dpp v35, v17 row_shr:1 row_mask:0xf bank_mask:0xf bound_ctrl:1
	v_pk_fma_f32 v[16:17], v[32:33], v[34:35], v[16:17]
	v_pk_mul_f32 v[48:49], v[44:45], v[48:49]
	v_exp_f32_e32 v19, v19
	v_mov_b32_dpp v32, v16 row_shr:2 row_mask:0xf bank_mask:0xf bound_ctrl:1
	v_mov_b32_dpp v33, v17 row_shr:2 row_mask:0xf bank_mask:0xf bound_ctrl:1
	v_pk_fma_f32 v[16:17], v[44:45], v[32:33], v[16:17]
	v_mov_b32_dpp v50, v48 row_shr:4 row_mask:0xf bank_mask:0xf
	v_mov_b32_dpp v51, v49 row_shr:4 row_mask:0xf bank_mask:0xf
	v_mov_b32_dpp v32, v16 row_shr:4 row_mask:0xf bank_mask:0xf bound_ctrl:1
	v_mov_b32_dpp v33, v17 row_shr:4 row_mask:0xf bank_mask:0xf bound_ctrl:1
	v_pk_fma_f32 v[16:17], v[48:49], v[32:33], v[16:17]
	v_pk_mul_f32 v[50:51], v[48:49], v[50:51]
	v_add_f32_e32 v18, 1.0, v18
	v_mov_b32_dpp v32, v16 row_shr:8 row_mask:0xf bank_mask:0xf bound_ctrl:1
	v_mov_b32_dpp v33, v17 row_shr:8 row_mask:0xf bank_mask:0xf bound_ctrl:1
	v_pk_fma_f32 v[16:17], v[50:51], v[32:33], v[16:17]
	v_add_f32_e32 v32, v42, v46
	v_mul_f32_e32 v32, 0xbfb8aa3b, v32
	v_exp_f32_e32 v32, v32
	v_add_f32_e32 v19, 1.0, v19
	v_rcp_f32_e32 v18, v18
	v_rcp_f32_e32 v19, v19
	v_add_f32_e32 v32, 1.0, v32
	v_rcp_f32_e32 v32, v32
	v_mov_b32_e32 v46, 1.0
	v_pk_mul_f32 v[18:19], v[18:19], v[64:65]
	v_mov_b32_dpp v52, v50 row_shr:8 row_mask:0xf bank_mask:0xf
	v_mul_f32_e32 v32, 0xc1000000, v32
	v_mul_f32_e32 v32, v2, v32
	v_mul_f32_e32 v32, 0x3fb8aa3b, v32
; __device__ __forceinline__ unsigned pk2(float lo, float hi) { const f32x2_t v = {lo, hi}; const bf16x2_t b = __builtin_convertvector(v, bf16x2_t); return __builtin_bit_cast(unsigned, b); }
; __device__ __forceinline__ float sigmoidf_(float x) { return __builtin_amdgcn_rcpf(1.0f + __expf(-x)); }
; __device__ __forceinline__ float bcast15(float v, int lane) { return bperm_f((lane & 48) | 15, v); }
; __device__ __forceinline__ void w_lru_m1(const Args& a, int l, unsigned char* ws, const bf16_t* proj, bf16_t* y, LAS unsigned char* wl, int b, int ck_, int h, int lane) {
;     ...
;         for (int tb = 0; tb < 4; ++tb) { const int tok = 16 * tb + lo;
;             f32x4 ga = {0.f, 0.f, 0.f, 0.f}, gx = {0.f, 0.f, 0.f, 0.f};
; #pragma unroll
;             for (int kk = 0; kk < 2; ++kk) { ga = __builtin_amdgcn_mfma_f32_16x16x32_bf16(WaF[kk], Xf[tb][kk], ga, 0, 0, 0); gx = __builtin_amdgcn_mfma_f32_16x16x32_bf16(WxF[kk], Xf[tb][kk], gx, 0, 0, 0); }
;             float hv[4], pv[4];
; #pragma unroll
;             for (int r = 0; r < 4; ++r) {
;                 const float rg = sigmoidf_(ga[r] + bav[r]), ig = sigmoidf_(gx[r] + bxv[r]);
;                 const float la = -8.0f * rg * sp[r]; float A = __expf(la);
;                 float U = __builtin_amdgcn_sqrtf(1.0f - A * A) * (ig * xcf[tok * 65 + j0 + r]);
;                 { const float As = dpp_shr1<1>(A), Us = dpp_shr0<1>(U); U = A * Us + U; A = A * As; }
;                 { const float As = dpp_shr1<2>(A), Us = dpp_shr0<2>(U); U = A * Us + U; A = A * As; }
;                 { const float As = dpp_shr1<4>(A), Us = dpp_shr0<4>(U); U = A * Us + U; A = A * As; }
;                 { const float As = dpp_shr1<8>(A), Us = dpp_shr0<8>(U); U = A * Us + U; A = A * As; }
;                 const float hh = U + A * hc[r], PP = A * Pc[r];
;                 hc[r] = bcast15(hh, lane); Pc[r] = bcast15(PP, lane); hv[r] = hh; pv[r] = PP; }
;             *(unsigned long long*)(y + (size_t)(row0 + tok) * DM + 64 * h + j0) = (unsigned long long)pk2(hv[0], hv[1]) | ((unsigned long long)pk2(hv[2], hv[3]) << 32);
;             *(unsigned long long*)((bf16_t*)(ws + WS_P) + (size_t)(row0 + tok) * 512 + 64 * h + j0) = (unsigned long long)pk2(pv[0], pv[1]) | ((unsigned long long)pk2(pv[2], pv[3]) << 32);
	v_exp_f32_e32 v32, v32
	v_mov_b32_dpp v53, v51 row_shr:8 row_mask:0xf bank_mask:0xf
	v_pk_mul_f32 v[52:53], v[50:51], v[52:53]
	ds_bpermute_b32 v56, v1, v52
	v_fma_f32 v33, -v32, v32, 1.0
	v_sqrt_f32_e32 v44, v33
	v_add_f32_e32 v33, v43, v47
	v_mul_f32_e32 v33, 0xbfb8aa3b, v33
	v_exp_f32_e32 v33, v33
	v_mov_b32_e32 v47, 1.0
	v_mov_b32_dpp v46, v32 row_shr:1 row_mask:0xf bank_mask:0xf
	v_pk_fma_f32 v[16:17], v[52:53], 0, v[16:17] op_sel_hi:[1,0,1]
	v_add_f32_e32 v33, 1.0, v33
	v_rcp_f32_e32 v33, v33
	ds_bpermute_b32 v34, v1, v16
	ds_bpermute_b32 v35, v1, v17
	v_cvt_pk_bf16_f32 v16, v16, v17
	v_mul_f32_e32 v33, 0xc1000000, v33
	v_mul_f32_e32 v33, v59, v33
	v_mul_f32_e32 v33, 0x3fb8aa3b, v33
	v_exp_f32_e32 v33, v33
	ds_bpermute_b32 v57, v1, v53
	v_fma_f32 v45, -v33, v33, 1.0
	v_sqrt_f32_e32 v45, v45
	v_mov_b32_dpp v47, v33 row_shr:1 row_mask:0xf bank_mask:0xf
	v_pk_mul_f32 v[48:49], v[32:33], v[46:47]
	v_mov_b32_e32 v46, 1.0
	v_pk_mul_f32 v[18:19], v[44:45], v[18:19]
	v_mov_b32_e32 v47, 1.0
	v_mov_b32_dpp v46, v48 row_shr:2 row_mask:0xf bank_mask:0xf
	v_mov_b32_dpp v44, v18 row_shr:1 row_mask:0xf bank_mask:0xf bound_ctrl:1
	v_mov_b32_dpp v45, v19 row_shr:1 row_mask:0xf bank_mask:0xf bound_ctrl:1
	v_pk_fma_f32 v[18:19], v[32:33], v[44:45], v[18:19]
	v_mov_b32_dpp v47, v49 row_shr:2 row_mask:0xf bank_mask:0xf
	v_pk_mul_f32 v[50:51], v[48:49], v[46:47]
	v_mov_b32_dpp v32, v18 row_shr:2 row_mask:0xf bank_mask:0xf bound_ctrl:1
	v_mov_b32_dpp v33, v19 row_shr:2 row_mask:0xf bank_mask:0xf bound_ctrl:1
	v_mov_b32_e32 v46, 1.0
	v_mov_b32_e32 v47, 1.0
	v_pk_fma_f32 v[18:19], v[48:49], v[32:33], v[18:19]
	v_mov_b32_dpp v46, v50 row_shr:4 row_mask:0xf bank_mask:0xf
	v_mov_b32_dpp v47, v51 row_shr:4 row_mask:0xf bank_mask:0xf
	v_mov_b32_dpp v32, v18 row_shr:4 row_mask:0xf bank_mask:0xf bound_ctrl:1
	v_mov_b32_dpp v33, v19 row_shr:4 row_mask:0xf bank_mask:0xf bound_ctrl:1
	v_pk_mul_f32 v[54:55], v[50:51], v[46:47]
	v_mov_b32_e32 v46, 1.0
	v_mov_b32_e32 v47, 1.0
	v_pk_fma_f32 v[18:19], v[50:51], v[32:33], v[18:19]
	v_mov_b32_dpp v46, v54 row_shr:8 row_mask:0xf bank_mask:0xf
	v_mov_b32_dpp v47, v55 row_shr:8 row_mask:0xf bank_mask:0xf
	v_mov_b32_dpp v32, v18 row_shr:8 row_mask:0xf bank_mask:0xf bound_ctrl:1
	v_mov_b32_dpp v33, v19 row_shr:8 row_mask:0xf bank_mask:0xf bound_ctrl:1
	v_pk_mul_f32 v[62:63], v[54:55], v[46:47]
	v_pk_fma_f32 v[18:19], v[54:55], v[32:33], v[18:19]
	ds_bpermute_b32 v46, v1, v62
	v_pk_fma_f32 v[18:19], v[62:63], 0, v[18:19] op_sel_hi:[1,0,1]
	ds_bpermute_b32 v32, v1, v18
	v_cvt_pk_bf16_f32 v17, v18, v19
	global_store_dwordx2 v[100:101], v[16:17], off offset:96
	v_cvt_pk_bf16_f32 v16, v52, v53
	v_cvt_pk_bf16_f32 v17, v62, v63
	ds_bpermute_b32 v33, v1, v19
	global_store_dwordx2 v[102:103], v[16:17], off offset:96
	v_mfma_f32_16x16x32_bf16 v[16:19], v[68:71], v[12:15], 0
	ds_bpermute_b32 v47, v1, v63
	v_mfma_f32_16x16x32_bf16 v[12:15], v[72:75], v[12:15], 0
	v_mfma_f32_16x16x32_bf16 v[16:19], v[76:79], v[28:31], v[16:19]
	v_mfma_f32_16x16x32_bf16 v[12:15], v[80:83], v[28:31], v[12:15]
	s_nop 6
	v_add_f32_e32 v16, v40, v16
	v_mul_f32_e32 v16, 0xbfb8aa3b, v16
	v_exp_f32_e32 v16, v16
	v_add_f32_e32 v12, v36, v12
	v_mul_f32_e32 v12, 0xbfb8aa3b, v12
	v_exp_f32_e32 v12, v12
	v_add_f32_e32 v16, 1.0, v16
	v_rcp_f32_e32 v16, v16
	v_add_f32_e32 v13, v37, v13
	v_add_f32_e32 v12, 1.0, v12
	v_rcp_f32_e32 v28, v12
	v_mul_f32_e32 v12, 0xc1000000, v16
	v_add_f32_e32 v16, v41, v17
	v_mul_f32_e32 v16, 0xbfb8aa3b, v16
	v_exp_f32_e32 v16, v16
	v_mul_f32_e32 v13, 0xbfb8aa3b, v13
	v_exp_f32_e32 v13, v13
	v_mul_f32_e32 v12, v58, v12
	v_add_f32_e32 v16, 1.0, v16
	v_rcp_f32_e32 v16, v16
	v_add_f32_e32 v13, 1.0, v13
	v_rcp_f32_e32 v29, v13
	v_mul_f32_e32 v12, 0x3fb8aa3b, v12
	v_mul_f32_e32 v13, 0xc1000000, v16
	v_mul_f32_e32 v13, v60, v13
	v_mul_f32_e32 v13, 0x3fb8aa3b, v13
	v_exp_f32_e32 v30, v12
	v_exp_f32_e32 v31, v13
	v_add_f32_e32 v18, v42, v18
	v_add_f32_e32 v19, v43, v19
	v_fma_f32 v12, -v30, v30, 1.0
	v_fma_f32 v13, -v31, v31, 1.0
	v_sqrt_f32_e32 v44, v12
	v_mov_b32_e32 v12, 1.0
	v_sqrt_f32_e32 v45, v13
	v_mov_b32_e32 v13, 1.0
	v_mov_b32_dpp v12, v30 row_shr:1 row_mask:0xf bank_mask:0xf
	v_mul_f32_e32 v18, 0xbfb8aa3b, v18
	v_mov_b32_dpp v13, v31 row_shr:1 row_mask:0xf bank_mask:0xf
	v_pk_mul_f32 v[48:49], v[30:31], v[12:13]
	v_mov_b32_e32 v12, 1.0
	v_mov_b32_e32 v13, 1.0
	v_mul_f32_e32 v19, 0xbfb8aa3b, v19
	v_mov_b32_dpp v12, v48 row_shr:2 row_mask:0xf bank_mask:0xf
	v_mov_b32_dpp v13, v49 row_shr:2 row_mask:0xf bank_mask:0xf
	v_pk_mul_f32 v[50:51], v[48:49], v[12:13]
	v_mov_b32_e32 v12, 1.0
	v_mov_b32_e32 v13, 1.0
	v_exp_f32_e32 v18, v18
	v_mov_b32_dpp v12, v50 row_shr:4 row_mask:0xf bank_mask:0xf
	v_mov_b32_dpp v13, v51 row_shr:4 row_mask:0xf bank_mask:0xf
	v_pk_mul_f32 v[52:53], v[50:51], v[12:13]
	v_mov_b32_e32 v12, 1.0
	v_mov_b32_e32 v13, 1.0
	v_exp_f32_e32 v19, v19
	v_mov_b32_dpp v12, v52 row_shr:8 row_mask:0xf bank_mask:0xf
	v_mov_b32_dpp v13, v53 row_shr:8 row_mask:0xf bank_mask:0xf
	v_pk_mul_f32 v[54:55], v[52:53], v[12:13]
	v_add_u32_e32 v13, 0x1100, v145
	s_waitcnt lgkmcnt(0)
	v_pk_mul_f32 v[16:17], v[54:55], v[56:57]
	ds_read2_b32 v[56:57], v13 offset1:1
	v_add_f32_e32 v14, v38, v14
	v_add_f32_e32 v15, v39, v15
	v_mul_f32_e32 v14, 0xbfb8aa3b, v14
	v_mul_f32_e32 v15, 0xbfb8aa3b, v15
	s_waitcnt lgkmcnt(0)
; __device__ __forceinline__ unsigned pk2(float lo, float hi) { const f32x2_t v = {lo, hi}; const bf16x2_t b = __builtin_convertvector(v, bf16x2_t); return __builtin_bit_cast(unsigned, b); }
; __device__ __forceinline__ float sigmoidf_(float x) { return __builtin_amdgcn_rcpf(1.0f + __expf(-x)); }
; __device__ __forceinline__ float bcast15(float v, int lane) { return bperm_f((lane & 48) | 15, v); }
; __device__ __forceinline__ void w_lru_m1(const Args& a, int l, unsigned char* ws, const bf16_t* proj, bf16_t* y, LAS unsigned char* wl, int b, int ck_, int h, int lane) {
;     ...
;         for (int tb = 0; tb < 4; ++tb) { const int tok = 16 * tb + lo;
;             f32x4 ga = {0.f, 0.f, 0.f, 0.f}, gx = {0.f, 0.f, 0.f, 0.f};
; #pragma unroll
;             for (int kk = 0; kk < 2; ++kk) { ga = __builtin_amdgcn_mfma_f32_16x16x32_bf16(WaF[kk], Xf[tb][kk], ga, 0, 0, 0); gx = __builtin_amdgcn_mfma_f32_16x16x32_bf16(WxF[kk], Xf[tb][kk], gx, 0, 0, 0); }
;             float hv[4], pv[4];
; #pragma unroll
;             for (int r = 0; r < 4; ++r) {
;                 const float rg = sigmoidf_(ga[r] + bav[r]), ig = sigmoidf_(gx[r] + bxv[r]);
;                 const float la = -8.0f * rg * sp[r]; float A = __expf(la);
;                 float U = __builtin_amdgcn_sqrtf(1.0f - A * A) * (ig * xcf[tok * 65 + j0 + r]);
;                 { const float As = dpp_shr1<1>(A), Us = dpp_shr0<1>(U); U = A * Us + U; A = A * As; }
;                 { const float As = dpp_shr1<2>(A), Us = dpp_shr0<2>(U); U = A * Us + U; A = A * As; }
;                 { const float As = dpp_shr1<4>(A), Us = dpp_shr0<4>(U); U = A * Us + U; A = A * As; }
;                 { const float As = dpp_shr1<8>(A), Us = dpp_shr0<8>(U); U = A * Us + U; A = A * As; }
;                 const float hh = U + A * hc[r], PP = A * Pc[r];
;                 hc[r] = bcast15(hh, lane); Pc[r] = bcast15(PP, lane); hv[r] = hh; pv[r] = PP; }
;             *(unsigned long long*)(y + (size_t)(row0 + tok) * DM + 64 * h + j0) = (unsigned long long)pk2(hv[0], hv[1]) | ((unsigned long long)pk2(hv[2], hv[3]) << 32);
;             *(unsigned long long*)((bf16_t*)(ws + WS_P) + (size_t)(row0 + tok) * 512 + 64 * h + j0) = (unsigned long long)pk2(pv[0], pv[1]) | ((unsigned long long)pk2(pv[2], pv[3]) << 32);
	v_pk_mul_f32 v[28:29], v[56:57], v[28:29]
	v_add_f32_e32 v18, 1.0, v18
	v_pk_mul_f32 v[28:29], v[28:29], v[44:45]
	v_exp_f32_e32 v14, v14
	v_add_f32_e32 v19, 1.0, v19
	v_mov_b32_dpp v44, v28 row_shr:1 row_mask:0xf bank_mask:0xf bound_ctrl:1
	v_mov_b32_dpp v45, v29 row_shr:1 row_mask:0xf bank_mask:0xf bound_ctrl:1
	v_pk_fma_f32 v[28:29], v[30:31], v[44:45], v[28:29]
	v_exp_f32_e32 v15, v15
	v_rcp_f32_e32 v18, v18
	v_mov_b32_dpp v30, v28 row_shr:2 row_mask:0xf bank_mask:0xf bound_ctrl:1
	v_mov_b32_dpp v31, v29 row_shr:2 row_mask:0xf bank_mask:0xf bound_ctrl:1
	v_pk_fma_f32 v[28:29], v[48:49], v[30:31], v[28:29]
	v_rcp_f32_e32 v19, v19
	v_add_f32_e32 v14, 1.0, v14
	v_mov_b32_dpp v30, v28 row_shr:4 row_mask:0xf bank_mask:0xf bound_ctrl:1
	v_mov_b32_dpp v31, v29 row_shr:4 row_mask:0xf bank_mask:0xf bound_ctrl:1
	v_pk_fma_f32 v[28:29], v[50:51], v[30:31], v[28:29]
	v_add_f32_e32 v15, 1.0, v15
	ds_bpermute_b32 v12, v1, v16
	v_mov_b32_dpp v30, v28 row_shr:8 row_mask:0xf bank_mask:0xf bound_ctrl:1
	v_mov_b32_dpp v31, v29 row_shr:8 row_mask:0xf bank_mask:0xf bound_ctrl:1
	v_pk_fma_f32 v[28:29], v[52:53], v[30:31], v[28:29]
	ds_bpermute_b32 v13, v1, v17
	v_pk_fma_f32 v[30:31], v[54:55], v[34:35], v[28:29]
	v_rcp_f32_e32 v34, v14
	v_mul_f32_e32 v14, 0xc1000000, v18
	v_rcp_f32_e32 v35, v15
	v_mul_f32_e32 v15, 0xc1000000, v19
	v_mul_f32_e32 v14, v2, v14
	v_mul_f32_e32 v15, v59, v15
	v_mul_f32_e32 v14, 0x3fb8aa3b, v14
	v_mul_f32_e32 v15, 0x3fb8aa3b, v15
	v_exp_f32_e32 v18, v14
	v_exp_f32_e32 v19, v15
	ds_bpermute_b32 v28, v1, v30
	ds_bpermute_b32 v29, v1, v31
	v_fma_f32 v14, -v18, v18, 1.0
	v_fma_f32 v15, -v19, v19, 1.0
	v_sqrt_f32_e32 v44, v14
	v_mov_b32_e32 v14, 1.0
	v_sqrt_f32_e32 v45, v15
	v_mov_b32_e32 v15, 1.0
	v_mov_b32_dpp v14, v18 row_shr:1 row_mask:0xf bank_mask:0xf
	v_cvt_pk_bf16_f32 v30, v30, v31
	v_mov_b32_dpp v15, v19 row_shr:1 row_mask:0xf bank_mask:0xf
	v_pk_mul_f32 v[48:49], v[18:19], v[14:15]
	v_mov_b32_e32 v14, 1.0
	v_mov_b32_e32 v15, 1.0
	v_cvt_pk_bf16_f32 v16, v16, v17
	v_mov_b32_dpp v14, v48 row_shr:2 row_mask:0xf bank_mask:0xf
	v_mov_b32_dpp v15, v49 row_shr:2 row_mask:0xf bank_mask:0xf
	v_pk_mul_f32 v[50:51], v[48:49], v[14:15]
	v_mov_b32_e32 v14, 1.0
	v_mov_b32_e32 v15, 1.0
	s_nop 0
	v_mov_b32_dpp v14, v50 row_shr:4 row_mask:0xf bank_mask:0xf
	v_mov_b32_dpp v15, v51 row_shr:4 row_mask:0xf bank_mask:0xf
	v_pk_mul_f32 v[52:53], v[50:51], v[14:15]
	v_mov_b32_e32 v14, 1.0
	v_mov_b32_e32 v15, 1.0
	s_nop 0
	v_mov_b32_dpp v14, v52 row_shr:8 row_mask:0xf bank_mask:0xf
	v_mov_b32_dpp v15, v53 row_shr:8 row_mask:0xf bank_mask:0xf
	v_pk_mul_f32 v[54:55], v[52:53], v[14:15]
	v_add_u32_e32 v15, 0x1108, v145
	ds_read2_b32 v[56:57], v15 offset1:1
	v_pk_mul_f32 v[46:47], v[54:55], v[46:47]
	ds_bpermute_b32 v14, v1, v46
	v_cvt_pk_bf16_f32 v17, v46, v47
	ds_bpermute_b32 v15, v1, v47
	s_waitcnt lgkmcnt(0)
	v_pk_mul_f32 v[34:35], v[34:35], v[56:57]
	s_nop 0
	v_pk_mul_f32 v[34:35], v[44:45], v[34:35]
	s_nop 1
	v_mov_b32_dpp v44, v34 row_shr:1 row_mask:0xf bank_mask:0xf bound_ctrl:1
	v_mov_b32_dpp v45, v35 row_shr:1 row_mask:0xf bank_mask:0xf bound_ctrl:1
	v_pk_fma_f32 v[18:19], v[18:19], v[44:45], v[34:35]
	s_nop 1
	v_mov_b32_dpp v34, v18 row_shr:2 row_mask:0xf bank_mask:0xf bound_ctrl:1
	v_mov_b32_dpp v35, v19 row_shr:2 row_mask:0xf bank_mask:0xf bound_ctrl:1
	v_pk_fma_f32 v[18:19], v[48:49], v[34:35], v[18:19]
	s_nop 1
	v_mov_b32_dpp v34, v18 row_shr:4 row_mask:0xf bank_mask:0xf bound_ctrl:1
	v_mov_b32_dpp v35, v19 row_shr:4 row_mask:0xf bank_mask:0xf bound_ctrl:1
	v_pk_fma_f32 v[18:19], v[50:51], v[34:35], v[18:19]
	s_nop 1
	v_mov_b32_dpp v34, v18 row_shr:8 row_mask:0xf bank_mask:0xf bound_ctrl:1
	v_mov_b32_dpp v35, v19 row_shr:8 row_mask:0xf bank_mask:0xf bound_ctrl:1
	v_pk_fma_f32 v[18:19], v[52:53], v[34:35], v[18:19]
	s_nop 0
	v_pk_fma_f32 v[32:33], v[54:55], v[32:33], v[18:19]
	ds_bpermute_b32 v18, v1, v32
	v_cvt_pk_bf16_f32 v31, v32, v33
	ds_bpermute_b32 v19, v1, v33
	global_store_dwordx2 v[104:105], v[30:31], off offset:96
	v_mfma_f32_16x16x32_bf16 v[30:33], v[68:71], v[8:11], 0
	global_store_dwordx2 v[106:107], v[16:17], off offset:96
	v_mfma_f32_16x16x32_bf16 v[8:11], v[72:75], v[8:11], 0
	v_mfma_f32_16x16x32_bf16 v[30:33], v[76:79], v[24:27], v[30:33]
	v_mfma_f32_16x16x32_bf16 v[24:27], v[80:83], v[24:27], v[8:11]
	s_nop 6
	v_add_f32_e32 v8, v40, v30
	v_add_f32_e32 v9, v36, v24
	v_mul_f32_e32 v9, 0xbfb8aa3b, v9
	v_exp_f32_e32 v9, v9
	v_mul_f32_e32 v8, 0xbfb8aa3b, v8
	v_exp_f32_e32 v8, v8
	v_add_f32_e32 v11, v37, v25
	v_add_f32_e32 v9, 1.0, v9
	v_rcp_f32_e32 v10, v9
	v_add_f32_e32 v9, v41, v31
	v_mul_f32_e32 v9, 0xbfb8aa3b, v9
	v_exp_f32_e32 v9, v9
	v_add_f32_e32 v8, 1.0, v8
	v_rcp_f32_e32 v8, v8
	v_mul_f32_e32 v11, 0xbfb8aa3b, v11
	v_add_f32_e32 v9, 1.0, v9
	v_rcp_f32_e32 v9, v9
	v_mul_f32_e32 v8, 0xc1000000, v8
	v_mul_f32_e32 v8, v58, v8
	v_mul_f32_e32 v8, 0x3fb8aa3b, v8
	v_mul_f32_e32 v9, 0xc1000000, v9
	v_mul_f32_e32 v9, v60, v9
	v_mul_f32_e32 v9, 0x3fb8aa3b, v9
	v_exp_f32_e32 v16, v8
	v_exp_f32_e32 v17, v9
	v_exp_f32_e32 v11, v11
	v_fma_f32 v8, -v16, v16, 1.0
	v_fma_f32 v9, -v17, v17, 1.0
	v_sqrt_f32_e32 v30, v8
	v_mov_b32_e32 v8, 1.0
	v_sqrt_f32_e32 v31, v9
	v_mov_b32_e32 v9, 1.0
	v_mov_b32_dpp v8, v16 row_shr:1 row_mask:0xf bank_mask:0xf
	v_add_f32_e32 v11, 1.0, v11
	v_mov_b32_dpp v9, v17 row_shr:1 row_mask:0xf bank_mask:0xf
	v_pk_mul_f32 v[34:35], v[16:17], v[8:9]
	v_mov_b32_e32 v8, 1.0
	v_mov_b32_e32 v9, 1.0
	v_rcp_f32_e32 v11, v11
	v_mov_b32_dpp v8, v34 row_shr:2 row_mask:0xf bank_mask:0xf
	v_mov_b32_dpp v9, v35 row_shr:2 row_mask:0xf bank_mask:0xf
	v_pk_mul_f32 v[44:45], v[34:35], v[8:9]
	v_mov_b32_e32 v8, 1.0
	v_mov_b32_e32 v9, 1.0
	s_nop 0
	v_mov_b32_dpp v8, v44 row_shr:4 row_mask:0xf bank_mask:0xf
	v_mov_b32_dpp v9, v45 row_shr:4 row_mask:0xf bank_mask:0xf
	v_pk_mul_f32 v[46:47], v[44:45], v[8:9]
	v_mov_b32_e32 v8, 1.0
	v_mov_b32_e32 v9, 1.0
	s_nop 0
	v_mov_b32_dpp v8, v46 row_shr:8 row_mask:0xf bank_mask:0xf
	v_mov_b32_dpp v9, v47 row_shr:8 row_mask:0xf bank_mask:0xf
	v_pk_mul_f32 v[48:49], v[46:47], v[8:9]
	s_nop 0
	v_pk_mul_f32 v[8:9], v[48:49], v[12:13]
	v_add_u32_e32 v12, 0x2140, v145
	ds_read2_b32 v[12:13], v12 offset1:1
	ds_bpermute_b32 v24, v1, v8
	ds_bpermute_b32 v25, v1, v9
	v_cvt_pk_bf16_f32 v8, v8, v9
	s_waitcnt lgkmcnt(0)
; __device__ __forceinline__ unsigned pk2(float lo, float hi) { const f32x2_t v = {lo, hi}; const bf16x2_t b = __builtin_convertvector(v, bf16x2_t); return __builtin_bit_cast(unsigned, b); }
; __device__ __forceinline__ float sigmoidf_(float x) { return __builtin_amdgcn_rcpf(1.0f + __expf(-x)); }
; __device__ __forceinline__ float bcast15(float v, int lane) { return bperm_f((lane & 48) | 15, v); }
; __device__ __forceinline__ void w_lru_m1(const Args& a, int l, unsigned char* ws, const bf16_t* proj, bf16_t* y, LAS unsigned char* wl, int b, int ck_, int h, int lane) {
;     ...
;         for (int tb = 0; tb < 4; ++tb) { const int tok = 16 * tb + lo;
;             f32x4 ga = {0.f, 0.f, 0.f, 0.f}, gx = {0.f, 0.f, 0.f, 0.f};
; #pragma unroll
;             for (int kk = 0; kk < 2; ++kk) { ga = __builtin_amdgcn_mfma_f32_16x16x32_bf16(WaF[kk], Xf[tb][kk], ga, 0, 0, 0); gx = __builtin_amdgcn_mfma_f32_16x16x32_bf16(WxF[kk], Xf[tb][kk], gx, 0, 0, 0); }
;             float hv[4], pv[4];
; #pragma unroll
;             for (int r = 0; r < 4; ++r) {
;                 const float rg = sigmoidf_(ga[r] + bav[r]), ig = sigmoidf_(gx[r] + bxv[r]);
;                 const float la = -8.0f * rg * sp[r]; float A = __expf(la);
;                 float U = __builtin_amdgcn_sqrtf(1.0f - A * A) * (ig * xcf[tok * 65 + j0 + r]);
;                 { const float As = dpp_shr1<1>(A), Us = dpp_shr0<1>(U); U = A * Us + U; A = A * As; }
;                 { const float As = dpp_shr1<2>(A), Us = dpp_shr0<2>(U); U = A * Us + U; A = A * As; }
;                 { const float As = dpp_shr1<4>(A), Us = dpp_shr0<4>(U); U = A * Us + U; A = A * As; }
;                 { const float As = dpp_shr1<8>(A), Us = dpp_shr0<8>(U); U = A * Us + U; A = A * As; }
;                 const float hh = U + A * hc[r], PP = A * Pc[r];
;                 hc[r] = bcast15(hh, lane); Pc[r] = bcast15(PP, lane); hv[r] = hh; pv[r] = PP; }
;             *(unsigned long long*)(y + (size_t)(row0 + tok) * DM + 64 * h + j0) = (unsigned long long)pk2(hv[0], hv[1]) | ((unsigned long long)pk2(hv[2], hv[3]) << 32);
;             *(unsigned long long*)((bf16_t*)(ws + WS_P) + (size_t)(row0 + tok) * 512 + 64 * h + j0) = (unsigned long long)pk2(pv[0], pv[1]) | ((unsigned long long)pk2(pv[2], pv[3]) << 32);
	v_pk_mul_f32 v[10:11], v[12:13], v[10:11]
	s_nop 0
	v_pk_mul_f32 v[10:11], v[10:11], v[30:31]
	v_mov_b32_e32 v30, 1.0
	v_mov_b32_e32 v31, 1.0
	v_mov_b32_dpp v12, v10 row_shr:1 row_mask:0xf bank_mask:0xf bound_ctrl:1
	v_mov_b32_dpp v13, v11 row_shr:1 row_mask:0xf bank_mask:0xf bound_ctrl:1
	v_pk_fma_f32 v[10:11], v[16:17], v[12:13], v[10:11]
	s_nop 1
	v_mov_b32_dpp v12, v10 row_shr:2 row_mask:0xf bank_mask:0xf bound_ctrl:1
	v_mov_b32_dpp v13, v11 row_shr:2 row_mask:0xf bank_mask:0xf bound_ctrl:1
	v_pk_fma_f32 v[10:11], v[34:35], v[12:13], v[10:11]
	s_nop 1
	v_mov_b32_dpp v12, v10 row_shr:4 row_mask:0xf bank_mask:0xf bound_ctrl:1
	v_mov_b32_dpp v13, v11 row_shr:4 row_mask:0xf bank_mask:0xf bound_ctrl:1
	v_pk_fma_f32 v[10:11], v[44:45], v[12:13], v[10:11]
	s_nop 1
	v_mov_b32_dpp v12, v10 row_shr:8 row_mask:0xf bank_mask:0xf bound_ctrl:1
	v_mov_b32_dpp v13, v11 row_shr:8 row_mask:0xf bank_mask:0xf bound_ctrl:1
	v_pk_fma_f32 v[10:11], v[46:47], v[12:13], v[10:11]
	v_add_f32_e32 v12, v42, v32
	v_mul_f32_e32 v12, 0xbfb8aa3b, v12
	v_exp_f32_e32 v12, v12
	v_pk_fma_f32 v[10:11], v[48:49], v[28:29], v[10:11]
	v_mov_b32_e32 v32, 1.0
	ds_bpermute_b32 v16, v1, v10
	v_add_f32_e32 v12, 1.0, v12
	v_rcp_f32_e32 v13, v12
	v_add_f32_e32 v12, v38, v26
	v_mul_f32_e32 v12, 0xbfb8aa3b, v12
	v_exp_f32_e32 v12, v12
	v_mul_f32_e32 v13, 0xc1000000, v13
	v_mul_f32_e32 v13, v2, v13
	v_mul_f32_e32 v13, 0x3fb8aa3b, v13
	v_exp_f32_e32 v26, v13
	v_add_f32_e32 v12, 1.0, v12
	v_rcp_f32_e32 v12, v12
	ds_bpermute_b32 v17, v1, v11
	v_fma_f32 v13, -v26, v26, 1.0
	v_sqrt_f32_e32 v28, v13
	v_add_f32_e32 v13, v43, v33
	v_mul_f32_e32 v13, 0xbfb8aa3b, v13
	v_exp_f32_e32 v13, v13
	v_mov_b32_dpp v30, v26 row_shr:1 row_mask:0xf bank_mask:0xf
	v_mov_b32_e32 v33, 1.0
	v_cvt_pk_bf16_f32 v10, v10, v11
	v_add_f32_e32 v13, 1.0, v13
	v_rcp_f32_e32 v29, v13
	v_add_f32_e32 v13, v39, v27
	v_mul_f32_e32 v13, 0xbfb8aa3b, v13
	v_exp_f32_e32 v13, v13
	v_mul_f32_e32 v27, 0xc1000000, v29
	v_mul_f32_e32 v27, v59, v27
	v_mul_f32_e32 v27, 0x3fb8aa3b, v27
	v_exp_f32_e32 v27, v27
	v_add_f32_e32 v13, 1.0, v13
	v_rcp_f32_e32 v13, v13
	v_mov_b32_dpp v31, v27 row_shr:1 row_mask:0xf bank_mask:0xf
	v_pk_mul_f32 v[30:31], v[26:27], v[30:31]
	v_fma_f32 v29, -v27, v27, 1.0
	v_sqrt_f32_e32 v29, v29
	v_mov_b32_dpp v32, v30 row_shr:2 row_mask:0xf bank_mask:0xf
	v_mov_b32_dpp v33, v31 row_shr:2 row_mask:0xf bank_mask:0xf
	v_pk_mul_f32 v[34:35], v[30:31], v[32:33]
	v_mov_b32_e32 v32, 1.0
	v_mov_b32_e32 v33, 1.0
	s_nop 0
	v_mov_b32_dpp v32, v34 row_shr:4 row_mask:0xf bank_mask:0xf
	v_mov_b32_dpp v33, v35 row_shr:4 row_mask:0xf bank_mask:0xf
	v_pk_mul_f32 v[44:45], v[34:35], v[32:33]
	v_mov_b32_e32 v32, 1.0
	v_mov_b32_e32 v33, 1.0
	s_nop 0
	v_mov_b32_dpp v32, v44 row_shr:8 row_mask:0xf bank_mask:0xf
	v_mov_b32_dpp v33, v45 row_shr:8 row_mask:0xf bank_mask:0xf
	v_pk_mul_f32 v[46:47], v[44:45], v[32:33]
	v_add_u32_e32 v33, 0x2148, v145
	ds_read2_b32 v[48:49], v33 offset1:1
	v_pk_mul_f32 v[14:15], v[46:47], v[14:15]
	ds_bpermute_b32 v32, v1, v14
	v_cvt_pk_bf16_f32 v9, v14, v15
	ds_bpermute_b32 v33, v1, v15
	s_waitcnt lgkmcnt(0)
	v_pk_mul_f32 v[12:13], v[12:13], v[48:49]
	s_nop 0
	v_pk_mul_f32 v[12:13], v[28:29], v[12:13]
	s_nop 1
	v_mov_b32_dpp v28, v12 row_shr:1 row_mask:0xf bank_mask:0xf bound_ctrl:1
	v_mov_b32_dpp v29, v13 row_shr:1 row_mask:0xf bank_mask:0xf bound_ctrl:1
	v_pk_fma_f32 v[12:13], v[26:27], v[28:29], v[12:13]
	s_nop 1
	v_mov_b32_dpp v26, v12 row_shr:2 row_mask:0xf bank_mask:0xf bound_ctrl:1
	v_mov_b32_dpp v27, v13 row_shr:2 row_mask:0xf bank_mask:0xf bound_ctrl:1
	v_pk_fma_f32 v[12:13], v[30:31], v[26:27], v[12:13]
	s_nop 1
	v_mov_b32_dpp v26, v12 row_shr:4 row_mask:0xf bank_mask:0xf bound_ctrl:1
	v_mov_b32_dpp v27, v13 row_shr:4 row_mask:0xf bank_mask:0xf bound_ctrl:1
	v_pk_fma_f32 v[12:13], v[34:35], v[26:27], v[12:13]
	s_nop 1
	v_mov_b32_dpp v26, v12 row_shr:8 row_mask:0xf bank_mask:0xf bound_ctrl:1
	v_mov_b32_dpp v27, v13 row_shr:8 row_mask:0xf bank_mask:0xf bound_ctrl:1
	v_pk_fma_f32 v[12:13], v[44:45], v[26:27], v[12:13]
	s_nop 0
	v_pk_fma_f32 v[18:19], v[46:47], v[18:19], v[12:13]
	ds_bpermute_b32 v12, v1, v18
	v_cvt_pk_bf16_f32 v11, v18, v19
	global_store_dwordx2 v[96:97], v[10:11], off offset:96
	global_store_dwordx2 v[98:99], v[8:9], off offset:96
	v_mfma_f32_16x16x32_bf16 v[8:11], v[68:71], v[4:7], 0
	ds_bpermute_b32 v13, v1, v19
	v_mfma_f32_16x16x32_bf16 v[4:7], v[72:75], v[4:7], 0
	v_mfma_f32_16x16x32_bf16 v[8:11], v[76:79], v[20:23], v[8:11]
	v_mfma_f32_16x16x32_bf16 v[4:7], v[80:83], v[20:23], v[4:7]
	s_nop 6
	v_add_f32_e32 v8, v40, v8
	v_mul_f32_e32 v8, 0xbfb8aa3b, v8
	v_exp_f32_e32 v8, v8
	v_add_f32_e32 v4, v36, v4
	v_add_f32_e32 v9, v41, v9
	v_mul_f32_e32 v4, 0xbfb8aa3b, v4
	v_mul_f32_e32 v9, 0xbfb8aa3b, v9
	v_add_f32_e32 v8, 1.0, v8
	v_exp_f32_e32 v4, v4
	v_exp_f32_e32 v9, v9
	v_rcp_f32_e32 v14, v8
	v_add_f32_e32 v5, v37, v5
	v_mul_f32_e32 v5, 0xbfb8aa3b, v5
	v_add_f32_e32 v4, 1.0, v4
	v_add_f32_e32 v9, 1.0, v9
	v_exp_f32_e32 v5, v5
	v_rcp_f32_e32 v8, v4
	v_mul_f32_e32 v4, 0xc1000000, v14
	v_rcp_f32_e32 v14, v9
	v_add_f32_e32 v5, 1.0, v5
	v_rcp_f32_e32 v9, v5
	v_mul_f32_e32 v4, v58, v4
	v_mul_f32_e32 v5, 0xc1000000, v14
	v_mul_f32_e32 v5, v60, v5
	v_mul_f32_e32 v4, 0x3fb8aa3b, v4
	v_mul_f32_e32 v5, 0x3fb8aa3b, v5
	v_exp_f32_e32 v18, v4
	v_exp_f32_e32 v19, v5
	v_add_f32_e32 v10, v42, v10
	v_mul_f32_e32 v10, 0xbfb8aa3b, v10
	v_fma_f32 v4, -v18, v18, 1.0
	v_fma_f32 v5, -v19, v19, 1.0
	v_sqrt_f32_e32 v20, v4
	v_mov_b32_e32 v4, 1.0
	v_sqrt_f32_e32 v21, v5
	v_mov_b32_e32 v5, 1.0
	v_mov_b32_dpp v4, v18 row_shr:1 row_mask:0xf bank_mask:0xf
	v_exp_f32_e32 v10, v10
	v_mov_b32_dpp v5, v19 row_shr:1 row_mask:0xf bank_mask:0xf
	v_pk_mul_f32 v[22:23], v[18:19], v[4:5]
	v_mov_b32_e32 v4, 1.0
	v_mov_b32_e32 v5, 1.0
	v_add_f32_e32 v6, v38, v6
	v_mov_b32_dpp v4, v22 row_shr:2 row_mask:0xf bank_mask:0xf
	v_mov_b32_dpp v5, v23 row_shr:2 row_mask:0xf bank_mask:0xf
	v_pk_mul_f32 v[26:27], v[22:23], v[4:5]
	v_mov_b32_e32 v4, 1.0
	v_mov_b32_e32 v5, 1.0
	v_mul_f32_e32 v6, 0xbfb8aa3b, v6
	v_mov_b32_dpp v4, v26 row_shr:4 row_mask:0xf bank_mask:0xf
	v_mov_b32_dpp v5, v27 row_shr:4 row_mask:0xf bank_mask:0xf
	v_pk_mul_f32 v[28:29], v[26:27], v[4:5]
	v_mov_b32_e32 v4, 1.0
	v_mov_b32_e32 v5, 1.0
	v_add_f32_e32 v10, 1.0, v10
	v_mov_b32_dpp v4, v28 row_shr:8 row_mask:0xf bank_mask:0xf
	v_mov_b32_dpp v5, v29 row_shr:8 row_mask:0xf bank_mask:0xf
	v_pk_mul_f32 v[30:31], v[28:29], v[4:5]
	v_add_u32_e32 v5, 0x3180, v145
	v_pk_mul_f32 v[14:15], v[30:31], v[24:25]
	ds_read2_b32 v[24:25], v5 offset1:1
	v_exp_f32_e32 v6, v6
	v_rcp_f32_e32 v10, v10
	v_add_f32_e32 v7, v39, v7
	v_mul_f32_e32 v7, 0xbfb8aa3b, v7
	s_waitcnt lgkmcnt(0)
; __device__ __forceinline__ unsigned pk2(float lo, float hi) { const f32x2_t v = {lo, hi}; const bf16x2_t b = __builtin_convertvector(v, bf16x2_t); return __builtin_bit_cast(unsigned, b); }
; __device__ __forceinline__ float bcast15(float v, int lane) { return bperm_f((lane & 48) | 15, v); }
; __device__ __forceinline__ void w_lru_m1(const Args& a, int l, unsigned char* ws, const bf16_t* proj, bf16_t* y, LAS unsigned char* wl, int b, int ck_, int h, int lane) {
;     ...
;                 { const float As = dpp_shr1<1>(A), Us = dpp_shr0<1>(U); U = A * Us + U; A = A * As; }
;                 { const float As = dpp_shr1<2>(A), Us = dpp_shr0<2>(U); U = A * Us + U; A = A * As; }
;                 { const float As = dpp_shr1<4>(A), Us = dpp_shr0<4>(U); U = A * Us + U; A = A * As; }
;                 { const float As = dpp_shr1<8>(A), Us = dpp_shr0<8>(U); U = A * Us + U; A = A * As; }
;                 const float hh = U + A * hc[r], PP = A * Pc[r];
;                 hc[r] = bcast15(hh, lane); Pc[r] = bcast15(PP, lane); hv[r] = hh; pv[r] = PP; }
;             *(unsigned long long*)(y + (size_t)(row0 + tok) * DM + 64 * h + j0) = (unsigned long long)pk2(hv[0], hv[1]) | ((unsigned long long)pk2(hv[2], hv[3]) << 32);
;             *(unsigned long long*)((bf16_t*)(ws + WS_P) + (size_t)(row0 + tok) * 512 + 64 * h + j0) = (unsigned long long)pk2(pv[0], pv[1]) | ((unsigned long long)pk2(pv[2], pv[3]) << 32);
;         }
;         if (lo == 0) { const size_t so = (size_t)(b * NCH + ck_) * 512 + 64 * h + j0;
; #pragma unroll
;             for (int r = 0; r < 4; ++r) { ((float*)(ws + WS_LRUA))[so + r] = Pc[r]; ((float*)(ws + WS_LRUH))[so + r] = hc[r]; } }
	v_pk_mul_f32 v[8:9], v[24:25], v[8:9]
	v_add_f32_e32 v6, 1.0, v6
	v_pk_mul_f32 v[8:9], v[8:9], v[20:21]
	v_exp_f32_e32 v7, v7
	ds_bpermute_b32 v4, v1, v14
	v_mov_b32_dpp v20, v8 row_shr:1 row_mask:0xf bank_mask:0xf bound_ctrl:1
	v_mov_b32_dpp v21, v9 row_shr:1 row_mask:0xf bank_mask:0xf bound_ctrl:1
	v_pk_fma_f32 v[8:9], v[18:19], v[20:21], v[8:9]
	v_add_f32_e32 v7, 1.0, v7
	ds_bpermute_b32 v5, v1, v15
	v_mov_b32_dpp v18, v8 row_shr:2 row_mask:0xf bank_mask:0xf bound_ctrl:1
	v_mov_b32_dpp v19, v9 row_shr:2 row_mask:0xf bank_mask:0xf bound_ctrl:1
	v_pk_fma_f32 v[8:9], v[22:23], v[18:19], v[8:9]
	s_nop 1
	v_mov_b32_dpp v18, v8 row_shr:4 row_mask:0xf bank_mask:0xf bound_ctrl:1
	v_mov_b32_dpp v19, v9 row_shr:4 row_mask:0xf bank_mask:0xf bound_ctrl:1
	v_pk_fma_f32 v[8:9], v[26:27], v[18:19], v[8:9]
	s_nop 1
	v_mov_b32_dpp v18, v8 row_shr:8 row_mask:0xf bank_mask:0xf bound_ctrl:1
	v_mov_b32_dpp v19, v9 row_shr:8 row_mask:0xf bank_mask:0xf bound_ctrl:1
	v_pk_fma_f32 v[8:9], v[28:29], v[18:19], v[8:9]
	v_rcp_f32_e32 v18, v6
	v_mul_f32_e32 v6, 0xc1000000, v10
	v_mul_f32_e32 v2, v2, v6
	v_mul_f32_e32 v2, 0x3fb8aa3b, v2
	v_exp_f32_e32 v10, v2
	v_mov_b32_e32 v6, 1.0
	v_rcp_f32_e32 v19, v7
	v_mov_b32_e32 v7, 1.0
	v_fma_f32 v2, -v10, v10, 1.0
	v_sqrt_f32_e32 v20, v2
	v_add_f32_e32 v2, v43, v11
	v_mul_f32_e32 v2, 0xbfb8aa3b, v2
	v_exp_f32_e32 v2, v2
	v_mov_b32_dpp v6, v10 row_shr:1 row_mask:0xf bank_mask:0xf
	v_pk_fma_f32 v[16:17], v[30:31], v[16:17], v[8:9]
	ds_bpermute_b32 v8, v1, v16
	v_add_f32_e32 v2, 1.0, v2
	v_rcp_f32_e32 v2, v2
	ds_bpermute_b32 v9, v1, v17
	v_cvt_pk_bf16_f32 v16, v16, v17
	v_mul_f32_e32 v2, 0xc1000000, v2
	v_mul_f32_e32 v2, v59, v2
	v_mul_f32_e32 v2, 0x3fb8aa3b, v2
	v_exp_f32_e32 v11, v2
	s_nop 0
	v_fma_f32 v2, -v11, v11, 1.0
	v_mov_b32_dpp v7, v11 row_shr:1 row_mask:0xf bank_mask:0xf
	v_pk_mul_f32 v[24:25], v[10:11], v[6:7]
	v_mov_b32_e32 v6, 1.0
	v_mov_b32_e32 v7, 1.0
	v_sqrt_f32_e32 v21, v2
	v_mov_b32_dpp v6, v24 row_shr:2 row_mask:0xf bank_mask:0xf
	v_mov_b32_dpp v7, v25 row_shr:2 row_mask:0xf bank_mask:0xf
	v_pk_mul_f32 v[26:27], v[24:25], v[6:7]
	v_mov_b32_e32 v6, 1.0
	v_mov_b32_e32 v7, 1.0
	v_add_u32_e32 v2, 0x3188, v145
	v_mov_b32_dpp v6, v26 row_shr:4 row_mask:0xf bank_mask:0xf
	v_mov_b32_dpp v7, v27 row_shr:4 row_mask:0xf bank_mask:0xf
	v_pk_mul_f32 v[28:29], v[26:27], v[6:7]
	v_mov_b32_e32 v6, 1.0
	v_mov_b32_e32 v7, 1.0
	s_nop 0
	v_mov_b32_dpp v6, v28 row_shr:8 row_mask:0xf bank_mask:0xf
	v_mov_b32_dpp v7, v29 row_shr:8 row_mask:0xf bank_mask:0xf
	v_pk_mul_f32 v[30:31], v[28:29], v[6:7]
	s_nop 0
	v_pk_mul_f32 v[22:23], v[30:31], v[32:33]
	ds_read2_b32 v[32:33], v2 offset1:1
	ds_bpermute_b32 v6, v1, v22
	ds_bpermute_b32 v7, v1, v23
	s_waitcnt lgkmcnt(0)
	v_pk_mul_f32 v[18:19], v[18:19], v[32:33]
	s_nop 0
	v_pk_mul_f32 v[18:19], v[20:21], v[18:19]
	s_nop 1
	v_mov_b32_dpp v20, v18 row_shr:1 row_mask:0xf bank_mask:0xf bound_ctrl:1
	v_mov_b32_dpp v21, v19 row_shr:1 row_mask:0xf bank_mask:0xf bound_ctrl:1
	v_pk_fma_f32 v[10:11], v[10:11], v[20:21], v[18:19]
	s_nop 1
	v_mov_b32_dpp v18, v10 row_shr:2 row_mask:0xf bank_mask:0xf bound_ctrl:1
	v_mov_b32_dpp v19, v11 row_shr:2 row_mask:0xf bank_mask:0xf bound_ctrl:1
	v_pk_fma_f32 v[10:11], v[24:25], v[18:19], v[10:11]
	s_nop 1
	v_mov_b32_dpp v18, v10 row_shr:4 row_mask:0xf bank_mask:0xf bound_ctrl:1
	v_mov_b32_dpp v19, v11 row_shr:4 row_mask:0xf bank_mask:0xf bound_ctrl:1
	v_pk_fma_f32 v[10:11], v[26:27], v[18:19], v[10:11]
	s_nop 1
	v_mov_b32_dpp v18, v10 row_shr:8 row_mask:0xf bank_mask:0xf bound_ctrl:1
	v_mov_b32_dpp v19, v11 row_shr:8 row_mask:0xf bank_mask:0xf bound_ctrl:1
	v_pk_fma_f32 v[10:11], v[28:29], v[18:19], v[10:11]
	s_nop 0
	v_pk_fma_f32 v[12:13], v[30:31], v[12:13], v[10:11]
	ds_bpermute_b32 v10, v1, v12
	ds_bpermute_b32 v11, v1, v13
	v_cvt_pk_bf16_f32 v17, v12, v13
	v_cvt_pk_bf16_f32 v12, v14, v15
	v_cvt_pk_bf16_f32 v13, v22, v23
	global_store_dwordx2 v[114:115], v[16:17], off offset:96
	global_store_dwordx2 v[116:117], v[12:13], off offset:96
	s_and_saveexec_b64 s[34:35], vcc
	s_cbranch_execz .LBB0_518
	v_add_u32_e32 v0, 48, v0
	v_ashrrev_i32_e32 v1, 31, v0
	v_lshl_add_u64 v[0:1], s[42:43], 0, v[0:1]
	v_lshlrev_b64 v[0:1], 2, v[0:1]
	v_lshl_add_u64 v[12:13], s[84:85], 0, v[0:1]
	v_lshl_add_u64 v[0:1], s[86:87], 0, v[0:1]
	global_store_dwordx4 v[12:13], v[4:7], off
	s_waitcnt lgkmcnt(0)
	global_store_dwordx4 v[0:1], v[8:11], off
	s_branch .LBB0_518
